# GEMM DMA loads use SGPR base + 32-bit VGPR offset (drops the 64-bit VALU address add per load) on top of the two barrier changes
# baseline (speedup 1.0000x reference)
; #define PG8_STAGE(bufoff, gbase, voff) do { _Pragma("unroll") for (int _i = 0; _i < 2; ++_i) \
;         __builtin_amdgcn_global_load_lds((const unsigned*)((const char*)(gbase) + (voff)[_i]), (LAS unsigned*)(lds + (bufoff) + ldsw + _i * 8192), 16, 0, 0); } while (0)
; #define PG8_WAIT_V(n) asm volatile("s_waitcnt vmcnt(" #n ")" ::: "memory")
; #define PG8_BAR __builtin_amdgcn_s_barrier()
; template <class Epi, class Sched, bool ABLK = false, bool ALIGN_EPI = true, bool SP2 = true, bool BBLK = true>
; __device__ __forceinline__ void gemm_phase(LAS unsigned char* lds, const Gemm g, const Sched& S, const Epi& E) {
;     ...
;     const int aoff = lds_byte(wr * 64 + fr, fq * 8), boff = lds_byte(wc * 32 + fr, fq * 8);
;     ...
;     Unit cur, nxt; int ui = 0;
;     if (!S.next(0, cur)) return;
;     f32x4 acc[2][2][4][2];
; #pragma unroll
;     for (int a = 0; a < 2; ++a)
; #pragma unroll
;         for (int b = 0; b < 2; ++b)
; #pragma unroll
;             for (int m = 0; m < 4; ++m)
; #pragma unroll
;                 for (int n = 0; n < 2; ++n) acc[a][b][m][n] = (f32x4){0.f, 0.f, 0.f, 0.f};
;     bf16x8 At[4][2], B0[2][2], B1[2][2];
;     auto a_unit = [&](const Unit& u) -> const char* { return ABLK ? (const char*)g.A + (size_t)u.pm * ((size_t)g.lda / 64) * 32768 : (const char*)g.A + (size_t)u.pm * 2 * hstepA; };
;     auto a_tile = [&](const char* ub, int tau) -> const char* { return ub + (size_t)tau * (ABLK ? (size_t)32768 : kstep); };
;     const char* uA = a_unit(cur); int tbA = cur.k0 / BK;
;     const char* cA = a_tile(uA, tbA); const char* cB = (const char*)g.Bt + (size_t)cur.pn * tstepB + b_k0(cur.k0);
;     S.a_ready(cur);
;     if constexpr (SP2) {
;         PG8_STAGE(PG8_SB(0, 0), cB, voffB); PG8_STAGE(PG8_SB(0, 1), cB + hstepB, voffB); PG8_STAGE(PG8_SA(0, 0), cA, voffA); PG8_STAGE(PG8_SA(0, 1), cA + hstepA, voffA);
;         if (wr == 1) PG8_BAR;
;         PG8_WAIT_V(2); PG8_BAR;
;         PG8_STAGE(PG8_SB(1, 0), cB + kstepB, voffB); PG8_STAGE(PG8_SA(1, 0), a_tile(uA, tbA + 1), voffA); PG8_STAGE(PG8_SB(1, 1), cB + hstepB + kstepB, voffB);
;         PG8_WAIT_V(6); PG8_BAR;
.LBB0_344:
	s_lshl_b32 s6, s6, 5
	s_and_b32 s9, s6, 0x60
	s_lshl_b32 s8, s5, 13
	s_lshl_b32 s10, s9, 7
	s_add_u32 s6, s26, 0x8000
	s_addc_u32 s7, s27, 0
	s_add_i32 m0, s21, 0x18000
	s_waitcnt vmcnt(0)
	v_lshl_add_u64 v[14:15], s[6:7], 0, v[134:135]
	s_waitcnt vmcnt(2)
	s_barrier
	global_load_lds_dwordx4 v[14:15], off
	v_lshl_add_u64 v[14:15], s[6:7], 0, v[130:131]
	s_add_i32 m0, s21, 0x1a000
	s_mov_b64 s[6:7], 0x80
	s_add_i32 s42, s21, 0x8000
	global_load_lds_dwordx4 v[14:15], off
	v_lshl_add_u64 v[2:3], v[2:3], 0, s[6:7]
	s_mov_b32 m0, s42
	s_add_i32 s43, s21, 0xa000
	global_load_lds_dwordx4 v[2:3], off
	v_lshl_add_u64 v[2:3], v[4:5], 0, s[6:7]
	s_add_u32 s6, s26, 0xc000
	s_mov_b32 m0, s43
	s_addc_u32 s7, s27, 0
	global_load_lds_dwordx4 v[2:3], off
	s_add_i32 m0, s21, 0x1c000
	s_nop 0
	global_load_lds_dwordx4 v134, s[6:7]
	s_add_i32 m0, s21, 0x1e000
	s_cmpk_lt_u32 s4, 0x100
	global_load_lds_dwordx4 v130, s[6:7]
	v_lshrrev_b32_e32 v3, 1, v6
	v_and_b32_e32 v3, 24, v3
	v_and_b32_e32 v2, 15, v6
	v_lshlrev_b32_e32 v4, 1, v3
	v_lshl_or_b32 v1, s5, 6, v2
	v_lshl_or_b32 v2, v2, 6, v4
	v_lshlrev_b32_e32 v4, 2, v6
	v_and_b32_e32 v4, 32, v4
	v_bitop3_b32 v5, v2, s8, v4 bitop3:0xde
	v_bitop3_b32 v146, v2, s10, v4 bitop3:0xde
	v_lshlrev_b32_e32 v2, 15, v10
	v_and_b32_e32 v2, 0xffff0000, v2
	v_or_b32_e32 v147, s9, v3
	v_lshl_add_u32 v2, v11, 12, v2
	v_and_b32_e32 v3, 1, v10
	v_lshl_or_b32 v2, v3, 6, v2
	v_lshl_add_u32 v2, v12, 1, v2
	v_mov_b32_e32 v3, v135
	s_mov_b64 s[4:5], 0x80080
	v_lshl_add_u64 v[138:139], v[2:3], 0, s[4:5]
	v_lshlrev_b32_e32 v2, 15, v7
	v_and_b32_e32 v2, 0xffff0000, v2
	v_lshl_add_u32 v2, v8, 12, v2
	v_and_b32_e32 v3, 1, v7
	s_waitcnt vmcnt(6)
	v_lshl_or_b32 v2, v3, 6, v2
	s_cselect_b64 s[6:7], -1, 0
	v_lshl_add_u32 v2, v9, 1, v2
	v_mov_b32_e32 v3, v135
	s_add_i32 s44, 0, 0x10000
	s_add_i32 s45, 0, 0x14000
	v_lshl_add_u64 v[140:141], v[2:3], 0, s[4:5]
	v_add_u32_e32 v148, s44, v146
	v_add_u32_e32 v149, s45, v146
	v_add_u32_e32 v150, 0, v5
	s_mov_b32 s46, 0x80000
	s_mov_b32 s47, 0x90000
	s_mov_b32 s48, 0xa0000
	s_add_i32 s49, s21, 0xc000
	s_barrier
	s_branch .LBB0_347

; #define PG8_STAGE(bufoff, gbase, voff) do { _Pragma("unroll") for (int _i = 0; _i < 2; ++_i) \
;         __builtin_amdgcn_global_load_lds((const unsigned*)((const char*)(gbase) + (voff)[_i]), (LAS unsigned*)(lds + (bufoff) + ldsw + _i * 8192), 16, 0, 0); } while (0)
; #define PG8_LDA(dst, b, h) do { _Pragma("unroll") for (int m = 0; m < 4; ++m) _Pragma("unroll") for (int k = 0; k < 2; ++k) dst[m][k] = *(const LAS bf16x8*)(lds + PG8_SA(b, h) + aoff + m * 2048 + k * 1024); } while (0)
; #define PG8_LDB(dst, b, h) do { _Pragma("unroll") for (int n = 0; n < 2; ++n) _Pragma("unroll") for (int k = 0; k < 2; ++k) dst[n][k] = *(const LAS bf16x8*)(lds + PG8_SB(b, h) + boff + n * 2048 + k * 1024); } while (0)
; #define PG8_MMA(ai, bj, At, Bt) do { __builtin_amdgcn_s_setprio(1); _Pragma("unroll") for (int m = 0; m < 4; ++m) _Pragma("unroll") for (int n = 0; n < 2; ++n) _Pragma("unroll") for (int k = 0; k < 2; ++k) \
;         acc[ai][bj][m][n] = __builtin_amdgcn_mfma_f32_16x16x32_bf16(Bt[n][k], At[m][k], acc[ai][bj][m][n], 0, 0, 0); __builtin_amdgcn_s_setprio(0); } while (0)
; #define PG8_WAIT_V(n) asm volatile("s_waitcnt vmcnt(" #n ")" ::: "memory")
; #define PG8_WAIT_L(n) asm volatile("s_waitcnt lgkmcnt(" #n ")" ::: "memory")
; #define PG8_BAR __builtin_amdgcn_s_barrier()
; #define PG8_SCHED __builtin_amdgcn_sched_barrier(0)
; template <class Epi, class Sched, bool ABLK = false, bool ALIGN_EPI = true, bool SP2 = true, bool BBLK = true>
; __device__ __forceinline__ void gemm_phase(LAS unsigned char* lds, const Gemm g, const Sched& S, const Epi& E) {
;     ...
;             const char* a1 = a_tile(uA, tbA + t + 1);
;             const char* a2 = last ? a_tile(nuA, ntbA) : a_tile(uA, tbA + t + 2); const char* b2 = last ? nB : cB + (size_t)(t + 2) * kstepB;
;             const char* a3 = last ? a_tile(nuA, ntbA + 1) : a_tile(uA, tbA + t + 3); const char* b3 = b2 + kstepB;
;             if (last && has_next) S.a_ready(nxt);
;             if constexpr (SP2) {
;             PG8_LDB(B0, 0, 0); PG8_LDB(B1, 0, 1); PG8_SCHED; PG8_LDA(At, 0, 0); PG8_STAGE(PG8_SA(1, 1), a1 + hstepA, voffA);
;             PG8_WAIT_V(8); PG8_WAIT_L(0); PG8_BAR; PG8_MMA(0, 0, At, B0); PG8_MMA(0, 1, At, B1); PG8_BAR; PG8_SCHED;
;             PG8_LDA(At, 0, 1); PG8_STAGE(PG8_SB(0, 0), b2, voffB); PG8_STAGE(PG8_SB(0, 1), b2 + hstepB, voffB); PG8_STAGE(PG8_SA(0, 0), a2, voffA);
.LBB0_350:
	ds_read_b128 v[152:155], v148
	ds_read_b128 v[156:159], v148 offset:1024
	ds_read_b128 v[160:163], v148 offset:2048
	ds_read_b128 v[164:167], v148 offset:3072
	ds_read_b128 v[168:171], v149
	ds_read_b128 v[172:175], v149 offset:1024
	ds_read_b128 v[176:179], v149 offset:2048
	ds_read_b128 v[180:183], v149 offset:3072
	s_add_u32 s28, s24, s26
	s_addc_u32 s29, s25, s27
	s_add_u32 s34, s28, 0x100
	s_addc_u32 s35, s29, 0
	s_add_u32 s28, s28, 0x180
	s_addc_u32 s29, s29, 0
	s_cmpk_eq_i32 s26, 0xf00
	s_cselect_b32 s29, s51, s29
	s_cselect_b32 s28, s50, s28
	s_cselect_b32 s31, s9, s53
	s_cselect_b32 s30, s11, s52
	s_cselect_b32 s35, s4, s35
	s_cselect_b32 s34, s5, s34
	s_mov_b32 m0, s49
	v_lshl_add_u64 v[216:217], v[142:143], 0, s[26:27]
	ds_read_b128 v[184:187], v150
	ds_read_b128 v[188:191], v150 offset:1024
	ds_read_b128 v[192:195], v150 offset:2048
	ds_read_b128 v[196:199], v150 offset:3072
	ds_read_b128 v[200:203], v150 offset:4096
	ds_read_b128 v[204:207], v150 offset:5120
	ds_read_b128 v[208:211], v150 offset:6144
	ds_read_b128 v[212:215], v150 offset:7168
	global_load_lds_dwordx4 v[216:217], off
	v_lshl_add_u64 v[216:217], v[144:145], 0, s[26:27]
	s_add_i32 m0, s21, 0xe000
	s_nop 0
	global_load_lds_dwordx4 v[216:217], off
	s_waitcnt vmcnt(8)
	s_waitcnt lgkmcnt(0)
	s_barrier
	s_setprio 1
	s_waitcnt lgkmcnt(0)
	v_mfma_f32_16x16x32_bf16 v[122:125], v[152:155], v[184:187], v[122:125]
	v_mfma_f32_16x16x32_bf16 v[118:121], v[160:163], v[184:187], v[118:121]
	v_mfma_f32_16x16x32_bf16 v[106:109], v[152:155], v[192:195], v[106:109]
	v_mfma_f32_16x16x32_bf16 v[102:105], v[160:163], v[192:195], v[102:105]
	v_mfma_f32_16x16x32_bf16 v[90:93], v[152:155], v[200:203], v[90:93]
	v_mfma_f32_16x16x32_bf16 v[86:89], v[160:163], v[200:203], v[86:89]
	v_mfma_f32_16x16x32_bf16 v[74:77], v[152:155], v[208:211], v[74:77]
	v_mfma_f32_16x16x32_bf16 v[70:73], v[160:163], v[208:211], v[70:73]
	v_mfma_f32_16x16x32_bf16 v[122:125], v[156:159], v[188:191], v[122:125]
	v_mfma_f32_16x16x32_bf16 v[118:121], v[164:167], v[188:191], v[118:121]
	v_mfma_f32_16x16x32_bf16 v[106:109], v[156:159], v[196:199], v[106:109]
	v_mfma_f32_16x16x32_bf16 v[102:105], v[164:167], v[196:199], v[102:105]
	v_mfma_f32_16x16x32_bf16 v[90:93], v[156:159], v[204:207], v[90:93]
	v_mfma_f32_16x16x32_bf16 v[86:89], v[164:167], v[204:207], v[86:89]
	v_mfma_f32_16x16x32_bf16 v[74:77], v[156:159], v[212:215], v[74:77]
	v_mfma_f32_16x16x32_bf16 v[70:73], v[164:167], v[212:215], v[70:73]
	s_setprio 0
	s_setprio 1
	v_mfma_f32_16x16x32_bf16 v[126:129], v[168:171], v[184:187], v[126:129]
	v_mfma_f32_16x16x32_bf16 v[114:117], v[176:179], v[184:187], v[114:117]
	v_mfma_f32_16x16x32_bf16 v[110:113], v[168:171], v[192:195], v[110:113]
	v_mfma_f32_16x16x32_bf16 v[98:101], v[176:179], v[192:195], v[98:101]
	v_mfma_f32_16x16x32_bf16 v[94:97], v[168:171], v[200:203], v[94:97]
	v_mfma_f32_16x16x32_bf16 v[82:85], v[176:179], v[200:203], v[82:85]
	v_mfma_f32_16x16x32_bf16 v[78:81], v[168:171], v[208:211], v[78:81]
	v_mfma_f32_16x16x32_bf16 v[66:69], v[176:179], v[208:211], v[66:69]
	v_mfma_f32_16x16x32_bf16 v[126:129], v[172:175], v[188:191], v[126:129]
	v_mfma_f32_16x16x32_bf16 v[114:117], v[180:183], v[188:191], v[114:117]
	v_mfma_f32_16x16x32_bf16 v[110:113], v[172:175], v[196:199], v[110:113]
	v_mfma_f32_16x16x32_bf16 v[98:101], v[180:183], v[196:199], v[98:101]
	v_mfma_f32_16x16x32_bf16 v[94:97], v[172:175], v[204:207], v[94:97]
	v_mfma_f32_16x16x32_bf16 v[82:85], v[180:183], v[204:207], v[82:85]
	v_mfma_f32_16x16x32_bf16 v[78:81], v[172:175], v[212:215], v[78:81]
	v_mfma_f32_16x16x32_bf16 v[66:69], v[180:183], v[212:215], v[66:69]
	s_setprio 0
	s_barrier
	s_add_i32 s55, s44, s33
	s_mov_b32 m0, s55
	ds_read_b128 v[184:187], v150 offset:16384
	ds_read_b128 v[188:191], v150 offset:17408
	ds_read_b128 v[192:195], v150 offset:18432
	ds_read_b128 v[196:199], v150 offset:19456
	ds_read_b128 v[200:203], v150 offset:20480
	ds_read_b128 v[204:207], v150 offset:21504
	ds_read_b128 v[208:211], v150 offset:22528
	ds_read_b128 v[212:215], v150 offset:23552
	global_load_lds_dwordx4 v134, s[30:31]
	s_add_i32 m0, s55, 0x2000
	s_add_u32 s56, s30, 0x4000
	s_addc_u32 s57, s31, 0
	s_add_i32 s55, s45, s33
	global_load_lds_dwordx4 v130, s[30:31]
	s_mov_b32 m0, s55
	s_nop 0
	global_load_lds_dwordx4 v134, s[56:57]
	s_add_i32 m0, s55, 0x2000
	s_nop 0
	global_load_lds_dwordx4 v130, s[56:57]
	s_mov_b32 m0, s21
	s_nop 0
	global_load_lds_dwordx4 v136, s[34:35]
	s_mov_b32 m0, s23
	s_nop 0
	global_load_lds_dwordx4 v132, s[34:35]
	s_waitcnt vmcnt(8)
	s_waitcnt lgkmcnt(0)
	s_barrier
; #define PG8_STAGE(bufoff, gbase, voff) do { _Pragma("unroll") for (int _i = 0; _i < 2; ++_i) \
;         __builtin_amdgcn_global_load_lds((const unsigned*)((const char*)(gbase) + (voff)[_i]), (LAS unsigned*)(lds + (bufoff) + ldsw + _i * 8192), 16, 0, 0); } while (0)
; #define PG8_LDA(dst, b, h) do { _Pragma("unroll") for (int m = 0; m < 4; ++m) _Pragma("unroll") for (int k = 0; k < 2; ++k) dst[m][k] = *(const LAS bf16x8*)(lds + PG8_SA(b, h) + aoff + m * 2048 + k * 1024); } while (0)
; #define PG8_LDB(dst, b, h) do { _Pragma("unroll") for (int n = 0; n < 2; ++n) _Pragma("unroll") for (int k = 0; k < 2; ++k) dst[n][k] = *(const LAS bf16x8*)(lds + PG8_SB(b, h) + boff + n * 2048 + k * 1024); } while (0)
; #define PG8_MMA(ai, bj, At, Bt) do { __builtin_amdgcn_s_setprio(1); _Pragma("unroll") for (int m = 0; m < 4; ++m) _Pragma("unroll") for (int n = 0; n < 2; ++n) _Pragma("unroll") for (int k = 0; k < 2; ++k) \
;         acc[ai][bj][m][n] = __builtin_amdgcn_mfma_f32_16x16x32_bf16(Bt[n][k], At[m][k], acc[ai][bj][m][n], 0, 0, 0); __builtin_amdgcn_s_setprio(0); } while (0)
; #define PG8_WAIT_V(n) asm volatile("s_waitcnt vmcnt(" #n ")" ::: "memory")
; #define PG8_WAIT_L(n) asm volatile("s_waitcnt lgkmcnt(" #n ")" ::: "memory")
; #define PG8_BAR __builtin_amdgcn_s_barrier()
; #define PG8_SCHED __builtin_amdgcn_sched_barrier(0)
; template <class Epi, class Sched, bool ABLK = false, bool ALIGN_EPI = true, bool SP2 = true, bool BBLK = true>
; __device__ __forceinline__ void gemm_phase(LAS unsigned char* lds, const Gemm g, const Sched& S, const Epi& E) {
;     ...
;             PG8_WAIT_V(8); PG8_WAIT_L(0); PG8_BAR; PG8_MMA(1, 0, At, B0); PG8_MMA(1, 1, At, B1); PG8_BAR; PG8_SCHED;
;             PG8_LDB(B0, 1, 0); PG8_LDB(B1, 1, 1); PG8_SCHED; PG8_LDA(At, 1, 0); PG8_STAGE(PG8_SA(0, 1), a2 + hstepA, voffA);
;             PG8_WAIT_V(8); PG8_WAIT_L(0); PG8_BAR; PG8_MMA(0, 0, At, B0); PG8_MMA(0, 1, At, B1); PG8_BAR; PG8_SCHED;
	s_setprio 1
	s_waitcnt lgkmcnt(0)
	v_mfma_f32_16x16x32_bf16 v[58:61], v[152:155], v[184:187], v[58:61]
	v_mfma_f32_16x16x32_bf16 v[54:57], v[160:163], v[184:187], v[54:57]
	v_mfma_f32_16x16x32_bf16 v[42:45], v[152:155], v[192:195], v[42:45]
	v_mfma_f32_16x16x32_bf16 v[38:41], v[160:163], v[192:195], v[38:41]
	v_mfma_f32_16x16x32_bf16 v[26:29], v[152:155], v[200:203], v[26:29]
	v_mfma_f32_16x16x32_bf16 v[22:25], v[160:163], v[200:203], v[22:25]
	v_mfma_f32_16x16x32_bf16 v[10:13], v[152:155], v[208:211], v[10:13]
	v_mfma_f32_16x16x32_bf16 v[6:9], v[160:163], v[208:211], v[6:9]
	v_mfma_f32_16x16x32_bf16 v[58:61], v[156:159], v[188:191], v[58:61]
	v_mfma_f32_16x16x32_bf16 v[54:57], v[164:167], v[188:191], v[54:57]
	v_mfma_f32_16x16x32_bf16 v[42:45], v[156:159], v[196:199], v[42:45]
	v_mfma_f32_16x16x32_bf16 v[38:41], v[164:167], v[196:199], v[38:41]
	v_mfma_f32_16x16x32_bf16 v[26:29], v[156:159], v[204:207], v[26:29]
	v_mfma_f32_16x16x32_bf16 v[22:25], v[164:167], v[204:207], v[22:25]
	v_mfma_f32_16x16x32_bf16 v[10:13], v[156:159], v[212:215], v[10:13]
	v_mfma_f32_16x16x32_bf16 v[6:9], v[164:167], v[212:215], v[6:9]
	s_setprio 0
	s_setprio 1
	v_mfma_f32_16x16x32_bf16 v[62:65], v[168:171], v[184:187], v[62:65]
	v_mfma_f32_16x16x32_bf16 v[50:53], v[176:179], v[184:187], v[50:53]
	v_mfma_f32_16x16x32_bf16 v[46:49], v[168:171], v[192:195], v[46:49]
	v_mfma_f32_16x16x32_bf16 v[34:37], v[176:179], v[192:195], v[34:37]
	v_mfma_f32_16x16x32_bf16 v[30:33], v[168:171], v[200:203], v[30:33]
	v_mfma_f32_16x16x32_bf16 v[18:21], v[176:179], v[200:203], v[18:21]
	v_mfma_f32_16x16x32_bf16 v[14:17], v[168:171], v[208:211], v[14:17]
	v_mfma_f32_16x16x32_bf16 v[2:5], v[176:179], v[208:211], v[2:5]
	v_mfma_f32_16x16x32_bf16 v[62:65], v[172:175], v[188:191], v[62:65]
	v_mfma_f32_16x16x32_bf16 v[50:53], v[180:183], v[188:191], v[50:53]
	v_mfma_f32_16x16x32_bf16 v[46:49], v[172:175], v[196:199], v[46:49]
	v_mfma_f32_16x16x32_bf16 v[34:37], v[180:183], v[196:199], v[34:37]
	v_mfma_f32_16x16x32_bf16 v[30:33], v[172:175], v[204:207], v[30:33]
	v_mfma_f32_16x16x32_bf16 v[18:21], v[180:183], v[204:207], v[18:21]
	v_mfma_f32_16x16x32_bf16 v[14:17], v[172:175], v[212:215], v[14:17]
	v_mfma_f32_16x16x32_bf16 v[2:5], v[180:183], v[212:215], v[2:5]
	s_setprio 0
	s_barrier
	s_add_i32 s55, 0, 0x18000
	v_add_u32_e32 v151, s55, v146
	s_add_i32 s56, 0, 0x1c000
	ds_read_b128 v[152:155], v151
	ds_read_b128 v[156:159], v151 offset:1024
	ds_read_b128 v[160:163], v151 offset:2048
	ds_read_b128 v[164:167], v151 offset:3072
	v_add_u32_e32 v151, s56, v146
	ds_read_b128 v[168:171], v151
	ds_read_b128 v[172:175], v151 offset:1024
	ds_read_b128 v[176:179], v151 offset:2048
	ds_read_b128 v[180:183], v151 offset:3072
	s_add_u32 s34, s34, 0x80000
	s_addc_u32 s35, s35, 0
	s_mov_b32 m0, s39
	ds_read_b128 v[184:187], v150 offset:32768
	ds_read_b128 v[188:191], v150 offset:33792
	ds_read_b128 v[192:195], v150 offset:34816
	ds_read_b128 v[196:199], v150 offset:35840
	ds_read_b128 v[200:203], v150 offset:36864
	ds_read_b128 v[204:207], v150 offset:37888
	ds_read_b128 v[208:211], v150 offset:38912
	ds_read_b128 v[212:215], v150 offset:39936
	global_load_lds_dwordx4 v136, s[34:35]
	s_mov_b32 m0, s40
	s_nop 0
	global_load_lds_dwordx4 v132, s[34:35]
	s_waitcnt vmcnt(8)
	s_waitcnt lgkmcnt(0)
	s_barrier
	s_setprio 1
	s_waitcnt lgkmcnt(0)
	v_mfma_f32_16x16x32_bf16 v[122:125], v[152:155], v[184:187], v[122:125]
	v_mfma_f32_16x16x32_bf16 v[118:121], v[160:163], v[184:187], v[118:121]
	v_mfma_f32_16x16x32_bf16 v[106:109], v[152:155], v[192:195], v[106:109]
	v_mfma_f32_16x16x32_bf16 v[102:105], v[160:163], v[192:195], v[102:105]
	v_mfma_f32_16x16x32_bf16 v[90:93], v[152:155], v[200:203], v[90:93]
	v_mfma_f32_16x16x32_bf16 v[86:89], v[160:163], v[200:203], v[86:89]
	v_mfma_f32_16x16x32_bf16 v[74:77], v[152:155], v[208:211], v[74:77]
	v_mfma_f32_16x16x32_bf16 v[70:73], v[160:163], v[208:211], v[70:73]
	v_mfma_f32_16x16x32_bf16 v[122:125], v[156:159], v[188:191], v[122:125]
	v_mfma_f32_16x16x32_bf16 v[118:121], v[164:167], v[188:191], v[118:121]
	v_mfma_f32_16x16x32_bf16 v[106:109], v[156:159], v[196:199], v[106:109]
	v_mfma_f32_16x16x32_bf16 v[102:105], v[164:167], v[196:199], v[102:105]
	v_mfma_f32_16x16x32_bf16 v[90:93], v[156:159], v[204:207], v[90:93]
	v_mfma_f32_16x16x32_bf16 v[86:89], v[164:167], v[204:207], v[86:89]
	v_mfma_f32_16x16x32_bf16 v[74:77], v[156:159], v[212:215], v[74:77]
	v_mfma_f32_16x16x32_bf16 v[70:73], v[164:167], v[212:215], v[70:73]
	s_setprio 0
	s_setprio 1
	v_mfma_f32_16x16x32_bf16 v[126:129], v[168:171], v[184:187], v[126:129]
	v_mfma_f32_16x16x32_bf16 v[114:117], v[176:179], v[184:187], v[114:117]
	v_mfma_f32_16x16x32_bf16 v[110:113], v[168:171], v[192:195], v[110:113]
	v_mfma_f32_16x16x32_bf16 v[98:101], v[176:179], v[192:195], v[98:101]
	v_mfma_f32_16x16x32_bf16 v[94:97], v[168:171], v[200:203], v[94:97]
	v_mfma_f32_16x16x32_bf16 v[82:85], v[176:179], v[200:203], v[82:85]
	v_mfma_f32_16x16x32_bf16 v[78:81], v[168:171], v[208:211], v[78:81]
	v_mfma_f32_16x16x32_bf16 v[66:69], v[176:179], v[208:211], v[66:69]
	v_mfma_f32_16x16x32_bf16 v[126:129], v[172:175], v[188:191], v[126:129]
	v_mfma_f32_16x16x32_bf16 v[114:117], v[180:183], v[188:191], v[114:117]
	v_mfma_f32_16x16x32_bf16 v[110:113], v[172:175], v[196:199], v[110:113]
	v_mfma_f32_16x16x32_bf16 v[98:101], v[180:183], v[196:199], v[98:101]
	v_mfma_f32_16x16x32_bf16 v[94:97], v[172:175], v[204:207], v[94:97]
	v_mfma_f32_16x16x32_bf16 v[82:85], v[180:183], v[204:207], v[82:85]
	v_mfma_f32_16x16x32_bf16 v[78:81], v[172:175], v[212:215], v[78:81]
	v_mfma_f32_16x16x32_bf16 v[66:69], v[180:183], v[212:215], v[66:69]
	s_setprio 0
	s_barrier
; #define PG8_STAGE(bufoff, gbase, voff) do { _Pragma("unroll") for (int _i = 0; _i < 2; ++_i) \
;         __builtin_amdgcn_global_load_lds((const unsigned*)((const char*)(gbase) + (voff)[_i]), (LAS unsigned*)(lds + (bufoff) + ldsw + _i * 8192), 16, 0, 0); } while (0)
; #define PG8_LDA(dst, b, h) do { _Pragma("unroll") for (int m = 0; m < 4; ++m) _Pragma("unroll") for (int k = 0; k < 2; ++k) dst[m][k] = *(const LAS bf16x8*)(lds + PG8_SA(b, h) + aoff + m * 2048 + k * 1024); } while (0)
; #define PG8_MMA(ai, bj, At, Bt) do { __builtin_amdgcn_s_setprio(1); _Pragma("unroll") for (int m = 0; m < 4; ++m) _Pragma("unroll") for (int n = 0; n < 2; ++n) _Pragma("unroll") for (int k = 0; k < 2; ++k) \
;         acc[ai][bj][m][n] = __builtin_amdgcn_mfma_f32_16x16x32_bf16(Bt[n][k], At[m][k], acc[ai][bj][m][n], 0, 0, 0); __builtin_amdgcn_s_setprio(0); } while (0)
; #define PG8_WAIT_V(n) asm volatile("s_waitcnt vmcnt(" #n ")" ::: "memory")
; #define PG8_WAIT_L(n) asm volatile("s_waitcnt lgkmcnt(" #n ")" ::: "memory")
; #define PG8_BAR __builtin_amdgcn_s_barrier()
; #define PG8_SCHED __builtin_amdgcn_sched_barrier(0)
; template <class Epi, class Sched, bool ABLK = false, bool ALIGN_EPI = true, bool SP2 = true, bool BBLK = true>
; __device__ __forceinline__ void gemm_phase(LAS unsigned char* lds, const Gemm g, const Sched& S, const Epi& E) {
;     ...
;             PG8_LDA(At, 1, 1); PG8_STAGE(PG8_SB(1, 0), b3, voffB); PG8_STAGE(PG8_SB(1, 1), b3 + hstepB, voffB); PG8_STAGE(PG8_SA(1, 0), a3, voffA);
;             PG8_WAIT_V(8); PG8_WAIT_L(0); PG8_BAR; PG8_MMA(1, 0, At, B0); PG8_MMA(1, 1, At, B1); PG8_BAR; PG8_SCHED;
	s_add_u32 s34, s30, 0x8000
	s_addc_u32 s35, s31, 0
	s_add_i32 s55, s55, s33
	s_mov_b32 m0, s55
	ds_read_b128 v[184:187], v150 offset:49152
	ds_read_b128 v[188:191], v150 offset:50176
	ds_read_b128 v[192:195], v150 offset:51200
	ds_read_b128 v[196:199], v150 offset:52224
	ds_read_b128 v[200:203], v150 offset:53248
	ds_read_b128 v[204:207], v150 offset:54272
	ds_read_b128 v[208:211], v150 offset:55296
	ds_read_b128 v[212:215], v150 offset:56320
	global_load_lds_dwordx4 v134, s[34:35]
	s_add_i32 m0, s55, 0x2000
	s_add_u32 s30, s30, 0xc000
	v_lshl_add_u64 v[216:217], s[34:35], 0, v[130:131]
	s_addc_u32 s31, s31, 0
	s_add_i32 s34, s56, s33
	global_load_lds_dwordx4 v[216:217], off
	s_mov_b32 m0, s34
	s_nop 0
	global_load_lds_dwordx4 v134, s[30:31]
	s_add_i32 m0, s34, 0x2000
	s_nop 0
	global_load_lds_dwordx4 v130, s[30:31]
	s_mov_b32 m0, s42
	s_nop 0
	global_load_lds_dwordx4 v136, s[28:29]
	s_mov_b32 m0, s43
	s_nop 0
	global_load_lds_dwordx4 v132, s[28:29]
	s_waitcnt vmcnt(8)
	s_waitcnt lgkmcnt(0)
	s_barrier
	s_setprio 1
	s_waitcnt lgkmcnt(0)
	v_mfma_f32_16x16x32_bf16 v[58:61], v[152:155], v[184:187], v[58:61]
	v_mfma_f32_16x16x32_bf16 v[54:57], v[160:163], v[184:187], v[54:57]
	v_mfma_f32_16x16x32_bf16 v[42:45], v[152:155], v[192:195], v[42:45]
	v_mfma_f32_16x16x32_bf16 v[38:41], v[160:163], v[192:195], v[38:41]
	v_mfma_f32_16x16x32_bf16 v[26:29], v[152:155], v[200:203], v[26:29]
	v_mfma_f32_16x16x32_bf16 v[22:25], v[160:163], v[200:203], v[22:25]
	v_mfma_f32_16x16x32_bf16 v[10:13], v[152:155], v[208:211], v[10:13]
	v_mfma_f32_16x16x32_bf16 v[6:9], v[160:163], v[208:211], v[6:9]
	v_mfma_f32_16x16x32_bf16 v[58:61], v[156:159], v[188:191], v[58:61]
	v_mfma_f32_16x16x32_bf16 v[54:57], v[164:167], v[188:191], v[54:57]
	v_mfma_f32_16x16x32_bf16 v[42:45], v[156:159], v[196:199], v[42:45]
	v_mfma_f32_16x16x32_bf16 v[38:41], v[164:167], v[196:199], v[38:41]
	v_mfma_f32_16x16x32_bf16 v[26:29], v[156:159], v[204:207], v[26:29]
	v_mfma_f32_16x16x32_bf16 v[22:25], v[164:167], v[204:207], v[22:25]
	v_mfma_f32_16x16x32_bf16 v[10:13], v[156:159], v[212:215], v[10:13]
	v_mfma_f32_16x16x32_bf16 v[6:9], v[164:167], v[212:215], v[6:9]
	s_setprio 0
	s_setprio 1
	v_mfma_f32_16x16x32_bf16 v[62:65], v[168:171], v[184:187], v[62:65]
	v_mfma_f32_16x16x32_bf16 v[50:53], v[176:179], v[184:187], v[50:53]
	v_mfma_f32_16x16x32_bf16 v[46:49], v[168:171], v[192:195], v[46:49]
	v_mfma_f32_16x16x32_bf16 v[34:37], v[176:179], v[192:195], v[34:37]
	v_mfma_f32_16x16x32_bf16 v[30:33], v[168:171], v[200:203], v[30:33]
	v_mfma_f32_16x16x32_bf16 v[18:21], v[176:179], v[200:203], v[18:21]
	v_mfma_f32_16x16x32_bf16 v[14:17], v[168:171], v[208:211], v[14:17]
	v_mfma_f32_16x16x32_bf16 v[2:5], v[176:179], v[208:211], v[2:5]
	v_mfma_f32_16x16x32_bf16 v[62:65], v[172:175], v[188:191], v[62:65]
	v_mfma_f32_16x16x32_bf16 v[50:53], v[180:183], v[188:191], v[50:53]
	v_mfma_f32_16x16x32_bf16 v[46:49], v[172:175], v[196:199], v[46:49]
	v_mfma_f32_16x16x32_bf16 v[34:37], v[180:183], v[196:199], v[34:37]
	v_mfma_f32_16x16x32_bf16 v[30:33], v[172:175], v[204:207], v[30:33]
	v_mfma_f32_16x16x32_bf16 v[18:21], v[180:183], v[204:207], v[18:21]
	v_mfma_f32_16x16x32_bf16 v[14:17], v[172:175], v[212:215], v[14:17]
	v_mfma_f32_16x16x32_bf16 v[2:5], v[180:183], v[212:215], v[2:5]
	s_setprio 0
	s_barrier
	s_add_i32 s54, s54, 2
	s_add_u32 s26, s26, 0x100
	s_addc_u32 s27, s27, 0
	s_add_u32 s52, s52, 0x10000
	s_addc_u32 s53, s53, 0
	s_cmp_gt_u32 s54, 29
	s_cbranch_scc0 .LBB0_350
	s_and_b64 vcc, exec, s[6:7]
	s_cbranch_vccz .LBB0_353
	s_barrier

; __device__ __forceinline__ unsigned pk2(float lo, float hi) { const f32x2 v = {lo, hi}; return __builtin_bit_cast(unsigned, __builtin_convertvector(v, bf16x2_t)); }
; #define PG8_STAGE(bufoff, gbase, voff) do { _Pragma("unroll") for (int _i = 0; _i < 2; ++_i) \
;         __builtin_amdgcn_global_load_lds((const unsigned*)((const char*)(gbase) + (voff)[_i]), (LAS unsigned*)(lds + (bufoff) + ldsw + _i * 8192), 16, 0, 0); } while (0)
; #define PG8_WAIT_V(n) asm volatile("s_waitcnt vmcnt(" #n ")" ::: "memory")
; #define PG8_BAR __builtin_amdgcn_s_barrier()
; template <class Epi, class Sched, bool ABLK = false, bool ALIGN_EPI = true, bool SP2 = true, bool BBLK = true>
; __device__ __forceinline__ void gemm_phase(LAS unsigned char* lds, const Gemm g, const Sched& S, const Epi& E) {
;     ...
;         PG8_STAGE(PG8_SB(1, 0), cB + kstepB, voffB); PG8_STAGE(PG8_SA(1, 0), a_tile(uA, tbA + 1), voffA); PG8_STAGE(PG8_SB(1, 1), cB + hstepB + kstepB, voffB);
;         PG8_WAIT_V(6); PG8_BAR;
;     __device__ __forceinline__ void operator()(const f32x4 (&acc)[2][2][4][2], const Unit& u, int wr, int wc, int fr, int fq) const {
; #pragma unroll
;         for (int ai = 0; ai < 2; ++ai)
; #pragma unroll
;             for (int m = 0; m < 4; ++m) { unsigned char* rowp = (unsigned char*)(H + ((size_t)(u.pm * (FF / 64) + u.pn * 4 + wc) * 256 + (wr * 64 + fr + ai * 128 + m * 16)) * 64 + 8 * fq); u32x4 w[2];
; #pragma unroll
;                 for (int bj = 0; bj < 2; ++bj) { f32x4 v0 = acc[ai][bj][m][0], v1 = acc[ai][bj][m][1];
; #pragma unroll
;                     for (int j = 0; j < 4; ++j) { const float a = fmaxf(v0[j], 0.f), b = fmaxf(v1[j], 0.f); v0[j] = a * a; v1[j] = b * b; }
;                     w[bj].x = pk2(v0[0], v0[1]); w[bj].y = pk2(v0[2], v0[3]); w[bj].z = pk2(v1[0], v1[1]); w[bj].w = pk2(v1[2], v1[3]); }
;                 store_pair(rowp, (size_t)8 * 64 * 2, 64, w[0], w[1], fr >= 8); }
.LBB0_469:
	s_and_b32 s49, s8, 3
	s_lshl_b32 s10, s7, 13
	s_lshl_b32 s11, s49, 12
	s_add_u32 s8, s28, 0x8000
	s_addc_u32 s9, s29, 0
	s_add_i32 m0, s25, 0x18000
	v_lshl_add_u64 v[12:13], s[8:9], 0, v[134:135]
	s_waitcnt vmcnt(2)
	s_barrier
	global_load_lds_dwordx4 v[12:13], off
	v_lshl_add_u64 v[12:13], s[8:9], 0, v[130:131]
	s_add_i32 m0, s25, 0x1a000
	s_mov_b64 s[8:9], 0x80
	s_add_i32 s50, s25, 0x8000
	global_load_lds_dwordx4 v[12:13], off
	v_lshl_add_u64 v[2:3], v[2:3], 0, s[8:9]
	s_mov_b32 m0, s50
	s_add_i32 s51, s25, 0xa000
	global_load_lds_dwordx4 v[2:3], off
	v_lshl_add_u64 v[2:3], v[4:5], 0, s[8:9]
	s_add_u32 s8, s28, 0xc000
	s_mov_b32 m0, s51
	s_addc_u32 s9, s29, 0
	global_load_lds_dwordx4 v[2:3], off
	s_add_i32 m0, s25, 0x1c000
	s_nop 0
	global_load_lds_dwordx4 v134, s[8:9]
	s_add_i32 m0, s25, 0x1e000
	v_lshrrev_b32_e32 v4, 1, v1
	global_load_lds_dwordx4 v130, s[8:9]
	v_and_b32_e32 v4, 24, v4
	v_and_b32_e32 v3, 15, v1
	v_lshlrev_b32_e32 v5, 1, v4
	v_lshl_or_b32 v2, s7, 6, v3
	v_lshl_or_b32 v5, v3, 6, v5
	s_cmpk_lt_u32 s6, 0x100
	v_cmp_lt_u32_e64 s[6:7], 7, v3
	v_mov_b32_e32 v3, 0xfffffc40
	v_or_b32_e32 v12, 16, v2
	v_cndmask_b32_e64 v140, 0, v3, s[6:7]
	v_mov_b32_e32 v3, 0x400
	v_cndmask_b32_e64 v142, v3, 64, s[6:7]
	v_ashrrev_i32_e32 v3, 31, v2
	v_ashrrev_i32_e32 v13, 31, v12
	v_lshlrev_b64 v[144:145], 7, v[2:3]
	v_lshlrev_b64 v[146:147], 7, v[12:13]
	v_or_b32_e32 v12, 32, v2
	v_or_b32_e32 v2, 48, v2
	v_ashrrev_i32_e32 v3, 31, v2
	v_lshlrev_b64 v[150:151], 7, v[2:3]
	v_lshlrev_b32_e32 v2, 15, v9
	v_and_b32_e32 v2, 0xffff0000, v2
	v_lshl_add_u32 v2, v10, 12, v2
	v_and_b32_e32 v3, 1, v9
	v_lshl_or_b32 v2, v3, 6, v2
	v_lshl_add_u64 v[152:153], v[144:145], 0, s[4:5]
	s_mov_b64 s[4:5], 0x4800
	v_lshl_add_u32 v138, v11, 1, v2
	v_lshlrev_b32_e32 v2, 15, v6
	v_lshlrev_b32_e32 v1, 2, v1
	v_lshl_add_u64 v[154:155], v[144:145], 0, s[4:5]
	s_mov_b64 s[4:5], 0x5000
	v_and_b32_e32 v2, 0xffff0000, v2
	v_and_b32_e32 v1, 32, v1
	v_lshl_add_u64 v[156:157], v[144:145], 0, s[4:5]
	s_mov_b64 s[4:5], 0x5800
	v_lshl_add_u32 v2, v7, 12, v2
	v_and_b32_e32 v3, 1, v6
	v_bitop3_b32 v14, v5, s10, v1 bitop3:0xde
	v_bitop3_b32 v1, v5, s11, v1 bitop3:0xde
	s_waitcnt vmcnt(6)
	s_cselect_b64 s[8:9], -1, 0
	v_lshl_add_u64 v[158:159], v[144:145], 0, s[4:5]
	s_mov_b64 s[4:5], 0x80080
	v_lshl_or_b32 v2, v3, 6, v2
	s_add_i32 s55, 0, 0x10000
	v_ashrrev_i32_e32 v13, 31, v12
	v_lshl_add_u64 v[160:161], v[138:139], 0, s[4:5]
	v_lshl_add_u32 v138, v8, 1, v2
	s_add_i32 s52, 0, 0x14000
	v_add_u32_e32 v168, s55, v1
	s_add_i32 s55, s55, s40
	v_cndmask_b32_e64 v141, 0, -1, s[6:7]
	v_mov_b32_e32 v143, v139
	v_lshlrev_b64 v[148:149], 7, v[12:13]
	v_lshl_add_u64 v[162:163], v[138:139], 0, s[4:5]
	v_add_u32_e32 v169, s52, v1
	v_add_u32_e32 v170, 0, v14
	v_lshlrev_b32_e32 v138, 1, v4
	s_add_i32 s53, s25, 0xc000
	s_add_i32 s54, s25, 0xe000
	s_add_i32 s56, s55, 0x2000
	s_barrier
	s_branch .LBB0_472

; #define PG8_STAGE(bufoff, gbase, voff) do { _Pragma("unroll") for (int _i = 0; _i < 2; ++_i) \
;         __builtin_amdgcn_global_load_lds((const unsigned*)((const char*)(gbase) + (voff)[_i]), (LAS unsigned*)(lds + (bufoff) + ldsw + _i * 8192), 16, 0, 0); } while (0)
; #define PG8_LDA(dst, b, h) do { _Pragma("unroll") for (int m = 0; m < 4; ++m) _Pragma("unroll") for (int k = 0; k < 2; ++k) dst[m][k] = *(const LAS bf16x8*)(lds + PG8_SA(b, h) + aoff + m * 2048 + k * 1024); } while (0)
; #define PG8_LDB(dst, b, h) do { _Pragma("unroll") for (int n = 0; n < 2; ++n) _Pragma("unroll") for (int k = 0; k < 2; ++k) dst[n][k] = *(const LAS bf16x8*)(lds + PG8_SB(b, h) + boff + n * 2048 + k * 1024); } while (0)
; #define PG8_MMA(ai, bj, At, Bt) do { __builtin_amdgcn_s_setprio(1); _Pragma("unroll") for (int m = 0; m < 4; ++m) _Pragma("unroll") for (int n = 0; n < 2; ++n) _Pragma("unroll") for (int k = 0; k < 2; ++k) \
;         acc[ai][bj][m][n] = __builtin_amdgcn_mfma_f32_16x16x32_bf16(Bt[n][k], At[m][k], acc[ai][bj][m][n], 0, 0, 0); __builtin_amdgcn_s_setprio(0); } while (0)
; #define PG8_WAIT_V(n) asm volatile("s_waitcnt vmcnt(" #n ")" ::: "memory")
; #define PG8_WAIT_L(n) asm volatile("s_waitcnt lgkmcnt(" #n ")" ::: "memory")
; #define PG8_BAR __builtin_amdgcn_s_barrier()
; #define PG8_SCHED __builtin_amdgcn_sched_barrier(0)
; template <class Epi, class Sched, bool ABLK = false, bool ALIGN_EPI = true, bool SP2 = true, bool BBLK = true>
; __device__ __forceinline__ void gemm_phase(LAS unsigned char* lds, const Gemm g, const Sched& S, const Epi& E) {
;     ...
;             const char* a1 = a_tile(uA, tbA + t + 1);
;             const char* a2 = last ? a_tile(nuA, ntbA) : a_tile(uA, tbA + t + 2); const char* b2 = last ? nB : cB + (size_t)(t + 2) * kstepB;
;             const char* a3 = last ? a_tile(nuA, ntbA + 1) : a_tile(uA, tbA + t + 3); const char* b3 = b2 + kstepB;
;             if (last && has_next) S.a_ready(nxt);
;             if constexpr (SP2) {
;             PG8_LDB(B0, 0, 0); PG8_LDB(B1, 0, 1); PG8_SCHED; PG8_LDA(At, 0, 0); PG8_STAGE(PG8_SA(1, 1), a1 + hstepA, voffA);
;             PG8_WAIT_V(8); PG8_WAIT_L(0); PG8_BAR; PG8_MMA(0, 0, At, B0); PG8_MMA(0, 1, At, B1); PG8_BAR; PG8_SCHED;
;             PG8_LDA(At, 0, 1); PG8_STAGE(PG8_SB(0, 0), b2, voffB); PG8_STAGE(PG8_SB(0, 1), b2 + hstepB, voffB); PG8_STAGE(PG8_SA(0, 0), a2, voffA);
.LBB0_475:
	ds_read_b128 v[172:175], v168
	ds_read_b128 v[176:179], v168 offset:1024
	ds_read_b128 v[180:183], v168 offset:2048
	ds_read_b128 v[184:187], v168 offset:3072
	ds_read_b128 v[188:191], v169
	ds_read_b128 v[192:195], v169 offset:1024
	ds_read_b128 v[196:199], v169 offset:2048
	ds_read_b128 v[200:203], v169 offset:3072
	s_add_u32 s30, s26, s28
	s_addc_u32 s31, s27, s29
	s_add_u32 s36, s30, 0x100
	s_addc_u32 s37, s31, 0
	s_add_u32 s30, s30, 0x180
	s_addc_u32 s31, s31, 0
	s_cmpk_eq_i32 s28, 0xf00
	s_cselect_b32 s31, s57, s31
	s_cselect_b32 s30, s23, s30
	s_cselect_b32 s35, s11, s59
	s_cselect_b32 s34, s13, s58
	s_cselect_b32 s37, s4, s37
	s_cselect_b32 s36, s5, s36
	s_mov_b32 m0, s53
	v_lshl_add_u64 v[236:237], v[164:165], 0, s[28:29]
	ds_read_b128 v[204:207], v170
	ds_read_b128 v[208:211], v170 offset:1024
	ds_read_b128 v[212:215], v170 offset:2048
	ds_read_b128 v[216:219], v170 offset:3072
	ds_read_b128 v[220:223], v170 offset:4096
	ds_read_b128 v[224:227], v170 offset:5120
	ds_read_b128 v[228:231], v170 offset:6144
	ds_read_b128 v[232:235], v170 offset:7168
	global_load_lds_dwordx4 v[236:237], off
	v_lshl_add_u64 v[236:237], v[166:167], 0, s[28:29]
	s_mov_b32 m0, s54
	s_nop 0
	global_load_lds_dwordx4 v[236:237], off
	s_waitcnt vmcnt(8)
	s_waitcnt lgkmcnt(0)
	s_barrier
	s_setprio 1
	s_waitcnt lgkmcnt(0)
	v_mfma_f32_16x16x32_bf16 v[126:129], v[172:175], v[204:207], v[126:129]
	v_mfma_f32_16x16x32_bf16 v[122:125], v[180:183], v[204:207], v[122:125]
	v_mfma_f32_16x16x32_bf16 v[110:113], v[172:175], v[212:215], v[110:113]
	v_mfma_f32_16x16x32_bf16 v[106:109], v[180:183], v[212:215], v[106:109]
	v_mfma_f32_16x16x32_bf16 v[94:97], v[172:175], v[220:223], v[94:97]
	v_mfma_f32_16x16x32_bf16 v[90:93], v[180:183], v[220:223], v[90:93]
	v_mfma_f32_16x16x32_bf16 v[78:81], v[172:175], v[228:231], v[78:81]
	v_mfma_f32_16x16x32_bf16 v[74:77], v[180:183], v[228:231], v[74:77]
	v_mfma_f32_16x16x32_bf16 v[126:129], v[176:179], v[208:211], v[126:129]
	v_mfma_f32_16x16x32_bf16 v[122:125], v[184:187], v[208:211], v[122:125]
	v_mfma_f32_16x16x32_bf16 v[110:113], v[176:179], v[216:219], v[110:113]
	v_mfma_f32_16x16x32_bf16 v[106:109], v[184:187], v[216:219], v[106:109]
	v_mfma_f32_16x16x32_bf16 v[94:97], v[176:179], v[224:227], v[94:97]
	v_mfma_f32_16x16x32_bf16 v[90:93], v[184:187], v[224:227], v[90:93]
	v_mfma_f32_16x16x32_bf16 v[78:81], v[176:179], v[232:235], v[78:81]
	v_mfma_f32_16x16x32_bf16 v[74:77], v[184:187], v[232:235], v[74:77]
	s_setprio 0
	s_setprio 1
	v_mfma_f32_16x16x32_bf16 v[118:121], v[188:191], v[204:207], v[118:121]
	v_mfma_f32_16x16x32_bf16 v[114:117], v[196:199], v[204:207], v[114:117]
	v_mfma_f32_16x16x32_bf16 v[102:105], v[188:191], v[212:215], v[102:105]
	v_mfma_f32_16x16x32_bf16 v[98:101], v[196:199], v[212:215], v[98:101]
	v_mfma_f32_16x16x32_bf16 v[86:89], v[188:191], v[220:223], v[86:89]
	v_mfma_f32_16x16x32_bf16 v[82:85], v[196:199], v[220:223], v[82:85]
	v_mfma_f32_16x16x32_bf16 v[70:73], v[188:191], v[228:231], v[70:73]
	v_mfma_f32_16x16x32_bf16 v[66:69], v[196:199], v[228:231], v[66:69]
	v_mfma_f32_16x16x32_bf16 v[118:121], v[192:195], v[208:211], v[118:121]
	v_mfma_f32_16x16x32_bf16 v[114:117], v[200:203], v[208:211], v[114:117]
	v_mfma_f32_16x16x32_bf16 v[102:105], v[192:195], v[216:219], v[102:105]
	v_mfma_f32_16x16x32_bf16 v[98:101], v[200:203], v[216:219], v[98:101]
	v_mfma_f32_16x16x32_bf16 v[86:89], v[192:195], v[224:227], v[86:89]
	v_mfma_f32_16x16x32_bf16 v[82:85], v[200:203], v[224:227], v[82:85]
	v_mfma_f32_16x16x32_bf16 v[70:73], v[192:195], v[232:235], v[70:73]
	v_mfma_f32_16x16x32_bf16 v[66:69], v[200:203], v[232:235], v[66:69]
	s_setprio 0
	s_barrier
	s_mov_b32 m0, s55
	s_add_u32 s62, s34, 0x4000
	ds_read_b128 v[204:207], v170 offset:16384
	ds_read_b128 v[208:211], v170 offset:17408
	ds_read_b128 v[212:215], v170 offset:18432
	ds_read_b128 v[216:219], v170 offset:19456
	ds_read_b128 v[220:223], v170 offset:20480
	ds_read_b128 v[224:227], v170 offset:21504
	ds_read_b128 v[228:231], v170 offset:22528
	ds_read_b128 v[232:235], v170 offset:23552
	global_load_lds_dwordx4 v134, s[34:35]
	s_mov_b32 m0, s56
	s_addc_u32 s63, s35, 0
	s_add_i32 s61, s52, s40
	global_load_lds_dwordx4 v130, s[34:35]
	s_mov_b32 m0, s61
	s_nop 0
	global_load_lds_dwordx4 v134, s[62:63]
	s_add_i32 m0, s61, 0x2000
	s_nop 0
	global_load_lds_dwordx4 v130, s[62:63]
	s_mov_b32 m0, s25
	s_nop 0
	global_load_lds_dwordx4 v136, s[36:37]
	s_mov_b32 m0, s43
	s_nop 0
	global_load_lds_dwordx4 v132, s[36:37]
	s_waitcnt vmcnt(8)
	s_waitcnt lgkmcnt(0)
	s_barrier
; #define PG8_STAGE(bufoff, gbase, voff) do { _Pragma("unroll") for (int _i = 0; _i < 2; ++_i) \
;         __builtin_amdgcn_global_load_lds((const unsigned*)((const char*)(gbase) + (voff)[_i]), (LAS unsigned*)(lds + (bufoff) + ldsw + _i * 8192), 16, 0, 0); } while (0)
; #define PG8_LDA(dst, b, h) do { _Pragma("unroll") for (int m = 0; m < 4; ++m) _Pragma("unroll") for (int k = 0; k < 2; ++k) dst[m][k] = *(const LAS bf16x8*)(lds + PG8_SA(b, h) + aoff + m * 2048 + k * 1024); } while (0)
; #define PG8_LDB(dst, b, h) do { _Pragma("unroll") for (int n = 0; n < 2; ++n) _Pragma("unroll") for (int k = 0; k < 2; ++k) dst[n][k] = *(const LAS bf16x8*)(lds + PG8_SB(b, h) + boff + n * 2048 + k * 1024); } while (0)
; #define PG8_MMA(ai, bj, At, Bt) do { __builtin_amdgcn_s_setprio(1); _Pragma("unroll") for (int m = 0; m < 4; ++m) _Pragma("unroll") for (int n = 0; n < 2; ++n) _Pragma("unroll") for (int k = 0; k < 2; ++k) \
;         acc[ai][bj][m][n] = __builtin_amdgcn_mfma_f32_16x16x32_bf16(Bt[n][k], At[m][k], acc[ai][bj][m][n], 0, 0, 0); __builtin_amdgcn_s_setprio(0); } while (0)
; #define PG8_WAIT_V(n) asm volatile("s_waitcnt vmcnt(" #n ")" ::: "memory")
; #define PG8_WAIT_L(n) asm volatile("s_waitcnt lgkmcnt(" #n ")" ::: "memory")
; #define PG8_BAR __builtin_amdgcn_s_barrier()
; #define PG8_SCHED __builtin_amdgcn_sched_barrier(0)
; template <class Epi, class Sched, bool ABLK = false, bool ALIGN_EPI = true, bool SP2 = true, bool BBLK = true>
; __device__ __forceinline__ void gemm_phase(LAS unsigned char* lds, const Gemm g, const Sched& S, const Epi& E) {
;     ...
;             PG8_WAIT_V(8); PG8_WAIT_L(0); PG8_BAR; PG8_MMA(1, 0, At, B0); PG8_MMA(1, 1, At, B1); PG8_BAR; PG8_SCHED;
;             PG8_LDB(B0, 1, 0); PG8_LDB(B1, 1, 1); PG8_SCHED; PG8_LDA(At, 1, 0); PG8_STAGE(PG8_SA(0, 1), a2 + hstepA, voffA);
;             PG8_WAIT_V(8); PG8_WAIT_L(0); PG8_BAR; PG8_MMA(0, 0, At, B0); PG8_MMA(0, 1, At, B1); PG8_BAR; PG8_SCHED;
	s_setprio 1
	s_waitcnt lgkmcnt(0)
	v_mfma_f32_16x16x32_bf16 v[62:65], v[172:175], v[204:207], v[62:65]
	v_mfma_f32_16x16x32_bf16 v[58:61], v[180:183], v[204:207], v[58:61]
	v_mfma_f32_16x16x32_bf16 v[46:49], v[172:175], v[212:215], v[46:49]
	v_mfma_f32_16x16x32_bf16 v[42:45], v[180:183], v[212:215], v[42:45]
	v_mfma_f32_16x16x32_bf16 v[30:33], v[172:175], v[220:223], v[30:33]
	v_mfma_f32_16x16x32_bf16 v[26:29], v[180:183], v[220:223], v[26:29]
	v_mfma_f32_16x16x32_bf16 v[14:17], v[172:175], v[228:231], v[14:17]
	v_mfma_f32_16x16x32_bf16 v[10:13], v[180:183], v[228:231], v[10:13]
	v_mfma_f32_16x16x32_bf16 v[62:65], v[176:179], v[208:211], v[62:65]
	v_mfma_f32_16x16x32_bf16 v[58:61], v[184:187], v[208:211], v[58:61]
	v_mfma_f32_16x16x32_bf16 v[46:49], v[176:179], v[216:219], v[46:49]
	v_mfma_f32_16x16x32_bf16 v[42:45], v[184:187], v[216:219], v[42:45]
	v_mfma_f32_16x16x32_bf16 v[30:33], v[176:179], v[224:227], v[30:33]
	v_mfma_f32_16x16x32_bf16 v[26:29], v[184:187], v[224:227], v[26:29]
	v_mfma_f32_16x16x32_bf16 v[14:17], v[176:179], v[232:235], v[14:17]
	v_mfma_f32_16x16x32_bf16 v[10:13], v[184:187], v[232:235], v[10:13]
	s_setprio 0
	s_setprio 1
	v_mfma_f32_16x16x32_bf16 v[54:57], v[188:191], v[204:207], v[54:57]
	v_mfma_f32_16x16x32_bf16 v[50:53], v[196:199], v[204:207], v[50:53]
	v_mfma_f32_16x16x32_bf16 v[38:41], v[188:191], v[212:215], v[38:41]
	v_mfma_f32_16x16x32_bf16 v[34:37], v[196:199], v[212:215], v[34:37]
	v_mfma_f32_16x16x32_bf16 v[22:25], v[188:191], v[220:223], v[22:25]
	v_mfma_f32_16x16x32_bf16 v[18:21], v[196:199], v[220:223], v[18:21]
	v_mfma_f32_16x16x32_bf16 v[6:9], v[188:191], v[228:231], v[6:9]
	v_mfma_f32_16x16x32_bf16 v[2:5], v[196:199], v[228:231], v[2:5]
	v_mfma_f32_16x16x32_bf16 v[54:57], v[192:195], v[208:211], v[54:57]
	v_mfma_f32_16x16x32_bf16 v[50:53], v[200:203], v[208:211], v[50:53]
	v_mfma_f32_16x16x32_bf16 v[38:41], v[192:195], v[216:219], v[38:41]
	v_mfma_f32_16x16x32_bf16 v[34:37], v[200:203], v[216:219], v[34:37]
	v_mfma_f32_16x16x32_bf16 v[22:25], v[192:195], v[224:227], v[22:25]
	v_mfma_f32_16x16x32_bf16 v[18:21], v[200:203], v[224:227], v[18:21]
	v_mfma_f32_16x16x32_bf16 v[6:9], v[192:195], v[232:235], v[6:9]
	v_mfma_f32_16x16x32_bf16 v[2:5], v[200:203], v[232:235], v[2:5]
	s_setprio 0
	s_barrier
	s_add_i32 s61, 0, 0x18000
	v_add_u32_e32 v171, s61, v1
	s_add_i32 s62, 0, 0x1c000
	ds_read_b128 v[172:175], v171
	ds_read_b128 v[176:179], v171 offset:1024
	ds_read_b128 v[180:183], v171 offset:2048
	ds_read_b128 v[184:187], v171 offset:3072
	v_add_u32_e32 v171, s62, v1
	ds_read_b128 v[188:191], v171
	ds_read_b128 v[192:195], v171 offset:1024
	ds_read_b128 v[196:199], v171 offset:2048
	ds_read_b128 v[200:203], v171 offset:3072
	s_add_u32 s36, s36, 0x80000
	s_addc_u32 s37, s37, 0
	s_mov_b32 m0, s46
	ds_read_b128 v[204:207], v170 offset:32768
	ds_read_b128 v[208:211], v170 offset:33792
	ds_read_b128 v[212:215], v170 offset:34816
	ds_read_b128 v[216:219], v170 offset:35840
	ds_read_b128 v[220:223], v170 offset:36864
	ds_read_b128 v[224:227], v170 offset:37888
	ds_read_b128 v[228:231], v170 offset:38912
	ds_read_b128 v[232:235], v170 offset:39936
	global_load_lds_dwordx4 v136, s[36:37]
	s_mov_b32 m0, s47
	s_nop 0
	global_load_lds_dwordx4 v132, s[36:37]
	s_waitcnt vmcnt(8)
	s_waitcnt lgkmcnt(0)
	s_barrier
	s_setprio 1
	s_waitcnt lgkmcnt(0)
	v_mfma_f32_16x16x32_bf16 v[126:129], v[172:175], v[204:207], v[126:129]
	v_mfma_f32_16x16x32_bf16 v[122:125], v[180:183], v[204:207], v[122:125]
	v_mfma_f32_16x16x32_bf16 v[110:113], v[172:175], v[212:215], v[110:113]
	v_mfma_f32_16x16x32_bf16 v[106:109], v[180:183], v[212:215], v[106:109]
	v_mfma_f32_16x16x32_bf16 v[94:97], v[172:175], v[220:223], v[94:97]
	v_mfma_f32_16x16x32_bf16 v[90:93], v[180:183], v[220:223], v[90:93]
	v_mfma_f32_16x16x32_bf16 v[78:81], v[172:175], v[228:231], v[78:81]
	v_mfma_f32_16x16x32_bf16 v[74:77], v[180:183], v[228:231], v[74:77]
	v_mfma_f32_16x16x32_bf16 v[126:129], v[176:179], v[208:211], v[126:129]
	v_mfma_f32_16x16x32_bf16 v[122:125], v[184:187], v[208:211], v[122:125]
	v_mfma_f32_16x16x32_bf16 v[110:113], v[176:179], v[216:219], v[110:113]
	v_mfma_f32_16x16x32_bf16 v[106:109], v[184:187], v[216:219], v[106:109]
	v_mfma_f32_16x16x32_bf16 v[94:97], v[176:179], v[224:227], v[94:97]
	v_mfma_f32_16x16x32_bf16 v[90:93], v[184:187], v[224:227], v[90:93]
	v_mfma_f32_16x16x32_bf16 v[78:81], v[176:179], v[232:235], v[78:81]
	v_mfma_f32_16x16x32_bf16 v[74:77], v[184:187], v[232:235], v[74:77]
	s_setprio 0
	s_setprio 1
	v_mfma_f32_16x16x32_bf16 v[118:121], v[188:191], v[204:207], v[118:121]
	v_mfma_f32_16x16x32_bf16 v[114:117], v[196:199], v[204:207], v[114:117]
	v_mfma_f32_16x16x32_bf16 v[102:105], v[188:191], v[212:215], v[102:105]
	v_mfma_f32_16x16x32_bf16 v[98:101], v[196:199], v[212:215], v[98:101]
	v_mfma_f32_16x16x32_bf16 v[86:89], v[188:191], v[220:223], v[86:89]
	v_mfma_f32_16x16x32_bf16 v[82:85], v[196:199], v[220:223], v[82:85]
	v_mfma_f32_16x16x32_bf16 v[70:73], v[188:191], v[228:231], v[70:73]
	v_mfma_f32_16x16x32_bf16 v[66:69], v[196:199], v[228:231], v[66:69]
	v_mfma_f32_16x16x32_bf16 v[118:121], v[192:195], v[208:211], v[118:121]
	v_mfma_f32_16x16x32_bf16 v[114:117], v[200:203], v[208:211], v[114:117]
	v_mfma_f32_16x16x32_bf16 v[102:105], v[192:195], v[216:219], v[102:105]
	v_mfma_f32_16x16x32_bf16 v[98:101], v[200:203], v[216:219], v[98:101]
	v_mfma_f32_16x16x32_bf16 v[86:89], v[192:195], v[224:227], v[86:89]
	v_mfma_f32_16x16x32_bf16 v[82:85], v[200:203], v[224:227], v[82:85]
	v_mfma_f32_16x16x32_bf16 v[70:73], v[192:195], v[232:235], v[70:73]
	v_mfma_f32_16x16x32_bf16 v[66:69], v[200:203], v[232:235], v[66:69]
	s_setprio 0
	s_barrier
; #define PG8_STAGE(bufoff, gbase, voff) do { _Pragma("unroll") for (int _i = 0; _i < 2; ++_i) \
;         __builtin_amdgcn_global_load_lds((const unsigned*)((const char*)(gbase) + (voff)[_i]), (LAS unsigned*)(lds + (bufoff) + ldsw + _i * 8192), 16, 0, 0); } while (0)
; #define PG8_LDA(dst, b, h) do { _Pragma("unroll") for (int m = 0; m < 4; ++m) _Pragma("unroll") for (int k = 0; k < 2; ++k) dst[m][k] = *(const LAS bf16x8*)(lds + PG8_SA(b, h) + aoff + m * 2048 + k * 1024); } while (0)
; #define PG8_MMA(ai, bj, At, Bt) do { __builtin_amdgcn_s_setprio(1); _Pragma("unroll") for (int m = 0; m < 4; ++m) _Pragma("unroll") for (int n = 0; n < 2; ++n) _Pragma("unroll") for (int k = 0; k < 2; ++k) \
;         acc[ai][bj][m][n] = __builtin_amdgcn_mfma_f32_16x16x32_bf16(Bt[n][k], At[m][k], acc[ai][bj][m][n], 0, 0, 0); __builtin_amdgcn_s_setprio(0); } while (0)
; #define PG8_WAIT_V(n) asm volatile("s_waitcnt vmcnt(" #n ")" ::: "memory")
; #define PG8_WAIT_L(n) asm volatile("s_waitcnt lgkmcnt(" #n ")" ::: "memory")
; #define PG8_BAR __builtin_amdgcn_s_barrier()
; #define PG8_SCHED __builtin_amdgcn_sched_barrier(0)
; template <class Epi, class Sched, bool ABLK = false, bool ALIGN_EPI = true, bool SP2 = true, bool BBLK = true>
; __device__ __forceinline__ void gemm_phase(LAS unsigned char* lds, const Gemm g, const Sched& S, const Epi& E) {
;     ...
;             PG8_LDA(At, 1, 1); PG8_STAGE(PG8_SB(1, 0), b3, voffB); PG8_STAGE(PG8_SB(1, 1), b3 + hstepB, voffB); PG8_STAGE(PG8_SA(1, 0), a3, voffA);
;             PG8_WAIT_V(8); PG8_WAIT_L(0); PG8_BAR; PG8_MMA(1, 0, At, B0); PG8_MMA(1, 1, At, B1); PG8_BAR; PG8_SCHED;
	s_add_u32 s36, s34, 0x8000
	s_addc_u32 s37, s35, 0
	s_add_i32 s61, s61, s40
	s_mov_b32 m0, s61
	ds_read_b128 v[204:207], v170 offset:49152
	ds_read_b128 v[208:211], v170 offset:50176
	ds_read_b128 v[212:215], v170 offset:51200
	ds_read_b128 v[216:219], v170 offset:52224
	ds_read_b128 v[220:223], v170 offset:53248
	ds_read_b128 v[224:227], v170 offset:54272
	ds_read_b128 v[228:231], v170 offset:55296
	ds_read_b128 v[232:235], v170 offset:56320
	global_load_lds_dwordx4 v134, s[36:37]
	s_add_i32 m0, s61, 0x2000
	s_add_u32 s34, s34, 0xc000
	v_lshl_add_u64 v[236:237], s[36:37], 0, v[130:131]
	s_addc_u32 s35, s35, 0
	s_add_i32 s36, s62, s40
	global_load_lds_dwordx4 v[236:237], off
	s_mov_b32 m0, s36
	s_nop 0
	global_load_lds_dwordx4 v134, s[34:35]
	s_add_i32 m0, s36, 0x2000
	s_nop 0
	global_load_lds_dwordx4 v130, s[34:35]
	s_mov_b32 m0, s50
	s_nop 0
	global_load_lds_dwordx4 v136, s[30:31]
	s_mov_b32 m0, s51
	s_nop 0
	global_load_lds_dwordx4 v132, s[30:31]
	s_waitcnt vmcnt(8)
	s_waitcnt lgkmcnt(0)
	s_barrier
	s_setprio 1
	s_waitcnt lgkmcnt(0)
	v_mfma_f32_16x16x32_bf16 v[62:65], v[172:175], v[204:207], v[62:65]
	v_mfma_f32_16x16x32_bf16 v[58:61], v[180:183], v[204:207], v[58:61]
	v_mfma_f32_16x16x32_bf16 v[46:49], v[172:175], v[212:215], v[46:49]
	v_mfma_f32_16x16x32_bf16 v[42:45], v[180:183], v[212:215], v[42:45]
	v_mfma_f32_16x16x32_bf16 v[30:33], v[172:175], v[220:223], v[30:33]
	v_mfma_f32_16x16x32_bf16 v[26:29], v[180:183], v[220:223], v[26:29]
	v_mfma_f32_16x16x32_bf16 v[14:17], v[172:175], v[228:231], v[14:17]
	v_mfma_f32_16x16x32_bf16 v[10:13], v[180:183], v[228:231], v[10:13]
	v_mfma_f32_16x16x32_bf16 v[62:65], v[176:179], v[208:211], v[62:65]
	v_mfma_f32_16x16x32_bf16 v[58:61], v[184:187], v[208:211], v[58:61]
	v_mfma_f32_16x16x32_bf16 v[46:49], v[176:179], v[216:219], v[46:49]
	v_mfma_f32_16x16x32_bf16 v[42:45], v[184:187], v[216:219], v[42:45]
	v_mfma_f32_16x16x32_bf16 v[30:33], v[176:179], v[224:227], v[30:33]
	v_mfma_f32_16x16x32_bf16 v[26:29], v[184:187], v[224:227], v[26:29]
	v_mfma_f32_16x16x32_bf16 v[14:17], v[176:179], v[232:235], v[14:17]
	v_mfma_f32_16x16x32_bf16 v[10:13], v[184:187], v[232:235], v[10:13]
	s_setprio 0
	s_setprio 1
	v_mfma_f32_16x16x32_bf16 v[54:57], v[188:191], v[204:207], v[54:57]
	v_mfma_f32_16x16x32_bf16 v[50:53], v[196:199], v[204:207], v[50:53]
	v_mfma_f32_16x16x32_bf16 v[38:41], v[188:191], v[212:215], v[38:41]
	v_mfma_f32_16x16x32_bf16 v[34:37], v[196:199], v[212:215], v[34:37]
	v_mfma_f32_16x16x32_bf16 v[22:25], v[188:191], v[220:223], v[22:25]
	v_mfma_f32_16x16x32_bf16 v[18:21], v[196:199], v[220:223], v[18:21]
	v_mfma_f32_16x16x32_bf16 v[6:9], v[188:191], v[228:231], v[6:9]
	v_mfma_f32_16x16x32_bf16 v[2:5], v[196:199], v[228:231], v[2:5]
	v_mfma_f32_16x16x32_bf16 v[54:57], v[192:195], v[208:211], v[54:57]
	v_mfma_f32_16x16x32_bf16 v[50:53], v[200:203], v[208:211], v[50:53]
	v_mfma_f32_16x16x32_bf16 v[38:41], v[192:195], v[216:219], v[38:41]
	v_mfma_f32_16x16x32_bf16 v[34:37], v[200:203], v[216:219], v[34:37]
	v_mfma_f32_16x16x32_bf16 v[22:25], v[192:195], v[224:227], v[22:25]
	v_mfma_f32_16x16x32_bf16 v[18:21], v[200:203], v[224:227], v[18:21]
	v_mfma_f32_16x16x32_bf16 v[6:9], v[192:195], v[232:235], v[6:9]
	v_mfma_f32_16x16x32_bf16 v[2:5], v[200:203], v[232:235], v[2:5]
	s_setprio 0
	s_barrier
	s_add_i32 s60, s60, 2
	s_add_u32 s28, s28, 0x100
	s_addc_u32 s29, s29, 0
	s_add_u32 s58, s58, 0x10000
	s_addc_u32 s59, s59, 0
	s_cmp_gt_u32 s60, 29
	s_cbranch_scc0 .LBB0_475
	s_and_b64 vcc, exec, s[8:9]
	s_cbranch_vccz .LBB0_478
	s_barrier

; __device__ __forceinline__ unsigned pk2(float lo, float hi) { const f32x2 v = {lo, hi}; return __builtin_bit_cast(unsigned, __builtin_convertvector(v, bf16x2_t)); }
; #define PG8_STAGE(bufoff, gbase, voff) do { _Pragma("unroll") for (int _i = 0; _i < 2; ++_i) \
;         __builtin_amdgcn_global_load_lds((const unsigned*)((const char*)(gbase) + (voff)[_i]), (LAS unsigned*)(lds + (bufoff) + ldsw + _i * 8192), 16, 0, 0); } while (0)
; #define PG8_WAIT_V(n) asm volatile("s_waitcnt vmcnt(" #n ")" ::: "memory")
; #define PG8_BAR __builtin_amdgcn_s_barrier()
; template <class Epi, class Sched, bool ABLK = false, bool ALIGN_EPI = true, bool SP2 = true, bool BBLK = true>
; __device__ __forceinline__ void gemm_phase(LAS unsigned char* lds, const Gemm g, const Sched& S, const Epi& E) {
;     ...
;         PG8_STAGE(PG8_SB(1, 0), cB + kstepB, voffB); PG8_STAGE(PG8_SA(1, 0), a_tile(uA, tbA + 1), voffA); PG8_STAGE(PG8_SB(1, 1), cB + hstepB + kstepB, voffB);
;         PG8_WAIT_V(6); PG8_BAR;
;     __device__ __forceinline__ void operator()(const f32x4 (&acc)[2][2][4][2], const Unit& u, int wr, int wc, int fr, int fq) const {
;         const int row0 = u.pm * 256 + wr * 64 + fr, col0 = u.pn * 256 + wc * 64 + 8 * fq;
;         bf16_t* base = u.part == 0 ? Z + (size_t)row0 * D + col0 : P + ((size_t)(u.part - 1) * MS + (row0 - MP)) * D + col0;
; #pragma unroll
;         for (int ai = 0; ai < 2; ++ai)
; #pragma unroll
;             for (int m = 0; m < 4; ++m) { u32x4 w[2];
; #pragma unroll
;                 for (int bj = 0; bj < 2; ++bj) { const f32x4 v0 = acc[ai][bj][m][0], v1 = acc[ai][bj][m][1]; w[bj].x = pk2(v0[0], v0[1]); w[bj].y = pk2(v0[2], v0[3]); w[bj].z = pk2(v1[0], v1[1]); w[bj].w = pk2(v1[2], v1[3]); }
;                 store_pair((unsigned char*)(base + (size_t)(ai * 128 + m * 16) * D), (size_t)8 * D * 2, 64, w[0], w[1], fr >= 8); }
.LBB0_536:
	s_and_b32 s8, s5, 3
	s_lshl_b32 s5, s4, 13
	s_lshl_b32 s9, s8, 12
	s_add_u32 s10, s68, 0x3c900000
	s_addc_u32 s11, s69, 0
	s_add_u32 s6, s40, 0x8000
	s_addc_u32 s7, s41, 0
	s_add_i32 m0, s52, 0x18000
	v_lshl_add_u64 v[10:11], s[6:7], 0, v[130:131]
	s_waitcnt vmcnt(2)
	s_barrier
	global_load_lds_dwordx4 v[10:11], off
	s_add_i32 m0, s52, 0x1a000
	v_lshl_add_u64 v[10:11], s[6:7], 0, v[132:133]
	s_add_u32 s6, s42, 0x8000
	s_addc_u32 s7, s43, 0
	s_add_i32 s56, s52, 0x8000
	global_load_lds_dwordx4 v[10:11], off
	s_mov_b32 m0, s56
	s_add_i32 s57, s52, 0xa000
	global_load_lds_dwordx4 v130, s[6:7]
	v_lshl_add_u64 v[10:11], s[6:7], 0, v[132:133]
	s_add_u32 s6, s40, 0xc000
	s_mov_b32 m0, s57
	s_addc_u32 s7, s41, 0
	global_load_lds_dwordx4 v[10:11], off
	s_add_i32 m0, s52, 0x1c000
	s_nop 0
	global_load_lds_dwordx4 v130, s[6:7]
	s_add_i32 m0, s52, 0x1e000
	v_and_b32_e32 v9, 15, v6
	global_load_lds_dwordx4 v132, s[6:7]
	v_lshrrev_b32_e32 v10, 1, v6
	v_and_b32_e32 v10, 24, v10
	v_lshlrev_b32_e32 v11, 1, v10
	v_lshl_or_b32 v1, s4, 6, v9
	v_lshl_or_b32 v11, v9, 6, v11
	v_cmp_lt_u32_e64 s[6:7], 7, v9
	v_mov_b32_e32 v9, 0xffff8040
	v_lshlrev_b32_e32 v6, 2, v6
	v_cndmask_b32_e64 v134, 0, v9, s[6:7]
	v_mov_b32_e32 v9, 0x8000
	v_cndmask_b32_e64 v136, v9, 64, s[6:7]
	v_lshlrev_b32_e32 v9, 10, v2
	v_and_b32_e32 v9, 0xfffff800, v9
	v_lshl_add_u32 v3, v3, 7, v9
	v_and_b32_e32 v2, 1, v2
	v_and_b32_e32 v6, 32, v6
	v_lshl_or_b32 v2, v2, 6, v3
	v_bitop3_b32 v146, v11, s9, v6 bitop3:0xde
	v_bitop3_b32 v6, v11, s5, v6 bitop3:0xde
	s_mov_b64 s[4:5], 0xc000
	v_lshl_add_u32 v2, v4, 1, v2
	v_mov_b32_e32 v3, v131
	v_lshl_add_u64 v[138:139], v[2:3], 0, s[4:5]
	v_lshlrev_b32_e32 v2, 10, v5
	v_and_b32_e32 v2, 0xfffff800, v2
	v_lshl_add_u32 v2, v7, 7, v2
	v_and_b32_e32 v3, 1, v5
	s_waitcnt vmcnt(6)
	s_cmpk_lt_u32 s0, 0x100
	v_lshl_or_b32 v2, v3, 6, v2
	s_cselect_b64 s[12:13], -1, 0
	s_bfe_u32 s71, s90, 0x20006
	s_ashr_i32 s0, s82, 2
	v_lshl_add_u32 v2, v8, 1, v2
	v_mov_b32_e32 v3, v131
	s_add_i32 s72, 0, 0x10000
	s_add_i32 s73, 0, 0x14000
	v_cndmask_b32_e64 v135, 0, -1, s[6:7]
	v_mov_b32_e32 v137, v131
	s_add_i32 s80, s0, 32
	s_lshl_b32 s0, s71, 11
	v_lshl_or_b32 v147, s8, 6, v10
	v_lshl_add_u64 v[140:141], v[2:3], 0, s[4:5]
	s_mov_b64 s[4:5], -1
	s_movk_i32 s59, 0x80
	s_mov_b64 s[14:15], 0x10000
	v_add_u32_e32 v148, s72, v146
	v_add_u32_e32 v149, s73, v146
	v_add_u32_e32 v150, 0, v6
	s_mov_b64 s[18:19], 0x20000
	s_mov_b64 s[20:21], 0x30000
	s_mov_b64 s[22:23], 0x80000
	s_mov_b64 s[24:25], 0x90000
	s_mov_b64 s[26:27], 0xa0000
	s_mov_b64 s[28:29], 0xb0000
	s_mov_b32 s62, s82
	s_mov_b32 s46, 0
	s_barrier
	s_branch .LBB0_539

; #define PG8_STAGE(bufoff, gbase, voff) do { _Pragma("unroll") for (int _i = 0; _i < 2; ++_i) \
;         __builtin_amdgcn_global_load_lds((const unsigned*)((const char*)(gbase) + (voff)[_i]), (LAS unsigned*)(lds + (bufoff) + ldsw + _i * 8192), 16, 0, 0); } while (0)
; #define PG8_LDA(dst, b, h) do { _Pragma("unroll") for (int m = 0; m < 4; ++m) _Pragma("unroll") for (int k = 0; k < 2; ++k) dst[m][k] = *(const LAS bf16x8*)(lds + PG8_SA(b, h) + aoff + m * 2048 + k * 1024); } while (0)
; #define PG8_LDB(dst, b, h) do { _Pragma("unroll") for (int n = 0; n < 2; ++n) _Pragma("unroll") for (int k = 0; k < 2; ++k) dst[n][k] = *(const LAS bf16x8*)(lds + PG8_SB(b, h) + boff + n * 2048 + k * 1024); } while (0)
; #define PG8_MMA(ai, bj, At, Bt) do { __builtin_amdgcn_s_setprio(1); _Pragma("unroll") for (int m = 0; m < 4; ++m) _Pragma("unroll") for (int n = 0; n < 2; ++n) _Pragma("unroll") for (int k = 0; k < 2; ++k) \
;         acc[ai][bj][m][n] = __builtin_amdgcn_mfma_f32_16x16x32_bf16(Bt[n][k], At[m][k], acc[ai][bj][m][n], 0, 0, 0); __builtin_amdgcn_s_setprio(0); } while (0)
; #define PG8_WAIT_V(n) asm volatile("s_waitcnt vmcnt(" #n ")" ::: "memory")
; #define PG8_WAIT_L(n) asm volatile("s_waitcnt lgkmcnt(" #n ")" ::: "memory")
; #define PG8_BAR __builtin_amdgcn_s_barrier()
; #define PG8_SCHED __builtin_amdgcn_sched_barrier(0)
; template <class Epi, class Sched, bool ABLK = false, bool ALIGN_EPI = true, bool SP2 = true, bool BBLK = true>
; __device__ __forceinline__ void gemm_phase(LAS unsigned char* lds, const Gemm g, const Sched& S, const Epi& E) {
;     ...
;             const char* a1 = a_tile(uA, tbA + t + 1);
;             const char* a2 = last ? a_tile(nuA, ntbA) : a_tile(uA, tbA + t + 2); const char* b2 = last ? nB : cB + (size_t)(t + 2) * kstepB;
;             const char* a3 = last ? a_tile(nuA, ntbA + 1) : a_tile(uA, tbA + t + 3); const char* b3 = b2 + kstepB;
;             if (last && has_next) S.a_ready(nxt);
;             if constexpr (SP2) {
;             PG8_LDB(B0, 0, 0); PG8_LDB(B1, 0, 1); PG8_SCHED; PG8_LDA(At, 0, 0); PG8_STAGE(PG8_SA(1, 1), a1 + hstepA, voffA);
;             PG8_WAIT_V(8); PG8_WAIT_L(0); PG8_BAR; PG8_MMA(0, 0, At, B0); PG8_MMA(0, 1, At, B1); PG8_BAR; PG8_SCHED;
;             PG8_LDA(At, 0, 1); PG8_STAGE(PG8_SB(0, 0), b2, voffB); PG8_STAGE(PG8_SB(0, 1), b2 + hstepB, voffB); PG8_STAGE(PG8_SA(0, 0), a2, voffA);
.LBB0_540:
	ds_read_b128 v[152:155], v148
	ds_read_b128 v[156:159], v148 offset:1024
	ds_read_b128 v[160:163], v148 offset:2048
	ds_read_b128 v[164:167], v148 offset:3072
	ds_read_b128 v[168:171], v149
	ds_read_b128 v[172:175], v149 offset:1024
	ds_read_b128 v[176:179], v149 offset:2048
	ds_read_b128 v[180:183], v149 offset:3072
	s_add_u32 s42, s75, s40
	s_addc_u32 s43, s76, s41
	s_add_u32 s48, s42, 0x10000
	s_addc_u32 s49, s43, 0
	s_add_i32 s79, s79, 2
	s_add_u32 s46, s66, s40
	s_addc_u32 s47, s67, s41
	s_add_u32 s42, s42, 0x18000
	s_addc_u32 s43, s43, 0
	s_cmp_eq_u32 s77, s40
	s_cselect_b32 s43, s65, s43
	s_cselect_b32 s42, s64, s42
	s_cselect_b32 s47, s4, s47
	s_cselect_b32 s46, s5, s46
	s_cselect_b32 s49, s63, s49
	s_cselect_b32 s48, s35, s48
	v_lshl_add_u64 v[216:217], v[142:143], 0, s[40:41]
	s_add_i32 m0, s52, 0xc000
	ds_read_b128 v[184:187], v150
	ds_read_b128 v[188:191], v150 offset:1024
	ds_read_b128 v[192:195], v150 offset:2048
	ds_read_b128 v[196:199], v150 offset:3072
	ds_read_b128 v[200:203], v150 offset:4096
	ds_read_b128 v[204:207], v150 offset:5120
	ds_read_b128 v[208:211], v150 offset:6144
	ds_read_b128 v[212:215], v150 offset:7168
	global_load_lds_dwordx4 v[216:217], off
	v_lshl_add_u64 v[216:217], v[144:145], 0, s[40:41]
	s_add_i32 m0, s52, 0xe000
	s_nop 0
	global_load_lds_dwordx4 v[216:217], off
	s_waitcnt vmcnt(8)
	s_waitcnt lgkmcnt(0)
	s_barrier
	s_setprio 1
	s_waitcnt lgkmcnt(0)
	v_mfma_f32_16x16x32_bf16 v[126:129], v[152:155], v[184:187], v[126:129]
	v_mfma_f32_16x16x32_bf16 v[122:125], v[160:163], v[184:187], v[122:125]
	v_mfma_f32_16x16x32_bf16 v[110:113], v[152:155], v[192:195], v[110:113]
	v_mfma_f32_16x16x32_bf16 v[106:109], v[160:163], v[192:195], v[106:109]
	v_mfma_f32_16x16x32_bf16 v[94:97], v[152:155], v[200:203], v[94:97]
	v_mfma_f32_16x16x32_bf16 v[90:93], v[160:163], v[200:203], v[90:93]
	v_mfma_f32_16x16x32_bf16 v[78:81], v[152:155], v[208:211], v[78:81]
	v_mfma_f32_16x16x32_bf16 v[74:77], v[160:163], v[208:211], v[74:77]
	v_mfma_f32_16x16x32_bf16 v[126:129], v[156:159], v[188:191], v[126:129]
	v_mfma_f32_16x16x32_bf16 v[122:125], v[164:167], v[188:191], v[122:125]
	v_mfma_f32_16x16x32_bf16 v[110:113], v[156:159], v[196:199], v[110:113]
	v_mfma_f32_16x16x32_bf16 v[106:109], v[164:167], v[196:199], v[106:109]
	v_mfma_f32_16x16x32_bf16 v[94:97], v[156:159], v[204:207], v[94:97]
	v_mfma_f32_16x16x32_bf16 v[90:93], v[164:167], v[204:207], v[90:93]
	v_mfma_f32_16x16x32_bf16 v[78:81], v[156:159], v[212:215], v[78:81]
	v_mfma_f32_16x16x32_bf16 v[74:77], v[164:167], v[212:215], v[74:77]
	s_setprio 0
	s_setprio 1
	v_mfma_f32_16x16x32_bf16 v[118:121], v[168:171], v[184:187], v[118:121]
	v_mfma_f32_16x16x32_bf16 v[114:117], v[176:179], v[184:187], v[114:117]
	v_mfma_f32_16x16x32_bf16 v[102:105], v[168:171], v[192:195], v[102:105]
	v_mfma_f32_16x16x32_bf16 v[98:101], v[176:179], v[192:195], v[98:101]
	v_mfma_f32_16x16x32_bf16 v[86:89], v[168:171], v[200:203], v[86:89]
	v_mfma_f32_16x16x32_bf16 v[82:85], v[176:179], v[200:203], v[82:85]
	v_mfma_f32_16x16x32_bf16 v[70:73], v[168:171], v[208:211], v[70:73]
	v_mfma_f32_16x16x32_bf16 v[66:69], v[176:179], v[208:211], v[66:69]
	v_mfma_f32_16x16x32_bf16 v[118:121], v[172:175], v[188:191], v[118:121]
	v_mfma_f32_16x16x32_bf16 v[114:117], v[180:183], v[188:191], v[114:117]
	v_mfma_f32_16x16x32_bf16 v[102:105], v[172:175], v[196:199], v[102:105]
	v_mfma_f32_16x16x32_bf16 v[98:101], v[180:183], v[196:199], v[98:101]
	v_mfma_f32_16x16x32_bf16 v[86:89], v[172:175], v[204:207], v[86:89]
	v_mfma_f32_16x16x32_bf16 v[82:85], v[180:183], v[204:207], v[82:85]
	v_mfma_f32_16x16x32_bf16 v[70:73], v[172:175], v[212:215], v[70:73]
	v_mfma_f32_16x16x32_bf16 v[66:69], v[180:183], v[212:215], v[66:69]
	s_setprio 0
	s_barrier
	s_add_i32 s60, s72, s51
	s_mov_b32 m0, s60
	ds_read_b128 v[184:187], v150 offset:16384
	ds_read_b128 v[188:191], v150 offset:17408
	ds_read_b128 v[192:195], v150 offset:18432
	ds_read_b128 v[196:199], v150 offset:19456
	ds_read_b128 v[200:203], v150 offset:20480
	ds_read_b128 v[204:207], v150 offset:21504
	ds_read_b128 v[208:211], v150 offset:22528
	ds_read_b128 v[212:215], v150 offset:23552
	global_load_lds_dwordx4 v130, s[46:47]
	s_add_i32 m0, s60, 0x2000
	s_add_u32 s60, s46, 0x4000
	s_addc_u32 s61, s47, 0
	s_add_i32 s81, s73, s51
	global_load_lds_dwordx4 v132, s[46:47]
	s_mov_b32 m0, s81
	s_nop 0
	global_load_lds_dwordx4 v130, s[60:61]
	s_add_i32 m0, s81, 0x2000
	s_nop 0
	global_load_lds_dwordx4 v132, s[60:61]
	s_mov_b32 m0, s52
	s_nop 0
	global_load_lds_dwordx4 v130, s[48:49]
	s_mov_b32 m0, s53
	s_nop 0
	global_load_lds_dwordx4 v132, s[48:49]
	s_waitcnt vmcnt(8)
	s_waitcnt lgkmcnt(0)
	s_barrier
; #define PG8_STAGE(bufoff, gbase, voff) do { _Pragma("unroll") for (int _i = 0; _i < 2; ++_i) \
;         __builtin_amdgcn_global_load_lds((const unsigned*)((const char*)(gbase) + (voff)[_i]), (LAS unsigned*)(lds + (bufoff) + ldsw + _i * 8192), 16, 0, 0); } while (0)
; #define PG8_LDA(dst, b, h) do { _Pragma("unroll") for (int m = 0; m < 4; ++m) _Pragma("unroll") for (int k = 0; k < 2; ++k) dst[m][k] = *(const LAS bf16x8*)(lds + PG8_SA(b, h) + aoff + m * 2048 + k * 1024); } while (0)
; #define PG8_LDB(dst, b, h) do { _Pragma("unroll") for (int n = 0; n < 2; ++n) _Pragma("unroll") for (int k = 0; k < 2; ++k) dst[n][k] = *(const LAS bf16x8*)(lds + PG8_SB(b, h) + boff + n * 2048 + k * 1024); } while (0)
; #define PG8_MMA(ai, bj, At, Bt) do { __builtin_amdgcn_s_setprio(1); _Pragma("unroll") for (int m = 0; m < 4; ++m) _Pragma("unroll") for (int n = 0; n < 2; ++n) _Pragma("unroll") for (int k = 0; k < 2; ++k) \
;         acc[ai][bj][m][n] = __builtin_amdgcn_mfma_f32_16x16x32_bf16(Bt[n][k], At[m][k], acc[ai][bj][m][n], 0, 0, 0); __builtin_amdgcn_s_setprio(0); } while (0)
; #define PG8_WAIT_V(n) asm volatile("s_waitcnt vmcnt(" #n ")" ::: "memory")
; #define PG8_WAIT_L(n) asm volatile("s_waitcnt lgkmcnt(" #n ")" ::: "memory")
; #define PG8_BAR __builtin_amdgcn_s_barrier()
; #define PG8_SCHED __builtin_amdgcn_sched_barrier(0)
; template <class Epi, class Sched, bool ABLK = false, bool ALIGN_EPI = true, bool SP2 = true, bool BBLK = true>
; __device__ __forceinline__ void gemm_phase(LAS unsigned char* lds, const Gemm g, const Sched& S, const Epi& E) {
;     ...
;             PG8_WAIT_V(8); PG8_WAIT_L(0); PG8_BAR; PG8_MMA(1, 0, At, B0); PG8_MMA(1, 1, At, B1); PG8_BAR; PG8_SCHED;
;             PG8_LDB(B0, 1, 0); PG8_LDB(B1, 1, 1); PG8_SCHED; PG8_LDA(At, 1, 0); PG8_STAGE(PG8_SA(0, 1), a2 + hstepA, voffA);
;             PG8_WAIT_V(8); PG8_WAIT_L(0); PG8_BAR; PG8_MMA(0, 0, At, B0); PG8_MMA(0, 1, At, B1); PG8_BAR; PG8_SCHED;
	s_setprio 1
	s_waitcnt lgkmcnt(0)
	v_mfma_f32_16x16x32_bf16 v[62:65], v[152:155], v[184:187], v[62:65]
	v_mfma_f32_16x16x32_bf16 v[58:61], v[160:163], v[184:187], v[58:61]
	v_mfma_f32_16x16x32_bf16 v[46:49], v[152:155], v[192:195], v[46:49]
	v_mfma_f32_16x16x32_bf16 v[42:45], v[160:163], v[192:195], v[42:45]
	v_mfma_f32_16x16x32_bf16 v[30:33], v[152:155], v[200:203], v[30:33]
	v_mfma_f32_16x16x32_bf16 v[26:29], v[160:163], v[200:203], v[26:29]
	v_mfma_f32_16x16x32_bf16 v[14:17], v[152:155], v[208:211], v[14:17]
	v_mfma_f32_16x16x32_bf16 v[10:13], v[160:163], v[208:211], v[10:13]
	v_mfma_f32_16x16x32_bf16 v[62:65], v[156:159], v[188:191], v[62:65]
	v_mfma_f32_16x16x32_bf16 v[58:61], v[164:167], v[188:191], v[58:61]
	v_mfma_f32_16x16x32_bf16 v[46:49], v[156:159], v[196:199], v[46:49]
	v_mfma_f32_16x16x32_bf16 v[42:45], v[164:167], v[196:199], v[42:45]
	v_mfma_f32_16x16x32_bf16 v[30:33], v[156:159], v[204:207], v[30:33]
	v_mfma_f32_16x16x32_bf16 v[26:29], v[164:167], v[204:207], v[26:29]
	v_mfma_f32_16x16x32_bf16 v[14:17], v[156:159], v[212:215], v[14:17]
	v_mfma_f32_16x16x32_bf16 v[10:13], v[164:167], v[212:215], v[10:13]
	s_setprio 0
	s_setprio 1
	v_mfma_f32_16x16x32_bf16 v[54:57], v[168:171], v[184:187], v[54:57]
	v_mfma_f32_16x16x32_bf16 v[50:53], v[176:179], v[184:187], v[50:53]
	v_mfma_f32_16x16x32_bf16 v[38:41], v[168:171], v[192:195], v[38:41]
	v_mfma_f32_16x16x32_bf16 v[34:37], v[176:179], v[192:195], v[34:37]
	v_mfma_f32_16x16x32_bf16 v[22:25], v[168:171], v[200:203], v[22:25]
	v_mfma_f32_16x16x32_bf16 v[18:21], v[176:179], v[200:203], v[18:21]
	v_mfma_f32_16x16x32_bf16 v[6:9], v[168:171], v[208:211], v[6:9]
	v_mfma_f32_16x16x32_bf16 v[2:5], v[176:179], v[208:211], v[2:5]
	v_mfma_f32_16x16x32_bf16 v[54:57], v[172:175], v[188:191], v[54:57]
	v_mfma_f32_16x16x32_bf16 v[50:53], v[180:183], v[188:191], v[50:53]
	v_mfma_f32_16x16x32_bf16 v[38:41], v[172:175], v[196:199], v[38:41]
	v_mfma_f32_16x16x32_bf16 v[34:37], v[180:183], v[196:199], v[34:37]
	v_mfma_f32_16x16x32_bf16 v[22:25], v[172:175], v[204:207], v[22:25]
	v_mfma_f32_16x16x32_bf16 v[18:21], v[180:183], v[204:207], v[18:21]
	v_mfma_f32_16x16x32_bf16 v[6:9], v[172:175], v[212:215], v[6:9]
	v_mfma_f32_16x16x32_bf16 v[2:5], v[180:183], v[212:215], v[2:5]
	s_setprio 0
	s_barrier
	s_add_i32 s60, 0, 0x18000
	v_add_u32_e32 v151, s60, v146
	s_add_i32 s61, 0, 0x1c000
	ds_read_b128 v[152:155], v151
	ds_read_b128 v[156:159], v151 offset:1024
	ds_read_b128 v[160:163], v151 offset:2048
	ds_read_b128 v[164:167], v151 offset:3072
	v_add_u32_e32 v151, s61, v146
	ds_read_b128 v[168:171], v151
	ds_read_b128 v[172:175], v151 offset:1024
	ds_read_b128 v[176:179], v151 offset:2048
	ds_read_b128 v[180:183], v151 offset:3072
	s_add_u32 s48, s48, 0x4000
	s_addc_u32 s49, s49, 0
	s_mov_b32 m0, s54
	ds_read_b128 v[184:187], v150 offset:32768
	ds_read_b128 v[188:191], v150 offset:33792
	ds_read_b128 v[192:195], v150 offset:34816
	ds_read_b128 v[196:199], v150 offset:35840
	ds_read_b128 v[200:203], v150 offset:36864
	ds_read_b128 v[204:207], v150 offset:37888
	ds_read_b128 v[208:211], v150 offset:38912
	ds_read_b128 v[212:215], v150 offset:39936
	global_load_lds_dwordx4 v130, s[48:49]
	s_mov_b32 m0, s55
	s_nop 0
	global_load_lds_dwordx4 v132, s[48:49]
	s_waitcnt vmcnt(8)
	s_waitcnt lgkmcnt(0)
	s_barrier
	s_setprio 1
	s_waitcnt lgkmcnt(0)
	v_mfma_f32_16x16x32_bf16 v[126:129], v[152:155], v[184:187], v[126:129]
	v_mfma_f32_16x16x32_bf16 v[122:125], v[160:163], v[184:187], v[122:125]
	v_mfma_f32_16x16x32_bf16 v[110:113], v[152:155], v[192:195], v[110:113]
	v_mfma_f32_16x16x32_bf16 v[106:109], v[160:163], v[192:195], v[106:109]
	v_mfma_f32_16x16x32_bf16 v[94:97], v[152:155], v[200:203], v[94:97]
	v_mfma_f32_16x16x32_bf16 v[90:93], v[160:163], v[200:203], v[90:93]
	v_mfma_f32_16x16x32_bf16 v[78:81], v[152:155], v[208:211], v[78:81]
	v_mfma_f32_16x16x32_bf16 v[74:77], v[160:163], v[208:211], v[74:77]
	v_mfma_f32_16x16x32_bf16 v[126:129], v[156:159], v[188:191], v[126:129]
	v_mfma_f32_16x16x32_bf16 v[122:125], v[164:167], v[188:191], v[122:125]
	v_mfma_f32_16x16x32_bf16 v[110:113], v[156:159], v[196:199], v[110:113]
	v_mfma_f32_16x16x32_bf16 v[106:109], v[164:167], v[196:199], v[106:109]
	v_mfma_f32_16x16x32_bf16 v[94:97], v[156:159], v[204:207], v[94:97]
	v_mfma_f32_16x16x32_bf16 v[90:93], v[164:167], v[204:207], v[90:93]
	v_mfma_f32_16x16x32_bf16 v[78:81], v[156:159], v[212:215], v[78:81]
	v_mfma_f32_16x16x32_bf16 v[74:77], v[164:167], v[212:215], v[74:77]
	s_setprio 0
	s_setprio 1
	v_mfma_f32_16x16x32_bf16 v[118:121], v[168:171], v[184:187], v[118:121]
	v_mfma_f32_16x16x32_bf16 v[114:117], v[176:179], v[184:187], v[114:117]
	v_mfma_f32_16x16x32_bf16 v[102:105], v[168:171], v[192:195], v[102:105]
	v_mfma_f32_16x16x32_bf16 v[98:101], v[176:179], v[192:195], v[98:101]
	v_mfma_f32_16x16x32_bf16 v[86:89], v[168:171], v[200:203], v[86:89]
	v_mfma_f32_16x16x32_bf16 v[82:85], v[176:179], v[200:203], v[82:85]
	v_mfma_f32_16x16x32_bf16 v[70:73], v[168:171], v[208:211], v[70:73]
	v_mfma_f32_16x16x32_bf16 v[66:69], v[176:179], v[208:211], v[66:69]
	v_mfma_f32_16x16x32_bf16 v[118:121], v[172:175], v[188:191], v[118:121]
	v_mfma_f32_16x16x32_bf16 v[114:117], v[180:183], v[188:191], v[114:117]
	v_mfma_f32_16x16x32_bf16 v[102:105], v[172:175], v[196:199], v[102:105]
	v_mfma_f32_16x16x32_bf16 v[98:101], v[180:183], v[196:199], v[98:101]
	v_mfma_f32_16x16x32_bf16 v[86:89], v[172:175], v[204:207], v[86:89]
	v_mfma_f32_16x16x32_bf16 v[82:85], v[180:183], v[204:207], v[82:85]
	v_mfma_f32_16x16x32_bf16 v[70:73], v[172:175], v[212:215], v[70:73]
	v_mfma_f32_16x16x32_bf16 v[66:69], v[180:183], v[212:215], v[66:69]
	s_setprio 0
	s_barrier
; #define PG8_STAGE(bufoff, gbase, voff) do { _Pragma("unroll") for (int _i = 0; _i < 2; ++_i) \
;         __builtin_amdgcn_global_load_lds((const unsigned*)((const char*)(gbase) + (voff)[_i]), (LAS unsigned*)(lds + (bufoff) + ldsw + _i * 8192), 16, 0, 0); } while (0)
; #define PG8_LDA(dst, b, h) do { _Pragma("unroll") for (int m = 0; m < 4; ++m) _Pragma("unroll") for (int k = 0; k < 2; ++k) dst[m][k] = *(const LAS bf16x8*)(lds + PG8_SA(b, h) + aoff + m * 2048 + k * 1024); } while (0)
; #define PG8_MMA(ai, bj, At, Bt) do { __builtin_amdgcn_s_setprio(1); _Pragma("unroll") for (int m = 0; m < 4; ++m) _Pragma("unroll") for (int n = 0; n < 2; ++n) _Pragma("unroll") for (int k = 0; k < 2; ++k) \
;         acc[ai][bj][m][n] = __builtin_amdgcn_mfma_f32_16x16x32_bf16(Bt[n][k], At[m][k], acc[ai][bj][m][n], 0, 0, 0); __builtin_amdgcn_s_setprio(0); } while (0)
; #define PG8_WAIT_V(n) asm volatile("s_waitcnt vmcnt(" #n ")" ::: "memory")
; #define PG8_WAIT_L(n) asm volatile("s_waitcnt lgkmcnt(" #n ")" ::: "memory")
; #define PG8_BAR __builtin_amdgcn_s_barrier()
; #define PG8_SCHED __builtin_amdgcn_sched_barrier(0)
; template <class Epi, class Sched, bool ABLK = false, bool ALIGN_EPI = true, bool SP2 = true, bool BBLK = true>
; __device__ __forceinline__ void gemm_phase(LAS unsigned char* lds, const Gemm g, const Sched& S, const Epi& E) {
;     ...
;             PG8_LDA(At, 1, 1); PG8_STAGE(PG8_SB(1, 0), b3, voffB); PG8_STAGE(PG8_SB(1, 1), b3 + hstepB, voffB); PG8_STAGE(PG8_SA(1, 0), a3, voffA);
;             PG8_WAIT_V(8); PG8_WAIT_L(0); PG8_BAR; PG8_MMA(1, 0, At, B0); PG8_MMA(1, 1, At, B1); PG8_BAR; PG8_SCHED;
	s_add_u32 s48, s46, 0x8000
	s_addc_u32 s49, s47, 0
	s_add_i32 s81, s60, s51
	s_mov_b32 m0, s81
	ds_read_b128 v[184:187], v150 offset:49152
	ds_read_b128 v[188:191], v150 offset:50176
	ds_read_b128 v[192:195], v150 offset:51200
	ds_read_b128 v[196:199], v150 offset:52224
	ds_read_b128 v[200:203], v150 offset:53248
	ds_read_b128 v[204:207], v150 offset:54272
	ds_read_b128 v[208:211], v150 offset:55296
	ds_read_b128 v[212:215], v150 offset:56320
	global_load_lds_dwordx4 v130, s[48:49]
	s_add_i32 m0, s81, 0x2000
	s_add_u32 s46, s46, 0xc000
	v_lshl_add_u64 v[216:217], s[48:49], 0, v[132:133]
	s_addc_u32 s47, s47, 0
	s_add_i32 s48, s61, s51
	global_load_lds_dwordx4 v[216:217], off
	s_mov_b32 m0, s48
	s_nop 0
	global_load_lds_dwordx4 v130, s[46:47]
	s_add_i32 m0, s48, 0x2000
	s_nop 0
	global_load_lds_dwordx4 v132, s[46:47]
	s_mov_b32 m0, s56
	s_nop 0
	global_load_lds_dwordx4 v130, s[42:43]
	s_mov_b32 m0, s57
	s_nop 0
	global_load_lds_dwordx4 v132, s[42:43]
	s_waitcnt vmcnt(8)
	s_waitcnt lgkmcnt(0)
	s_barrier
	s_setprio 1
	s_waitcnt lgkmcnt(0)
	v_mfma_f32_16x16x32_bf16 v[62:65], v[152:155], v[184:187], v[62:65]
	v_mfma_f32_16x16x32_bf16 v[58:61], v[160:163], v[184:187], v[58:61]
	v_mfma_f32_16x16x32_bf16 v[46:49], v[152:155], v[192:195], v[46:49]
	v_mfma_f32_16x16x32_bf16 v[42:45], v[160:163], v[192:195], v[42:45]
	v_mfma_f32_16x16x32_bf16 v[30:33], v[152:155], v[200:203], v[30:33]
	v_mfma_f32_16x16x32_bf16 v[26:29], v[160:163], v[200:203], v[26:29]
	v_mfma_f32_16x16x32_bf16 v[14:17], v[152:155], v[208:211], v[14:17]
	v_mfma_f32_16x16x32_bf16 v[10:13], v[160:163], v[208:211], v[10:13]
	v_mfma_f32_16x16x32_bf16 v[62:65], v[156:159], v[188:191], v[62:65]
	v_mfma_f32_16x16x32_bf16 v[58:61], v[164:167], v[188:191], v[58:61]
	v_mfma_f32_16x16x32_bf16 v[46:49], v[156:159], v[196:199], v[46:49]
	v_mfma_f32_16x16x32_bf16 v[42:45], v[164:167], v[196:199], v[42:45]
	v_mfma_f32_16x16x32_bf16 v[30:33], v[156:159], v[204:207], v[30:33]
	v_mfma_f32_16x16x32_bf16 v[26:29], v[164:167], v[204:207], v[26:29]
	v_mfma_f32_16x16x32_bf16 v[14:17], v[156:159], v[212:215], v[14:17]
	v_mfma_f32_16x16x32_bf16 v[10:13], v[164:167], v[212:215], v[10:13]
	s_setprio 0
	s_setprio 1
	v_mfma_f32_16x16x32_bf16 v[54:57], v[168:171], v[184:187], v[54:57]
	v_mfma_f32_16x16x32_bf16 v[50:53], v[176:179], v[184:187], v[50:53]
	v_mfma_f32_16x16x32_bf16 v[38:41], v[168:171], v[192:195], v[38:41]
	v_mfma_f32_16x16x32_bf16 v[34:37], v[176:179], v[192:195], v[34:37]
	v_mfma_f32_16x16x32_bf16 v[22:25], v[168:171], v[200:203], v[22:25]
	v_mfma_f32_16x16x32_bf16 v[18:21], v[176:179], v[200:203], v[18:21]
	v_mfma_f32_16x16x32_bf16 v[6:9], v[168:171], v[208:211], v[6:9]
	v_mfma_f32_16x16x32_bf16 v[2:5], v[176:179], v[208:211], v[2:5]
	v_mfma_f32_16x16x32_bf16 v[54:57], v[172:175], v[188:191], v[54:57]
	v_mfma_f32_16x16x32_bf16 v[50:53], v[180:183], v[188:191], v[50:53]
	v_mfma_f32_16x16x32_bf16 v[38:41], v[172:175], v[196:199], v[38:41]
	v_mfma_f32_16x16x32_bf16 v[34:37], v[180:183], v[196:199], v[34:37]
	v_mfma_f32_16x16x32_bf16 v[22:25], v[172:175], v[204:207], v[22:25]
	v_mfma_f32_16x16x32_bf16 v[18:21], v[180:183], v[204:207], v[18:21]
	v_mfma_f32_16x16x32_bf16 v[6:9], v[172:175], v[212:215], v[6:9]
	v_mfma_f32_16x16x32_bf16 v[2:5], v[180:183], v[212:215], v[2:5]
	s_setprio 0
	s_barrier
	s_add_u32 s40, s40, 0x10000
	s_addc_u32 s41, s41, 0
	s_cmp_ge_u32 s79, s59
	s_cbranch_scc0 .LBB0_540
	s_and_b64 vcc, exec, s[12:13]
	s_cbranch_vccz .LBB0_543
	s_barrier

; __device__ __forceinline__ unsigned pk2(float lo, float hi) { const f32x2 v = {lo, hi}; return __builtin_bit_cast(unsigned, __builtin_convertvector(v, bf16x2_t)); }
; #define PG8_STAGE(bufoff, gbase, voff) do { _Pragma("unroll") for (int _i = 0; _i < 2; ++_i) \
;         __builtin_amdgcn_global_load_lds((const unsigned*)((const char*)(gbase) + (voff)[_i]), (LAS unsigned*)(lds + (bufoff) + ldsw + _i * 8192), 16, 0, 0); } while (0)
; #define PG8_WAIT_V(n) asm volatile("s_waitcnt vmcnt(" #n ")" ::: "memory")
; #define PG8_BAR __builtin_amdgcn_s_barrier()
; template <class Epi, class Sched, bool ABLK = false, bool ALIGN_EPI = true, bool SP2 = true, bool BBLK = true>
; __device__ __forceinline__ void gemm_phase(LAS unsigned char* lds, const Gemm g, const Sched& S, const Epi& E) {
;     ...
;         PG8_STAGE(PG8_SB(1, 0), cB + kstepB, voffB); PG8_STAGE(PG8_SA(1, 0), a_tile(uA, tbA + 1), voffA); PG8_STAGE(PG8_SB(1, 1), cB + hstepB + kstepB, voffB);
;         PG8_WAIT_V(6); PG8_BAR;
;     __device__ __forceinline__ void operator()(const f32x4 (&acc)[2][2][4][2], const Unit& u, int wr, int wc, int fr, int fq) const {
;         const int t = u.pn >> 3; const int colt = (u.pn & 7) * 256;
;         const int col0 = colt + wc * 64 + 8 * fq;
;         bf16_t* base = QKV + (size_t)t * M * D;
;         float* fdst = nullptr;
;         if (t >= 1) {
;             if (u.pm < 32) { if ((u.pm & 7) >= 6) { const int n = u.pm >> 3; fdst = out + (t == 1 ? O_KP : O_VP) + ((size_t)n * 512 + (size_t)((u.pm & 7) - 6) * 256) * D; } }
;             else fdst = out + (t == 1 ? O_KS : O_VS) + (size_t)(u.pm - 32) * 256 * D;
;         }
; #pragma unroll
;         for (int ai = 0; ai < 2; ++ai)
; #pragma unroll
;             for (int m = 0; m < 4; ++m) { const int rl = wr * 64 + fr + ai * 128 + m * 16; u32x4 w[2];
; #pragma unroll
;                 for (int bj = 0; bj < 2; ++bj) { const f32x4 v0 = acc[ai][bj][m][0], v1 = acc[ai][bj][m][1];
;                     w[bj].x = pk2(v0[0], v0[1]); w[bj].y = pk2(v0[2], v0[3]); w[bj].z = pk2(v1[0], v1[1]); w[bj].w = pk2(v1[2], v1[3]);
;                     if (fdst) { float* fp = fdst + (size_t)rl * D + col0 + bj * 32; *(f32x4*)fp = v0; *(f32x4*)(fp + 4) = v1; } }
;                 store_pair((unsigned char*)(base + (size_t)(u.pm * 256 + rl) * D + col0), (size_t)8 * D * 2, 64, w[0], w[1], fr >= 8); }
.LBB0_662:
	s_and_b32 s2, s2, 3
	s_lshl_b32 s9, s5, 13
	s_lshl_b32 s12, s2, 12
	s_add_u32 s6, s28, 0x8000
	s_addc_u32 s7, s29, 0
	s_add_i32 m0, s25, 0x18000
	v_lshl_add_u64 v[12:13], s[6:7], 0, v[132:133]
	s_waitcnt vmcnt(2)
	s_barrier
	global_load_lds_dwordx4 v[12:13], off
	v_lshl_add_u64 v[12:13], s[6:7], 0, v[136:137]
	s_add_i32 m0, s25, 0x1a000
	s_mov_b64 s[6:7], 0x80
	s_add_i32 s47, s25, 0x8000
	global_load_lds_dwordx4 v[12:13], off
	v_lshl_add_u64 v[2:3], v[2:3], 0, s[6:7]
	s_mov_b32 m0, s47
	s_add_i32 s48, s25, 0xa000
	global_load_lds_dwordx4 v[2:3], off
	v_lshl_add_u64 v[2:3], v[4:5], 0, s[6:7]
	s_add_u32 s6, s28, 0xc000
	s_mov_b32 m0, s48
	s_addc_u32 s7, s29, 0
	global_load_lds_dwordx4 v[2:3], off
	s_add_i32 m0, s25, 0x1c000
	s_nop 0
	global_load_lds_dwordx4 v132, s[6:7]
	s_add_i32 m0, s25, 0x1e000
	s_cmpk_lt_u32 s4, 0x100
	global_load_lds_dwordx4 v136, s[6:7]
	v_lshrrev_b32_e32 v3, 1, v1
	v_and_b32_e32 v3, 24, v3
	v_and_b32_e32 v2, 15, v1
	v_lshlrev_b32_e32 v4, 1, v3
	v_lshl_or_b32 v140, s5, 6, v2
	v_lshl_or_b32 v4, v2, 6, v4
	v_cmp_lt_u32_e64 s[6:7], 7, v2
	v_mov_b32_e32 v2, 0xffff8040
	v_ashrrev_i32_e32 v141, 31, v140
	v_cndmask_b32_e64 v142, 0, v2, s[6:7]
	v_mov_b32_e32 v2, 0x8000
	v_cndmask_b32_e64 v144, v2, 64, s[6:7]
	v_lshlrev_b32_e32 v2, 15, v6
	v_and_b32_e32 v2, 0xffff0000, v2
	v_lshlrev_b64 v[146:147], 13, v[140:141]
	v_lshl_or_b32 v141, s2, 6, v3
	v_lshl_add_u32 v2, v7, 12, v2
	v_and_b32_e32 v3, 1, v6
	v_lshl_or_b32 v2, v3, 6, v2
	v_lshl_add_u32 v138, v8, 1, v2
	v_lshlrev_b32_e32 v2, 15, v9
	v_and_b32_e32 v2, 0xffff0000, v2
	v_lshlrev_b32_e32 v1, 2, v1
	v_lshl_add_u32 v2, v10, 12, v2
	v_and_b32_e32 v3, 1, v9
	v_and_b32_e32 v1, 32, v1
	s_waitcnt vmcnt(6)
	v_or_b32_e32 v148, 16, v140
	v_or_b32_e32 v152, 32, v140
	v_or_b32_e32 v156, 48, v140
	v_add_u32_e32 v160, 0x80, v140
	v_add_u32_e32 v164, 0x90, v140
	v_add_u32_e32 v168, 0xa0, v140
	v_add_u32_e32 v172, 0xb0, v140
	s_mov_b64 s[4:5], 0x80080
	v_lshl_or_b32 v2, v3, 6, v2
	v_bitop3_b32 v5, v4, s9, v1 bitop3:0xde
	v_bitop3_b32 v1, v4, s12, v1 bitop3:0xde
	v_ashrrev_i32_e32 v149, 31, v148
	v_ashrrev_i32_e32 v153, 31, v152
	v_ashrrev_i32_e32 v157, 31, v156
	v_ashrrev_i32_e32 v161, 31, v160
	v_ashrrev_i32_e32 v165, 31, v164
	v_ashrrev_i32_e32 v169, 31, v168
	v_ashrrev_i32_e32 v173, 31, v172
	v_lshl_add_u64 v[176:177], v[138:139], 0, s[4:5]
	v_lshl_add_u32 v138, v11, 1, v2
	s_cselect_b64 s[12:13], -1, 0
	v_cndmask_b32_e64 v143, 0, -1, s[6:7]
	v_mov_b32_e32 v145, v139
	v_lshlrev_b64 v[150:151], 13, v[148:149]
	v_lshlrev_b64 v[154:155], 13, v[152:153]
	v_lshlrev_b64 v[158:159], 13, v[156:157]
	v_lshlrev_b64 v[162:163], 13, v[160:161]
	v_lshlrev_b64 v[166:167], 13, v[164:165]
	v_lshlrev_b64 v[170:171], 13, v[168:169]
	v_lshlrev_b64 v[174:175], 13, v[172:173]
	v_lshl_add_u64 v[178:179], v[138:139], 0, s[4:5]
	v_add_u32_e32 v149, 0, v5
	s_mov_b32 s49, 0x7880000
	s_mov_b32 s50, 0x5080000
	v_add_u32_e32 v153, s72, v1
	v_add_u32_e32 v157, s73, v1
	s_mov_b32 s51, 0
	s_barrier
	s_branch .LBB0_665

; #define PG8_STAGE(bufoff, gbase, voff) do { _Pragma("unroll") for (int _i = 0; _i < 2; ++_i) \
;         __builtin_amdgcn_global_load_lds((const unsigned*)((const char*)(gbase) + (voff)[_i]), (LAS unsigned*)(lds + (bufoff) + ldsw + _i * 8192), 16, 0, 0); } while (0)
; #define PG8_LDA(dst, b, h) do { _Pragma("unroll") for (int m = 0; m < 4; ++m) _Pragma("unroll") for (int k = 0; k < 2; ++k) dst[m][k] = *(const LAS bf16x8*)(lds + PG8_SA(b, h) + aoff + m * 2048 + k * 1024); } while (0)
; #define PG8_LDB(dst, b, h) do { _Pragma("unroll") for (int n = 0; n < 2; ++n) _Pragma("unroll") for (int k = 0; k < 2; ++k) dst[n][k] = *(const LAS bf16x8*)(lds + PG8_SB(b, h) + boff + n * 2048 + k * 1024); } while (0)
; #define PG8_MMA(ai, bj, At, Bt) do { __builtin_amdgcn_s_setprio(1); _Pragma("unroll") for (int m = 0; m < 4; ++m) _Pragma("unroll") for (int n = 0; n < 2; ++n) _Pragma("unroll") for (int k = 0; k < 2; ++k) \
;         acc[ai][bj][m][n] = __builtin_amdgcn_mfma_f32_16x16x32_bf16(Bt[n][k], At[m][k], acc[ai][bj][m][n], 0, 0, 0); __builtin_amdgcn_s_setprio(0); } while (0)
; #define PG8_WAIT_V(n) asm volatile("s_waitcnt vmcnt(" #n ")" ::: "memory")
; #define PG8_WAIT_L(n) asm volatile("s_waitcnt lgkmcnt(" #n ")" ::: "memory")
; #define PG8_BAR __builtin_amdgcn_s_barrier()
; #define PG8_SCHED __builtin_amdgcn_sched_barrier(0)
; template <class Epi, class Sched, bool ABLK = false, bool ALIGN_EPI = true, bool SP2 = true, bool BBLK = true>
; __device__ __forceinline__ void gemm_phase(LAS unsigned char* lds, const Gemm g, const Sched& S, const Epi& E) {
;     ...
;             const char* a1 = a_tile(uA, tbA + t + 1);
;             const char* a2 = last ? a_tile(nuA, ntbA) : a_tile(uA, tbA + t + 2); const char* b2 = last ? nB : cB + (size_t)(t + 2) * kstepB;
;             const char* a3 = last ? a_tile(nuA, ntbA + 1) : a_tile(uA, tbA + t + 3); const char* b3 = b2 + kstepB;
;             if (last && has_next) S.a_ready(nxt);
;             if constexpr (SP2) {
;             PG8_LDB(B0, 0, 0); PG8_LDB(B1, 0, 1); PG8_SCHED; PG8_LDA(At, 0, 0); PG8_STAGE(PG8_SA(1, 1), a1 + hstepA, voffA);
;             PG8_WAIT_V(8); PG8_WAIT_L(0); PG8_BAR; PG8_MMA(0, 0, At, B0); PG8_MMA(0, 1, At, B1); PG8_BAR; PG8_SCHED;
;             PG8_LDA(At, 0, 1); PG8_STAGE(PG8_SB(0, 0), b2, voffB); PG8_STAGE(PG8_SB(0, 1), b2 + hstepB, voffB); PG8_STAGE(PG8_SA(0, 0), a2, voffA);
.LBB0_668:
	ds_read_b128 v[184:187], v153
	ds_read_b128 v[188:191], v153 offset:1024
	ds_read_b128 v[192:195], v153 offset:2048
	ds_read_b128 v[196:199], v153 offset:3072
	ds_read_b128 v[200:203], v157
	ds_read_b128 v[204:207], v157 offset:1024
	ds_read_b128 v[208:211], v157 offset:2048
	ds_read_b128 v[212:215], v157 offset:3072
	s_add_u32 s30, s26, s28
	s_addc_u32 s31, s27, s29
	s_add_u32 s36, s30, 0x100
	s_addc_u32 s37, s31, 0
	s_add_u32 s30, s30, 0x180
	s_addc_u32 s31, s31, 0
	s_cmpk_eq_i32 s28, 0xf00
	s_cselect_b32 s31, s17, s31
	s_cselect_b32 s30, s15, s30
	s_cselect_b32 s35, s5, s53
	s_cselect_b32 s34, s9, s52
	s_cselect_b32 s37, s2, s37
	s_cselect_b32 s36, s4, s36
	v_lshl_add_u64 v[248:249], v[180:181], 0, s[28:29]
	s_add_i32 m0, s25, 0xc000
	ds_read_b128 v[216:219], v149
	ds_read_b128 v[220:223], v149 offset:1024
	ds_read_b128 v[224:227], v149 offset:2048
	ds_read_b128 v[228:231], v149 offset:3072
	ds_read_b128 v[232:235], v149 offset:4096
	ds_read_b128 v[236:239], v149 offset:5120
	ds_read_b128 v[240:243], v149 offset:6144
	ds_read_b128 v[244:247], v149 offset:7168
	global_load_lds_dwordx4 v[248:249], off
	v_lshl_add_u64 v[248:249], v[182:183], 0, s[28:29]
	s_add_i32 m0, s25, 0xe000
	s_nop 0
	global_load_lds_dwordx4 v[248:249], off
	s_waitcnt vmcnt(8)
	s_waitcnt lgkmcnt(0)
	s_barrier
	s_setprio 1
	s_waitcnt lgkmcnt(0)
	v_mfma_f32_16x16x32_bf16 v[126:129], v[184:187], v[216:219], v[126:129]
	v_mfma_f32_16x16x32_bf16 v[122:125], v[192:195], v[216:219], v[122:125]
	v_mfma_f32_16x16x32_bf16 v[110:113], v[184:187], v[224:227], v[110:113]
	v_mfma_f32_16x16x32_bf16 v[106:109], v[192:195], v[224:227], v[106:109]
	v_mfma_f32_16x16x32_bf16 v[94:97], v[184:187], v[232:235], v[94:97]
	v_mfma_f32_16x16x32_bf16 v[90:93], v[192:195], v[232:235], v[90:93]
	v_mfma_f32_16x16x32_bf16 v[78:81], v[184:187], v[240:243], v[78:81]
	v_mfma_f32_16x16x32_bf16 v[74:77], v[192:195], v[240:243], v[74:77]
	v_mfma_f32_16x16x32_bf16 v[126:129], v[188:191], v[220:223], v[126:129]
	v_mfma_f32_16x16x32_bf16 v[122:125], v[196:199], v[220:223], v[122:125]
	v_mfma_f32_16x16x32_bf16 v[110:113], v[188:191], v[228:231], v[110:113]
	v_mfma_f32_16x16x32_bf16 v[106:109], v[196:199], v[228:231], v[106:109]
	v_mfma_f32_16x16x32_bf16 v[94:97], v[188:191], v[236:239], v[94:97]
	v_mfma_f32_16x16x32_bf16 v[90:93], v[196:199], v[236:239], v[90:93]
	v_mfma_f32_16x16x32_bf16 v[78:81], v[188:191], v[244:247], v[78:81]
	v_mfma_f32_16x16x32_bf16 v[74:77], v[196:199], v[244:247], v[74:77]
	s_setprio 0
	s_setprio 1
	v_mfma_f32_16x16x32_bf16 v[118:121], v[200:203], v[216:219], v[118:121]
	v_mfma_f32_16x16x32_bf16 v[114:117], v[208:211], v[216:219], v[114:117]
	v_mfma_f32_16x16x32_bf16 v[102:105], v[200:203], v[224:227], v[102:105]
	v_mfma_f32_16x16x32_bf16 v[98:101], v[208:211], v[224:227], v[98:101]
	v_mfma_f32_16x16x32_bf16 v[86:89], v[200:203], v[232:235], v[86:89]
	v_mfma_f32_16x16x32_bf16 v[82:85], v[208:211], v[232:235], v[82:85]
	v_mfma_f32_16x16x32_bf16 v[70:73], v[200:203], v[240:243], v[70:73]
	v_mfma_f32_16x16x32_bf16 v[66:69], v[208:211], v[240:243], v[66:69]
	v_mfma_f32_16x16x32_bf16 v[118:121], v[204:207], v[220:223], v[118:121]
	v_mfma_f32_16x16x32_bf16 v[114:117], v[212:215], v[220:223], v[114:117]
	v_mfma_f32_16x16x32_bf16 v[102:105], v[204:207], v[228:231], v[102:105]
	v_mfma_f32_16x16x32_bf16 v[98:101], v[212:215], v[228:231], v[98:101]
	v_mfma_f32_16x16x32_bf16 v[86:89], v[204:207], v[236:239], v[86:89]
	v_mfma_f32_16x16x32_bf16 v[82:85], v[212:215], v[236:239], v[82:85]
	v_mfma_f32_16x16x32_bf16 v[70:73], v[204:207], v[244:247], v[70:73]
	v_mfma_f32_16x16x32_bf16 v[66:69], v[212:215], v[244:247], v[66:69]
	s_setprio 0
	s_barrier
	s_add_i32 s55, s72, s41
	s_mov_b32 m0, s55
	ds_read_b128 v[216:219], v149 offset:16384
	ds_read_b128 v[220:223], v149 offset:17408
	ds_read_b128 v[224:227], v149 offset:18432
	ds_read_b128 v[228:231], v149 offset:19456
	ds_read_b128 v[232:235], v149 offset:20480
	ds_read_b128 v[236:239], v149 offset:21504
	ds_read_b128 v[240:243], v149 offset:22528
	ds_read_b128 v[244:247], v149 offset:23552
	global_load_lds_dwordx4 v132, s[34:35]
	s_add_i32 m0, s55, 0x2000
	s_add_u32 s56, s34, 0x4000
	s_addc_u32 s57, s35, 0
	s_add_i32 s55, s73, s41
	global_load_lds_dwordx4 v136, s[34:35]
	s_mov_b32 m0, s55
	s_nop 0
	global_load_lds_dwordx4 v132, s[56:57]
	s_add_i32 m0, s55, 0x2000
	s_nop 0
	global_load_lds_dwordx4 v136, s[56:57]
	s_mov_b32 m0, s25
	s_nop 0
	global_load_lds_dwordx4 v130, s[36:37]
	s_mov_b32 m0, s42
	s_nop 0
	global_load_lds_dwordx4 v134, s[36:37]
	s_waitcnt vmcnt(8)
	s_waitcnt lgkmcnt(0)
	s_barrier
; #define PG8_STAGE(bufoff, gbase, voff) do { _Pragma("unroll") for (int _i = 0; _i < 2; ++_i) \
;         __builtin_amdgcn_global_load_lds((const unsigned*)((const char*)(gbase) + (voff)[_i]), (LAS unsigned*)(lds + (bufoff) + ldsw + _i * 8192), 16, 0, 0); } while (0)
; #define PG8_LDA(dst, b, h) do { _Pragma("unroll") for (int m = 0; m < 4; ++m) _Pragma("unroll") for (int k = 0; k < 2; ++k) dst[m][k] = *(const LAS bf16x8*)(lds + PG8_SA(b, h) + aoff + m * 2048 + k * 1024); } while (0)
; #define PG8_LDB(dst, b, h) do { _Pragma("unroll") for (int n = 0; n < 2; ++n) _Pragma("unroll") for (int k = 0; k < 2; ++k) dst[n][k] = *(const LAS bf16x8*)(lds + PG8_SB(b, h) + boff + n * 2048 + k * 1024); } while (0)
; #define PG8_MMA(ai, bj, At, Bt) do { __builtin_amdgcn_s_setprio(1); _Pragma("unroll") for (int m = 0; m < 4; ++m) _Pragma("unroll") for (int n = 0; n < 2; ++n) _Pragma("unroll") for (int k = 0; k < 2; ++k) \
;         acc[ai][bj][m][n] = __builtin_amdgcn_mfma_f32_16x16x32_bf16(Bt[n][k], At[m][k], acc[ai][bj][m][n], 0, 0, 0); __builtin_amdgcn_s_setprio(0); } while (0)
; #define PG8_WAIT_V(n) asm volatile("s_waitcnt vmcnt(" #n ")" ::: "memory")
; #define PG8_WAIT_L(n) asm volatile("s_waitcnt lgkmcnt(" #n ")" ::: "memory")
; #define PG8_BAR __builtin_amdgcn_s_barrier()
; #define PG8_SCHED __builtin_amdgcn_sched_barrier(0)
; template <class Epi, class Sched, bool ABLK = false, bool ALIGN_EPI = true, bool SP2 = true, bool BBLK = true>
; __device__ __forceinline__ void gemm_phase(LAS unsigned char* lds, const Gemm g, const Sched& S, const Epi& E) {
;     ...
;             PG8_WAIT_V(8); PG8_WAIT_L(0); PG8_BAR; PG8_MMA(1, 0, At, B0); PG8_MMA(1, 1, At, B1); PG8_BAR; PG8_SCHED;
;             PG8_LDB(B0, 1, 0); PG8_LDB(B1, 1, 1); PG8_SCHED; PG8_LDA(At, 1, 0); PG8_STAGE(PG8_SA(0, 1), a2 + hstepA, voffA);
;             PG8_WAIT_V(8); PG8_WAIT_L(0); PG8_BAR; PG8_MMA(0, 0, At, B0); PG8_MMA(0, 1, At, B1); PG8_BAR; PG8_SCHED;
	s_setprio 1
	s_waitcnt lgkmcnt(0)
	v_mfma_f32_16x16x32_bf16 v[62:65], v[184:187], v[216:219], v[62:65]
	v_mfma_f32_16x16x32_bf16 v[58:61], v[192:195], v[216:219], v[58:61]
	v_mfma_f32_16x16x32_bf16 v[46:49], v[184:187], v[224:227], v[46:49]
	v_mfma_f32_16x16x32_bf16 v[42:45], v[192:195], v[224:227], v[42:45]
	v_mfma_f32_16x16x32_bf16 v[30:33], v[184:187], v[232:235], v[30:33]
	v_mfma_f32_16x16x32_bf16 v[26:29], v[192:195], v[232:235], v[26:29]
	v_mfma_f32_16x16x32_bf16 v[14:17], v[184:187], v[240:243], v[14:17]
	v_mfma_f32_16x16x32_bf16 v[10:13], v[192:195], v[240:243], v[10:13]
	v_mfma_f32_16x16x32_bf16 v[62:65], v[188:191], v[220:223], v[62:65]
	v_mfma_f32_16x16x32_bf16 v[58:61], v[196:199], v[220:223], v[58:61]
	v_mfma_f32_16x16x32_bf16 v[46:49], v[188:191], v[228:231], v[46:49]
	v_mfma_f32_16x16x32_bf16 v[42:45], v[196:199], v[228:231], v[42:45]
	v_mfma_f32_16x16x32_bf16 v[30:33], v[188:191], v[236:239], v[30:33]
	v_mfma_f32_16x16x32_bf16 v[26:29], v[196:199], v[236:239], v[26:29]
	v_mfma_f32_16x16x32_bf16 v[14:17], v[188:191], v[244:247], v[14:17]
	v_mfma_f32_16x16x32_bf16 v[10:13], v[196:199], v[244:247], v[10:13]
	s_setprio 0
	s_setprio 1
	v_mfma_f32_16x16x32_bf16 v[54:57], v[200:203], v[216:219], v[54:57]
	v_mfma_f32_16x16x32_bf16 v[50:53], v[208:211], v[216:219], v[50:53]
	v_mfma_f32_16x16x32_bf16 v[38:41], v[200:203], v[224:227], v[38:41]
	v_mfma_f32_16x16x32_bf16 v[34:37], v[208:211], v[224:227], v[34:37]
	v_mfma_f32_16x16x32_bf16 v[22:25], v[200:203], v[232:235], v[22:25]
	v_mfma_f32_16x16x32_bf16 v[18:21], v[208:211], v[232:235], v[18:21]
	v_mfma_f32_16x16x32_bf16 v[6:9], v[200:203], v[240:243], v[6:9]
	v_mfma_f32_16x16x32_bf16 v[2:5], v[208:211], v[240:243], v[2:5]
	v_mfma_f32_16x16x32_bf16 v[54:57], v[204:207], v[220:223], v[54:57]
	v_mfma_f32_16x16x32_bf16 v[50:53], v[212:215], v[220:223], v[50:53]
	v_mfma_f32_16x16x32_bf16 v[38:41], v[204:207], v[228:231], v[38:41]
	v_mfma_f32_16x16x32_bf16 v[34:37], v[212:215], v[228:231], v[34:37]
	v_mfma_f32_16x16x32_bf16 v[22:25], v[204:207], v[236:239], v[22:25]
	v_mfma_f32_16x16x32_bf16 v[18:21], v[212:215], v[236:239], v[18:21]
	v_mfma_f32_16x16x32_bf16 v[6:9], v[204:207], v[244:247], v[6:9]
	v_mfma_f32_16x16x32_bf16 v[2:5], v[212:215], v[244:247], v[2:5]
	s_setprio 0
	s_barrier
	v_add_u32_e32 v138, s60, v1
	ds_read_b128 v[184:187], v138
	ds_read_b128 v[188:191], v138 offset:1024
	ds_read_b128 v[192:195], v138 offset:2048
	ds_read_b128 v[196:199], v138 offset:3072
	v_add_u32_e32 v138, s61, v1
	ds_read_b128 v[200:203], v138
	ds_read_b128 v[204:207], v138 offset:1024
	ds_read_b128 v[208:211], v138 offset:2048
	ds_read_b128 v[212:215], v138 offset:3072
	s_add_u32 s36, s36, 0x80000
	s_addc_u32 s37, s37, 0
	s_mov_b32 m0, s43
	ds_read_b128 v[216:219], v149 offset:32768
	ds_read_b128 v[220:223], v149 offset:33792
	ds_read_b128 v[224:227], v149 offset:34816
	ds_read_b128 v[228:231], v149 offset:35840
	ds_read_b128 v[232:235], v149 offset:36864
	ds_read_b128 v[236:239], v149 offset:37888
	ds_read_b128 v[240:243], v149 offset:38912
	ds_read_b128 v[244:247], v149 offset:39936
	global_load_lds_dwordx4 v130, s[36:37]
	s_mov_b32 m0, s46
	s_nop 0
	global_load_lds_dwordx4 v134, s[36:37]
	s_waitcnt vmcnt(8)
	s_waitcnt lgkmcnt(0)
	s_barrier
	s_setprio 1
	s_waitcnt lgkmcnt(0)
	v_mfma_f32_16x16x32_bf16 v[126:129], v[184:187], v[216:219], v[126:129]
	v_mfma_f32_16x16x32_bf16 v[122:125], v[192:195], v[216:219], v[122:125]
	v_mfma_f32_16x16x32_bf16 v[110:113], v[184:187], v[224:227], v[110:113]
	v_mfma_f32_16x16x32_bf16 v[106:109], v[192:195], v[224:227], v[106:109]
	v_mfma_f32_16x16x32_bf16 v[94:97], v[184:187], v[232:235], v[94:97]
	v_mfma_f32_16x16x32_bf16 v[90:93], v[192:195], v[232:235], v[90:93]
	v_mfma_f32_16x16x32_bf16 v[78:81], v[184:187], v[240:243], v[78:81]
	v_mfma_f32_16x16x32_bf16 v[74:77], v[192:195], v[240:243], v[74:77]
	v_mfma_f32_16x16x32_bf16 v[126:129], v[188:191], v[220:223], v[126:129]
	v_mfma_f32_16x16x32_bf16 v[122:125], v[196:199], v[220:223], v[122:125]
	v_mfma_f32_16x16x32_bf16 v[110:113], v[188:191], v[228:231], v[110:113]
	v_mfma_f32_16x16x32_bf16 v[106:109], v[196:199], v[228:231], v[106:109]
	v_mfma_f32_16x16x32_bf16 v[94:97], v[188:191], v[236:239], v[94:97]
	v_mfma_f32_16x16x32_bf16 v[90:93], v[196:199], v[236:239], v[90:93]
	v_mfma_f32_16x16x32_bf16 v[78:81], v[188:191], v[244:247], v[78:81]
	v_mfma_f32_16x16x32_bf16 v[74:77], v[196:199], v[244:247], v[74:77]
	s_setprio 0
	s_setprio 1
	v_mfma_f32_16x16x32_bf16 v[118:121], v[200:203], v[216:219], v[118:121]
	v_mfma_f32_16x16x32_bf16 v[114:117], v[208:211], v[216:219], v[114:117]
	v_mfma_f32_16x16x32_bf16 v[102:105], v[200:203], v[224:227], v[102:105]
	v_mfma_f32_16x16x32_bf16 v[98:101], v[208:211], v[224:227], v[98:101]
	v_mfma_f32_16x16x32_bf16 v[86:89], v[200:203], v[232:235], v[86:89]
	v_mfma_f32_16x16x32_bf16 v[82:85], v[208:211], v[232:235], v[82:85]
	v_mfma_f32_16x16x32_bf16 v[70:73], v[200:203], v[240:243], v[70:73]
	v_mfma_f32_16x16x32_bf16 v[66:69], v[208:211], v[240:243], v[66:69]
	v_mfma_f32_16x16x32_bf16 v[118:121], v[204:207], v[220:223], v[118:121]
	v_mfma_f32_16x16x32_bf16 v[114:117], v[212:215], v[220:223], v[114:117]
	v_mfma_f32_16x16x32_bf16 v[102:105], v[204:207], v[228:231], v[102:105]
	v_mfma_f32_16x16x32_bf16 v[98:101], v[212:215], v[228:231], v[98:101]
	v_mfma_f32_16x16x32_bf16 v[86:89], v[204:207], v[236:239], v[86:89]
	v_mfma_f32_16x16x32_bf16 v[82:85], v[212:215], v[236:239], v[82:85]
	v_mfma_f32_16x16x32_bf16 v[70:73], v[204:207], v[244:247], v[70:73]
	v_mfma_f32_16x16x32_bf16 v[66:69], v[212:215], v[244:247], v[66:69]
	s_setprio 0
	s_barrier
; #define PG8_STAGE(bufoff, gbase, voff) do { _Pragma("unroll") for (int _i = 0; _i < 2; ++_i) \
;         __builtin_amdgcn_global_load_lds((const unsigned*)((const char*)(gbase) + (voff)[_i]), (LAS unsigned*)(lds + (bufoff) + ldsw + _i * 8192), 16, 0, 0); } while (0)
; #define PG8_LDA(dst, b, h) do { _Pragma("unroll") for (int m = 0; m < 4; ++m) _Pragma("unroll") for (int k = 0; k < 2; ++k) dst[m][k] = *(const LAS bf16x8*)(lds + PG8_SA(b, h) + aoff + m * 2048 + k * 1024); } while (0)
; #define PG8_MMA(ai, bj, At, Bt) do { __builtin_amdgcn_s_setprio(1); _Pragma("unroll") for (int m = 0; m < 4; ++m) _Pragma("unroll") for (int n = 0; n < 2; ++n) _Pragma("unroll") for (int k = 0; k < 2; ++k) \
;         acc[ai][bj][m][n] = __builtin_amdgcn_mfma_f32_16x16x32_bf16(Bt[n][k], At[m][k], acc[ai][bj][m][n], 0, 0, 0); __builtin_amdgcn_s_setprio(0); } while (0)
; #define PG8_WAIT_V(n) asm volatile("s_waitcnt vmcnt(" #n ")" ::: "memory")
; #define PG8_WAIT_L(n) asm volatile("s_waitcnt lgkmcnt(" #n ")" ::: "memory")
; #define PG8_BAR __builtin_amdgcn_s_barrier()
; #define PG8_SCHED __builtin_amdgcn_sched_barrier(0)
; template <class Epi, class Sched, bool ABLK = false, bool ALIGN_EPI = true, bool SP2 = true, bool BBLK = true>
; __device__ __forceinline__ void gemm_phase(LAS unsigned char* lds, const Gemm g, const Sched& S, const Epi& E) {
;     ...
;             PG8_LDA(At, 1, 1); PG8_STAGE(PG8_SB(1, 0), b3, voffB); PG8_STAGE(PG8_SB(1, 1), b3 + hstepB, voffB); PG8_STAGE(PG8_SA(1, 0), a3, voffA);
;             PG8_WAIT_V(8); PG8_WAIT_L(0); PG8_BAR; PG8_MMA(1, 0, At, B0); PG8_MMA(1, 1, At, B1); PG8_BAR; PG8_SCHED;
	s_add_u32 s36, s34, 0x8000
	s_addc_u32 s37, s35, 0
	s_add_i32 s55, s60, s41
	s_mov_b32 m0, s55
	ds_read_b128 v[216:219], v149 offset:49152
	ds_read_b128 v[220:223], v149 offset:50176
	ds_read_b128 v[224:227], v149 offset:51200
	ds_read_b128 v[228:231], v149 offset:52224
	ds_read_b128 v[232:235], v149 offset:53248
	ds_read_b128 v[236:239], v149 offset:54272
	ds_read_b128 v[240:243], v149 offset:55296
	ds_read_b128 v[244:247], v149 offset:56320
	global_load_lds_dwordx4 v132, s[36:37]
	s_add_i32 m0, s55, 0x2000
	s_add_u32 s34, s34, 0xc000
	v_lshl_add_u64 v[248:249], s[36:37], 0, v[136:137]
	s_addc_u32 s35, s35, 0
	s_add_i32 s36, s61, s41
	global_load_lds_dwordx4 v[248:249], off
	s_mov_b32 m0, s36
	s_nop 0
	global_load_lds_dwordx4 v132, s[34:35]
	s_add_i32 m0, s36, 0x2000
	s_nop 0
	global_load_lds_dwordx4 v136, s[34:35]
	s_mov_b32 m0, s47
	s_nop 0
	global_load_lds_dwordx4 v130, s[30:31]
	s_mov_b32 m0, s48
	s_nop 0
	global_load_lds_dwordx4 v134, s[30:31]
	s_waitcnt vmcnt(8)
	s_waitcnt lgkmcnt(0)
	s_barrier
	s_setprio 1
	s_waitcnt lgkmcnt(0)
	v_mfma_f32_16x16x32_bf16 v[62:65], v[184:187], v[216:219], v[62:65]
	v_mfma_f32_16x16x32_bf16 v[58:61], v[192:195], v[216:219], v[58:61]
	v_mfma_f32_16x16x32_bf16 v[46:49], v[184:187], v[224:227], v[46:49]
	v_mfma_f32_16x16x32_bf16 v[42:45], v[192:195], v[224:227], v[42:45]
	v_mfma_f32_16x16x32_bf16 v[30:33], v[184:187], v[232:235], v[30:33]
	v_mfma_f32_16x16x32_bf16 v[26:29], v[192:195], v[232:235], v[26:29]
	v_mfma_f32_16x16x32_bf16 v[14:17], v[184:187], v[240:243], v[14:17]
	v_mfma_f32_16x16x32_bf16 v[10:13], v[192:195], v[240:243], v[10:13]
	v_mfma_f32_16x16x32_bf16 v[62:65], v[188:191], v[220:223], v[62:65]
	v_mfma_f32_16x16x32_bf16 v[58:61], v[196:199], v[220:223], v[58:61]
	v_mfma_f32_16x16x32_bf16 v[46:49], v[188:191], v[228:231], v[46:49]
	v_mfma_f32_16x16x32_bf16 v[42:45], v[196:199], v[228:231], v[42:45]
	v_mfma_f32_16x16x32_bf16 v[30:33], v[188:191], v[236:239], v[30:33]
	v_mfma_f32_16x16x32_bf16 v[26:29], v[196:199], v[236:239], v[26:29]
	v_mfma_f32_16x16x32_bf16 v[14:17], v[188:191], v[244:247], v[14:17]
	v_mfma_f32_16x16x32_bf16 v[10:13], v[196:199], v[244:247], v[10:13]
	s_setprio 0
	s_setprio 1
	v_mfma_f32_16x16x32_bf16 v[54:57], v[200:203], v[216:219], v[54:57]
	v_mfma_f32_16x16x32_bf16 v[50:53], v[208:211], v[216:219], v[50:53]
	v_mfma_f32_16x16x32_bf16 v[38:41], v[200:203], v[224:227], v[38:41]
	v_mfma_f32_16x16x32_bf16 v[34:37], v[208:211], v[224:227], v[34:37]
	v_mfma_f32_16x16x32_bf16 v[22:25], v[200:203], v[232:235], v[22:25]
	v_mfma_f32_16x16x32_bf16 v[18:21], v[208:211], v[232:235], v[18:21]
	v_mfma_f32_16x16x32_bf16 v[6:9], v[200:203], v[240:243], v[6:9]
	v_mfma_f32_16x16x32_bf16 v[2:5], v[208:211], v[240:243], v[2:5]
	v_mfma_f32_16x16x32_bf16 v[54:57], v[204:207], v[220:223], v[54:57]
	v_mfma_f32_16x16x32_bf16 v[50:53], v[212:215], v[220:223], v[50:53]
	v_mfma_f32_16x16x32_bf16 v[38:41], v[204:207], v[228:231], v[38:41]
	v_mfma_f32_16x16x32_bf16 v[34:37], v[212:215], v[228:231], v[34:37]
	v_mfma_f32_16x16x32_bf16 v[22:25], v[204:207], v[236:239], v[22:25]
	v_mfma_f32_16x16x32_bf16 v[18:21], v[212:215], v[236:239], v[18:21]
	v_mfma_f32_16x16x32_bf16 v[6:9], v[204:207], v[244:247], v[6:9]
	v_mfma_f32_16x16x32_bf16 v[2:5], v[212:215], v[244:247], v[2:5]
	s_setprio 0
	s_barrier
	s_add_i32 s54, s54, 2
	s_add_u32 s28, s28, 0x100
	s_addc_u32 s29, s29, 0
	s_add_u32 s52, s52, 0x10000
	s_addc_u32 s53, s53, 0
	s_cmp_gt_u32 s54, 29
	s_cbranch_scc0 .LBB0_668
	s_and_b64 vcc, exec, s[12:13]
	s_cbranch_vccz .LBB0_671
	s_barrier

; __device__ __forceinline__ unsigned pk2(float lo, float hi) { const f32x2 v = {lo, hi}; return __builtin_bit_cast(unsigned, __builtin_convertvector(v, bf16x2_t)); }
; #define PG8_STAGE(bufoff, gbase, voff) do { _Pragma("unroll") for (int _i = 0; _i < 2; ++_i) \
;         __builtin_amdgcn_global_load_lds((const unsigned*)((const char*)(gbase) + (voff)[_i]), (LAS unsigned*)(lds + (bufoff) + ldsw + _i * 8192), 16, 0, 0); } while (0)
; #define PG8_WAIT_V(n) asm volatile("s_waitcnt vmcnt(" #n ")" ::: "memory")
; #define PG8_BAR __builtin_amdgcn_s_barrier()
; template <class Epi, class Sched, bool ABLK = false, bool ALIGN_EPI = true, bool SP2 = true, bool BBLK = true>
; __device__ __forceinline__ void gemm_phase(LAS unsigned char* lds, const Gemm g, const Sched& S, const Epi& E) {
;     ...
;         PG8_STAGE(PG8_SB(1, 0), cB + kstepB, voffB); PG8_STAGE(PG8_SA(1, 0), a_tile(uA, tbA + 1), voffA); PG8_STAGE(PG8_SB(1, 1), cB + hstepB + kstepB, voffB);
;         PG8_WAIT_V(6); PG8_BAR;
;     __device__ __forceinline__ void operator()(const f32x4 (&acc)[2][2][4][2], const Unit& u, int wr, int wc, int fr, int fq) const {
;         const int row0 = u.pm * 256 + wr * 64 + fr, col0 = u.pn * 256 + wc * 64 + 8 * fq;
;         bf16_t* base = u.part == 0 ? Z + (size_t)row0 * D + col0 : P + ((size_t)(u.part - 1) * MS + (row0 - MP)) * D + col0;
; #pragma unroll
;         for (int ai = 0; ai < 2; ++ai)
; #pragma unroll
;             for (int m = 0; m < 4; ++m) { u32x4 w[2];
; #pragma unroll
;                 for (int bj = 0; bj < 2; ++bj) { const f32x4 v0 = acc[ai][bj][m][0], v1 = acc[ai][bj][m][1]; w[bj].x = pk2(v0[0], v0[1]); w[bj].y = pk2(v0[2], v0[3]); w[bj].z = pk2(v1[0], v1[1]); w[bj].w = pk2(v1[2], v1[3]); }
;                 store_pair((unsigned char*)(base + (size_t)(ai * 128 + m * 16) * D), (size_t)8 * D * 2, 64, w[0], w[1], fr >= 8); }
.LBB0_1034:
	s_and_b32 s5, s5, 3
	v_readlane_b32 s12, v252, 19
	s_lshl_b32 s7, s6, 13
	s_lshl_b32 s10, s5, 12
	v_readlane_b32 s14, v252, 21
	v_readlane_b32 s15, v252, 22
	s_add_u32 s52, s14, 0x1e100000
	s_addc_u32 s54, s15, 0
	v_readlane_b32 s13, v252, 20
	s_add_u32 s12, s14, 0x3c900000
	s_addc_u32 s13, s15, 0
	s_add_u32 s8, s20, 0x8000
	s_addc_u32 s9, s21, 0
	s_add_i32 m0, s35, 0x18000
	s_waitcnt vmcnt(0)
	v_lshl_add_u64 v[14:15], s[8:9], 0, v[132:133]
	s_waitcnt vmcnt(2)
	s_barrier
	global_load_lds_dwordx4 v[14:15], off
	v_lshl_add_u64 v[14:15], s[8:9], 0, v[136:137]
	s_add_i32 m0, s35, 0x1a000
	s_mov_b64 s[8:9], 0x80
	s_add_i32 s41, s35, 0x8000
	global_load_lds_dwordx4 v[14:15], off
	v_lshl_add_u64 v[2:3], v[2:3], 0, s[8:9]
	s_mov_b32 m0, s41
	s_add_i32 s42, s35, 0xa000
	global_load_lds_dwordx4 v[2:3], off
	v_lshl_add_u64 v[2:3], v[4:5], 0, s[8:9]
	s_add_u32 s8, s20, 0xc000
	s_mov_b32 m0, s42
	s_addc_u32 s9, s21, 0
	global_load_lds_dwordx4 v[2:3], off
	s_add_i32 m0, s35, 0x1c000
	s_nop 0
	global_load_lds_dwordx4 v132, s[8:9]
	s_add_i32 m0, s35, 0x1e000
	v_lshlrev_b32_e32 v5, 2, v8
	global_load_lds_dwordx4 v136, s[8:9]
	v_lshrrev_b32_e32 v3, 1, v8
	v_and_b32_e32 v3, 24, v3
	v_and_b32_e32 v2, 15, v8
	v_lshlrev_b32_e32 v4, 1, v3
	v_lshl_or_b32 v4, v2, 6, v4
	v_and_b32_e32 v5, 32, v5
	v_lshl_or_b32 v150, s6, 6, v2
	v_bitop3_b32 v151, v4, s10, v5 bitop3:0xde
	v_bitop3_b32 v4, v4, s7, v5 bitop3:0xde
	v_cmp_lt_u32_e64 s[6:7], 7, v2
	v_mov_b32_e32 v2, 0xffff8040
	v_lshl_or_b32 v152, s5, 6, v3
	v_cndmask_b32_e64 v138, 0, v2, s[6:7]
	v_mov_b32_e32 v2, 0x8000
	v_cndmask_b32_e64 v140, v2, 64, s[6:7]
	v_lshlrev_b32_e32 v2, 15, v6
	v_and_b32_e32 v2, 0xffff0000, v2
	v_lshl_add_u32 v2, v7, 12, v2
	v_and_b32_e32 v3, 1, v6
	v_lshl_or_b32 v2, v3, 6, v2
	s_cmpk_lt_u32 s4, 0x100
	v_lshl_add_u32 v2, v9, 1, v2
	v_mov_b32_e32 v3, v133
	s_mov_b64 s[4:5], 0x80080
	v_lshl_add_u64 v[142:143], v[2:3], 0, s[4:5]
	v_lshlrev_b32_e32 v2, 15, v10
	v_and_b32_e32 v2, 0xffff0000, v2
	v_lshl_add_u32 v2, v11, 12, v2
	v_and_b32_e32 v3, 1, v10
	s_waitcnt vmcnt(6)
	v_lshl_or_b32 v2, v3, 6, v2
	v_lshl_add_u32 v2, v12, 1, v2
	v_mov_b32_e32 v3, v133
	s_cselect_b64 s[10:11], -1, 0
	v_cndmask_b32_e64 v139, 0, -1, s[6:7]
	v_mov_b32_e32 v141, v133
	s_lshl_b32 s63, s71, 9
	v_lshl_add_u64 v[144:145], v[2:3], 0, s[4:5]
	s_mov_b64 s[4:5], -1
	v_add_u32_e32 v153, s72, v151
	v_add_u32_e32 v154, s73, v151
	v_add_u32_e32 v155, 0, v4
	s_mov_b32 s47, s82
	s_mov_b32 s24, 0
	s_barrier
	s_branch .LBB0_1037

; #define PG8_STAGE(bufoff, gbase, voff) do { _Pragma("unroll") for (int _i = 0; _i < 2; ++_i) \
;         __builtin_amdgcn_global_load_lds((const unsigned*)((const char*)(gbase) + (voff)[_i]), (LAS unsigned*)(lds + (bufoff) + ldsw + _i * 8192), 16, 0, 0); } while (0)
; #define PG8_LDA(dst, b, h) do { _Pragma("unroll") for (int m = 0; m < 4; ++m) _Pragma("unroll") for (int k = 0; k < 2; ++k) dst[m][k] = *(const LAS bf16x8*)(lds + PG8_SA(b, h) + aoff + m * 2048 + k * 1024); } while (0)
; #define PG8_LDB(dst, b, h) do { _Pragma("unroll") for (int n = 0; n < 2; ++n) _Pragma("unroll") for (int k = 0; k < 2; ++k) dst[n][k] = *(const LAS bf16x8*)(lds + PG8_SB(b, h) + boff + n * 2048 + k * 1024); } while (0)
; #define PG8_MMA(ai, bj, At, Bt) do { __builtin_amdgcn_s_setprio(1); _Pragma("unroll") for (int m = 0; m < 4; ++m) _Pragma("unroll") for (int n = 0; n < 2; ++n) _Pragma("unroll") for (int k = 0; k < 2; ++k) \
;         acc[ai][bj][m][n] = __builtin_amdgcn_mfma_f32_16x16x32_bf16(Bt[n][k], At[m][k], acc[ai][bj][m][n], 0, 0, 0); __builtin_amdgcn_s_setprio(0); } while (0)
; #define PG8_WAIT_V(n) asm volatile("s_waitcnt vmcnt(" #n ")" ::: "memory")
; #define PG8_WAIT_L(n) asm volatile("s_waitcnt lgkmcnt(" #n ")" ::: "memory")
; #define PG8_BAR __builtin_amdgcn_s_barrier()
; #define PG8_SCHED __builtin_amdgcn_sched_barrier(0)
; template <class Epi, class Sched, bool ABLK = false, bool ALIGN_EPI = true, bool SP2 = true, bool BBLK = true>
; __device__ __forceinline__ void gemm_phase(LAS unsigned char* lds, const Gemm g, const Sched& S, const Epi& E) {
;     ...
;             const char* a1 = a_tile(uA, tbA + t + 1);
;             const char* a2 = last ? a_tile(nuA, ntbA) : a_tile(uA, tbA + t + 2); const char* b2 = last ? nB : cB + (size_t)(t + 2) * kstepB;
;             const char* a3 = last ? a_tile(nuA, ntbA + 1) : a_tile(uA, tbA + t + 3); const char* b3 = b2 + kstepB;
;             if (last && has_next) S.a_ready(nxt);
;             if constexpr (SP2) {
;             PG8_LDB(B0, 0, 0); PG8_LDB(B1, 0, 1); PG8_SCHED; PG8_LDA(At, 0, 0); PG8_STAGE(PG8_SA(1, 1), a1 + hstepA, voffA);
;             PG8_WAIT_V(8); PG8_WAIT_L(0); PG8_BAR; PG8_MMA(0, 0, At, B0); PG8_MMA(0, 1, At, B1); PG8_BAR; PG8_SCHED;
;             PG8_LDA(At, 0, 1); PG8_STAGE(PG8_SB(0, 0), b2, voffB); PG8_STAGE(PG8_SB(0, 1), b2 + hstepB, voffB); PG8_STAGE(PG8_SA(0, 0), a2, voffA);
.LBB0_1038:
	ds_read_b128 v[156:159], v153
	ds_read_b128 v[160:163], v153 offset:1024
	ds_read_b128 v[164:167], v153 offset:2048
	ds_read_b128 v[168:171], v153 offset:3072
	ds_read_b128 v[172:175], v154
	ds_read_b128 v[176:179], v154 offset:1024
	ds_read_b128 v[180:183], v154 offset:2048
	ds_read_b128 v[184:187], v154 offset:3072
	s_add_u32 s22, s56, s20
	s_addc_u32 s23, s57, s21
	s_add_u32 s26, s22, 0x100
	s_addc_u32 s27, s23, 0
	s_add_i32 s65, s65, 2
	s_add_u32 s22, s22, 0x180
	s_addc_u32 s23, s23, 0
	s_cmp_eq_u32 s64, s20
	s_cselect_b32 s23, s50, s23
	s_cselect_b32 s22, s49, s22
	s_cselect_b32 s25, s4, s55
	s_cselect_b32 s24, s5, s51
	s_cselect_b32 s27, s48, s27
	s_cselect_b32 s26, s17, s26
	v_lshl_add_u64 v[220:221], v[146:147], 0, s[20:21]
	s_add_i32 m0, s35, 0xc000
	ds_read_b128 v[188:191], v155
	ds_read_b128 v[192:195], v155 offset:1024
	ds_read_b128 v[196:199], v155 offset:2048
	ds_read_b128 v[200:203], v155 offset:3072
	ds_read_b128 v[204:207], v155 offset:4096
	ds_read_b128 v[208:211], v155 offset:5120
	ds_read_b128 v[212:215], v155 offset:6144
	ds_read_b128 v[216:219], v155 offset:7168
	global_load_lds_dwordx4 v[220:221], off
	v_lshl_add_u64 v[220:221], v[148:149], 0, s[20:21]
	s_add_i32 m0, s35, 0xe000
	s_nop 0
	global_load_lds_dwordx4 v[220:221], off
	s_waitcnt vmcnt(8)
	s_waitcnt lgkmcnt(0)
	s_barrier
	s_setprio 1
	s_waitcnt lgkmcnt(0)
	v_mfma_f32_16x16x32_bf16 v[126:129], v[156:159], v[188:191], v[126:129]
	v_mfma_f32_16x16x32_bf16 v[122:125], v[164:167], v[188:191], v[122:125]
	v_mfma_f32_16x16x32_bf16 v[110:113], v[156:159], v[196:199], v[110:113]
	v_mfma_f32_16x16x32_bf16 v[106:109], v[164:167], v[196:199], v[106:109]
	v_mfma_f32_16x16x32_bf16 v[94:97], v[156:159], v[204:207], v[94:97]
	v_mfma_f32_16x16x32_bf16 v[90:93], v[164:167], v[204:207], v[90:93]
	v_mfma_f32_16x16x32_bf16 v[78:81], v[156:159], v[212:215], v[78:81]
	v_mfma_f32_16x16x32_bf16 v[74:77], v[164:167], v[212:215], v[74:77]
	v_mfma_f32_16x16x32_bf16 v[126:129], v[160:163], v[192:195], v[126:129]
	v_mfma_f32_16x16x32_bf16 v[122:125], v[168:171], v[192:195], v[122:125]
	v_mfma_f32_16x16x32_bf16 v[110:113], v[160:163], v[200:203], v[110:113]
	v_mfma_f32_16x16x32_bf16 v[106:109], v[168:171], v[200:203], v[106:109]
	v_mfma_f32_16x16x32_bf16 v[94:97], v[160:163], v[208:211], v[94:97]
	v_mfma_f32_16x16x32_bf16 v[90:93], v[168:171], v[208:211], v[90:93]
	v_mfma_f32_16x16x32_bf16 v[78:81], v[160:163], v[216:219], v[78:81]
	v_mfma_f32_16x16x32_bf16 v[74:77], v[168:171], v[216:219], v[74:77]
	s_setprio 0
	s_setprio 1
	v_mfma_f32_16x16x32_bf16 v[118:121], v[172:175], v[188:191], v[118:121]
	v_mfma_f32_16x16x32_bf16 v[114:117], v[180:183], v[188:191], v[114:117]
	v_mfma_f32_16x16x32_bf16 v[102:105], v[172:175], v[196:199], v[102:105]
	v_mfma_f32_16x16x32_bf16 v[98:101], v[180:183], v[196:199], v[98:101]
	v_mfma_f32_16x16x32_bf16 v[86:89], v[172:175], v[204:207], v[86:89]
	v_mfma_f32_16x16x32_bf16 v[82:85], v[180:183], v[204:207], v[82:85]
	v_mfma_f32_16x16x32_bf16 v[70:73], v[172:175], v[212:215], v[70:73]
	v_mfma_f32_16x16x32_bf16 v[66:69], v[180:183], v[212:215], v[66:69]
	v_mfma_f32_16x16x32_bf16 v[118:121], v[176:179], v[192:195], v[118:121]
	v_mfma_f32_16x16x32_bf16 v[114:117], v[184:187], v[192:195], v[114:117]
	v_mfma_f32_16x16x32_bf16 v[102:105], v[176:179], v[200:203], v[102:105]
	v_mfma_f32_16x16x32_bf16 v[98:101], v[184:187], v[200:203], v[98:101]
	v_mfma_f32_16x16x32_bf16 v[86:89], v[176:179], v[208:211], v[86:89]
	v_mfma_f32_16x16x32_bf16 v[82:85], v[184:187], v[208:211], v[82:85]
	v_mfma_f32_16x16x32_bf16 v[70:73], v[176:179], v[216:219], v[70:73]
	v_mfma_f32_16x16x32_bf16 v[66:69], v[184:187], v[216:219], v[66:69]
	s_setprio 0
	s_barrier
	s_add_i32 s66, s72, s34
	s_mov_b32 m0, s66
	ds_read_b128 v[188:191], v155 offset:16384
	ds_read_b128 v[192:195], v155 offset:17408
	ds_read_b128 v[196:199], v155 offset:18432
	ds_read_b128 v[200:203], v155 offset:19456
	ds_read_b128 v[204:207], v155 offset:20480
	ds_read_b128 v[208:211], v155 offset:21504
	ds_read_b128 v[212:215], v155 offset:22528
	ds_read_b128 v[216:219], v155 offset:23552
	global_load_lds_dwordx4 v132, s[24:25]
	s_add_i32 m0, s66, 0x2000
	s_add_u32 s66, s24, 0x4000
	s_addc_u32 s67, s25, 0
	s_add_i32 s75, s73, s34
	global_load_lds_dwordx4 v136, s[24:25]
	s_mov_b32 m0, s75
	s_nop 0
	global_load_lds_dwordx4 v132, s[66:67]
	s_add_i32 m0, s75, 0x2000
	s_nop 0
	global_load_lds_dwordx4 v136, s[66:67]
	s_mov_b32 m0, s35
	s_nop 0
	global_load_lds_dwordx4 v130, s[26:27]
	s_mov_b32 m0, s36
	s_nop 0
	global_load_lds_dwordx4 v134, s[26:27]
	s_waitcnt vmcnt(8)
	s_waitcnt lgkmcnt(0)
	s_barrier
; #define PG8_STAGE(bufoff, gbase, voff) do { _Pragma("unroll") for (int _i = 0; _i < 2; ++_i) \
;         __builtin_amdgcn_global_load_lds((const unsigned*)((const char*)(gbase) + (voff)[_i]), (LAS unsigned*)(lds + (bufoff) + ldsw + _i * 8192), 16, 0, 0); } while (0)
; #define PG8_LDA(dst, b, h) do { _Pragma("unroll") for (int m = 0; m < 4; ++m) _Pragma("unroll") for (int k = 0; k < 2; ++k) dst[m][k] = *(const LAS bf16x8*)(lds + PG8_SA(b, h) + aoff + m * 2048 + k * 1024); } while (0)
; #define PG8_LDB(dst, b, h) do { _Pragma("unroll") for (int n = 0; n < 2; ++n) _Pragma("unroll") for (int k = 0; k < 2; ++k) dst[n][k] = *(const LAS bf16x8*)(lds + PG8_SB(b, h) + boff + n * 2048 + k * 1024); } while (0)
; #define PG8_MMA(ai, bj, At, Bt) do { __builtin_amdgcn_s_setprio(1); _Pragma("unroll") for (int m = 0; m < 4; ++m) _Pragma("unroll") for (int n = 0; n < 2; ++n) _Pragma("unroll") for (int k = 0; k < 2; ++k) \
;         acc[ai][bj][m][n] = __builtin_amdgcn_mfma_f32_16x16x32_bf16(Bt[n][k], At[m][k], acc[ai][bj][m][n], 0, 0, 0); __builtin_amdgcn_s_setprio(0); } while (0)
; #define PG8_WAIT_V(n) asm volatile("s_waitcnt vmcnt(" #n ")" ::: "memory")
; #define PG8_WAIT_L(n) asm volatile("s_waitcnt lgkmcnt(" #n ")" ::: "memory")
; #define PG8_BAR __builtin_amdgcn_s_barrier()
; #define PG8_SCHED __builtin_amdgcn_sched_barrier(0)
; template <class Epi, class Sched, bool ABLK = false, bool ALIGN_EPI = true, bool SP2 = true, bool BBLK = true>
; __device__ __forceinline__ void gemm_phase(LAS unsigned char* lds, const Gemm g, const Sched& S, const Epi& E) {
;     ...
;             PG8_WAIT_V(8); PG8_WAIT_L(0); PG8_BAR; PG8_MMA(1, 0, At, B0); PG8_MMA(1, 1, At, B1); PG8_BAR; PG8_SCHED;
;             PG8_LDB(B0, 1, 0); PG8_LDB(B1, 1, 1); PG8_SCHED; PG8_LDA(At, 1, 0); PG8_STAGE(PG8_SA(0, 1), a2 + hstepA, voffA);
;             PG8_WAIT_V(8); PG8_WAIT_L(0); PG8_BAR; PG8_MMA(0, 0, At, B0); PG8_MMA(0, 1, At, B1); PG8_BAR; PG8_SCHED;
	s_setprio 1
	s_waitcnt lgkmcnt(0)
	v_mfma_f32_16x16x32_bf16 v[62:65], v[156:159], v[188:191], v[62:65]
	v_mfma_f32_16x16x32_bf16 v[58:61], v[164:167], v[188:191], v[58:61]
	v_mfma_f32_16x16x32_bf16 v[46:49], v[156:159], v[196:199], v[46:49]
	v_mfma_f32_16x16x32_bf16 v[42:45], v[164:167], v[196:199], v[42:45]
	v_mfma_f32_16x16x32_bf16 v[30:33], v[156:159], v[204:207], v[30:33]
	v_mfma_f32_16x16x32_bf16 v[26:29], v[164:167], v[204:207], v[26:29]
	v_mfma_f32_16x16x32_bf16 v[14:17], v[156:159], v[212:215], v[14:17]
	v_mfma_f32_16x16x32_bf16 v[10:13], v[164:167], v[212:215], v[10:13]
	v_mfma_f32_16x16x32_bf16 v[62:65], v[160:163], v[192:195], v[62:65]
	v_mfma_f32_16x16x32_bf16 v[58:61], v[168:171], v[192:195], v[58:61]
	v_mfma_f32_16x16x32_bf16 v[46:49], v[160:163], v[200:203], v[46:49]
	v_mfma_f32_16x16x32_bf16 v[42:45], v[168:171], v[200:203], v[42:45]
	v_mfma_f32_16x16x32_bf16 v[30:33], v[160:163], v[208:211], v[30:33]
	v_mfma_f32_16x16x32_bf16 v[26:29], v[168:171], v[208:211], v[26:29]
	v_mfma_f32_16x16x32_bf16 v[14:17], v[160:163], v[216:219], v[14:17]
	v_mfma_f32_16x16x32_bf16 v[10:13], v[168:171], v[216:219], v[10:13]
	s_setprio 0
	s_setprio 1
	v_mfma_f32_16x16x32_bf16 v[54:57], v[172:175], v[188:191], v[54:57]
	v_mfma_f32_16x16x32_bf16 v[50:53], v[180:183], v[188:191], v[50:53]
	v_mfma_f32_16x16x32_bf16 v[38:41], v[172:175], v[196:199], v[38:41]
	v_mfma_f32_16x16x32_bf16 v[34:37], v[180:183], v[196:199], v[34:37]
	v_mfma_f32_16x16x32_bf16 v[22:25], v[172:175], v[204:207], v[22:25]
	v_mfma_f32_16x16x32_bf16 v[18:21], v[180:183], v[204:207], v[18:21]
	v_mfma_f32_16x16x32_bf16 v[6:9], v[172:175], v[212:215], v[6:9]
	v_mfma_f32_16x16x32_bf16 v[2:5], v[180:183], v[212:215], v[2:5]
	v_mfma_f32_16x16x32_bf16 v[54:57], v[176:179], v[192:195], v[54:57]
	v_mfma_f32_16x16x32_bf16 v[50:53], v[184:187], v[192:195], v[50:53]
	v_mfma_f32_16x16x32_bf16 v[38:41], v[176:179], v[200:203], v[38:41]
	v_mfma_f32_16x16x32_bf16 v[34:37], v[184:187], v[200:203], v[34:37]
	v_mfma_f32_16x16x32_bf16 v[22:25], v[176:179], v[208:211], v[22:25]
	v_mfma_f32_16x16x32_bf16 v[18:21], v[184:187], v[208:211], v[18:21]
	v_mfma_f32_16x16x32_bf16 v[6:9], v[176:179], v[216:219], v[6:9]
	v_mfma_f32_16x16x32_bf16 v[2:5], v[184:187], v[216:219], v[2:5]
	s_setprio 0
	s_barrier
	v_add_u32_e32 v168, s60, v151
	v_add_u32_e32 v184, s61, v151
	ds_read_b128 v[156:159], v168
	ds_read_b128 v[160:163], v168 offset:1024
	ds_read_b128 v[164:167], v168 offset:2048
	ds_read_b128 v[168:171], v168 offset:3072
	ds_read_b128 v[172:175], v184
	ds_read_b128 v[176:179], v184 offset:1024
	ds_read_b128 v[180:183], v184 offset:2048
	ds_read_b128 v[184:187], v184 offset:3072
	s_add_u32 s26, s26, 0x80000
	s_addc_u32 s27, s27, 0
	s_mov_b32 m0, s37
	ds_read_b128 v[188:191], v155 offset:32768
	ds_read_b128 v[192:195], v155 offset:33792
	ds_read_b128 v[196:199], v155 offset:34816
	ds_read_b128 v[200:203], v155 offset:35840
	ds_read_b128 v[204:207], v155 offset:36864
	ds_read_b128 v[208:211], v155 offset:37888
	ds_read_b128 v[212:215], v155 offset:38912
	ds_read_b128 v[216:219], v155 offset:39936
	global_load_lds_dwordx4 v130, s[26:27]
	s_mov_b32 m0, s40
	s_nop 0
	global_load_lds_dwordx4 v134, s[26:27]
	s_waitcnt vmcnt(8)
	s_waitcnt lgkmcnt(0)
	s_barrier
	s_setprio 1
	s_waitcnt lgkmcnt(0)
	v_mfma_f32_16x16x32_bf16 v[126:129], v[156:159], v[188:191], v[126:129]
	v_mfma_f32_16x16x32_bf16 v[122:125], v[164:167], v[188:191], v[122:125]
	v_mfma_f32_16x16x32_bf16 v[110:113], v[156:159], v[196:199], v[110:113]
	v_mfma_f32_16x16x32_bf16 v[106:109], v[164:167], v[196:199], v[106:109]
	v_mfma_f32_16x16x32_bf16 v[94:97], v[156:159], v[204:207], v[94:97]
	v_mfma_f32_16x16x32_bf16 v[90:93], v[164:167], v[204:207], v[90:93]
	v_mfma_f32_16x16x32_bf16 v[78:81], v[156:159], v[212:215], v[78:81]
	v_mfma_f32_16x16x32_bf16 v[74:77], v[164:167], v[212:215], v[74:77]
	v_mfma_f32_16x16x32_bf16 v[126:129], v[160:163], v[192:195], v[126:129]
	v_mfma_f32_16x16x32_bf16 v[122:125], v[168:171], v[192:195], v[122:125]
	v_mfma_f32_16x16x32_bf16 v[110:113], v[160:163], v[200:203], v[110:113]
	v_mfma_f32_16x16x32_bf16 v[106:109], v[168:171], v[200:203], v[106:109]
	v_mfma_f32_16x16x32_bf16 v[94:97], v[160:163], v[208:211], v[94:97]
	v_mfma_f32_16x16x32_bf16 v[90:93], v[168:171], v[208:211], v[90:93]
	v_mfma_f32_16x16x32_bf16 v[78:81], v[160:163], v[216:219], v[78:81]
	v_mfma_f32_16x16x32_bf16 v[74:77], v[168:171], v[216:219], v[74:77]
	s_setprio 0
	s_setprio 1
	v_mfma_f32_16x16x32_bf16 v[118:121], v[172:175], v[188:191], v[118:121]
	v_mfma_f32_16x16x32_bf16 v[114:117], v[180:183], v[188:191], v[114:117]
	v_mfma_f32_16x16x32_bf16 v[102:105], v[172:175], v[196:199], v[102:105]
	v_mfma_f32_16x16x32_bf16 v[98:101], v[180:183], v[196:199], v[98:101]
	v_mfma_f32_16x16x32_bf16 v[86:89], v[172:175], v[204:207], v[86:89]
	v_mfma_f32_16x16x32_bf16 v[82:85], v[180:183], v[204:207], v[82:85]
	v_mfma_f32_16x16x32_bf16 v[70:73], v[172:175], v[212:215], v[70:73]
	v_mfma_f32_16x16x32_bf16 v[66:69], v[180:183], v[212:215], v[66:69]
	v_mfma_f32_16x16x32_bf16 v[118:121], v[176:179], v[192:195], v[118:121]
	v_mfma_f32_16x16x32_bf16 v[114:117], v[184:187], v[192:195], v[114:117]
	v_mfma_f32_16x16x32_bf16 v[102:105], v[176:179], v[200:203], v[102:105]
	v_mfma_f32_16x16x32_bf16 v[98:101], v[184:187], v[200:203], v[98:101]
	v_mfma_f32_16x16x32_bf16 v[86:89], v[176:179], v[208:211], v[86:89]
	v_mfma_f32_16x16x32_bf16 v[82:85], v[184:187], v[208:211], v[82:85]
	v_mfma_f32_16x16x32_bf16 v[70:73], v[176:179], v[216:219], v[70:73]
	v_mfma_f32_16x16x32_bf16 v[66:69], v[184:187], v[216:219], v[66:69]
	s_setprio 0
	s_barrier
; #define PG8_STAGE(bufoff, gbase, voff) do { _Pragma("unroll") for (int _i = 0; _i < 2; ++_i) \
;         __builtin_amdgcn_global_load_lds((const unsigned*)((const char*)(gbase) + (voff)[_i]), (LAS unsigned*)(lds + (bufoff) + ldsw + _i * 8192), 16, 0, 0); } while (0)
; #define PG8_LDA(dst, b, h) do { _Pragma("unroll") for (int m = 0; m < 4; ++m) _Pragma("unroll") for (int k = 0; k < 2; ++k) dst[m][k] = *(const LAS bf16x8*)(lds + PG8_SA(b, h) + aoff + m * 2048 + k * 1024); } while (0)
; #define PG8_MMA(ai, bj, At, Bt) do { __builtin_amdgcn_s_setprio(1); _Pragma("unroll") for (int m = 0; m < 4; ++m) _Pragma("unroll") for (int n = 0; n < 2; ++n) _Pragma("unroll") for (int k = 0; k < 2; ++k) \
;         acc[ai][bj][m][n] = __builtin_amdgcn_mfma_f32_16x16x32_bf16(Bt[n][k], At[m][k], acc[ai][bj][m][n], 0, 0, 0); __builtin_amdgcn_s_setprio(0); } while (0)
; #define PG8_WAIT_V(n) asm volatile("s_waitcnt vmcnt(" #n ")" ::: "memory")
; #define PG8_WAIT_L(n) asm volatile("s_waitcnt lgkmcnt(" #n ")" ::: "memory")
; #define PG8_BAR __builtin_amdgcn_s_barrier()
; #define PG8_SCHED __builtin_amdgcn_sched_barrier(0)
; template <class Epi, class Sched, bool ABLK = false, bool ALIGN_EPI = true, bool SP2 = true, bool BBLK = true>
; __device__ __forceinline__ void gemm_phase(LAS unsigned char* lds, const Gemm g, const Sched& S, const Epi& E) {
;     ...
;             PG8_LDA(At, 1, 1); PG8_STAGE(PG8_SB(1, 0), b3, voffB); PG8_STAGE(PG8_SB(1, 1), b3 + hstepB, voffB); PG8_STAGE(PG8_SA(1, 0), a3, voffA);
;             PG8_WAIT_V(8); PG8_WAIT_L(0); PG8_BAR; PG8_MMA(1, 0, At, B0); PG8_MMA(1, 1, At, B1); PG8_BAR; PG8_SCHED;
	s_add_u32 s26, s24, 0x8000
	s_addc_u32 s27, s25, 0
	s_add_i32 s66, s60, s34
	s_mov_b32 m0, s66
	ds_read_b128 v[188:191], v155 offset:49152
	ds_read_b128 v[192:195], v155 offset:50176
	ds_read_b128 v[196:199], v155 offset:51200
	ds_read_b128 v[200:203], v155 offset:52224
	ds_read_b128 v[204:207], v155 offset:53248
	ds_read_b128 v[208:211], v155 offset:54272
	ds_read_b128 v[212:215], v155 offset:55296
	ds_read_b128 v[216:219], v155 offset:56320
	global_load_lds_dwordx4 v132, s[26:27]
	s_add_i32 m0, s66, 0x2000
	s_add_u32 s24, s24, 0xc000
	v_lshl_add_u64 v[220:221], s[26:27], 0, v[136:137]
	s_addc_u32 s25, s25, 0
	s_add_i32 s26, s61, s34
	global_load_lds_dwordx4 v[220:221], off
	s_mov_b32 m0, s26
	s_nop 0
	global_load_lds_dwordx4 v132, s[24:25]
	s_add_i32 m0, s26, 0x2000
	s_nop 0
	global_load_lds_dwordx4 v136, s[24:25]
	s_mov_b32 m0, s41
	s_nop 0
	global_load_lds_dwordx4 v130, s[22:23]
	s_mov_b32 m0, s42
	s_nop 0
	global_load_lds_dwordx4 v134, s[22:23]
	s_waitcnt vmcnt(8)
	s_waitcnt lgkmcnt(0)
	s_barrier
	s_setprio 1
	s_waitcnt lgkmcnt(0)
	v_mfma_f32_16x16x32_bf16 v[62:65], v[156:159], v[188:191], v[62:65]
	v_mfma_f32_16x16x32_bf16 v[58:61], v[164:167], v[188:191], v[58:61]
	v_mfma_f32_16x16x32_bf16 v[46:49], v[156:159], v[196:199], v[46:49]
	v_mfma_f32_16x16x32_bf16 v[42:45], v[164:167], v[196:199], v[42:45]
	v_mfma_f32_16x16x32_bf16 v[30:33], v[156:159], v[204:207], v[30:33]
	v_mfma_f32_16x16x32_bf16 v[26:29], v[164:167], v[204:207], v[26:29]
	v_mfma_f32_16x16x32_bf16 v[14:17], v[156:159], v[212:215], v[14:17]
	v_mfma_f32_16x16x32_bf16 v[10:13], v[164:167], v[212:215], v[10:13]
	v_mfma_f32_16x16x32_bf16 v[62:65], v[160:163], v[192:195], v[62:65]
	v_mfma_f32_16x16x32_bf16 v[58:61], v[168:171], v[192:195], v[58:61]
	v_mfma_f32_16x16x32_bf16 v[46:49], v[160:163], v[200:203], v[46:49]
	v_mfma_f32_16x16x32_bf16 v[42:45], v[168:171], v[200:203], v[42:45]
	v_mfma_f32_16x16x32_bf16 v[30:33], v[160:163], v[208:211], v[30:33]
	v_mfma_f32_16x16x32_bf16 v[26:29], v[168:171], v[208:211], v[26:29]
	v_mfma_f32_16x16x32_bf16 v[14:17], v[160:163], v[216:219], v[14:17]
	v_mfma_f32_16x16x32_bf16 v[10:13], v[168:171], v[216:219], v[10:13]
	s_setprio 0
	s_setprio 1
	v_mfma_f32_16x16x32_bf16 v[54:57], v[172:175], v[188:191], v[54:57]
	v_mfma_f32_16x16x32_bf16 v[50:53], v[180:183], v[188:191], v[50:53]
	v_mfma_f32_16x16x32_bf16 v[38:41], v[172:175], v[196:199], v[38:41]
	v_mfma_f32_16x16x32_bf16 v[34:37], v[180:183], v[196:199], v[34:37]
	v_mfma_f32_16x16x32_bf16 v[22:25], v[172:175], v[204:207], v[22:25]
	v_mfma_f32_16x16x32_bf16 v[18:21], v[180:183], v[204:207], v[18:21]
	v_mfma_f32_16x16x32_bf16 v[6:9], v[172:175], v[212:215], v[6:9]
	v_mfma_f32_16x16x32_bf16 v[2:5], v[180:183], v[212:215], v[2:5]
	v_mfma_f32_16x16x32_bf16 v[54:57], v[176:179], v[192:195], v[54:57]
	v_mfma_f32_16x16x32_bf16 v[50:53], v[184:187], v[192:195], v[50:53]
	v_mfma_f32_16x16x32_bf16 v[38:41], v[176:179], v[200:203], v[38:41]
	v_mfma_f32_16x16x32_bf16 v[34:37], v[184:187], v[200:203], v[34:37]
	v_mfma_f32_16x16x32_bf16 v[22:25], v[176:179], v[208:211], v[22:25]
	v_mfma_f32_16x16x32_bf16 v[18:21], v[184:187], v[208:211], v[18:21]
	v_mfma_f32_16x16x32_bf16 v[6:9], v[176:179], v[216:219], v[6:9]
	v_mfma_f32_16x16x32_bf16 v[2:5], v[184:187], v[216:219], v[2:5]
	s_setprio 0
	s_barrier
	s_add_u32 s51, s51, 0x10000
	s_addc_u32 s55, s55, 0
	s_add_u32 s20, s20, 0x100
	s_addc_u32 s21, s21, 0
	s_cmp_ge_u32 s65, s46
	s_cbranch_scc0 .LBB0_1038
	s_and_b64 vcc, exec, s[10:11]
	s_cbranch_vccz .LBB0_1041
	s_barrier

; __device__ __forceinline__ unsigned pk2(float lo, float hi) { const f32x2 v = {lo, hi}; return __builtin_bit_cast(unsigned, __builtin_convertvector(v, bf16x2_t)); }
; #define PG8_STAGE(bufoff, gbase, voff) do { _Pragma("unroll") for (int _i = 0; _i < 2; ++_i) \
;         __builtin_amdgcn_global_load_lds((const unsigned*)((const char*)(gbase) + (voff)[_i]), (LAS unsigned*)(lds + (bufoff) + ldsw + _i * 8192), 16, 0, 0); } while (0)
; #define PG8_WAIT_V(n) asm volatile("s_waitcnt vmcnt(" #n ")" ::: "memory")
; #define PG8_BAR __builtin_amdgcn_s_barrier()
; template <class Epi, class Sched, bool ABLK = false, bool ALIGN_EPI = true, bool SP2 = true, bool BBLK = true>
; __device__ __forceinline__ void gemm_phase(LAS unsigned char* lds, const Gemm g, const Sched& S, const Epi& E) {
;     ...
;         PG8_STAGE(PG8_SB(1, 0), cB + kstepB, voffB); PG8_STAGE(PG8_SA(1, 0), a_tile(uA, tbA + 1), voffA); PG8_STAGE(PG8_SB(1, 1), cB + hstepB + kstepB, voffB);
;         PG8_WAIT_V(6); PG8_BAR;
;     __device__ __forceinline__ void operator()(const f32x4 (&acc)[2][2][4][2], const Unit& u, int wr, int wc, int fr, int fq) const {
; #pragma unroll
;         for (int ai = 0; ai < 2; ++ai)
; #pragma unroll
;             for (int m = 0; m < 4; ++m) { unsigned char* rowp = (unsigned char*)(H + ((size_t)(u.pm * (FF / 64) + u.pn * 4 + wc) * 256 + (wr * 64 + fr + ai * 128 + m * 16)) * 64 + 8 * fq); u32x4 w[2];
; #pragma unroll
;                 for (int bj = 0; bj < 2; ++bj) { f32x4 v0 = acc[ai][bj][m][0], v1 = acc[ai][bj][m][1];
; #pragma unroll
;                     for (int j = 0; j < 4; ++j) { const float a = fmaxf(v0[j], 0.f), b = fmaxf(v1[j], 0.f); v0[j] = a * a; v1[j] = b * b; }
;                     w[bj].x = pk2(v0[0], v0[1]); w[bj].y = pk2(v0[2], v0[3]); w[bj].z = pk2(v1[0], v1[1]); w[bj].w = pk2(v1[2], v1[3]); }
;                 store_pair(rowp, (size_t)8 * 64 * 2, 64, w[0], w[1], fr >= 8); }
.LBB0_1158:
	s_and_b32 s47, s8, 3
	s_lshl_b32 s10, s7, 13
	s_lshl_b32 s11, s47, 12
	s_add_u32 s8, s28, 0x8000
	s_addc_u32 s9, s29, 0
	s_add_i32 m0, s25, 0x18000
	v_lshl_add_u64 v[14:15], s[8:9], 0, v[134:135]
	s_waitcnt vmcnt(2)
	s_barrier
	global_load_lds_dwordx4 v[14:15], off
	v_lshl_add_u64 v[14:15], s[8:9], 0, v[130:131]
	s_add_i32 m0, s25, 0x1a000
	s_mov_b64 s[8:9], 0x80
	s_add_i32 s48, s25, 0x8000
	global_load_lds_dwordx4 v[14:15], off
	v_lshl_add_u64 v[2:3], v[2:3], 0, s[8:9]
	s_mov_b32 m0, s48
	s_add_i32 s49, s25, 0xa000
	global_load_lds_dwordx4 v[2:3], off
	v_lshl_add_u64 v[2:3], v[4:5], 0, s[8:9]
	s_add_u32 s8, s28, 0xc000
	s_mov_b32 m0, s49
	s_addc_u32 s9, s29, 0
	global_load_lds_dwordx4 v[2:3], off
	s_add_i32 m0, s25, 0x1c000
	s_nop 0
	global_load_lds_dwordx4 v134, s[8:9]
	s_add_i32 m0, s25, 0x1e000
	v_lshrrev_b32_e32 v4, 1, v9
	global_load_lds_dwordx4 v130, s[8:9]
	v_and_b32_e32 v4, 24, v4
	v_and_b32_e32 v3, 15, v9
	v_lshlrev_b32_e32 v5, 1, v4
	v_lshl_or_b32 v2, s7, 6, v3
	v_lshl_or_b32 v5, v3, 6, v5
	v_cmp_lt_u32_e64 s[8:9], 7, v3
	v_mov_b32_e32 v3, 0xfffffc40
	v_or_b32_e32 v14, 16, v2
	v_cndmask_b32_e64 v140, 0, v3, s[8:9]
	v_mov_b32_e32 v3, 0x400
	v_cndmask_b32_e64 v142, v3, 64, s[8:9]
	v_ashrrev_i32_e32 v3, 31, v2
	v_ashrrev_i32_e32 v15, 31, v14
	v_lshlrev_b64 v[144:145], 7, v[2:3]
	v_lshlrev_b64 v[146:147], 7, v[14:15]
	v_or_b32_e32 v14, 32, v2
	v_or_b32_e32 v2, 48, v2
	v_ashrrev_i32_e32 v3, 31, v2
	v_lshlrev_b64 v[150:151], 7, v[2:3]
	v_lshlrev_b32_e32 v2, 15, v10
	v_and_b32_e32 v2, 0xffff0000, v2
	v_lshl_add_u32 v2, v11, 12, v2
	v_and_b32_e32 v3, 1, v10
	v_lshl_or_b32 v2, v3, 6, v2
	v_lshl_add_u64 v[152:153], v[144:145], 0, s[4:5]
	s_mov_b64 s[4:5], 0x4800
	v_lshl_add_u32 v138, v12, 1, v2
	v_lshlrev_b32_e32 v2, 15, v6
	v_lshl_add_u64 v[154:155], v[144:145], 0, s[4:5]
	s_mov_b64 s[4:5], 0x5000
	v_and_b32_e32 v2, 0xffff0000, v2
	v_lshlrev_b32_e32 v9, 2, v9
	v_lshl_add_u64 v[156:157], v[144:145], 0, s[4:5]
	s_mov_b64 s[4:5], 0x5800
	v_lshl_add_u32 v2, v7, 12, v2
	v_and_b32_e32 v3, 1, v6
	v_and_b32_e32 v9, 32, v9
	s_waitcnt vmcnt(6)
	s_cmpk_lt_u32 s6, 0x100
	v_lshl_add_u64 v[158:159], v[144:145], 0, s[4:5]
	s_mov_b64 s[4:5], 0x80080
	v_lshl_or_b32 v2, v3, 6, v2
	v_bitop3_b32 v13, v5, s10, v9 bitop3:0xde
	v_bitop3_b32 v168, v5, s11, v9 bitop3:0xde
	s_cselect_b64 s[6:7], -1, 0
	v_ashrrev_i32_e32 v15, 31, v14
	v_lshl_add_u64 v[160:161], v[138:139], 0, s[4:5]
	v_lshl_add_u32 v138, v8, 1, v2
	s_add_i32 s55, s72, s42
	v_cndmask_b32_e64 v141, 0, -1, s[8:9]
	v_mov_b32_e32 v143, v139
	v_lshlrev_b64 v[148:149], 7, v[14:15]
	v_lshl_add_u64 v[162:163], v[138:139], 0, s[4:5]
	v_add_u32_e32 v169, s72, v168
	v_add_u32_e32 v170, s73, v168
	v_add_u32_e32 v171, 0, v13
	v_lshlrev_b32_e32 v138, 1, v4
	s_add_i32 s50, s25, 0xc000
	s_add_i32 s51, s25, 0xe000
	s_add_i32 s56, s55, 0x2000
	s_barrier
	s_branch .LBB0_1161

; #define PG8_STAGE(bufoff, gbase, voff) do { _Pragma("unroll") for (int _i = 0; _i < 2; ++_i) \
;         __builtin_amdgcn_global_load_lds((const unsigned*)((const char*)(gbase) + (voff)[_i]), (LAS unsigned*)(lds + (bufoff) + ldsw + _i * 8192), 16, 0, 0); } while (0)
; #define PG8_LDA(dst, b, h) do { _Pragma("unroll") for (int m = 0; m < 4; ++m) _Pragma("unroll") for (int k = 0; k < 2; ++k) dst[m][k] = *(const LAS bf16x8*)(lds + PG8_SA(b, h) + aoff + m * 2048 + k * 1024); } while (0)
; #define PG8_LDB(dst, b, h) do { _Pragma("unroll") for (int n = 0; n < 2; ++n) _Pragma("unroll") for (int k = 0; k < 2; ++k) dst[n][k] = *(const LAS bf16x8*)(lds + PG8_SB(b, h) + boff + n * 2048 + k * 1024); } while (0)
; #define PG8_MMA(ai, bj, At, Bt) do { __builtin_amdgcn_s_setprio(1); _Pragma("unroll") for (int m = 0; m < 4; ++m) _Pragma("unroll") for (int n = 0; n < 2; ++n) _Pragma("unroll") for (int k = 0; k < 2; ++k) \
;         acc[ai][bj][m][n] = __builtin_amdgcn_mfma_f32_16x16x32_bf16(Bt[n][k], At[m][k], acc[ai][bj][m][n], 0, 0, 0); __builtin_amdgcn_s_setprio(0); } while (0)
; #define PG8_WAIT_V(n) asm volatile("s_waitcnt vmcnt(" #n ")" ::: "memory")
; #define PG8_WAIT_L(n) asm volatile("s_waitcnt lgkmcnt(" #n ")" ::: "memory")
; #define PG8_BAR __builtin_amdgcn_s_barrier()
; #define PG8_SCHED __builtin_amdgcn_sched_barrier(0)
; template <class Epi, class Sched, bool ABLK = false, bool ALIGN_EPI = true, bool SP2 = true, bool BBLK = true>
; __device__ __forceinline__ void gemm_phase(LAS unsigned char* lds, const Gemm g, const Sched& S, const Epi& E) {
;     ...
;             const char* a1 = a_tile(uA, tbA + t + 1);
;             const char* a2 = last ? a_tile(nuA, ntbA) : a_tile(uA, tbA + t + 2); const char* b2 = last ? nB : cB + (size_t)(t + 2) * kstepB;
;             const char* a3 = last ? a_tile(nuA, ntbA + 1) : a_tile(uA, tbA + t + 3); const char* b3 = b2 + kstepB;
;             if (last && has_next) S.a_ready(nxt);
;             if constexpr (SP2) {
;             PG8_LDB(B0, 0, 0); PG8_LDB(B1, 0, 1); PG8_SCHED; PG8_LDA(At, 0, 0); PG8_STAGE(PG8_SA(1, 1), a1 + hstepA, voffA);
;             PG8_WAIT_V(8); PG8_WAIT_L(0); PG8_BAR; PG8_MMA(0, 0, At, B0); PG8_MMA(0, 1, At, B1); PG8_BAR; PG8_SCHED;
;             PG8_LDA(At, 0, 1); PG8_STAGE(PG8_SB(0, 0), b2, voffB); PG8_STAGE(PG8_SB(0, 1), b2 + hstepB, voffB); PG8_STAGE(PG8_SA(0, 0), a2, voffA);
.LBB0_1164:
	ds_read_b128 v[172:175], v169
	ds_read_b128 v[176:179], v169 offset:1024
	ds_read_b128 v[180:183], v169 offset:2048
	ds_read_b128 v[184:187], v169 offset:3072
	ds_read_b128 v[188:191], v170
	ds_read_b128 v[192:195], v170 offset:1024
	ds_read_b128 v[196:199], v170 offset:2048
	ds_read_b128 v[200:203], v170 offset:3072
	s_add_u32 s30, s26, s28
	s_addc_u32 s31, s27, s29
	s_add_u32 s36, s30, 0x100
	s_addc_u32 s37, s31, 0
	s_add_u32 s30, s30, 0x180
	s_addc_u32 s31, s31, 0
	s_cmpk_eq_i32 s28, 0xf00
	s_cselect_b32 s31, s57, s31
	s_cselect_b32 s30, s23, s30
	s_cselect_b32 s35, s11, s65
	s_cselect_b32 s34, s15, s64
	s_cselect_b32 s37, s4, s37
	s_cselect_b32 s36, s5, s36
	s_mov_b32 m0, s50
	v_lshl_add_u64 v[236:237], v[164:165], 0, s[28:29]
	ds_read_b128 v[204:207], v171
	ds_read_b128 v[208:211], v171 offset:1024
	ds_read_b128 v[212:215], v171 offset:2048
	ds_read_b128 v[216:219], v171 offset:3072
	ds_read_b128 v[220:223], v171 offset:4096
	ds_read_b128 v[224:227], v171 offset:5120
	ds_read_b128 v[228:231], v171 offset:6144
	ds_read_b128 v[232:235], v171 offset:7168
	global_load_lds_dwordx4 v[236:237], off
	v_lshl_add_u64 v[236:237], v[166:167], 0, s[28:29]
	s_mov_b32 m0, s51
	s_nop 0
	global_load_lds_dwordx4 v[236:237], off
	s_waitcnt vmcnt(8)
	s_waitcnt lgkmcnt(0)
	s_barrier
	s_setprio 1
	s_waitcnt lgkmcnt(0)
	v_mfma_f32_16x16x32_bf16 v[126:129], v[172:175], v[204:207], v[126:129]
	v_mfma_f32_16x16x32_bf16 v[122:125], v[180:183], v[204:207], v[122:125]
	v_mfma_f32_16x16x32_bf16 v[110:113], v[172:175], v[212:215], v[110:113]
	v_mfma_f32_16x16x32_bf16 v[106:109], v[180:183], v[212:215], v[106:109]
	v_mfma_f32_16x16x32_bf16 v[94:97], v[172:175], v[220:223], v[94:97]
	v_mfma_f32_16x16x32_bf16 v[90:93], v[180:183], v[220:223], v[90:93]
	v_mfma_f32_16x16x32_bf16 v[78:81], v[172:175], v[228:231], v[78:81]
	v_mfma_f32_16x16x32_bf16 v[74:77], v[180:183], v[228:231], v[74:77]
	v_mfma_f32_16x16x32_bf16 v[126:129], v[176:179], v[208:211], v[126:129]
	v_mfma_f32_16x16x32_bf16 v[122:125], v[184:187], v[208:211], v[122:125]
	v_mfma_f32_16x16x32_bf16 v[110:113], v[176:179], v[216:219], v[110:113]
	v_mfma_f32_16x16x32_bf16 v[106:109], v[184:187], v[216:219], v[106:109]
	v_mfma_f32_16x16x32_bf16 v[94:97], v[176:179], v[224:227], v[94:97]
	v_mfma_f32_16x16x32_bf16 v[90:93], v[184:187], v[224:227], v[90:93]
	v_mfma_f32_16x16x32_bf16 v[78:81], v[176:179], v[232:235], v[78:81]
	v_mfma_f32_16x16x32_bf16 v[74:77], v[184:187], v[232:235], v[74:77]
	s_setprio 0
	s_setprio 1
	v_mfma_f32_16x16x32_bf16 v[118:121], v[188:191], v[204:207], v[118:121]
	v_mfma_f32_16x16x32_bf16 v[114:117], v[196:199], v[204:207], v[114:117]
	v_mfma_f32_16x16x32_bf16 v[102:105], v[188:191], v[212:215], v[102:105]
	v_mfma_f32_16x16x32_bf16 v[98:101], v[196:199], v[212:215], v[98:101]
	v_mfma_f32_16x16x32_bf16 v[86:89], v[188:191], v[220:223], v[86:89]
	v_mfma_f32_16x16x32_bf16 v[82:85], v[196:199], v[220:223], v[82:85]
	v_mfma_f32_16x16x32_bf16 v[70:73], v[188:191], v[228:231], v[70:73]
	v_mfma_f32_16x16x32_bf16 v[66:69], v[196:199], v[228:231], v[66:69]
	v_mfma_f32_16x16x32_bf16 v[118:121], v[192:195], v[208:211], v[118:121]
	v_mfma_f32_16x16x32_bf16 v[114:117], v[200:203], v[208:211], v[114:117]
	v_mfma_f32_16x16x32_bf16 v[102:105], v[192:195], v[216:219], v[102:105]
	v_mfma_f32_16x16x32_bf16 v[98:101], v[200:203], v[216:219], v[98:101]
	v_mfma_f32_16x16x32_bf16 v[86:89], v[192:195], v[224:227], v[86:89]
	v_mfma_f32_16x16x32_bf16 v[82:85], v[200:203], v[224:227], v[82:85]
	v_mfma_f32_16x16x32_bf16 v[70:73], v[192:195], v[232:235], v[70:73]
	v_mfma_f32_16x16x32_bf16 v[66:69], v[200:203], v[232:235], v[66:69]
	s_setprio 0
	s_barrier
	s_mov_b32 m0, s55
	s_add_u32 s76, s34, 0x4000
	ds_read_b128 v[204:207], v171 offset:16384
	ds_read_b128 v[208:211], v171 offset:17408
	ds_read_b128 v[212:215], v171 offset:18432
	ds_read_b128 v[216:219], v171 offset:19456
	ds_read_b128 v[220:223], v171 offset:20480
	ds_read_b128 v[224:227], v171 offset:21504
	ds_read_b128 v[228:231], v171 offset:22528
	ds_read_b128 v[232:235], v171 offset:23552
	global_load_lds_dwordx4 v134, s[34:35]
	s_mov_b32 m0, s56
	s_addc_u32 s77, s35, 0
	s_add_i32 s67, s73, s42
	global_load_lds_dwordx4 v130, s[34:35]
	s_mov_b32 m0, s67
	s_nop 0
	global_load_lds_dwordx4 v134, s[76:77]
	s_add_i32 m0, s67, 0x2000
	s_nop 0
	global_load_lds_dwordx4 v130, s[76:77]
	s_mov_b32 m0, s25
	s_nop 0
	global_load_lds_dwordx4 v136, s[36:37]
	s_mov_b32 m0, s43
	s_nop 0
	global_load_lds_dwordx4 v132, s[36:37]
	s_waitcnt vmcnt(8)
	s_waitcnt lgkmcnt(0)
	s_barrier
; #define PG8_STAGE(bufoff, gbase, voff) do { _Pragma("unroll") for (int _i = 0; _i < 2; ++_i) \
;         __builtin_amdgcn_global_load_lds((const unsigned*)((const char*)(gbase) + (voff)[_i]), (LAS unsigned*)(lds + (bufoff) + ldsw + _i * 8192), 16, 0, 0); } while (0)
; #define PG8_LDA(dst, b, h) do { _Pragma("unroll") for (int m = 0; m < 4; ++m) _Pragma("unroll") for (int k = 0; k < 2; ++k) dst[m][k] = *(const LAS bf16x8*)(lds + PG8_SA(b, h) + aoff + m * 2048 + k * 1024); } while (0)
; #define PG8_LDB(dst, b, h) do { _Pragma("unroll") for (int n = 0; n < 2; ++n) _Pragma("unroll") for (int k = 0; k < 2; ++k) dst[n][k] = *(const LAS bf16x8*)(lds + PG8_SB(b, h) + boff + n * 2048 + k * 1024); } while (0)
; #define PG8_MMA(ai, bj, At, Bt) do { __builtin_amdgcn_s_setprio(1); _Pragma("unroll") for (int m = 0; m < 4; ++m) _Pragma("unroll") for (int n = 0; n < 2; ++n) _Pragma("unroll") for (int k = 0; k < 2; ++k) \
;         acc[ai][bj][m][n] = __builtin_amdgcn_mfma_f32_16x16x32_bf16(Bt[n][k], At[m][k], acc[ai][bj][m][n], 0, 0, 0); __builtin_amdgcn_s_setprio(0); } while (0)
; #define PG8_WAIT_V(n) asm volatile("s_waitcnt vmcnt(" #n ")" ::: "memory")
; #define PG8_WAIT_L(n) asm volatile("s_waitcnt lgkmcnt(" #n ")" ::: "memory")
; #define PG8_BAR __builtin_amdgcn_s_barrier()
; #define PG8_SCHED __builtin_amdgcn_sched_barrier(0)
; template <class Epi, class Sched, bool ABLK = false, bool ALIGN_EPI = true, bool SP2 = true, bool BBLK = true>
; __device__ __forceinline__ void gemm_phase(LAS unsigned char* lds, const Gemm g, const Sched& S, const Epi& E) {
;     ...
;             PG8_WAIT_V(8); PG8_WAIT_L(0); PG8_BAR; PG8_MMA(1, 0, At, B0); PG8_MMA(1, 1, At, B1); PG8_BAR; PG8_SCHED;
;             PG8_LDB(B0, 1, 0); PG8_LDB(B1, 1, 1); PG8_SCHED; PG8_LDA(At, 1, 0); PG8_STAGE(PG8_SA(0, 1), a2 + hstepA, voffA);
;             PG8_WAIT_V(8); PG8_WAIT_L(0); PG8_BAR; PG8_MMA(0, 0, At, B0); PG8_MMA(0, 1, At, B1); PG8_BAR; PG8_SCHED;
	s_setprio 1
	s_waitcnt lgkmcnt(0)
	v_mfma_f32_16x16x32_bf16 v[62:65], v[172:175], v[204:207], v[62:65]
	v_mfma_f32_16x16x32_bf16 v[58:61], v[180:183], v[204:207], v[58:61]
	v_mfma_f32_16x16x32_bf16 v[46:49], v[172:175], v[212:215], v[46:49]
	v_mfma_f32_16x16x32_bf16 v[42:45], v[180:183], v[212:215], v[42:45]
	v_mfma_f32_16x16x32_bf16 v[30:33], v[172:175], v[220:223], v[30:33]
	v_mfma_f32_16x16x32_bf16 v[26:29], v[180:183], v[220:223], v[26:29]
	v_mfma_f32_16x16x32_bf16 v[14:17], v[172:175], v[228:231], v[14:17]
	v_mfma_f32_16x16x32_bf16 v[10:13], v[180:183], v[228:231], v[10:13]
	v_mfma_f32_16x16x32_bf16 v[62:65], v[176:179], v[208:211], v[62:65]
	v_mfma_f32_16x16x32_bf16 v[58:61], v[184:187], v[208:211], v[58:61]
	v_mfma_f32_16x16x32_bf16 v[46:49], v[176:179], v[216:219], v[46:49]
	v_mfma_f32_16x16x32_bf16 v[42:45], v[184:187], v[216:219], v[42:45]
	v_mfma_f32_16x16x32_bf16 v[30:33], v[176:179], v[224:227], v[30:33]
	v_mfma_f32_16x16x32_bf16 v[26:29], v[184:187], v[224:227], v[26:29]
	v_mfma_f32_16x16x32_bf16 v[14:17], v[176:179], v[232:235], v[14:17]
	v_mfma_f32_16x16x32_bf16 v[10:13], v[184:187], v[232:235], v[10:13]
	s_setprio 0
	s_setprio 1
	v_mfma_f32_16x16x32_bf16 v[54:57], v[188:191], v[204:207], v[54:57]
	v_mfma_f32_16x16x32_bf16 v[50:53], v[196:199], v[204:207], v[50:53]
	v_mfma_f32_16x16x32_bf16 v[38:41], v[188:191], v[212:215], v[38:41]
	v_mfma_f32_16x16x32_bf16 v[34:37], v[196:199], v[212:215], v[34:37]
	v_mfma_f32_16x16x32_bf16 v[22:25], v[188:191], v[220:223], v[22:25]
	v_mfma_f32_16x16x32_bf16 v[18:21], v[196:199], v[220:223], v[18:21]
	v_mfma_f32_16x16x32_bf16 v[6:9], v[188:191], v[228:231], v[6:9]
	v_mfma_f32_16x16x32_bf16 v[2:5], v[196:199], v[228:231], v[2:5]
	v_mfma_f32_16x16x32_bf16 v[54:57], v[192:195], v[208:211], v[54:57]
	v_mfma_f32_16x16x32_bf16 v[50:53], v[200:203], v[208:211], v[50:53]
	v_mfma_f32_16x16x32_bf16 v[38:41], v[192:195], v[216:219], v[38:41]
	v_mfma_f32_16x16x32_bf16 v[34:37], v[200:203], v[216:219], v[34:37]
	v_mfma_f32_16x16x32_bf16 v[22:25], v[192:195], v[224:227], v[22:25]
	v_mfma_f32_16x16x32_bf16 v[18:21], v[200:203], v[224:227], v[18:21]
	v_mfma_f32_16x16x32_bf16 v[6:9], v[192:195], v[232:235], v[6:9]
	v_mfma_f32_16x16x32_bf16 v[2:5], v[200:203], v[232:235], v[2:5]
	s_setprio 0
	s_barrier
	v_add_u32_e32 v184, s60, v168
	v_add_u32_e32 v200, s61, v168
	ds_read_b128 v[172:175], v184
	ds_read_b128 v[176:179], v184 offset:1024
	ds_read_b128 v[180:183], v184 offset:2048
	ds_read_b128 v[184:187], v184 offset:3072
	ds_read_b128 v[188:191], v200
	ds_read_b128 v[192:195], v200 offset:1024
	ds_read_b128 v[196:199], v200 offset:2048
	ds_read_b128 v[200:203], v200 offset:3072
	s_add_u32 s36, s36, 0x80000
	s_addc_u32 s37, s37, 0
	s_mov_b32 m0, s44
	ds_read_b128 v[204:207], v171 offset:32768
	ds_read_b128 v[208:211], v171 offset:33792
	ds_read_b128 v[212:215], v171 offset:34816
	ds_read_b128 v[216:219], v171 offset:35840
	ds_read_b128 v[220:223], v171 offset:36864
	ds_read_b128 v[224:227], v171 offset:37888
	ds_read_b128 v[228:231], v171 offset:38912
	ds_read_b128 v[232:235], v171 offset:39936
	global_load_lds_dwordx4 v136, s[36:37]
	s_mov_b32 m0, s45
	s_nop 0
	global_load_lds_dwordx4 v132, s[36:37]
	s_waitcnt vmcnt(8)
	s_waitcnt lgkmcnt(0)
	s_barrier
	s_setprio 1
	s_waitcnt lgkmcnt(0)
	v_mfma_f32_16x16x32_bf16 v[126:129], v[172:175], v[204:207], v[126:129]
	v_mfma_f32_16x16x32_bf16 v[122:125], v[180:183], v[204:207], v[122:125]
	v_mfma_f32_16x16x32_bf16 v[110:113], v[172:175], v[212:215], v[110:113]
	v_mfma_f32_16x16x32_bf16 v[106:109], v[180:183], v[212:215], v[106:109]
	v_mfma_f32_16x16x32_bf16 v[94:97], v[172:175], v[220:223], v[94:97]
	v_mfma_f32_16x16x32_bf16 v[90:93], v[180:183], v[220:223], v[90:93]
	v_mfma_f32_16x16x32_bf16 v[78:81], v[172:175], v[228:231], v[78:81]
	v_mfma_f32_16x16x32_bf16 v[74:77], v[180:183], v[228:231], v[74:77]
	v_mfma_f32_16x16x32_bf16 v[126:129], v[176:179], v[208:211], v[126:129]
	v_mfma_f32_16x16x32_bf16 v[122:125], v[184:187], v[208:211], v[122:125]
	v_mfma_f32_16x16x32_bf16 v[110:113], v[176:179], v[216:219], v[110:113]
	v_mfma_f32_16x16x32_bf16 v[106:109], v[184:187], v[216:219], v[106:109]
	v_mfma_f32_16x16x32_bf16 v[94:97], v[176:179], v[224:227], v[94:97]
	v_mfma_f32_16x16x32_bf16 v[90:93], v[184:187], v[224:227], v[90:93]
	v_mfma_f32_16x16x32_bf16 v[78:81], v[176:179], v[232:235], v[78:81]
	v_mfma_f32_16x16x32_bf16 v[74:77], v[184:187], v[232:235], v[74:77]
	s_setprio 0
	s_setprio 1
	v_mfma_f32_16x16x32_bf16 v[118:121], v[188:191], v[204:207], v[118:121]
	v_mfma_f32_16x16x32_bf16 v[114:117], v[196:199], v[204:207], v[114:117]
	v_mfma_f32_16x16x32_bf16 v[102:105], v[188:191], v[212:215], v[102:105]
	v_mfma_f32_16x16x32_bf16 v[98:101], v[196:199], v[212:215], v[98:101]
	v_mfma_f32_16x16x32_bf16 v[86:89], v[188:191], v[220:223], v[86:89]
	v_mfma_f32_16x16x32_bf16 v[82:85], v[196:199], v[220:223], v[82:85]
	v_mfma_f32_16x16x32_bf16 v[70:73], v[188:191], v[228:231], v[70:73]
	v_mfma_f32_16x16x32_bf16 v[66:69], v[196:199], v[228:231], v[66:69]
	v_mfma_f32_16x16x32_bf16 v[118:121], v[192:195], v[208:211], v[118:121]
	v_mfma_f32_16x16x32_bf16 v[114:117], v[200:203], v[208:211], v[114:117]
	v_mfma_f32_16x16x32_bf16 v[102:105], v[192:195], v[216:219], v[102:105]
	v_mfma_f32_16x16x32_bf16 v[98:101], v[200:203], v[216:219], v[98:101]
	v_mfma_f32_16x16x32_bf16 v[86:89], v[192:195], v[224:227], v[86:89]
	v_mfma_f32_16x16x32_bf16 v[82:85], v[200:203], v[224:227], v[82:85]
	v_mfma_f32_16x16x32_bf16 v[70:73], v[192:195], v[232:235], v[70:73]
	v_mfma_f32_16x16x32_bf16 v[66:69], v[200:203], v[232:235], v[66:69]
	s_setprio 0
	s_barrier
; #define PG8_STAGE(bufoff, gbase, voff) do { _Pragma("unroll") for (int _i = 0; _i < 2; ++_i) \
;         __builtin_amdgcn_global_load_lds((const unsigned*)((const char*)(gbase) + (voff)[_i]), (LAS unsigned*)(lds + (bufoff) + ldsw + _i * 8192), 16, 0, 0); } while (0)
; #define PG8_LDA(dst, b, h) do { _Pragma("unroll") for (int m = 0; m < 4; ++m) _Pragma("unroll") for (int k = 0; k < 2; ++k) dst[m][k] = *(const LAS bf16x8*)(lds + PG8_SA(b, h) + aoff + m * 2048 + k * 1024); } while (0)
; #define PG8_MMA(ai, bj, At, Bt) do { __builtin_amdgcn_s_setprio(1); _Pragma("unroll") for (int m = 0; m < 4; ++m) _Pragma("unroll") for (int n = 0; n < 2; ++n) _Pragma("unroll") for (int k = 0; k < 2; ++k) \
;         acc[ai][bj][m][n] = __builtin_amdgcn_mfma_f32_16x16x32_bf16(Bt[n][k], At[m][k], acc[ai][bj][m][n], 0, 0, 0); __builtin_amdgcn_s_setprio(0); } while (0)
; #define PG8_WAIT_V(n) asm volatile("s_waitcnt vmcnt(" #n ")" ::: "memory")
; #define PG8_WAIT_L(n) asm volatile("s_waitcnt lgkmcnt(" #n ")" ::: "memory")
; #define PG8_BAR __builtin_amdgcn_s_barrier()
; #define PG8_SCHED __builtin_amdgcn_sched_barrier(0)
; template <class Epi, class Sched, bool ABLK = false, bool ALIGN_EPI = true, bool SP2 = true, bool BBLK = true>
; __device__ __forceinline__ void gemm_phase(LAS unsigned char* lds, const Gemm g, const Sched& S, const Epi& E) {
;     ...
;             PG8_LDA(At, 1, 1); PG8_STAGE(PG8_SB(1, 0), b3, voffB); PG8_STAGE(PG8_SB(1, 1), b3 + hstepB, voffB); PG8_STAGE(PG8_SA(1, 0), a3, voffA);
;             PG8_WAIT_V(8); PG8_WAIT_L(0); PG8_BAR; PG8_MMA(1, 0, At, B0); PG8_MMA(1, 1, At, B1); PG8_BAR; PG8_SCHED;
	s_add_u32 s36, s34, 0x8000
	s_addc_u32 s37, s35, 0
	s_add_i32 s67, s60, s42
	s_mov_b32 m0, s67
	ds_read_b128 v[204:207], v171 offset:49152
	ds_read_b128 v[208:211], v171 offset:50176
	ds_read_b128 v[212:215], v171 offset:51200
	ds_read_b128 v[216:219], v171 offset:52224
	ds_read_b128 v[220:223], v171 offset:53248
	ds_read_b128 v[224:227], v171 offset:54272
	ds_read_b128 v[228:231], v171 offset:55296
	ds_read_b128 v[232:235], v171 offset:56320
	global_load_lds_dwordx4 v134, s[36:37]
	s_add_i32 m0, s67, 0x2000
	s_add_u32 s34, s34, 0xc000
	v_lshl_add_u64 v[236:237], s[36:37], 0, v[130:131]
	s_addc_u32 s35, s35, 0
	s_add_i32 s36, s61, s42
	global_load_lds_dwordx4 v[236:237], off
	s_mov_b32 m0, s36
	s_nop 0
	global_load_lds_dwordx4 v134, s[34:35]
	s_add_i32 m0, s36, 0x2000
	s_nop 0
	global_load_lds_dwordx4 v130, s[34:35]
	s_mov_b32 m0, s48
	s_nop 0
	global_load_lds_dwordx4 v136, s[30:31]
	s_mov_b32 m0, s49
	s_nop 0
	global_load_lds_dwordx4 v132, s[30:31]
	s_waitcnt vmcnt(8)
	s_waitcnt lgkmcnt(0)
	s_barrier
	s_setprio 1
	s_waitcnt lgkmcnt(0)
	v_mfma_f32_16x16x32_bf16 v[62:65], v[172:175], v[204:207], v[62:65]
	v_mfma_f32_16x16x32_bf16 v[58:61], v[180:183], v[204:207], v[58:61]
	v_mfma_f32_16x16x32_bf16 v[46:49], v[172:175], v[212:215], v[46:49]
	v_mfma_f32_16x16x32_bf16 v[42:45], v[180:183], v[212:215], v[42:45]
	v_mfma_f32_16x16x32_bf16 v[30:33], v[172:175], v[220:223], v[30:33]
	v_mfma_f32_16x16x32_bf16 v[26:29], v[180:183], v[220:223], v[26:29]
	v_mfma_f32_16x16x32_bf16 v[14:17], v[172:175], v[228:231], v[14:17]
	v_mfma_f32_16x16x32_bf16 v[10:13], v[180:183], v[228:231], v[10:13]
	v_mfma_f32_16x16x32_bf16 v[62:65], v[176:179], v[208:211], v[62:65]
	v_mfma_f32_16x16x32_bf16 v[58:61], v[184:187], v[208:211], v[58:61]
	v_mfma_f32_16x16x32_bf16 v[46:49], v[176:179], v[216:219], v[46:49]
	v_mfma_f32_16x16x32_bf16 v[42:45], v[184:187], v[216:219], v[42:45]
	v_mfma_f32_16x16x32_bf16 v[30:33], v[176:179], v[224:227], v[30:33]
	v_mfma_f32_16x16x32_bf16 v[26:29], v[184:187], v[224:227], v[26:29]
	v_mfma_f32_16x16x32_bf16 v[14:17], v[176:179], v[232:235], v[14:17]
	v_mfma_f32_16x16x32_bf16 v[10:13], v[184:187], v[232:235], v[10:13]
	s_setprio 0
	s_setprio 1
	v_mfma_f32_16x16x32_bf16 v[54:57], v[188:191], v[204:207], v[54:57]
	v_mfma_f32_16x16x32_bf16 v[50:53], v[196:199], v[204:207], v[50:53]
	v_mfma_f32_16x16x32_bf16 v[38:41], v[188:191], v[212:215], v[38:41]
	v_mfma_f32_16x16x32_bf16 v[34:37], v[196:199], v[212:215], v[34:37]
	v_mfma_f32_16x16x32_bf16 v[22:25], v[188:191], v[220:223], v[22:25]
	v_mfma_f32_16x16x32_bf16 v[18:21], v[196:199], v[220:223], v[18:21]
	v_mfma_f32_16x16x32_bf16 v[6:9], v[188:191], v[228:231], v[6:9]
	v_mfma_f32_16x16x32_bf16 v[2:5], v[196:199], v[228:231], v[2:5]
	v_mfma_f32_16x16x32_bf16 v[54:57], v[192:195], v[208:211], v[54:57]
	v_mfma_f32_16x16x32_bf16 v[50:53], v[200:203], v[208:211], v[50:53]
	v_mfma_f32_16x16x32_bf16 v[38:41], v[192:195], v[216:219], v[38:41]
	v_mfma_f32_16x16x32_bf16 v[34:37], v[200:203], v[216:219], v[34:37]
	v_mfma_f32_16x16x32_bf16 v[22:25], v[192:195], v[224:227], v[22:25]
	v_mfma_f32_16x16x32_bf16 v[18:21], v[200:203], v[224:227], v[18:21]
	v_mfma_f32_16x16x32_bf16 v[6:9], v[192:195], v[232:235], v[6:9]
	v_mfma_f32_16x16x32_bf16 v[2:5], v[200:203], v[232:235], v[2:5]
	s_setprio 0
	s_barrier
	s_add_i32 s66, s66, 2
	s_add_u32 s28, s28, 0x100
	s_addc_u32 s29, s29, 0
	s_add_u32 s64, s64, 0x10000
	s_addc_u32 s65, s65, 0
	s_cmp_gt_u32 s66, 29
	s_cbranch_scc0 .LBB0_1164
	s_and_b64 vcc, exec, s[6:7]
	s_cbranch_vccz .LBB0_1167
	s_barrier

; __device__ __forceinline__ unsigned pk2(float lo, float hi) { const f32x2 v = {lo, hi}; return __builtin_bit_cast(unsigned, __builtin_convertvector(v, bf16x2_t)); }
; #define PG8_STAGE(bufoff, gbase, voff) do { _Pragma("unroll") for (int _i = 0; _i < 2; ++_i) \
;         __builtin_amdgcn_global_load_lds((const unsigned*)((const char*)(gbase) + (voff)[_i]), (LAS unsigned*)(lds + (bufoff) + ldsw + _i * 8192), 16, 0, 0); } while (0)
; #define PG8_WAIT_V(n) asm volatile("s_waitcnt vmcnt(" #n ")" ::: "memory")
; #define PG8_BAR __builtin_amdgcn_s_barrier()
; template <class Epi, class Sched, bool ABLK = false, bool ALIGN_EPI = true, bool SP2 = true, bool BBLK = true>
; __device__ __forceinline__ void gemm_phase(LAS unsigned char* lds, const Gemm g, const Sched& S, const Epi& E) {
;     ...
;         PG8_STAGE(PG8_SB(1, 0), cB + kstepB, voffB); PG8_STAGE(PG8_SA(1, 0), a_tile(uA, tbA + 1), voffA); PG8_STAGE(PG8_SB(1, 1), cB + hstepB + kstepB, voffB);
;         PG8_WAIT_V(6); PG8_BAR;
;     __device__ __forceinline__ void operator()(const f32x4 (&acc)[2][2][4][2], const Unit& u, int wr, int wc, int fr, int fq) const {
;         const int row0 = u.pm * 256 + wr * 64 + fr, col0 = u.pn * 256 + wc * 64 + 8 * fq;
;         bf16_t* base = u.part == 0 ? Z + (size_t)row0 * D + col0 : P + ((size_t)(u.part - 1) * MS + (row0 - MP)) * D + col0;
; #pragma unroll
;         for (int ai = 0; ai < 2; ++ai)
; #pragma unroll
;             for (int m = 0; m < 4; ++m) { u32x4 w[2];
; #pragma unroll
;                 for (int bj = 0; bj < 2; ++bj) { const f32x4 v0 = acc[ai][bj][m][0], v1 = acc[ai][bj][m][1]; w[bj].x = pk2(v0[0], v0[1]); w[bj].y = pk2(v0[2], v0[3]); w[bj].z = pk2(v1[0], v1[1]); w[bj].w = pk2(v1[2], v1[3]); }
;                 store_pair((unsigned char*)(base + (size_t)(ai * 128 + m * 16) * D), (size_t)8 * D * 2, 64, w[0], w[1], fr >= 8); }
.LBB0_1225:
	s_and_b32 s5, s5, 3
	s_lshl_b32 s7, s6, 13
	s_lshl_b32 s10, s5, 12
	s_add_u32 s8, s22, 0x8000
	s_addc_u32 s9, s23, 0
	s_add_i32 m0, s35, 0x18000
	v_lshl_add_u64 v[10:11], s[8:9], 0, v[130:131]
	s_waitcnt vmcnt(2)
	s_barrier
	global_load_lds_dwordx4 v[10:11], off
	s_add_i32 m0, s35, 0x1a000
	v_lshl_add_u64 v[10:11], s[8:9], 0, v[132:133]
	s_add_u32 s8, s24, 0x8000
	s_addc_u32 s9, s25, 0
	s_add_i32 s41, s35, 0x8000
	global_load_lds_dwordx4 v[10:11], off
	s_mov_b32 m0, s41
	s_add_i32 s42, s35, 0xa000
	global_load_lds_dwordx4 v130, s[8:9]
	v_lshl_add_u64 v[10:11], s[8:9], 0, v[132:133]
	s_add_u32 s8, s22, 0xc000
	s_mov_b32 m0, s42
	s_addc_u32 s9, s23, 0
	global_load_lds_dwordx4 v[10:11], off
	s_add_i32 m0, s35, 0x1c000
	s_nop 0
	global_load_lds_dwordx4 v130, s[8:9]
	s_add_i32 m0, s35, 0x1e000
	v_and_b32_e32 v9, 15, v4
	global_load_lds_dwordx4 v132, s[8:9]
	v_lshrrev_b32_e32 v10, 1, v4
	v_and_b32_e32 v10, 24, v10
	v_lshlrev_b32_e32 v11, 1, v10
	v_lshl_or_b32 v146, s6, 6, v9
	v_lshl_or_b32 v11, v9, 6, v11
	v_cmp_lt_u32_e64 s[8:9], 7, v9
	v_mov_b32_e32 v9, 0xffff8040
	v_lshlrev_b32_e32 v4, 2, v4
	v_cndmask_b32_e64 v134, 0, v9, s[8:9]
	v_mov_b32_e32 v9, 0x8000
	v_cndmask_b32_e64 v136, v9, 64, s[8:9]
	v_lshlrev_b32_e32 v9, 10, v2
	v_and_b32_e32 v9, 0xfffff800, v9
	v_lshl_add_u32 v3, v3, 7, v9
	v_and_b32_e32 v2, 1, v2
	v_and_b32_e32 v4, 32, v4
	v_lshl_or_b32 v2, v2, 6, v3
	v_bitop3_b32 v147, v11, s10, v4 bitop3:0xde
	s_mov_b64 s[10:11], 0xc000
	v_lshl_add_u32 v2, v5, 1, v2
	v_mov_b32_e32 v3, v131
	v_lshl_add_u64 v[138:139], v[2:3], 0, s[10:11]
	v_lshlrev_b32_e32 v2, 10, v6
	v_and_b32_e32 v2, 0xfffff800, v2
	v_lshl_add_u32 v2, v7, 7, v2
	v_and_b32_e32 v3, 1, v6
	s_waitcnt vmcnt(6)
	v_lshl_or_b32 v2, v3, 6, v2
	v_bitop3_b32 v4, v11, s7, v4 bitop3:0xde
	s_cmpk_lt_u32 s4, 0x100
	v_lshl_add_u32 v2, v8, 1, v2
	v_mov_b32_e32 v3, v131
	s_cselect_b64 s[6:7], -1, 0
	v_cndmask_b32_e64 v135, 0, -1, s[8:9]
	v_mov_b32_e32 v137, v131
	v_lshl_or_b32 v148, s5, 6, v10
	v_lshl_add_u64 v[140:141], v[2:3], 0, s[10:11]
	s_mov_b64 s[4:5], -1
	s_movk_i32 s44, 0x80
	v_add_u32_e32 v149, s72, v147
	v_add_u32_e32 v150, s73, v147
	v_add_u32_e32 v151, 0, v4
	s_mov_b64 s[14:15], 0xb0000
	s_mov_b32 s45, s82
	s_mov_b32 s26, 0
	s_barrier
	s_branch .LBB0_1228

; #define PG8_STAGE(bufoff, gbase, voff) do { _Pragma("unroll") for (int _i = 0; _i < 2; ++_i) \
;         __builtin_amdgcn_global_load_lds((const unsigned*)((const char*)(gbase) + (voff)[_i]), (LAS unsigned*)(lds + (bufoff) + ldsw + _i * 8192), 16, 0, 0); } while (0)
; #define PG8_LDA(dst, b, h) do { _Pragma("unroll") for (int m = 0; m < 4; ++m) _Pragma("unroll") for (int k = 0; k < 2; ++k) dst[m][k] = *(const LAS bf16x8*)(lds + PG8_SA(b, h) + aoff + m * 2048 + k * 1024); } while (0)
; #define PG8_LDB(dst, b, h) do { _Pragma("unroll") for (int n = 0; n < 2; ++n) _Pragma("unroll") for (int k = 0; k < 2; ++k) dst[n][k] = *(const LAS bf16x8*)(lds + PG8_SB(b, h) + boff + n * 2048 + k * 1024); } while (0)
; #define PG8_MMA(ai, bj, At, Bt) do { __builtin_amdgcn_s_setprio(1); _Pragma("unroll") for (int m = 0; m < 4; ++m) _Pragma("unroll") for (int n = 0; n < 2; ++n) _Pragma("unroll") for (int k = 0; k < 2; ++k) \
;         acc[ai][bj][m][n] = __builtin_amdgcn_mfma_f32_16x16x32_bf16(Bt[n][k], At[m][k], acc[ai][bj][m][n], 0, 0, 0); __builtin_amdgcn_s_setprio(0); } while (0)
; #define PG8_WAIT_V(n) asm volatile("s_waitcnt vmcnt(" #n ")" ::: "memory")
; #define PG8_WAIT_L(n) asm volatile("s_waitcnt lgkmcnt(" #n ")" ::: "memory")
; #define PG8_BAR __builtin_amdgcn_s_barrier()
; #define PG8_SCHED __builtin_amdgcn_sched_barrier(0)
; template <class Epi, class Sched, bool ABLK = false, bool ALIGN_EPI = true, bool SP2 = true, bool BBLK = true>
; __device__ __forceinline__ void gemm_phase(LAS unsigned char* lds, const Gemm g, const Sched& S, const Epi& E) {
;     ...
;             const char* a1 = a_tile(uA, tbA + t + 1);
;             const char* a2 = last ? a_tile(nuA, ntbA) : a_tile(uA, tbA + t + 2); const char* b2 = last ? nB : cB + (size_t)(t + 2) * kstepB;
;             const char* a3 = last ? a_tile(nuA, ntbA + 1) : a_tile(uA, tbA + t + 3); const char* b3 = b2 + kstepB;
;             if (last && has_next) S.a_ready(nxt);
;             if constexpr (SP2) {
;             PG8_LDB(B0, 0, 0); PG8_LDB(B1, 0, 1); PG8_SCHED; PG8_LDA(At, 0, 0); PG8_STAGE(PG8_SA(1, 1), a1 + hstepA, voffA);
;             PG8_WAIT_V(8); PG8_WAIT_L(0); PG8_BAR; PG8_MMA(0, 0, At, B0); PG8_MMA(0, 1, At, B1); PG8_BAR; PG8_SCHED;
;             PG8_LDA(At, 0, 1); PG8_STAGE(PG8_SB(0, 0), b2, voffB); PG8_STAGE(PG8_SB(0, 1), b2 + hstepB, voffB); PG8_STAGE(PG8_SA(0, 0), a2, voffA);
.LBB0_1229:
	ds_read_b128 v[152:155], v149
	ds_read_b128 v[156:159], v149 offset:1024
	ds_read_b128 v[160:163], v149 offset:2048
	ds_read_b128 v[164:167], v149 offset:3072
	ds_read_b128 v[168:171], v150
	ds_read_b128 v[172:175], v150 offset:1024
	ds_read_b128 v[176:179], v150 offset:2048
	ds_read_b128 v[180:183], v150 offset:3072
	s_add_u32 s24, s51, s22
	s_addc_u32 s25, s55, s23
	s_add_u32 s28, s24, 0x10000
	s_addc_u32 s29, s25, 0
	s_add_i32 s57, s57, 2
	s_add_u32 s26, s49, s22
	s_addc_u32 s27, s50, s23
	s_add_u32 s24, s24, 0x18000
	s_addc_u32 s25, s25, 0
	s_cmp_eq_u32 s56, s22
	s_cselect_b32 s25, s48, s25
	s_cselect_b32 s24, s47, s24
	s_cselect_b32 s27, s4, s27
	s_cselect_b32 s26, s5, s26
	s_cselect_b32 s29, s46, s29
	s_cselect_b32 s28, s19, s28
	v_lshl_add_u64 v[216:217], v[142:143], 0, s[22:23]
	s_add_i32 m0, s35, 0xc000
	ds_read_b128 v[184:187], v151
	ds_read_b128 v[188:191], v151 offset:1024
	ds_read_b128 v[192:195], v151 offset:2048
	ds_read_b128 v[196:199], v151 offset:3072
	ds_read_b128 v[200:203], v151 offset:4096
	ds_read_b128 v[204:207], v151 offset:5120
	ds_read_b128 v[208:211], v151 offset:6144
	ds_read_b128 v[212:215], v151 offset:7168
	global_load_lds_dwordx4 v[216:217], off
	v_lshl_add_u64 v[216:217], v[144:145], 0, s[22:23]
	s_add_i32 m0, s35, 0xe000
	s_nop 0
	global_load_lds_dwordx4 v[216:217], off
	s_waitcnt vmcnt(8)
	s_waitcnt lgkmcnt(0)
	s_barrier
	s_setprio 1
	s_waitcnt lgkmcnt(0)
	v_mfma_f32_16x16x32_bf16 v[126:129], v[152:155], v[184:187], v[126:129]
	v_mfma_f32_16x16x32_bf16 v[122:125], v[160:163], v[184:187], v[122:125]
	v_mfma_f32_16x16x32_bf16 v[110:113], v[152:155], v[192:195], v[110:113]
	v_mfma_f32_16x16x32_bf16 v[106:109], v[160:163], v[192:195], v[106:109]
	v_mfma_f32_16x16x32_bf16 v[94:97], v[152:155], v[200:203], v[94:97]
	v_mfma_f32_16x16x32_bf16 v[90:93], v[160:163], v[200:203], v[90:93]
	v_mfma_f32_16x16x32_bf16 v[78:81], v[152:155], v[208:211], v[78:81]
	v_mfma_f32_16x16x32_bf16 v[74:77], v[160:163], v[208:211], v[74:77]
	v_mfma_f32_16x16x32_bf16 v[126:129], v[156:159], v[188:191], v[126:129]
	v_mfma_f32_16x16x32_bf16 v[122:125], v[164:167], v[188:191], v[122:125]
	v_mfma_f32_16x16x32_bf16 v[110:113], v[156:159], v[196:199], v[110:113]
	v_mfma_f32_16x16x32_bf16 v[106:109], v[164:167], v[196:199], v[106:109]
	v_mfma_f32_16x16x32_bf16 v[94:97], v[156:159], v[204:207], v[94:97]
	v_mfma_f32_16x16x32_bf16 v[90:93], v[164:167], v[204:207], v[90:93]
	v_mfma_f32_16x16x32_bf16 v[78:81], v[156:159], v[212:215], v[78:81]
	v_mfma_f32_16x16x32_bf16 v[74:77], v[164:167], v[212:215], v[74:77]
	s_setprio 0
	s_setprio 1
	v_mfma_f32_16x16x32_bf16 v[118:121], v[168:171], v[184:187], v[118:121]
	v_mfma_f32_16x16x32_bf16 v[114:117], v[176:179], v[184:187], v[114:117]
	v_mfma_f32_16x16x32_bf16 v[102:105], v[168:171], v[192:195], v[102:105]
	v_mfma_f32_16x16x32_bf16 v[98:101], v[176:179], v[192:195], v[98:101]
	v_mfma_f32_16x16x32_bf16 v[86:89], v[168:171], v[200:203], v[86:89]
	v_mfma_f32_16x16x32_bf16 v[82:85], v[176:179], v[200:203], v[82:85]
	v_mfma_f32_16x16x32_bf16 v[70:73], v[168:171], v[208:211], v[70:73]
	v_mfma_f32_16x16x32_bf16 v[66:69], v[176:179], v[208:211], v[66:69]
	v_mfma_f32_16x16x32_bf16 v[118:121], v[172:175], v[188:191], v[118:121]
	v_mfma_f32_16x16x32_bf16 v[114:117], v[180:183], v[188:191], v[114:117]
	v_mfma_f32_16x16x32_bf16 v[102:105], v[172:175], v[196:199], v[102:105]
	v_mfma_f32_16x16x32_bf16 v[98:101], v[180:183], v[196:199], v[98:101]
	v_mfma_f32_16x16x32_bf16 v[86:89], v[172:175], v[204:207], v[86:89]
	v_mfma_f32_16x16x32_bf16 v[82:85], v[180:183], v[204:207], v[82:85]
	v_mfma_f32_16x16x32_bf16 v[70:73], v[172:175], v[212:215], v[70:73]
	v_mfma_f32_16x16x32_bf16 v[66:69], v[180:183], v[212:215], v[66:69]
	s_setprio 0
	s_barrier
	s_add_i32 s59, s72, s34
	s_mov_b32 m0, s59
	ds_read_b128 v[184:187], v151 offset:16384
	ds_read_b128 v[188:191], v151 offset:17408
	ds_read_b128 v[192:195], v151 offset:18432
	ds_read_b128 v[196:199], v151 offset:19456
	ds_read_b128 v[200:203], v151 offset:20480
	ds_read_b128 v[204:207], v151 offset:21504
	ds_read_b128 v[208:211], v151 offset:22528
	ds_read_b128 v[212:215], v151 offset:23552
	global_load_lds_dwordx4 v130, s[26:27]
	s_add_i32 m0, s59, 0x2000
	s_add_u32 s64, s26, 0x4000
	s_addc_u32 s65, s27, 0
	s_add_i32 s59, s73, s34
	global_load_lds_dwordx4 v132, s[26:27]
	s_mov_b32 m0, s59
	s_nop 0
	global_load_lds_dwordx4 v130, s[64:65]
	s_add_i32 m0, s59, 0x2000
	s_nop 0
	global_load_lds_dwordx4 v132, s[64:65]
	s_mov_b32 m0, s35
	s_nop 0
	global_load_lds_dwordx4 v130, s[28:29]
	s_mov_b32 m0, s36
	s_nop 0
	global_load_lds_dwordx4 v132, s[28:29]
	s_waitcnt vmcnt(8)
	s_waitcnt lgkmcnt(0)
	s_barrier
; #define PG8_STAGE(bufoff, gbase, voff) do { _Pragma("unroll") for (int _i = 0; _i < 2; ++_i) \
;         __builtin_amdgcn_global_load_lds((const unsigned*)((const char*)(gbase) + (voff)[_i]), (LAS unsigned*)(lds + (bufoff) + ldsw + _i * 8192), 16, 0, 0); } while (0)
; #define PG8_LDA(dst, b, h) do { _Pragma("unroll") for (int m = 0; m < 4; ++m) _Pragma("unroll") for (int k = 0; k < 2; ++k) dst[m][k] = *(const LAS bf16x8*)(lds + PG8_SA(b, h) + aoff + m * 2048 + k * 1024); } while (0)
; #define PG8_LDB(dst, b, h) do { _Pragma("unroll") for (int n = 0; n < 2; ++n) _Pragma("unroll") for (int k = 0; k < 2; ++k) dst[n][k] = *(const LAS bf16x8*)(lds + PG8_SB(b, h) + boff + n * 2048 + k * 1024); } while (0)
; #define PG8_MMA(ai, bj, At, Bt) do { __builtin_amdgcn_s_setprio(1); _Pragma("unroll") for (int m = 0; m < 4; ++m) _Pragma("unroll") for (int n = 0; n < 2; ++n) _Pragma("unroll") for (int k = 0; k < 2; ++k) \
;         acc[ai][bj][m][n] = __builtin_amdgcn_mfma_f32_16x16x32_bf16(Bt[n][k], At[m][k], acc[ai][bj][m][n], 0, 0, 0); __builtin_amdgcn_s_setprio(0); } while (0)
; #define PG8_WAIT_V(n) asm volatile("s_waitcnt vmcnt(" #n ")" ::: "memory")
; #define PG8_WAIT_L(n) asm volatile("s_waitcnt lgkmcnt(" #n ")" ::: "memory")
; #define PG8_BAR __builtin_amdgcn_s_barrier()
; #define PG8_SCHED __builtin_amdgcn_sched_barrier(0)
; template <class Epi, class Sched, bool ABLK = false, bool ALIGN_EPI = true, bool SP2 = true, bool BBLK = true>
; __device__ __forceinline__ void gemm_phase(LAS unsigned char* lds, const Gemm g, const Sched& S, const Epi& E) {
;     ...
;             PG8_WAIT_V(8); PG8_WAIT_L(0); PG8_BAR; PG8_MMA(1, 0, At, B0); PG8_MMA(1, 1, At, B1); PG8_BAR; PG8_SCHED;
;             PG8_LDB(B0, 1, 0); PG8_LDB(B1, 1, 1); PG8_SCHED; PG8_LDA(At, 1, 0); PG8_STAGE(PG8_SA(0, 1), a2 + hstepA, voffA);
;             PG8_WAIT_V(8); PG8_WAIT_L(0); PG8_BAR; PG8_MMA(0, 0, At, B0); PG8_MMA(0, 1, At, B1); PG8_BAR; PG8_SCHED;
	s_setprio 1
	s_waitcnt lgkmcnt(0)
	v_mfma_f32_16x16x32_bf16 v[62:65], v[152:155], v[184:187], v[62:65]
	v_mfma_f32_16x16x32_bf16 v[58:61], v[160:163], v[184:187], v[58:61]
	v_mfma_f32_16x16x32_bf16 v[46:49], v[152:155], v[192:195], v[46:49]
	v_mfma_f32_16x16x32_bf16 v[42:45], v[160:163], v[192:195], v[42:45]
	v_mfma_f32_16x16x32_bf16 v[30:33], v[152:155], v[200:203], v[30:33]
	v_mfma_f32_16x16x32_bf16 v[26:29], v[160:163], v[200:203], v[26:29]
	v_mfma_f32_16x16x32_bf16 v[14:17], v[152:155], v[208:211], v[14:17]
	v_mfma_f32_16x16x32_bf16 v[10:13], v[160:163], v[208:211], v[10:13]
	v_mfma_f32_16x16x32_bf16 v[62:65], v[156:159], v[188:191], v[62:65]
	v_mfma_f32_16x16x32_bf16 v[58:61], v[164:167], v[188:191], v[58:61]
	v_mfma_f32_16x16x32_bf16 v[46:49], v[156:159], v[196:199], v[46:49]
	v_mfma_f32_16x16x32_bf16 v[42:45], v[164:167], v[196:199], v[42:45]
	v_mfma_f32_16x16x32_bf16 v[30:33], v[156:159], v[204:207], v[30:33]
	v_mfma_f32_16x16x32_bf16 v[26:29], v[164:167], v[204:207], v[26:29]
	v_mfma_f32_16x16x32_bf16 v[14:17], v[156:159], v[212:215], v[14:17]
	v_mfma_f32_16x16x32_bf16 v[10:13], v[164:167], v[212:215], v[10:13]
	s_setprio 0
	s_setprio 1
	v_mfma_f32_16x16x32_bf16 v[54:57], v[168:171], v[184:187], v[54:57]
	v_mfma_f32_16x16x32_bf16 v[50:53], v[176:179], v[184:187], v[50:53]
	v_mfma_f32_16x16x32_bf16 v[38:41], v[168:171], v[192:195], v[38:41]
	v_mfma_f32_16x16x32_bf16 v[34:37], v[176:179], v[192:195], v[34:37]
	v_mfma_f32_16x16x32_bf16 v[22:25], v[168:171], v[200:203], v[22:25]
	v_mfma_f32_16x16x32_bf16 v[18:21], v[176:179], v[200:203], v[18:21]
	v_mfma_f32_16x16x32_bf16 v[6:9], v[168:171], v[208:211], v[6:9]
	v_mfma_f32_16x16x32_bf16 v[2:5], v[176:179], v[208:211], v[2:5]
	v_mfma_f32_16x16x32_bf16 v[54:57], v[172:175], v[188:191], v[54:57]
	v_mfma_f32_16x16x32_bf16 v[50:53], v[180:183], v[188:191], v[50:53]
	v_mfma_f32_16x16x32_bf16 v[38:41], v[172:175], v[196:199], v[38:41]
	v_mfma_f32_16x16x32_bf16 v[34:37], v[180:183], v[196:199], v[34:37]
	v_mfma_f32_16x16x32_bf16 v[22:25], v[172:175], v[204:207], v[22:25]
	v_mfma_f32_16x16x32_bf16 v[18:21], v[180:183], v[204:207], v[18:21]
	v_mfma_f32_16x16x32_bf16 v[6:9], v[172:175], v[212:215], v[6:9]
	v_mfma_f32_16x16x32_bf16 v[2:5], v[180:183], v[212:215], v[2:5]
	s_setprio 0
	s_barrier
	v_add_u32_e32 v164, s60, v147
	v_add_u32_e32 v180, s61, v147
	ds_read_b128 v[152:155], v164
	ds_read_b128 v[156:159], v164 offset:1024
	ds_read_b128 v[160:163], v164 offset:2048
	ds_read_b128 v[164:167], v164 offset:3072
	ds_read_b128 v[168:171], v180
	ds_read_b128 v[172:175], v180 offset:1024
	ds_read_b128 v[176:179], v180 offset:2048
	ds_read_b128 v[180:183], v180 offset:3072
	s_add_u32 s28, s28, 0x4000
	s_addc_u32 s29, s29, 0
	s_mov_b32 m0, s37
	ds_read_b128 v[184:187], v151 offset:32768
	ds_read_b128 v[188:191], v151 offset:33792
	ds_read_b128 v[192:195], v151 offset:34816
	ds_read_b128 v[196:199], v151 offset:35840
	ds_read_b128 v[200:203], v151 offset:36864
	ds_read_b128 v[204:207], v151 offset:37888
	ds_read_b128 v[208:211], v151 offset:38912
	ds_read_b128 v[212:215], v151 offset:39936
	global_load_lds_dwordx4 v130, s[28:29]
	s_mov_b32 m0, s40
	s_nop 0
	global_load_lds_dwordx4 v132, s[28:29]
	s_waitcnt vmcnt(8)
	s_waitcnt lgkmcnt(0)
	s_barrier
	s_setprio 1
	s_waitcnt lgkmcnt(0)
	v_mfma_f32_16x16x32_bf16 v[126:129], v[152:155], v[184:187], v[126:129]
	v_mfma_f32_16x16x32_bf16 v[122:125], v[160:163], v[184:187], v[122:125]
	v_mfma_f32_16x16x32_bf16 v[110:113], v[152:155], v[192:195], v[110:113]
	v_mfma_f32_16x16x32_bf16 v[106:109], v[160:163], v[192:195], v[106:109]
	v_mfma_f32_16x16x32_bf16 v[94:97], v[152:155], v[200:203], v[94:97]
	v_mfma_f32_16x16x32_bf16 v[90:93], v[160:163], v[200:203], v[90:93]
	v_mfma_f32_16x16x32_bf16 v[78:81], v[152:155], v[208:211], v[78:81]
	v_mfma_f32_16x16x32_bf16 v[74:77], v[160:163], v[208:211], v[74:77]
	v_mfma_f32_16x16x32_bf16 v[126:129], v[156:159], v[188:191], v[126:129]
	v_mfma_f32_16x16x32_bf16 v[122:125], v[164:167], v[188:191], v[122:125]
	v_mfma_f32_16x16x32_bf16 v[110:113], v[156:159], v[196:199], v[110:113]
	v_mfma_f32_16x16x32_bf16 v[106:109], v[164:167], v[196:199], v[106:109]
	v_mfma_f32_16x16x32_bf16 v[94:97], v[156:159], v[204:207], v[94:97]
	v_mfma_f32_16x16x32_bf16 v[90:93], v[164:167], v[204:207], v[90:93]
	v_mfma_f32_16x16x32_bf16 v[78:81], v[156:159], v[212:215], v[78:81]
	v_mfma_f32_16x16x32_bf16 v[74:77], v[164:167], v[212:215], v[74:77]
	s_setprio 0
	s_setprio 1
	v_mfma_f32_16x16x32_bf16 v[118:121], v[168:171], v[184:187], v[118:121]
	v_mfma_f32_16x16x32_bf16 v[114:117], v[176:179], v[184:187], v[114:117]
	v_mfma_f32_16x16x32_bf16 v[102:105], v[168:171], v[192:195], v[102:105]
	v_mfma_f32_16x16x32_bf16 v[98:101], v[176:179], v[192:195], v[98:101]
	v_mfma_f32_16x16x32_bf16 v[86:89], v[168:171], v[200:203], v[86:89]
	v_mfma_f32_16x16x32_bf16 v[82:85], v[176:179], v[200:203], v[82:85]
	v_mfma_f32_16x16x32_bf16 v[70:73], v[168:171], v[208:211], v[70:73]
	v_mfma_f32_16x16x32_bf16 v[66:69], v[176:179], v[208:211], v[66:69]
	v_mfma_f32_16x16x32_bf16 v[118:121], v[172:175], v[188:191], v[118:121]
	v_mfma_f32_16x16x32_bf16 v[114:117], v[180:183], v[188:191], v[114:117]
	v_mfma_f32_16x16x32_bf16 v[102:105], v[172:175], v[196:199], v[102:105]
	v_mfma_f32_16x16x32_bf16 v[98:101], v[180:183], v[196:199], v[98:101]
	v_mfma_f32_16x16x32_bf16 v[86:89], v[172:175], v[204:207], v[86:89]
	v_mfma_f32_16x16x32_bf16 v[82:85], v[180:183], v[204:207], v[82:85]
	v_mfma_f32_16x16x32_bf16 v[70:73], v[172:175], v[212:215], v[70:73]
	v_mfma_f32_16x16x32_bf16 v[66:69], v[180:183], v[212:215], v[66:69]
	s_setprio 0
	s_barrier
; #define PG8_STAGE(bufoff, gbase, voff) do { _Pragma("unroll") for (int _i = 0; _i < 2; ++_i) \
;         __builtin_amdgcn_global_load_lds((const unsigned*)((const char*)(gbase) + (voff)[_i]), (LAS unsigned*)(lds + (bufoff) + ldsw + _i * 8192), 16, 0, 0); } while (0)
; #define PG8_LDA(dst, b, h) do { _Pragma("unroll") for (int m = 0; m < 4; ++m) _Pragma("unroll") for (int k = 0; k < 2; ++k) dst[m][k] = *(const LAS bf16x8*)(lds + PG8_SA(b, h) + aoff + m * 2048 + k * 1024); } while (0)
; #define PG8_MMA(ai, bj, At, Bt) do { __builtin_amdgcn_s_setprio(1); _Pragma("unroll") for (int m = 0; m < 4; ++m) _Pragma("unroll") for (int n = 0; n < 2; ++n) _Pragma("unroll") for (int k = 0; k < 2; ++k) \
;         acc[ai][bj][m][n] = __builtin_amdgcn_mfma_f32_16x16x32_bf16(Bt[n][k], At[m][k], acc[ai][bj][m][n], 0, 0, 0); __builtin_amdgcn_s_setprio(0); } while (0)
; #define PG8_WAIT_V(n) asm volatile("s_waitcnt vmcnt(" #n ")" ::: "memory")
; #define PG8_WAIT_L(n) asm volatile("s_waitcnt lgkmcnt(" #n ")" ::: "memory")
; #define PG8_BAR __builtin_amdgcn_s_barrier()
; #define PG8_SCHED __builtin_amdgcn_sched_barrier(0)
; template <class Epi, class Sched, bool ABLK = false, bool ALIGN_EPI = true, bool SP2 = true, bool BBLK = true>
; __device__ __forceinline__ void gemm_phase(LAS unsigned char* lds, const Gemm g, const Sched& S, const Epi& E) {
;     ...
;             PG8_LDA(At, 1, 1); PG8_STAGE(PG8_SB(1, 0), b3, voffB); PG8_STAGE(PG8_SB(1, 1), b3 + hstepB, voffB); PG8_STAGE(PG8_SA(1, 0), a3, voffA);
;             PG8_WAIT_V(8); PG8_WAIT_L(0); PG8_BAR; PG8_MMA(1, 0, At, B0); PG8_MMA(1, 1, At, B1); PG8_BAR; PG8_SCHED;
	s_add_u32 s28, s26, 0x8000
	s_addc_u32 s29, s27, 0
	s_add_i32 s59, s60, s34
	s_mov_b32 m0, s59
	ds_read_b128 v[184:187], v151 offset:49152
	ds_read_b128 v[188:191], v151 offset:50176
	ds_read_b128 v[192:195], v151 offset:51200
	ds_read_b128 v[196:199], v151 offset:52224
	ds_read_b128 v[200:203], v151 offset:53248
	ds_read_b128 v[204:207], v151 offset:54272
	ds_read_b128 v[208:211], v151 offset:55296
	ds_read_b128 v[212:215], v151 offset:56320
	global_load_lds_dwordx4 v130, s[28:29]
	s_add_i32 m0, s59, 0x2000
	s_add_u32 s26, s26, 0xc000
	v_lshl_add_u64 v[216:217], s[28:29], 0, v[132:133]
	s_addc_u32 s27, s27, 0
	s_add_i32 s28, s61, s34
	global_load_lds_dwordx4 v[216:217], off
	s_mov_b32 m0, s28
	s_nop 0
	global_load_lds_dwordx4 v130, s[26:27]
	s_add_i32 m0, s28, 0x2000
	s_nop 0
	global_load_lds_dwordx4 v132, s[26:27]
	s_mov_b32 m0, s41
	s_nop 0
	global_load_lds_dwordx4 v130, s[24:25]
	s_mov_b32 m0, s42
	s_nop 0
	global_load_lds_dwordx4 v132, s[24:25]
	s_waitcnt vmcnt(8)
	s_waitcnt lgkmcnt(0)
	s_barrier
	s_setprio 1
	s_waitcnt lgkmcnt(0)
	v_mfma_f32_16x16x32_bf16 v[62:65], v[152:155], v[184:187], v[62:65]
	v_mfma_f32_16x16x32_bf16 v[58:61], v[160:163], v[184:187], v[58:61]
	v_mfma_f32_16x16x32_bf16 v[46:49], v[152:155], v[192:195], v[46:49]
	v_mfma_f32_16x16x32_bf16 v[42:45], v[160:163], v[192:195], v[42:45]
	v_mfma_f32_16x16x32_bf16 v[30:33], v[152:155], v[200:203], v[30:33]
	v_mfma_f32_16x16x32_bf16 v[26:29], v[160:163], v[200:203], v[26:29]
	v_mfma_f32_16x16x32_bf16 v[14:17], v[152:155], v[208:211], v[14:17]
	v_mfma_f32_16x16x32_bf16 v[10:13], v[160:163], v[208:211], v[10:13]
	v_mfma_f32_16x16x32_bf16 v[62:65], v[156:159], v[188:191], v[62:65]
	v_mfma_f32_16x16x32_bf16 v[58:61], v[164:167], v[188:191], v[58:61]
	v_mfma_f32_16x16x32_bf16 v[46:49], v[156:159], v[196:199], v[46:49]
	v_mfma_f32_16x16x32_bf16 v[42:45], v[164:167], v[196:199], v[42:45]
	v_mfma_f32_16x16x32_bf16 v[30:33], v[156:159], v[204:207], v[30:33]
	v_mfma_f32_16x16x32_bf16 v[26:29], v[164:167], v[204:207], v[26:29]
	v_mfma_f32_16x16x32_bf16 v[14:17], v[156:159], v[212:215], v[14:17]
	v_mfma_f32_16x16x32_bf16 v[10:13], v[164:167], v[212:215], v[10:13]
	s_setprio 0
	s_setprio 1
	v_mfma_f32_16x16x32_bf16 v[54:57], v[168:171], v[184:187], v[54:57]
	v_mfma_f32_16x16x32_bf16 v[50:53], v[176:179], v[184:187], v[50:53]
	v_mfma_f32_16x16x32_bf16 v[38:41], v[168:171], v[192:195], v[38:41]
	v_mfma_f32_16x16x32_bf16 v[34:37], v[176:179], v[192:195], v[34:37]
	v_mfma_f32_16x16x32_bf16 v[22:25], v[168:171], v[200:203], v[22:25]
	v_mfma_f32_16x16x32_bf16 v[18:21], v[176:179], v[200:203], v[18:21]
	v_mfma_f32_16x16x32_bf16 v[6:9], v[168:171], v[208:211], v[6:9]
	v_mfma_f32_16x16x32_bf16 v[2:5], v[176:179], v[208:211], v[2:5]
	v_mfma_f32_16x16x32_bf16 v[54:57], v[172:175], v[188:191], v[54:57]
	v_mfma_f32_16x16x32_bf16 v[50:53], v[180:183], v[188:191], v[50:53]
	v_mfma_f32_16x16x32_bf16 v[38:41], v[172:175], v[196:199], v[38:41]
	v_mfma_f32_16x16x32_bf16 v[34:37], v[180:183], v[196:199], v[34:37]
	v_mfma_f32_16x16x32_bf16 v[22:25], v[172:175], v[204:207], v[22:25]
	v_mfma_f32_16x16x32_bf16 v[18:21], v[180:183], v[204:207], v[18:21]
	v_mfma_f32_16x16x32_bf16 v[6:9], v[172:175], v[212:215], v[6:9]
	v_mfma_f32_16x16x32_bf16 v[2:5], v[180:183], v[212:215], v[2:5]
	s_setprio 0
	s_barrier
	s_add_u32 s22, s22, 0x10000
	s_addc_u32 s23, s23, 0
	s_cmp_ge_u32 s57, s44
	s_cbranch_scc0 .LBB0_1229
	s_and_b64 vcc, exec, s[6:7]
	s_cbranch_vccz .LBB0_1232
	s_barrier

; #define PG8_STAGE(bufoff, gbase, voff) do { _Pragma("unroll") for (int _i = 0; _i < 2; ++_i) \
;         __builtin_amdgcn_global_load_lds((const unsigned*)((const char*)(gbase) + (voff)[_i]), (LAS unsigned*)(lds + (bufoff) + ldsw + _i * 8192), 16, 0, 0); } while (0)
; #define PG8_WAIT_V(n) asm volatile("s_waitcnt vmcnt(" #n ")" ::: "memory")
; #define PG8_BAR __builtin_amdgcn_s_barrier()
; template <class Epi, class Sched, bool ABLK = false, bool ALIGN_EPI = true, bool SP2 = true, bool BBLK = true>
; __device__ __forceinline__ void gemm_phase(LAS unsigned char* lds, const Gemm g, const Sched& S, const Epi& E) {
;     ...
;     const unsigned ldsw = (unsigned)wid * 1024u;
;     const int aoff = lds_byte(wr * 64 + fr, fq * 8), boff = lds_byte(wc * 32 + fr, fq * 8);
;     ...
;     if constexpr (SP2) {
;         PG8_STAGE(PG8_SB(0, 0), cB, voffB); PG8_STAGE(PG8_SB(0, 1), cB + hstepB, voffB); PG8_STAGE(PG8_SA(0, 0), cA, voffA); PG8_STAGE(PG8_SA(0, 1), cA + hstepA, voffA);
;         if (wr == 1) PG8_BAR;
;         PG8_WAIT_V(2); PG8_BAR;
;         PG8_STAGE(PG8_SB(1, 0), cB + kstepB, voffB); PG8_STAGE(PG8_SA(1, 0), a_tile(uA, tbA + 1), voffA); PG8_STAGE(PG8_SB(1, 1), cB + hstepB + kstepB, voffB);
;         PG8_WAIT_V(6); PG8_BAR;
.LBB0_1349:
	s_add_u32 s10, s68, 0x2fb20000
	s_addc_u32 s11, s69, 0
	s_and_b32 s14, s8, 3
	s_lshl_b32 s12, s5, 13
	s_lshl_b32 s13, s14, 12
	s_add_u32 s8, s40, 0x8000
	s_addc_u32 s9, s41, 0
	s_add_i32 m0, s31, 0x18000
	v_lshl_add_u64 v[14:15], s[8:9], 0, v[134:135]
	s_waitcnt vmcnt(2)
	s_barrier
	global_load_lds_dwordx4 v[14:15], off
	v_lshl_add_u64 v[14:15], s[8:9], 0, v[130:131]
	s_add_i32 m0, s31, 0x1a000
	s_mov_b64 s[8:9], 0x80
	s_add_i32 s54, s31, 0x8000
	s_add_i32 s55, s31, 0xa000
	global_load_lds_dwordx4 v[14:15], off
	v_lshl_add_u64 v[4:5], v[4:5], 0, s[8:9]
	s_mov_b32 m0, s54
	v_lshl_add_u64 v[2:3], v[2:3], 0, s[8:9]
	s_add_u32 s8, s40, 0xc000
	global_load_lds_dwordx4 v[4:5], off
	s_mov_b32 m0, s55
	s_addc_u32 s9, s41, 0
	global_load_lds_dwordx4 v[2:3], off
	s_add_i32 m0, s31, 0x1c000
	s_nop 0
	global_load_lds_dwordx4 v134, s[8:9]
	s_add_i32 m0, s31, 0x1e000
	v_lshlrev_b32_e32 v5, 2, v9
	global_load_lds_dwordx4 v130, s[8:9]
	v_lshrrev_b32_e32 v3, 1, v9
	v_and_b32_e32 v3, 24, v3
	v_and_b32_e32 v2, 15, v9
	v_lshlrev_b32_e32 v4, 1, v3
	v_lshl_or_b32 v160, s5, 6, v2
	v_lshl_or_b32 v4, v2, 6, v4
	v_cmp_lt_u32_e64 s[8:9], 7, v2
	v_mov_b32_e32 v2, 0xffff8040
	v_lshl_or_b32 v162, s14, 6, v3
	v_cndmask_b32_e64 v140, 0, v2, s[8:9]
	v_mov_b32_e32 v2, 0x8000
	v_cndmask_b32_e64 v142, v2, 64, s[8:9]
	v_lshlrev_b32_e32 v2, 15, v10
	v_and_b32_e32 v2, 0xffff0000, v2
	v_lshl_add_u32 v2, v11, 12, v2
	v_and_b32_e32 v3, 1, v10
	v_lshl_or_b32 v2, v3, 6, v2
	v_lshl_add_u32 v138, v12, 1, v2
	v_lshlrev_b32_e32 v2, 15, v6
	v_and_b32_e32 v2, 0xffff0000, v2
	v_lshl_add_u32 v2, v7, 12, v2
	v_and_b32_e32 v3, 1, v6
	v_and_b32_e32 v5, 32, v5
	s_waitcnt vmcnt(6)
	s_cmpk_lt_u32 s4, 0x100
	s_mov_b64 s[4:5], 0x80080
	v_lshl_or_b32 v2, v3, 6, v2
	v_bitop3_b32 v9, v4, s12, v5 bitop3:0xde
	v_bitop3_b32 v161, v4, s13, v5 bitop3:0xde
	v_lshl_add_u64 v[144:145], v[138:139], 0, s[4:5]
	v_lshl_add_u32 v138, v8, 1, v2
	s_cselect_b64 s[12:13], -1, 0
	v_cndmask_b32_e64 v141, 0, -1, s[8:9]
	v_mov_b32_e32 v143, v139
	v_lshl_add_u64 v[146:147], v[138:139], 0, s[4:5]
	v_add_u32_e32 v163, s72, v161
	v_add_u32_e32 v164, s73, v161
	v_add_u32_e32 v165, 0, v9
	s_mov_b64 s[14:15], 0x90000
	s_mov_b64 s[16:17], 0xa0000
	s_mov_b64 s[18:19], 0xb0000
	s_barrier
	s_branch .LBB0_1352

; #define PG8_STAGE(bufoff, gbase, voff) do { _Pragma("unroll") for (int _i = 0; _i < 2; ++_i) \
;         __builtin_amdgcn_global_load_lds((const unsigned*)((const char*)(gbase) + (voff)[_i]), (LAS unsigned*)(lds + (bufoff) + ldsw + _i * 8192), 16, 0, 0); } while (0)
; #define PG8_LDA(dst, b, h) do { _Pragma("unroll") for (int m = 0; m < 4; ++m) _Pragma("unroll") for (int k = 0; k < 2; ++k) dst[m][k] = *(const LAS bf16x8*)(lds + PG8_SA(b, h) + aoff + m * 2048 + k * 1024); } while (0)
; #define PG8_LDB(dst, b, h) do { _Pragma("unroll") for (int n = 0; n < 2; ++n) _Pragma("unroll") for (int k = 0; k < 2; ++k) dst[n][k] = *(const LAS bf16x8*)(lds + PG8_SB(b, h) + boff + n * 2048 + k * 1024); } while (0)
; #define PG8_MMA(ai, bj, At, Bt) do { __builtin_amdgcn_s_setprio(1); _Pragma("unroll") for (int m = 0; m < 4; ++m) _Pragma("unroll") for (int n = 0; n < 2; ++n) _Pragma("unroll") for (int k = 0; k < 2; ++k) \
;         acc[ai][bj][m][n] = __builtin_amdgcn_mfma_f32_16x16x32_bf16(Bt[n][k], At[m][k], acc[ai][bj][m][n], 0, 0, 0); __builtin_amdgcn_s_setprio(0); } while (0)
; #define PG8_WAIT_V(n) asm volatile("s_waitcnt vmcnt(" #n ")" ::: "memory")
; template <class Epi, class Sched, bool ABLK = false, bool ALIGN_EPI = true, bool SP2 = true, bool BBLK = true>
; __device__ __forceinline__ void gemm_phase(LAS unsigned char* lds, const Gemm g, const Sched& S, const Epi& E) {
;     ...
;         for (int t = 0; t < nt; t += 2) {
;             const bool last = (t == nt - 2);
;             const char* a1 = a_tile(uA, tbA + t + 1);
;             const char* a2 = last ? a_tile(nuA, ntbA) : a_tile(uA, tbA + t + 2); const char* b2 = last ? nB : cB + (size_t)(t + 2) * kstepB;
;             const char* a3 = last ? a_tile(nuA, ntbA + 1) : a_tile(uA, tbA + t + 3); const char* b3 = b2 + kstepB;
;             if (last && has_next) S.a_ready(nxt);
;             if constexpr (SP2) {
;             PG8_LDB(B0, 0, 0); PG8_LDB(B1, 0, 1); PG8_SCHED; PG8_LDA(At, 0, 0); PG8_STAGE(PG8_SA(1, 1), a1 + hstepA, voffA);
;             PG8_WAIT_V(8); PG8_WAIT_L(0); PG8_BAR; PG8_MMA(0, 0, At, B0); PG8_MMA(0, 1, At, B1); PG8_BAR; PG8_SCHED;
;             PG8_LDA(At, 0, 1); PG8_STAGE(PG8_SB(0, 0), b2, voffB); PG8_STAGE(PG8_SB(0, 1), b2 + hstepB, voffB); PG8_STAGE(PG8_SA(0, 0), a2, voffA);
;             PG8_WAIT_V(8); PG8_WAIT_L(0); PG8_BAR; PG8_MMA(1, 0, At, B0); PG8_MMA(1, 1, At, B1); PG8_BAR; PG8_SCHED;
.LBB0_1355:
	ds_read_b128 v[152:155], v163
	ds_read_b128 v[156:159], v163 offset:1024
	ds_read_b128 v[166:169], v163 offset:2048
	ds_read_b128 v[170:173], v163 offset:3072
	ds_read_b128 v[174:177], v164
	ds_read_b128 v[178:181], v164 offset:1024
	ds_read_b128 v[182:185], v164 offset:2048
	ds_read_b128 v[186:189], v164 offset:3072
	s_add_u32 s42, s36, s40
	s_addc_u32 s43, s37, s41
	s_add_u32 s46, s42, 0x100
	s_addc_u32 s47, s43, 0
	s_add_u32 s42, s42, 0x180
	s_addc_u32 s43, s43, 0
	s_cmpk_eq_i32 s40, 0xf00
	s_cselect_b32 s43, s57, s43
	s_cselect_b32 s42, s56, s42
	s_cselect_b32 s45, s21, s64
	s_cselect_b32 s44, s23, s59
	s_cselect_b32 s47, s4, s47
	s_cselect_b32 s46, s5, s46
	v_lshl_add_u64 v[222:223], v[148:149], 0, s[40:41]
	s_add_i32 m0, s31, 0xc000
	ds_read_b128 v[190:193], v165
	ds_read_b128 v[194:197], v165 offset:1024
	ds_read_b128 v[198:201], v165 offset:2048
	ds_read_b128 v[202:205], v165 offset:3072
	ds_read_b128 v[206:209], v165 offset:4096
	ds_read_b128 v[210:213], v165 offset:5120
	ds_read_b128 v[214:217], v165 offset:6144
	ds_read_b128 v[218:221], v165 offset:7168
	global_load_lds_dwordx4 v[222:223], off
	v_lshl_add_u64 v[222:223], v[150:151], 0, s[40:41]
	s_add_i32 m0, s31, 0xe000
	s_nop 0
	global_load_lds_dwordx4 v[222:223], off
	s_waitcnt vmcnt(8)
	s_waitcnt lgkmcnt(0)
	s_barrier
	s_setprio 1
	s_waitcnt lgkmcnt(0)
	v_mfma_f32_16x16x32_bf16 v[126:129], v[152:155], v[190:193], v[126:129]
	v_mfma_f32_16x16x32_bf16 v[122:125], v[166:169], v[190:193], v[122:125]
	v_mfma_f32_16x16x32_bf16 v[110:113], v[152:155], v[198:201], v[110:113]
	v_mfma_f32_16x16x32_bf16 v[106:109], v[166:169], v[198:201], v[106:109]
	v_mfma_f32_16x16x32_bf16 v[94:97], v[152:155], v[206:209], v[94:97]
	v_mfma_f32_16x16x32_bf16 v[90:93], v[166:169], v[206:209], v[90:93]
	v_mfma_f32_16x16x32_bf16 v[78:81], v[152:155], v[214:217], v[78:81]
	v_mfma_f32_16x16x32_bf16 v[74:77], v[166:169], v[214:217], v[74:77]
	v_mfma_f32_16x16x32_bf16 v[126:129], v[156:159], v[194:197], v[126:129]
	v_mfma_f32_16x16x32_bf16 v[122:125], v[170:173], v[194:197], v[122:125]
	v_mfma_f32_16x16x32_bf16 v[110:113], v[156:159], v[202:205], v[110:113]
	v_mfma_f32_16x16x32_bf16 v[106:109], v[170:173], v[202:205], v[106:109]
	v_mfma_f32_16x16x32_bf16 v[94:97], v[156:159], v[210:213], v[94:97]
	v_mfma_f32_16x16x32_bf16 v[90:93], v[170:173], v[210:213], v[90:93]
	v_mfma_f32_16x16x32_bf16 v[78:81], v[156:159], v[218:221], v[78:81]
	v_mfma_f32_16x16x32_bf16 v[74:77], v[170:173], v[218:221], v[74:77]
	s_setprio 0
	s_setprio 1
	v_mfma_f32_16x16x32_bf16 v[118:121], v[174:177], v[190:193], v[118:121]
	v_mfma_f32_16x16x32_bf16 v[114:117], v[182:185], v[190:193], v[114:117]
	v_mfma_f32_16x16x32_bf16 v[102:105], v[174:177], v[198:201], v[102:105]
	v_mfma_f32_16x16x32_bf16 v[98:101], v[182:185], v[198:201], v[98:101]
	v_mfma_f32_16x16x32_bf16 v[86:89], v[174:177], v[206:209], v[86:89]
	v_mfma_f32_16x16x32_bf16 v[82:85], v[182:185], v[206:209], v[82:85]
	v_mfma_f32_16x16x32_bf16 v[70:73], v[174:177], v[214:217], v[70:73]
	v_mfma_f32_16x16x32_bf16 v[66:69], v[182:185], v[214:217], v[66:69]
	v_mfma_f32_16x16x32_bf16 v[118:121], v[178:181], v[194:197], v[118:121]
	v_mfma_f32_16x16x32_bf16 v[114:117], v[186:189], v[194:197], v[114:117]
	v_mfma_f32_16x16x32_bf16 v[102:105], v[178:181], v[202:205], v[102:105]
	v_mfma_f32_16x16x32_bf16 v[98:101], v[186:189], v[202:205], v[98:101]
	v_mfma_f32_16x16x32_bf16 v[86:89], v[178:181], v[210:213], v[86:89]
	v_mfma_f32_16x16x32_bf16 v[82:85], v[186:189], v[210:213], v[82:85]
	v_mfma_f32_16x16x32_bf16 v[70:73], v[178:181], v[218:221], v[70:73]
	v_mfma_f32_16x16x32_bf16 v[66:69], v[186:189], v[218:221], v[66:69]
	s_setprio 0
	s_barrier
	s_add_i32 s66, s72, s49
	s_mov_b32 m0, s66
	ds_read_b128 v[190:193], v165 offset:16384
	ds_read_b128 v[194:197], v165 offset:17408
	ds_read_b128 v[198:201], v165 offset:18432
	ds_read_b128 v[202:205], v165 offset:19456
	ds_read_b128 v[206:209], v165 offset:20480
	ds_read_b128 v[210:213], v165 offset:21504
	ds_read_b128 v[214:217], v165 offset:22528
	ds_read_b128 v[218:221], v165 offset:23552
	global_load_lds_dwordx4 v134, s[44:45]
	s_add_i32 m0, s66, 0x2000
	s_add_u32 s66, s44, 0x4000
	s_addc_u32 s67, s45, 0
	s_add_i32 s75, s73, s49
	global_load_lds_dwordx4 v130, s[44:45]
	s_mov_b32 m0, s75
	s_nop 0
	global_load_lds_dwordx4 v134, s[66:67]
	s_add_i32 m0, s75, 0x2000
	s_nop 0
	global_load_lds_dwordx4 v130, s[66:67]
	s_mov_b32 m0, s31
	s_nop 0
	global_load_lds_dwordx4 v136, s[46:47]
	s_mov_b32 m0, s35
	s_nop 0
	global_load_lds_dwordx4 v132, s[46:47]
	s_waitcnt vmcnt(8)
	s_waitcnt lgkmcnt(0)
	s_barrier
; #define PG8_STAGE(bufoff, gbase, voff) do { _Pragma("unroll") for (int _i = 0; _i < 2; ++_i) \
;         __builtin_amdgcn_global_load_lds((const unsigned*)((const char*)(gbase) + (voff)[_i]), (LAS unsigned*)(lds + (bufoff) + ldsw + _i * 8192), 16, 0, 0); } while (0)
; #define PG8_LDA(dst, b, h) do { _Pragma("unroll") for (int m = 0; m < 4; ++m) _Pragma("unroll") for (int k = 0; k < 2; ++k) dst[m][k] = *(const LAS bf16x8*)(lds + PG8_SA(b, h) + aoff + m * 2048 + k * 1024); } while (0)
; #define PG8_LDB(dst, b, h) do { _Pragma("unroll") for (int n = 0; n < 2; ++n) _Pragma("unroll") for (int k = 0; k < 2; ++k) dst[n][k] = *(const LAS bf16x8*)(lds + PG8_SB(b, h) + boff + n * 2048 + k * 1024); } while (0)
; #define PG8_MMA(ai, bj, At, Bt) do { __builtin_amdgcn_s_setprio(1); _Pragma("unroll") for (int m = 0; m < 4; ++m) _Pragma("unroll") for (int n = 0; n < 2; ++n) _Pragma("unroll") for (int k = 0; k < 2; ++k) \
;         acc[ai][bj][m][n] = __builtin_amdgcn_mfma_f32_16x16x32_bf16(Bt[n][k], At[m][k], acc[ai][bj][m][n], 0, 0, 0); __builtin_amdgcn_s_setprio(0); } while (0)
; #define PG8_WAIT_V(n) asm volatile("s_waitcnt vmcnt(" #n ")" ::: "memory")
; #define PG8_WAIT_L(n) asm volatile("s_waitcnt lgkmcnt(" #n ")" ::: "memory")
; #define PG8_BAR __builtin_amdgcn_s_barrier()
; #define PG8_SCHED __builtin_amdgcn_sched_barrier(0)
; template <class Epi, class Sched, bool ABLK = false, bool ALIGN_EPI = true, bool SP2 = true, bool BBLK = true>
; __device__ __forceinline__ void gemm_phase(LAS unsigned char* lds, const Gemm g, const Sched& S, const Epi& E) {
;     ...
;             PG8_WAIT_V(8); PG8_WAIT_L(0); PG8_BAR; PG8_MMA(1, 0, At, B0); PG8_MMA(1, 1, At, B1); PG8_BAR; PG8_SCHED;
;             PG8_LDB(B0, 1, 0); PG8_LDB(B1, 1, 1); PG8_SCHED; PG8_LDA(At, 1, 0); PG8_STAGE(PG8_SA(0, 1), a2 + hstepA, voffA);
;             PG8_WAIT_V(8); PG8_WAIT_L(0); PG8_BAR; PG8_MMA(0, 0, At, B0); PG8_MMA(0, 1, At, B1); PG8_BAR; PG8_SCHED;
	s_setprio 1
	s_waitcnt lgkmcnt(0)
	v_mfma_f32_16x16x32_bf16 v[62:65], v[152:155], v[190:193], v[62:65]
	v_mfma_f32_16x16x32_bf16 v[58:61], v[166:169], v[190:193], v[58:61]
	v_mfma_f32_16x16x32_bf16 v[46:49], v[152:155], v[198:201], v[46:49]
	v_mfma_f32_16x16x32_bf16 v[42:45], v[166:169], v[198:201], v[42:45]
	v_mfma_f32_16x16x32_bf16 v[30:33], v[152:155], v[206:209], v[30:33]
	v_mfma_f32_16x16x32_bf16 v[26:29], v[166:169], v[206:209], v[26:29]
	v_mfma_f32_16x16x32_bf16 v[14:17], v[152:155], v[214:217], v[14:17]
	v_mfma_f32_16x16x32_bf16 v[10:13], v[166:169], v[214:217], v[10:13]
	v_mfma_f32_16x16x32_bf16 v[62:65], v[156:159], v[194:197], v[62:65]
	v_mfma_f32_16x16x32_bf16 v[58:61], v[170:173], v[194:197], v[58:61]
	v_mfma_f32_16x16x32_bf16 v[46:49], v[156:159], v[202:205], v[46:49]
	v_mfma_f32_16x16x32_bf16 v[42:45], v[170:173], v[202:205], v[42:45]
	v_mfma_f32_16x16x32_bf16 v[30:33], v[156:159], v[210:213], v[30:33]
	v_mfma_f32_16x16x32_bf16 v[26:29], v[170:173], v[210:213], v[26:29]
	v_mfma_f32_16x16x32_bf16 v[14:17], v[156:159], v[218:221], v[14:17]
	v_mfma_f32_16x16x32_bf16 v[10:13], v[170:173], v[218:221], v[10:13]
	s_setprio 0
	s_setprio 1
	v_mfma_f32_16x16x32_bf16 v[54:57], v[174:177], v[190:193], v[54:57]
	v_mfma_f32_16x16x32_bf16 v[50:53], v[182:185], v[190:193], v[50:53]
	v_mfma_f32_16x16x32_bf16 v[38:41], v[174:177], v[198:201], v[38:41]
	v_mfma_f32_16x16x32_bf16 v[34:37], v[182:185], v[198:201], v[34:37]
	v_mfma_f32_16x16x32_bf16 v[22:25], v[174:177], v[206:209], v[22:25]
	v_mfma_f32_16x16x32_bf16 v[18:21], v[182:185], v[206:209], v[18:21]
	v_mfma_f32_16x16x32_bf16 v[6:9], v[174:177], v[214:217], v[6:9]
	v_mfma_f32_16x16x32_bf16 v[2:5], v[182:185], v[214:217], v[2:5]
	v_mfma_f32_16x16x32_bf16 v[54:57], v[178:181], v[194:197], v[54:57]
	v_mfma_f32_16x16x32_bf16 v[50:53], v[186:189], v[194:197], v[50:53]
	v_mfma_f32_16x16x32_bf16 v[38:41], v[178:181], v[202:205], v[38:41]
	v_mfma_f32_16x16x32_bf16 v[34:37], v[186:189], v[202:205], v[34:37]
	v_mfma_f32_16x16x32_bf16 v[22:25], v[178:181], v[210:213], v[22:25]
	v_mfma_f32_16x16x32_bf16 v[18:21], v[186:189], v[210:213], v[18:21]
	v_mfma_f32_16x16x32_bf16 v[6:9], v[178:181], v[218:221], v[6:9]
	v_mfma_f32_16x16x32_bf16 v[2:5], v[186:189], v[218:221], v[2:5]
	s_setprio 0
	s_barrier
	v_add_u32_e32 v138, s60, v161
	ds_read_b128 v[152:155], v138
	ds_read_b128 v[156:159], v138 offset:1024
	ds_read_b128 v[166:169], v138 offset:2048
	ds_read_b128 v[170:173], v138 offset:3072
	v_add_u32_e32 v138, s61, v161
	ds_read_b128 v[174:177], v138
	ds_read_b128 v[178:181], v138 offset:1024
	ds_read_b128 v[182:185], v138 offset:2048
	ds_read_b128 v[186:189], v138 offset:3072
	s_add_u32 s46, s46, 0x80000
	s_addc_u32 s47, s47, 0
	s_mov_b32 m0, s50
	ds_read_b128 v[190:193], v165 offset:32768
	ds_read_b128 v[194:197], v165 offset:33792
	ds_read_b128 v[198:201], v165 offset:34816
	ds_read_b128 v[202:205], v165 offset:35840
	ds_read_b128 v[206:209], v165 offset:36864
	ds_read_b128 v[210:213], v165 offset:37888
	ds_read_b128 v[214:217], v165 offset:38912
	ds_read_b128 v[218:221], v165 offset:39936
	global_load_lds_dwordx4 v136, s[46:47]
	s_mov_b32 m0, s51
	s_nop 0
	global_load_lds_dwordx4 v132, s[46:47]
	s_waitcnt vmcnt(8)
	s_waitcnt lgkmcnt(0)
	s_barrier
	s_setprio 1
	s_waitcnt lgkmcnt(0)
	v_mfma_f32_16x16x32_bf16 v[126:129], v[152:155], v[190:193], v[126:129]
	v_mfma_f32_16x16x32_bf16 v[122:125], v[166:169], v[190:193], v[122:125]
	v_mfma_f32_16x16x32_bf16 v[110:113], v[152:155], v[198:201], v[110:113]
	v_mfma_f32_16x16x32_bf16 v[106:109], v[166:169], v[198:201], v[106:109]
	v_mfma_f32_16x16x32_bf16 v[94:97], v[152:155], v[206:209], v[94:97]
	v_mfma_f32_16x16x32_bf16 v[90:93], v[166:169], v[206:209], v[90:93]
	v_mfma_f32_16x16x32_bf16 v[78:81], v[152:155], v[214:217], v[78:81]
	v_mfma_f32_16x16x32_bf16 v[74:77], v[166:169], v[214:217], v[74:77]
	v_mfma_f32_16x16x32_bf16 v[126:129], v[156:159], v[194:197], v[126:129]
	v_mfma_f32_16x16x32_bf16 v[122:125], v[170:173], v[194:197], v[122:125]
	v_mfma_f32_16x16x32_bf16 v[110:113], v[156:159], v[202:205], v[110:113]
	v_mfma_f32_16x16x32_bf16 v[106:109], v[170:173], v[202:205], v[106:109]
	v_mfma_f32_16x16x32_bf16 v[94:97], v[156:159], v[210:213], v[94:97]
	v_mfma_f32_16x16x32_bf16 v[90:93], v[170:173], v[210:213], v[90:93]
	v_mfma_f32_16x16x32_bf16 v[78:81], v[156:159], v[218:221], v[78:81]
	v_mfma_f32_16x16x32_bf16 v[74:77], v[170:173], v[218:221], v[74:77]
	s_setprio 0
	s_setprio 1
	v_mfma_f32_16x16x32_bf16 v[118:121], v[174:177], v[190:193], v[118:121]
	v_mfma_f32_16x16x32_bf16 v[114:117], v[182:185], v[190:193], v[114:117]
	v_mfma_f32_16x16x32_bf16 v[102:105], v[174:177], v[198:201], v[102:105]
	v_mfma_f32_16x16x32_bf16 v[98:101], v[182:185], v[198:201], v[98:101]
	v_mfma_f32_16x16x32_bf16 v[86:89], v[174:177], v[206:209], v[86:89]
	v_mfma_f32_16x16x32_bf16 v[82:85], v[182:185], v[206:209], v[82:85]
	v_mfma_f32_16x16x32_bf16 v[70:73], v[174:177], v[214:217], v[70:73]
	v_mfma_f32_16x16x32_bf16 v[66:69], v[182:185], v[214:217], v[66:69]
	v_mfma_f32_16x16x32_bf16 v[118:121], v[178:181], v[194:197], v[118:121]
	v_mfma_f32_16x16x32_bf16 v[114:117], v[186:189], v[194:197], v[114:117]
	v_mfma_f32_16x16x32_bf16 v[102:105], v[178:181], v[202:205], v[102:105]
	v_mfma_f32_16x16x32_bf16 v[98:101], v[186:189], v[202:205], v[98:101]
	v_mfma_f32_16x16x32_bf16 v[86:89], v[178:181], v[210:213], v[86:89]
	v_mfma_f32_16x16x32_bf16 v[82:85], v[186:189], v[210:213], v[82:85]
	v_mfma_f32_16x16x32_bf16 v[70:73], v[178:181], v[218:221], v[70:73]
	v_mfma_f32_16x16x32_bf16 v[66:69], v[186:189], v[218:221], v[66:69]
	s_setprio 0
	s_barrier
; #define PG8_STAGE(bufoff, gbase, voff) do { _Pragma("unroll") for (int _i = 0; _i < 2; ++_i) \
;         __builtin_amdgcn_global_load_lds((const unsigned*)((const char*)(gbase) + (voff)[_i]), (LAS unsigned*)(lds + (bufoff) + ldsw + _i * 8192), 16, 0, 0); } while (0)
; #define PG8_LDA(dst, b, h) do { _Pragma("unroll") for (int m = 0; m < 4; ++m) _Pragma("unroll") for (int k = 0; k < 2; ++k) dst[m][k] = *(const LAS bf16x8*)(lds + PG8_SA(b, h) + aoff + m * 2048 + k * 1024); } while (0)
; #define PG8_MMA(ai, bj, At, Bt) do { __builtin_amdgcn_s_setprio(1); _Pragma("unroll") for (int m = 0; m < 4; ++m) _Pragma("unroll") for (int n = 0; n < 2; ++n) _Pragma("unroll") for (int k = 0; k < 2; ++k) \
;         acc[ai][bj][m][n] = __builtin_amdgcn_mfma_f32_16x16x32_bf16(Bt[n][k], At[m][k], acc[ai][bj][m][n], 0, 0, 0); __builtin_amdgcn_s_setprio(0); } while (0)
; #define PG8_WAIT_V(n) asm volatile("s_waitcnt vmcnt(" #n ")" ::: "memory")
; #define PG8_WAIT_L(n) asm volatile("s_waitcnt lgkmcnt(" #n ")" ::: "memory")
; #define PG8_BAR __builtin_amdgcn_s_barrier()
; #define PG8_SCHED __builtin_amdgcn_sched_barrier(0)
; template <class Epi, class Sched, bool ABLK = false, bool ALIGN_EPI = true, bool SP2 = true, bool BBLK = true>
; __device__ __forceinline__ void gemm_phase(LAS unsigned char* lds, const Gemm g, const Sched& S, const Epi& E) {
;     ...
;         for (int t = 0; t < nt; t += 2) {
;     ...
;             PG8_LDA(At, 1, 1); PG8_STAGE(PG8_SB(1, 0), b3, voffB); PG8_STAGE(PG8_SB(1, 1), b3 + hstepB, voffB); PG8_STAGE(PG8_SA(1, 0), a3, voffA);
;             PG8_WAIT_V(8); PG8_WAIT_L(0); PG8_BAR; PG8_MMA(1, 0, At, B0); PG8_MMA(1, 1, At, B1); PG8_BAR; PG8_SCHED;
	s_add_u32 s46, s44, 0x8000
	s_addc_u32 s47, s45, 0
	s_add_i32 s66, s60, s49
	s_mov_b32 m0, s66
	ds_read_b128 v[190:193], v165 offset:49152
	ds_read_b128 v[194:197], v165 offset:50176
	ds_read_b128 v[198:201], v165 offset:51200
	ds_read_b128 v[202:205], v165 offset:52224
	ds_read_b128 v[206:209], v165 offset:53248
	ds_read_b128 v[210:213], v165 offset:54272
	ds_read_b128 v[214:217], v165 offset:55296
	ds_read_b128 v[218:221], v165 offset:56320
	global_load_lds_dwordx4 v134, s[46:47]
	s_add_i32 m0, s66, 0x2000
	s_add_u32 s44, s44, 0xc000
	v_lshl_add_u64 v[222:223], s[46:47], 0, v[130:131]
	s_addc_u32 s45, s45, 0
	s_add_i32 s46, s61, s49
	global_load_lds_dwordx4 v[222:223], off
	s_mov_b32 m0, s46
	s_nop 0
	global_load_lds_dwordx4 v134, s[44:45]
	s_add_i32 m0, s46, 0x2000
	s_nop 0
	global_load_lds_dwordx4 v130, s[44:45]
	s_mov_b32 m0, s54
	s_nop 0
	global_load_lds_dwordx4 v136, s[42:43]
	s_mov_b32 m0, s55
	s_nop 0
	global_load_lds_dwordx4 v132, s[42:43]
	s_waitcnt vmcnt(8)
	s_waitcnt lgkmcnt(0)
	s_barrier
	s_setprio 1
	s_waitcnt lgkmcnt(0)
	v_mfma_f32_16x16x32_bf16 v[62:65], v[152:155], v[190:193], v[62:65]
	v_mfma_f32_16x16x32_bf16 v[58:61], v[166:169], v[190:193], v[58:61]
	v_mfma_f32_16x16x32_bf16 v[46:49], v[152:155], v[198:201], v[46:49]
	v_mfma_f32_16x16x32_bf16 v[42:45], v[166:169], v[198:201], v[42:45]
	v_mfma_f32_16x16x32_bf16 v[30:33], v[152:155], v[206:209], v[30:33]
	v_mfma_f32_16x16x32_bf16 v[26:29], v[166:169], v[206:209], v[26:29]
	v_mfma_f32_16x16x32_bf16 v[14:17], v[152:155], v[214:217], v[14:17]
	v_mfma_f32_16x16x32_bf16 v[10:13], v[166:169], v[214:217], v[10:13]
	v_mfma_f32_16x16x32_bf16 v[62:65], v[156:159], v[194:197], v[62:65]
	v_mfma_f32_16x16x32_bf16 v[58:61], v[170:173], v[194:197], v[58:61]
	v_mfma_f32_16x16x32_bf16 v[46:49], v[156:159], v[202:205], v[46:49]
	v_mfma_f32_16x16x32_bf16 v[42:45], v[170:173], v[202:205], v[42:45]
	v_mfma_f32_16x16x32_bf16 v[30:33], v[156:159], v[210:213], v[30:33]
	v_mfma_f32_16x16x32_bf16 v[26:29], v[170:173], v[210:213], v[26:29]
	v_mfma_f32_16x16x32_bf16 v[14:17], v[156:159], v[218:221], v[14:17]
	v_mfma_f32_16x16x32_bf16 v[10:13], v[170:173], v[218:221], v[10:13]
	s_setprio 0
	s_setprio 1
	v_mfma_f32_16x16x32_bf16 v[54:57], v[174:177], v[190:193], v[54:57]
	v_mfma_f32_16x16x32_bf16 v[50:53], v[182:185], v[190:193], v[50:53]
	v_mfma_f32_16x16x32_bf16 v[38:41], v[174:177], v[198:201], v[38:41]
	v_mfma_f32_16x16x32_bf16 v[34:37], v[182:185], v[198:201], v[34:37]
	v_mfma_f32_16x16x32_bf16 v[22:25], v[174:177], v[206:209], v[22:25]
	v_mfma_f32_16x16x32_bf16 v[18:21], v[182:185], v[206:209], v[18:21]
	v_mfma_f32_16x16x32_bf16 v[6:9], v[174:177], v[214:217], v[6:9]
	v_mfma_f32_16x16x32_bf16 v[2:5], v[182:185], v[214:217], v[2:5]
	v_mfma_f32_16x16x32_bf16 v[54:57], v[178:181], v[194:197], v[54:57]
	v_mfma_f32_16x16x32_bf16 v[50:53], v[186:189], v[194:197], v[50:53]
	v_mfma_f32_16x16x32_bf16 v[38:41], v[178:181], v[202:205], v[38:41]
	v_mfma_f32_16x16x32_bf16 v[34:37], v[186:189], v[202:205], v[34:37]
	v_mfma_f32_16x16x32_bf16 v[22:25], v[178:181], v[210:213], v[22:25]
	v_mfma_f32_16x16x32_bf16 v[18:21], v[186:189], v[210:213], v[18:21]
	v_mfma_f32_16x16x32_bf16 v[6:9], v[178:181], v[218:221], v[6:9]
	v_mfma_f32_16x16x32_bf16 v[2:5], v[186:189], v[218:221], v[2:5]
	s_setprio 0
	s_barrier
	s_add_i32 s65, s65, 2
	s_add_u32 s40, s40, 0x100
	s_addc_u32 s41, s41, 0
	s_add_u32 s59, s59, 0x10000
	s_addc_u32 s64, s64, 0
	s_cmp_gt_u32 s65, 29
	s_cbranch_scc0 .LBB0_1355
	s_and_b64 vcc, exec, s[12:13]
	s_cbranch_vccz .LBB0_1358
	s_barrier

; #define PG8_STAGE(bufoff, gbase, voff) do { _Pragma("unroll") for (int _i = 0; _i < 2; ++_i) \
;         __builtin_amdgcn_global_load_lds((const unsigned*)((const char*)(gbase) + (voff)[_i]), (LAS unsigned*)(lds + (bufoff) + ldsw + _i * 8192), 16, 0, 0); } while (0)
; #define PG8_WAIT_V(n) asm volatile("s_waitcnt vmcnt(" #n ")" ::: "memory")
; #define PG8_BAR __builtin_amdgcn_s_barrier()
; template <class Epi, class Sched, bool ABLK = false, bool ALIGN_EPI = true, bool SP2 = true, bool BBLK = true>
; __device__ __forceinline__ void gemm_phase(LAS unsigned char* lds, const Gemm g, const Sched& S, const Epi& E) {
;     ...
;     const unsigned ldsw = (unsigned)wid * 1024u;
;     const int aoff = lds_byte(wr * 64 + fr, fq * 8), boff = lds_byte(wc * 32 + fr, fq * 8);
;     ...
;     if constexpr (SP2) {
;         PG8_STAGE(PG8_SB(0, 0), cB, voffB); PG8_STAGE(PG8_SB(0, 1), cB + hstepB, voffB); PG8_STAGE(PG8_SA(0, 0), cA, voffA); PG8_STAGE(PG8_SA(0, 1), cA + hstepA, voffA);
;         if (wr == 1) PG8_BAR;
;         PG8_WAIT_V(2); PG8_BAR;
;         PG8_STAGE(PG8_SB(1, 0), cB + kstepB, voffB); PG8_STAGE(PG8_SA(1, 0), a_tile(uA, tbA + 1), voffA); PG8_STAGE(PG8_SB(1, 1), cB + hstepB + kstepB, voffB);
;         PG8_WAIT_V(6); PG8_BAR;
.LBB0_1712:
	s_and_b32 s5, s5, 3
	s_lshl_b32 s7, s6, 13
	s_lshl_b32 s10, s5, 12
	s_add_u32 s12, s68, 0x3c900000
	s_addc_u32 s13, s69, 0
	s_add_u32 s8, s26, 0x8000
	s_addc_u32 s9, s27, 0
	s_add_i32 m0, s40, 0x18000
	s_waitcnt vmcnt(0)
	v_lshl_add_u64 v[14:15], s[8:9], 0, v[132:133]
	s_waitcnt vmcnt(2)
	s_barrier
	global_load_lds_dwordx4 v[14:15], off
	v_lshl_add_u64 v[14:15], s[8:9], 0, v[136:137]
	s_add_i32 m0, s40, 0x1a000
	s_mov_b64 s[8:9], 0x80
	s_add_i32 s44, s40, 0x8000
	global_load_lds_dwordx4 v[14:15], off
	v_lshl_add_u64 v[2:3], v[2:3], 0, s[8:9]
	s_mov_b32 m0, s44
	s_add_i32 s45, s40, 0xa000
	global_load_lds_dwordx4 v[2:3], off
	v_lshl_add_u64 v[2:3], v[4:5], 0, s[8:9]
	s_add_u32 s8, s26, 0xc000
	s_mov_b32 m0, s45
	s_addc_u32 s9, s27, 0
	global_load_lds_dwordx4 v[2:3], off
	s_add_i32 m0, s40, 0x1c000
	s_nop 0
	global_load_lds_dwordx4 v132, s[8:9]
	s_add_i32 m0, s40, 0x1e000
	s_cmpk_lt_u32 s4, 0x100
	global_load_lds_dwordx4 v136, s[8:9]
	v_lshrrev_b32_e32 v3, 1, v7
	v_and_b32_e32 v3, 24, v3
	v_and_b32_e32 v2, 15, v7
	v_lshlrev_b32_e32 v4, 1, v3
	v_lshl_or_b32 v1, s6, 6, v2
	v_lshl_or_b32 v4, v2, 6, v4
	v_cmp_lt_u32_e64 s[8:9], 7, v2
	v_mov_b32_e32 v2, 0xffff8040
	v_lshl_or_b32 v151, s5, 6, v3
	v_cndmask_b32_e64 v138, 0, v2, s[8:9]
	v_mov_b32_e32 v2, 0x8000
	v_cndmask_b32_e64 v140, v2, 64, s[8:9]
	v_lshlrev_b32_e32 v2, 15, v6
	v_and_b32_e32 v2, 0xffff0000, v2
	v_lshl_add_u32 v2, v8, 12, v2
	v_and_b32_e32 v3, 1, v6
	v_lshl_or_b32 v2, v3, 6, v2
	v_lshl_add_u32 v2, v9, 1, v2
	v_mov_b32_e32 v3, v133
	s_mov_b64 s[4:5], 0x80080
	v_lshl_add_u64 v[142:143], v[2:3], 0, s[4:5]
	v_lshlrev_b32_e32 v2, 15, v10
	v_and_b32_e32 v2, 0xffff0000, v2
	v_lshlrev_b32_e32 v5, 2, v7
	v_lshl_add_u32 v2, v11, 12, v2
	v_and_b32_e32 v3, 1, v10
	v_and_b32_e32 v5, 32, v5
	s_waitcnt vmcnt(6)
	v_lshl_or_b32 v2, v3, 6, v2
	v_bitop3_b32 v150, v4, s10, v5 bitop3:0xde
	v_bitop3_b32 v4, v4, s7, v5 bitop3:0xde
	v_lshl_add_u32 v2, v12, 1, v2
	v_mov_b32_e32 v3, v133
	s_cselect_b64 s[6:7], -1, 0
	v_cndmask_b32_e64 v139, 0, -1, s[8:9]
	v_mov_b32_e32 v141, v133
	v_lshl_add_u64 v[144:145], v[2:3], 0, s[4:5]
	s_mov_b64 s[4:5], -1
	v_add_u32_e32 v152, s72, v150
	v_add_u32_e32 v153, s73, v150
	v_add_u32_e32 v154, 0, v4
	s_mov_b64 s[14:15], 0x90000
	s_mov_b64 s[16:17], 0xa0000
	s_mov_b64 s[18:19], 0xb0000
	s_mov_b32 s48, s82
	s_mov_b32 s30, 0
	s_barrier
	s_branch .LBB0_1715

; #define PG8_STAGE(bufoff, gbase, voff) do { _Pragma("unroll") for (int _i = 0; _i < 2; ++_i) \
;         __builtin_amdgcn_global_load_lds((const unsigned*)((const char*)(gbase) + (voff)[_i]), (LAS unsigned*)(lds + (bufoff) + ldsw + _i * 8192), 16, 0, 0); } while (0)
; #define PG8_LDA(dst, b, h) do { _Pragma("unroll") for (int m = 0; m < 4; ++m) _Pragma("unroll") for (int k = 0; k < 2; ++k) dst[m][k] = *(const LAS bf16x8*)(lds + PG8_SA(b, h) + aoff + m * 2048 + k * 1024); } while (0)
; #define PG8_LDB(dst, b, h) do { _Pragma("unroll") for (int n = 0; n < 2; ++n) _Pragma("unroll") for (int k = 0; k < 2; ++k) dst[n][k] = *(const LAS bf16x8*)(lds + PG8_SB(b, h) + boff + n * 2048 + k * 1024); } while (0)
; #define PG8_MMA(ai, bj, At, Bt) do { __builtin_amdgcn_s_setprio(1); _Pragma("unroll") for (int m = 0; m < 4; ++m) _Pragma("unroll") for (int n = 0; n < 2; ++n) _Pragma("unroll") for (int k = 0; k < 2; ++k) \
;         acc[ai][bj][m][n] = __builtin_amdgcn_mfma_f32_16x16x32_bf16(Bt[n][k], At[m][k], acc[ai][bj][m][n], 0, 0, 0); __builtin_amdgcn_s_setprio(0); } while (0)
; #define PG8_WAIT_V(n) asm volatile("s_waitcnt vmcnt(" #n ")" ::: "memory")
; template <class Epi, class Sched, bool ABLK = false, bool ALIGN_EPI = true, bool SP2 = true, bool BBLK = true>
; __device__ __forceinline__ void gemm_phase(LAS unsigned char* lds, const Gemm g, const Sched& S, const Epi& E) {
;     ...
;         for (int t = 0; t < nt; t += 2) {
;             const bool last = (t == nt - 2);
;             const char* a1 = a_tile(uA, tbA + t + 1);
;             const char* a2 = last ? a_tile(nuA, ntbA) : a_tile(uA, tbA + t + 2); const char* b2 = last ? nB : cB + (size_t)(t + 2) * kstepB;
;             const char* a3 = last ? a_tile(nuA, ntbA + 1) : a_tile(uA, tbA + t + 3); const char* b3 = b2 + kstepB;
;             if (last && has_next) S.a_ready(nxt);
;             if constexpr (SP2) {
;             PG8_LDB(B0, 0, 0); PG8_LDB(B1, 0, 1); PG8_SCHED; PG8_LDA(At, 0, 0); PG8_STAGE(PG8_SA(1, 1), a1 + hstepA, voffA);
;             PG8_WAIT_V(8); PG8_WAIT_L(0); PG8_BAR; PG8_MMA(0, 0, At, B0); PG8_MMA(0, 1, At, B1); PG8_BAR; PG8_SCHED;
;             PG8_LDA(At, 0, 1); PG8_STAGE(PG8_SB(0, 0), b2, voffB); PG8_STAGE(PG8_SB(0, 1), b2 + hstepB, voffB); PG8_STAGE(PG8_SA(0, 0), a2, voffA);
;             PG8_WAIT_V(8); PG8_WAIT_L(0); PG8_BAR; PG8_MMA(1, 0, At, B0); PG8_MMA(1, 1, At, B1); PG8_BAR; PG8_SCHED;
.LBB0_1716:
	ds_read_b128 v[156:159], v152
	ds_read_b128 v[160:163], v152 offset:1024
	ds_read_b128 v[164:167], v152 offset:2048
	ds_read_b128 v[168:171], v152 offset:3072
	ds_read_b128 v[172:175], v153
	ds_read_b128 v[176:179], v153 offset:1024
	ds_read_b128 v[180:183], v153 offset:2048
	ds_read_b128 v[184:187], v153 offset:3072
	s_add_u32 s28, s54, s26
	s_addc_u32 s29, s55, s27
	s_add_u32 s34, s28, 0x100
	s_addc_u32 s35, s29, 0
	s_add_i32 s57, s57, 2
	s_add_u32 s28, s28, 0x180
	s_addc_u32 s29, s29, 0
	s_cmp_eq_u32 s56, s26
	s_cselect_b32 s29, s51, s29
	s_cselect_b32 s28, s50, s28
	s_cselect_b32 s31, s4, s53
	s_cselect_b32 s30, s5, s52
	s_cselect_b32 s35, s49, s35
	s_cselect_b32 s34, s23, s34
	v_lshl_add_u64 v[220:221], v[146:147], 0, s[26:27]
	s_add_i32 m0, s40, 0xc000
	ds_read_b128 v[188:191], v154
	ds_read_b128 v[192:195], v154 offset:1024
	ds_read_b128 v[196:199], v154 offset:2048
	ds_read_b128 v[200:203], v154 offset:3072
	ds_read_b128 v[204:207], v154 offset:4096
	ds_read_b128 v[208:211], v154 offset:5120
	ds_read_b128 v[212:215], v154 offset:6144
	ds_read_b128 v[216:219], v154 offset:7168
	global_load_lds_dwordx4 v[220:221], off
	v_lshl_add_u64 v[220:221], v[148:149], 0, s[26:27]
	s_add_i32 m0, s40, 0xe000
	s_nop 0
	global_load_lds_dwordx4 v[220:221], off
	s_waitcnt vmcnt(8)
	s_waitcnt lgkmcnt(0)
	s_barrier
	s_setprio 1
	s_waitcnt lgkmcnt(0)
	v_mfma_f32_16x16x32_bf16 v[126:129], v[156:159], v[188:191], v[126:129]
	v_mfma_f32_16x16x32_bf16 v[122:125], v[164:167], v[188:191], v[122:125]
	v_mfma_f32_16x16x32_bf16 v[110:113], v[156:159], v[196:199], v[110:113]
	v_mfma_f32_16x16x32_bf16 v[106:109], v[164:167], v[196:199], v[106:109]
	v_mfma_f32_16x16x32_bf16 v[94:97], v[156:159], v[204:207], v[94:97]
	v_mfma_f32_16x16x32_bf16 v[90:93], v[164:167], v[204:207], v[90:93]
	v_mfma_f32_16x16x32_bf16 v[78:81], v[156:159], v[212:215], v[78:81]
	v_mfma_f32_16x16x32_bf16 v[74:77], v[164:167], v[212:215], v[74:77]
	v_mfma_f32_16x16x32_bf16 v[126:129], v[160:163], v[192:195], v[126:129]
	v_mfma_f32_16x16x32_bf16 v[122:125], v[168:171], v[192:195], v[122:125]
	v_mfma_f32_16x16x32_bf16 v[110:113], v[160:163], v[200:203], v[110:113]
	v_mfma_f32_16x16x32_bf16 v[106:109], v[168:171], v[200:203], v[106:109]
	v_mfma_f32_16x16x32_bf16 v[94:97], v[160:163], v[208:211], v[94:97]
	v_mfma_f32_16x16x32_bf16 v[90:93], v[168:171], v[208:211], v[90:93]
	v_mfma_f32_16x16x32_bf16 v[78:81], v[160:163], v[216:219], v[78:81]
	v_mfma_f32_16x16x32_bf16 v[74:77], v[168:171], v[216:219], v[74:77]
	s_setprio 0
	s_setprio 1
	v_mfma_f32_16x16x32_bf16 v[118:121], v[172:175], v[188:191], v[118:121]
	v_mfma_f32_16x16x32_bf16 v[114:117], v[180:183], v[188:191], v[114:117]
	v_mfma_f32_16x16x32_bf16 v[102:105], v[172:175], v[196:199], v[102:105]
	v_mfma_f32_16x16x32_bf16 v[98:101], v[180:183], v[196:199], v[98:101]
	v_mfma_f32_16x16x32_bf16 v[86:89], v[172:175], v[204:207], v[86:89]
	v_mfma_f32_16x16x32_bf16 v[82:85], v[180:183], v[204:207], v[82:85]
	v_mfma_f32_16x16x32_bf16 v[70:73], v[172:175], v[212:215], v[70:73]
	v_mfma_f32_16x16x32_bf16 v[66:69], v[180:183], v[212:215], v[66:69]
	v_mfma_f32_16x16x32_bf16 v[118:121], v[176:179], v[192:195], v[118:121]
	v_mfma_f32_16x16x32_bf16 v[114:117], v[184:187], v[192:195], v[114:117]
	v_mfma_f32_16x16x32_bf16 v[102:105], v[176:179], v[200:203], v[102:105]
	v_mfma_f32_16x16x32_bf16 v[98:101], v[184:187], v[200:203], v[98:101]
	v_mfma_f32_16x16x32_bf16 v[86:89], v[176:179], v[208:211], v[86:89]
	v_mfma_f32_16x16x32_bf16 v[82:85], v[184:187], v[208:211], v[82:85]
	v_mfma_f32_16x16x32_bf16 v[70:73], v[176:179], v[216:219], v[70:73]
	v_mfma_f32_16x16x32_bf16 v[66:69], v[184:187], v[216:219], v[66:69]
	s_setprio 0
	s_barrier
	s_add_i32 s58, s72, s39
	s_mov_b32 m0, s58
	ds_read_b128 v[188:191], v154 offset:16384
	ds_read_b128 v[192:195], v154 offset:17408
	ds_read_b128 v[196:199], v154 offset:18432
	ds_read_b128 v[200:203], v154 offset:19456
	ds_read_b128 v[204:207], v154 offset:20480
	ds_read_b128 v[208:211], v154 offset:21504
	ds_read_b128 v[212:215], v154 offset:22528
	ds_read_b128 v[216:219], v154 offset:23552
	global_load_lds_dwordx4 v132, s[30:31]
	s_add_i32 m0, s58, 0x2000
	s_add_u32 s58, s30, 0x4000
	s_addc_u32 s59, s31, 0
	s_add_i32 s64, s73, s39
	global_load_lds_dwordx4 v136, s[30:31]
	s_mov_b32 m0, s64
	s_nop 0
	global_load_lds_dwordx4 v132, s[58:59]
	s_add_i32 m0, s64, 0x2000
	s_nop 0
	global_load_lds_dwordx4 v136, s[58:59]
	s_mov_b32 m0, s40
	s_nop 0
	global_load_lds_dwordx4 v130, s[34:35]
	s_mov_b32 m0, s41
	s_nop 0
	global_load_lds_dwordx4 v134, s[34:35]
	s_waitcnt vmcnt(8)
	s_waitcnt lgkmcnt(0)
	s_barrier
; #define PG8_STAGE(bufoff, gbase, voff) do { _Pragma("unroll") for (int _i = 0; _i < 2; ++_i) \
;         __builtin_amdgcn_global_load_lds((const unsigned*)((const char*)(gbase) + (voff)[_i]), (LAS unsigned*)(lds + (bufoff) + ldsw + _i * 8192), 16, 0, 0); } while (0)
; #define PG8_LDA(dst, b, h) do { _Pragma("unroll") for (int m = 0; m < 4; ++m) _Pragma("unroll") for (int k = 0; k < 2; ++k) dst[m][k] = *(const LAS bf16x8*)(lds + PG8_SA(b, h) + aoff + m * 2048 + k * 1024); } while (0)
; #define PG8_LDB(dst, b, h) do { _Pragma("unroll") for (int n = 0; n < 2; ++n) _Pragma("unroll") for (int k = 0; k < 2; ++k) dst[n][k] = *(const LAS bf16x8*)(lds + PG8_SB(b, h) + boff + n * 2048 + k * 1024); } while (0)
; #define PG8_MMA(ai, bj, At, Bt) do { __builtin_amdgcn_s_setprio(1); _Pragma("unroll") for (int m = 0; m < 4; ++m) _Pragma("unroll") for (int n = 0; n < 2; ++n) _Pragma("unroll") for (int k = 0; k < 2; ++k) \
;         acc[ai][bj][m][n] = __builtin_amdgcn_mfma_f32_16x16x32_bf16(Bt[n][k], At[m][k], acc[ai][bj][m][n], 0, 0, 0); __builtin_amdgcn_s_setprio(0); } while (0)
; #define PG8_WAIT_V(n) asm volatile("s_waitcnt vmcnt(" #n ")" ::: "memory")
; #define PG8_WAIT_L(n) asm volatile("s_waitcnt lgkmcnt(" #n ")" ::: "memory")
; #define PG8_BAR __builtin_amdgcn_s_barrier()
; #define PG8_SCHED __builtin_amdgcn_sched_barrier(0)
; template <class Epi, class Sched, bool ABLK = false, bool ALIGN_EPI = true, bool SP2 = true, bool BBLK = true>
; __device__ __forceinline__ void gemm_phase(LAS unsigned char* lds, const Gemm g, const Sched& S, const Epi& E) {
;     ...
;             PG8_WAIT_V(8); PG8_WAIT_L(0); PG8_BAR; PG8_MMA(1, 0, At, B0); PG8_MMA(1, 1, At, B1); PG8_BAR; PG8_SCHED;
;             PG8_LDB(B0, 1, 0); PG8_LDB(B1, 1, 1); PG8_SCHED; PG8_LDA(At, 1, 0); PG8_STAGE(PG8_SA(0, 1), a2 + hstepA, voffA);
;             PG8_WAIT_V(8); PG8_WAIT_L(0); PG8_BAR; PG8_MMA(0, 0, At, B0); PG8_MMA(0, 1, At, B1); PG8_BAR; PG8_SCHED;
	s_setprio 1
	s_waitcnt lgkmcnt(0)
	v_mfma_f32_16x16x32_bf16 v[62:65], v[156:159], v[188:191], v[62:65]
	v_mfma_f32_16x16x32_bf16 v[58:61], v[164:167], v[188:191], v[58:61]
	v_mfma_f32_16x16x32_bf16 v[46:49], v[156:159], v[196:199], v[46:49]
	v_mfma_f32_16x16x32_bf16 v[42:45], v[164:167], v[196:199], v[42:45]
	v_mfma_f32_16x16x32_bf16 v[30:33], v[156:159], v[204:207], v[30:33]
	v_mfma_f32_16x16x32_bf16 v[26:29], v[164:167], v[204:207], v[26:29]
	v_mfma_f32_16x16x32_bf16 v[14:17], v[156:159], v[212:215], v[14:17]
	v_mfma_f32_16x16x32_bf16 v[10:13], v[164:167], v[212:215], v[10:13]
	v_mfma_f32_16x16x32_bf16 v[62:65], v[160:163], v[192:195], v[62:65]
	v_mfma_f32_16x16x32_bf16 v[58:61], v[168:171], v[192:195], v[58:61]
	v_mfma_f32_16x16x32_bf16 v[46:49], v[160:163], v[200:203], v[46:49]
	v_mfma_f32_16x16x32_bf16 v[42:45], v[168:171], v[200:203], v[42:45]
	v_mfma_f32_16x16x32_bf16 v[30:33], v[160:163], v[208:211], v[30:33]
	v_mfma_f32_16x16x32_bf16 v[26:29], v[168:171], v[208:211], v[26:29]
	v_mfma_f32_16x16x32_bf16 v[14:17], v[160:163], v[216:219], v[14:17]
	v_mfma_f32_16x16x32_bf16 v[10:13], v[168:171], v[216:219], v[10:13]
	s_setprio 0
	s_setprio 1
	v_mfma_f32_16x16x32_bf16 v[54:57], v[172:175], v[188:191], v[54:57]
	v_mfma_f32_16x16x32_bf16 v[50:53], v[180:183], v[188:191], v[50:53]
	v_mfma_f32_16x16x32_bf16 v[38:41], v[172:175], v[196:199], v[38:41]
	v_mfma_f32_16x16x32_bf16 v[34:37], v[180:183], v[196:199], v[34:37]
	v_mfma_f32_16x16x32_bf16 v[22:25], v[172:175], v[204:207], v[22:25]
	v_mfma_f32_16x16x32_bf16 v[18:21], v[180:183], v[204:207], v[18:21]
	v_mfma_f32_16x16x32_bf16 v[6:9], v[172:175], v[212:215], v[6:9]
	v_mfma_f32_16x16x32_bf16 v[2:5], v[180:183], v[212:215], v[2:5]
	v_mfma_f32_16x16x32_bf16 v[54:57], v[176:179], v[192:195], v[54:57]
	v_mfma_f32_16x16x32_bf16 v[50:53], v[184:187], v[192:195], v[50:53]
	v_mfma_f32_16x16x32_bf16 v[38:41], v[176:179], v[200:203], v[38:41]
	v_mfma_f32_16x16x32_bf16 v[34:37], v[184:187], v[200:203], v[34:37]
	v_mfma_f32_16x16x32_bf16 v[22:25], v[176:179], v[208:211], v[22:25]
	v_mfma_f32_16x16x32_bf16 v[18:21], v[184:187], v[208:211], v[18:21]
	v_mfma_f32_16x16x32_bf16 v[6:9], v[176:179], v[216:219], v[6:9]
	v_mfma_f32_16x16x32_bf16 v[2:5], v[184:187], v[216:219], v[2:5]
	s_setprio 0
	s_barrier
	v_add_u32_e32 v155, s60, v150
	ds_read_b128 v[156:159], v155
	ds_read_b128 v[160:163], v155 offset:1024
	ds_read_b128 v[164:167], v155 offset:2048
	ds_read_b128 v[168:171], v155 offset:3072
	v_add_u32_e32 v155, s61, v150
	ds_read_b128 v[172:175], v155
	ds_read_b128 v[176:179], v155 offset:1024
	ds_read_b128 v[180:183], v155 offset:2048
	ds_read_b128 v[184:187], v155 offset:3072
	s_add_u32 s34, s34, 0x80000
	s_addc_u32 s35, s35, 0
	s_mov_b32 m0, s42
	ds_read_b128 v[188:191], v154 offset:32768
	ds_read_b128 v[192:195], v154 offset:33792
	ds_read_b128 v[196:199], v154 offset:34816
	ds_read_b128 v[200:203], v154 offset:35840
	ds_read_b128 v[204:207], v154 offset:36864
	ds_read_b128 v[208:211], v154 offset:37888
	ds_read_b128 v[212:215], v154 offset:38912
	ds_read_b128 v[216:219], v154 offset:39936
	global_load_lds_dwordx4 v130, s[34:35]
	s_mov_b32 m0, s43
	s_nop 0
	global_load_lds_dwordx4 v134, s[34:35]
	s_waitcnt vmcnt(8)
	s_waitcnt lgkmcnt(0)
	s_barrier
	s_setprio 1
	s_waitcnt lgkmcnt(0)
	v_mfma_f32_16x16x32_bf16 v[126:129], v[156:159], v[188:191], v[126:129]
	v_mfma_f32_16x16x32_bf16 v[122:125], v[164:167], v[188:191], v[122:125]
	v_mfma_f32_16x16x32_bf16 v[110:113], v[156:159], v[196:199], v[110:113]
	v_mfma_f32_16x16x32_bf16 v[106:109], v[164:167], v[196:199], v[106:109]
	v_mfma_f32_16x16x32_bf16 v[94:97], v[156:159], v[204:207], v[94:97]
	v_mfma_f32_16x16x32_bf16 v[90:93], v[164:167], v[204:207], v[90:93]
	v_mfma_f32_16x16x32_bf16 v[78:81], v[156:159], v[212:215], v[78:81]
	v_mfma_f32_16x16x32_bf16 v[74:77], v[164:167], v[212:215], v[74:77]
	v_mfma_f32_16x16x32_bf16 v[126:129], v[160:163], v[192:195], v[126:129]
	v_mfma_f32_16x16x32_bf16 v[122:125], v[168:171], v[192:195], v[122:125]
	v_mfma_f32_16x16x32_bf16 v[110:113], v[160:163], v[200:203], v[110:113]
	v_mfma_f32_16x16x32_bf16 v[106:109], v[168:171], v[200:203], v[106:109]
	v_mfma_f32_16x16x32_bf16 v[94:97], v[160:163], v[208:211], v[94:97]
	v_mfma_f32_16x16x32_bf16 v[90:93], v[168:171], v[208:211], v[90:93]
	v_mfma_f32_16x16x32_bf16 v[78:81], v[160:163], v[216:219], v[78:81]
	v_mfma_f32_16x16x32_bf16 v[74:77], v[168:171], v[216:219], v[74:77]
	s_setprio 0
	s_setprio 1
	v_mfma_f32_16x16x32_bf16 v[118:121], v[172:175], v[188:191], v[118:121]
	v_mfma_f32_16x16x32_bf16 v[114:117], v[180:183], v[188:191], v[114:117]
	v_mfma_f32_16x16x32_bf16 v[102:105], v[172:175], v[196:199], v[102:105]
	v_mfma_f32_16x16x32_bf16 v[98:101], v[180:183], v[196:199], v[98:101]
	v_mfma_f32_16x16x32_bf16 v[86:89], v[172:175], v[204:207], v[86:89]
	v_mfma_f32_16x16x32_bf16 v[82:85], v[180:183], v[204:207], v[82:85]
	v_mfma_f32_16x16x32_bf16 v[70:73], v[172:175], v[212:215], v[70:73]
	v_mfma_f32_16x16x32_bf16 v[66:69], v[180:183], v[212:215], v[66:69]
	v_mfma_f32_16x16x32_bf16 v[118:121], v[176:179], v[192:195], v[118:121]
	v_mfma_f32_16x16x32_bf16 v[114:117], v[184:187], v[192:195], v[114:117]
	v_mfma_f32_16x16x32_bf16 v[102:105], v[176:179], v[200:203], v[102:105]
	v_mfma_f32_16x16x32_bf16 v[98:101], v[184:187], v[200:203], v[98:101]
	v_mfma_f32_16x16x32_bf16 v[86:89], v[176:179], v[208:211], v[86:89]
	v_mfma_f32_16x16x32_bf16 v[82:85], v[184:187], v[208:211], v[82:85]
	v_mfma_f32_16x16x32_bf16 v[70:73], v[176:179], v[216:219], v[70:73]
	v_mfma_f32_16x16x32_bf16 v[66:69], v[184:187], v[216:219], v[66:69]
	s_setprio 0
	s_barrier
; #define PG8_STAGE(bufoff, gbase, voff) do { _Pragma("unroll") for (int _i = 0; _i < 2; ++_i) \
;         __builtin_amdgcn_global_load_lds((const unsigned*)((const char*)(gbase) + (voff)[_i]), (LAS unsigned*)(lds + (bufoff) + ldsw + _i * 8192), 16, 0, 0); } while (0)
; #define PG8_LDA(dst, b, h) do { _Pragma("unroll") for (int m = 0; m < 4; ++m) _Pragma("unroll") for (int k = 0; k < 2; ++k) dst[m][k] = *(const LAS bf16x8*)(lds + PG8_SA(b, h) + aoff + m * 2048 + k * 1024); } while (0)
; #define PG8_MMA(ai, bj, At, Bt) do { __builtin_amdgcn_s_setprio(1); _Pragma("unroll") for (int m = 0; m < 4; ++m) _Pragma("unroll") for (int n = 0; n < 2; ++n) _Pragma("unroll") for (int k = 0; k < 2; ++k) \
;         acc[ai][bj][m][n] = __builtin_amdgcn_mfma_f32_16x16x32_bf16(Bt[n][k], At[m][k], acc[ai][bj][m][n], 0, 0, 0); __builtin_amdgcn_s_setprio(0); } while (0)
; #define PG8_WAIT_V(n) asm volatile("s_waitcnt vmcnt(" #n ")" ::: "memory")
; #define PG8_WAIT_L(n) asm volatile("s_waitcnt lgkmcnt(" #n ")" ::: "memory")
; #define PG8_BAR __builtin_amdgcn_s_barrier()
; #define PG8_SCHED __builtin_amdgcn_sched_barrier(0)
; template <class Epi, class Sched, bool ABLK = false, bool ALIGN_EPI = true, bool SP2 = true, bool BBLK = true>
; __device__ __forceinline__ void gemm_phase(LAS unsigned char* lds, const Gemm g, const Sched& S, const Epi& E) {
;     ...
;         for (int t = 0; t < nt; t += 2) {
;     ...
;             PG8_LDA(At, 1, 1); PG8_STAGE(PG8_SB(1, 0), b3, voffB); PG8_STAGE(PG8_SB(1, 1), b3 + hstepB, voffB); PG8_STAGE(PG8_SA(1, 0), a3, voffA);
;             PG8_WAIT_V(8); PG8_WAIT_L(0); PG8_BAR; PG8_MMA(1, 0, At, B0); PG8_MMA(1, 1, At, B1); PG8_BAR; PG8_SCHED;
	s_add_u32 s34, s30, 0x8000
	s_addc_u32 s35, s31, 0
	s_add_i32 s58, s60, s39
	s_mov_b32 m0, s58
	ds_read_b128 v[188:191], v154 offset:49152
	ds_read_b128 v[192:195], v154 offset:50176
	ds_read_b128 v[196:199], v154 offset:51200
	ds_read_b128 v[200:203], v154 offset:52224
	ds_read_b128 v[204:207], v154 offset:53248
	ds_read_b128 v[208:211], v154 offset:54272
	ds_read_b128 v[212:215], v154 offset:55296
	ds_read_b128 v[216:219], v154 offset:56320
	global_load_lds_dwordx4 v132, s[34:35]
	s_add_i32 m0, s58, 0x2000
	s_add_u32 s30, s30, 0xc000
	v_lshl_add_u64 v[220:221], s[34:35], 0, v[136:137]
	s_addc_u32 s31, s31, 0
	s_add_i32 s34, s61, s39
	global_load_lds_dwordx4 v[220:221], off
	s_mov_b32 m0, s34
	s_nop 0
	global_load_lds_dwordx4 v132, s[30:31]
	s_add_i32 m0, s34, 0x2000
	s_nop 0
	global_load_lds_dwordx4 v136, s[30:31]
	s_mov_b32 m0, s44
	s_nop 0
	global_load_lds_dwordx4 v130, s[28:29]
	s_mov_b32 m0, s45
	s_nop 0
	global_load_lds_dwordx4 v134, s[28:29]
	s_waitcnt vmcnt(8)
	s_waitcnt lgkmcnt(0)
	s_barrier
	s_setprio 1
	s_waitcnt lgkmcnt(0)
	v_mfma_f32_16x16x32_bf16 v[62:65], v[156:159], v[188:191], v[62:65]
	v_mfma_f32_16x16x32_bf16 v[58:61], v[164:167], v[188:191], v[58:61]
	v_mfma_f32_16x16x32_bf16 v[46:49], v[156:159], v[196:199], v[46:49]
	v_mfma_f32_16x16x32_bf16 v[42:45], v[164:167], v[196:199], v[42:45]
	v_mfma_f32_16x16x32_bf16 v[30:33], v[156:159], v[204:207], v[30:33]
	v_mfma_f32_16x16x32_bf16 v[26:29], v[164:167], v[204:207], v[26:29]
	v_mfma_f32_16x16x32_bf16 v[14:17], v[156:159], v[212:215], v[14:17]
	v_mfma_f32_16x16x32_bf16 v[10:13], v[164:167], v[212:215], v[10:13]
	v_mfma_f32_16x16x32_bf16 v[62:65], v[160:163], v[192:195], v[62:65]
	v_mfma_f32_16x16x32_bf16 v[58:61], v[168:171], v[192:195], v[58:61]
	v_mfma_f32_16x16x32_bf16 v[46:49], v[160:163], v[200:203], v[46:49]
	v_mfma_f32_16x16x32_bf16 v[42:45], v[168:171], v[200:203], v[42:45]
	v_mfma_f32_16x16x32_bf16 v[30:33], v[160:163], v[208:211], v[30:33]
	v_mfma_f32_16x16x32_bf16 v[26:29], v[168:171], v[208:211], v[26:29]
	v_mfma_f32_16x16x32_bf16 v[14:17], v[160:163], v[216:219], v[14:17]
	v_mfma_f32_16x16x32_bf16 v[10:13], v[168:171], v[216:219], v[10:13]
	s_setprio 0
	s_setprio 1
	v_mfma_f32_16x16x32_bf16 v[54:57], v[172:175], v[188:191], v[54:57]
	v_mfma_f32_16x16x32_bf16 v[50:53], v[180:183], v[188:191], v[50:53]
	v_mfma_f32_16x16x32_bf16 v[38:41], v[172:175], v[196:199], v[38:41]
	v_mfma_f32_16x16x32_bf16 v[34:37], v[180:183], v[196:199], v[34:37]
	v_mfma_f32_16x16x32_bf16 v[22:25], v[172:175], v[204:207], v[22:25]
	v_mfma_f32_16x16x32_bf16 v[18:21], v[180:183], v[204:207], v[18:21]
	v_mfma_f32_16x16x32_bf16 v[6:9], v[172:175], v[212:215], v[6:9]
	v_mfma_f32_16x16x32_bf16 v[2:5], v[180:183], v[212:215], v[2:5]
	v_mfma_f32_16x16x32_bf16 v[54:57], v[176:179], v[192:195], v[54:57]
	v_mfma_f32_16x16x32_bf16 v[50:53], v[184:187], v[192:195], v[50:53]
	v_mfma_f32_16x16x32_bf16 v[38:41], v[176:179], v[200:203], v[38:41]
	v_mfma_f32_16x16x32_bf16 v[34:37], v[184:187], v[200:203], v[34:37]
	v_mfma_f32_16x16x32_bf16 v[22:25], v[176:179], v[208:211], v[22:25]
	v_mfma_f32_16x16x32_bf16 v[18:21], v[184:187], v[208:211], v[18:21]
	v_mfma_f32_16x16x32_bf16 v[6:9], v[176:179], v[216:219], v[6:9]
	v_mfma_f32_16x16x32_bf16 v[2:5], v[184:187], v[216:219], v[2:5]
	s_setprio 0
	s_barrier
	s_add_u32 s52, s52, 0x10000
	s_addc_u32 s53, s53, 0
	s_add_u32 s26, s26, 0x100
	s_addc_u32 s27, s27, 0
	s_cmp_ge_u32 s57, s47
	s_cbranch_scc0 .LBB0_1716
	s_and_b64 vcc, exec, s[6:7]
	s_cbranch_vccz .LBB0_1719
	s_barrier

; #define PG8_STAGE(bufoff, gbase, voff) do { _Pragma("unroll") for (int _i = 0; _i < 2; ++_i) \
;         __builtin_amdgcn_global_load_lds((const unsigned*)((const char*)(gbase) + (voff)[_i]), (LAS unsigned*)(lds + (bufoff) + ldsw + _i * 8192), 16, 0, 0); } while (0)
; #define PG8_WAIT_V(n) asm volatile("s_waitcnt vmcnt(" #n ")" ::: "memory")
; #define PG8_BAR __builtin_amdgcn_s_barrier()
; template <class Epi, class Sched, bool ABLK = false, bool ALIGN_EPI = true, bool SP2 = true, bool BBLK = true>
; __device__ __forceinline__ void gemm_phase(LAS unsigned char* lds, const Gemm g, const Sched& S, const Epi& E) {
;     ...
;     const unsigned ldsw = (unsigned)wid * 1024u;
;     const int aoff = lds_byte(wr * 64 + fr, fq * 8), boff = lds_byte(wc * 32 + fr, fq * 8);
;     ...
;     if constexpr (SP2) {
;         PG8_STAGE(PG8_SB(0, 0), cB, voffB); PG8_STAGE(PG8_SB(0, 1), cB + hstepB, voffB); PG8_STAGE(PG8_SA(0, 0), cA, voffA); PG8_STAGE(PG8_SA(0, 1), cA + hstepA, voffA);
;         if (wr == 1) PG8_BAR;
;         PG8_WAIT_V(2); PG8_BAR;
;         PG8_STAGE(PG8_SB(1, 0), cB + kstepB, voffB); PG8_STAGE(PG8_SA(1, 0), a_tile(uA, tbA + 1), voffA); PG8_STAGE(PG8_SB(1, 1), cB + hstepB + kstepB, voffB);
;         PG8_WAIT_V(6); PG8_BAR;
.LBB0_1836:
	s_and_b32 s44, s8, 3
	s_lshl_b32 s10, s7, 13
	s_lshl_b32 s11, s44, 12
	s_add_u32 s8, s28, 0x8000
	s_addc_u32 s9, s29, 0
	s_add_i32 m0, s25, 0x18000
	v_lshl_add_u64 v[12:13], s[8:9], 0, v[134:135]
	s_waitcnt vmcnt(2)
	s_barrier
	global_load_lds_dwordx4 v[12:13], off
	v_lshl_add_u64 v[12:13], s[8:9], 0, v[130:131]
	s_add_i32 m0, s25, 0x1a000
	s_mov_b64 s[8:9], 0x80
	s_add_i32 s45, s25, 0x8000
	global_load_lds_dwordx4 v[12:13], off
	v_lshl_add_u64 v[2:3], v[2:3], 0, s[8:9]
	s_mov_b32 m0, s45
	s_add_i32 s46, s25, 0xa000
	global_load_lds_dwordx4 v[2:3], off
	v_lshl_add_u64 v[2:3], v[4:5], 0, s[8:9]
	s_add_u32 s8, s28, 0xc000
	s_mov_b32 m0, s46
	s_addc_u32 s9, s29, 0
	global_load_lds_dwordx4 v[2:3], off
	s_add_i32 m0, s25, 0x1c000
	s_nop 0
	global_load_lds_dwordx4 v134, s[8:9]
	s_add_i32 m0, s25, 0x1e000
	v_lshrrev_b32_e32 v4, 1, v1
	global_load_lds_dwordx4 v130, s[8:9]
	v_and_b32_e32 v4, 24, v4
	v_and_b32_e32 v3, 15, v1
	v_lshlrev_b32_e32 v5, 1, v4
	v_lshl_or_b32 v2, s7, 6, v3
	v_lshl_or_b32 v5, v3, 6, v5
	v_cmp_lt_u32_e64 s[8:9], 7, v3
	v_mov_b32_e32 v3, 0xfffffc40
	v_or_b32_e32 v12, 16, v2
	v_cndmask_b32_e64 v140, 0, v3, s[8:9]
	v_mov_b32_e32 v3, 0x400
	v_cndmask_b32_e64 v142, v3, 64, s[8:9]
	v_ashrrev_i32_e32 v3, 31, v2
	v_ashrrev_i32_e32 v13, 31, v12
	v_lshlrev_b64 v[144:145], 7, v[2:3]
	v_lshlrev_b64 v[146:147], 7, v[12:13]
	v_or_b32_e32 v12, 32, v2
	v_or_b32_e32 v2, 48, v2
	v_ashrrev_i32_e32 v3, 31, v2
	v_lshlrev_b64 v[150:151], 7, v[2:3]
	v_lshlrev_b32_e32 v2, 15, v9
	v_and_b32_e32 v2, 0xffff0000, v2
	v_lshl_add_u32 v2, v10, 12, v2
	v_and_b32_e32 v3, 1, v9
	v_lshl_or_b32 v2, v3, 6, v2
	v_lshl_add_u64 v[152:153], v[144:145], 0, s[4:5]
	s_mov_b64 s[4:5], 0x4800
	v_lshl_add_u32 v138, v11, 1, v2
	v_lshlrev_b32_e32 v2, 15, v6
	v_lshl_add_u64 v[154:155], v[144:145], 0, s[4:5]
	s_mov_b64 s[4:5], 0x5000
	v_and_b32_e32 v2, 0xffff0000, v2
	v_lshlrev_b32_e32 v1, 2, v1
	v_lshl_add_u64 v[156:157], v[144:145], 0, s[4:5]
	s_mov_b64 s[4:5], 0x5800
	v_lshl_add_u32 v2, v7, 12, v2
	v_and_b32_e32 v3, 1, v6
	v_and_b32_e32 v1, 32, v1
	s_waitcnt vmcnt(6)
	s_cmpk_lt_u32 s6, 0x100
	v_lshl_add_u64 v[158:159], v[144:145], 0, s[4:5]
	s_mov_b64 s[4:5], 0x80080
	v_lshl_or_b32 v2, v3, 6, v2
	v_bitop3_b32 v14, v5, s10, v1 bitop3:0xde
	v_bitop3_b32 v1, v5, s11, v1 bitop3:0xde
	s_cselect_b64 s[6:7], -1, 0
	v_ashrrev_i32_e32 v13, 31, v12
	v_lshl_add_u64 v[160:161], v[138:139], 0, s[4:5]
	v_lshl_add_u32 v138, v8, 1, v2
	s_add_i32 s49, s72, s39
	v_cndmask_b32_e64 v141, 0, -1, s[8:9]
	v_mov_b32_e32 v143, v139
	v_lshlrev_b64 v[148:149], 7, v[12:13]
	v_lshl_add_u64 v[162:163], v[138:139], 0, s[4:5]
	v_add_u32_e32 v168, s72, v1
	v_add_u32_e32 v169, s73, v1
	v_add_u32_e32 v170, 0, v14
	v_lshlrev_b32_e32 v138, 1, v4
	s_add_i32 s47, s25, 0xc000
	s_add_i32 s48, s25, 0xe000
	s_add_i32 s50, s49, 0x2000
	s_barrier
	s_branch .LBB0_1839

; #define PG8_STAGE(bufoff, gbase, voff) do { _Pragma("unroll") for (int _i = 0; _i < 2; ++_i) \
;         __builtin_amdgcn_global_load_lds((const unsigned*)((const char*)(gbase) + (voff)[_i]), (LAS unsigned*)(lds + (bufoff) + ldsw + _i * 8192), 16, 0, 0); } while (0)
; #define PG8_LDA(dst, b, h) do { _Pragma("unroll") for (int m = 0; m < 4; ++m) _Pragma("unroll") for (int k = 0; k < 2; ++k) dst[m][k] = *(const LAS bf16x8*)(lds + PG8_SA(b, h) + aoff + m * 2048 + k * 1024); } while (0)
; #define PG8_LDB(dst, b, h) do { _Pragma("unroll") for (int n = 0; n < 2; ++n) _Pragma("unroll") for (int k = 0; k < 2; ++k) dst[n][k] = *(const LAS bf16x8*)(lds + PG8_SB(b, h) + boff + n * 2048 + k * 1024); } while (0)
; #define PG8_MMA(ai, bj, At, Bt) do { __builtin_amdgcn_s_setprio(1); _Pragma("unroll") for (int m = 0; m < 4; ++m) _Pragma("unroll") for (int n = 0; n < 2; ++n) _Pragma("unroll") for (int k = 0; k < 2; ++k) \
;         acc[ai][bj][m][n] = __builtin_amdgcn_mfma_f32_16x16x32_bf16(Bt[n][k], At[m][k], acc[ai][bj][m][n], 0, 0, 0); __builtin_amdgcn_s_setprio(0); } while (0)
; #define PG8_WAIT_V(n) asm volatile("s_waitcnt vmcnt(" #n ")" ::: "memory")
; template <class Epi, class Sched, bool ABLK = false, bool ALIGN_EPI = true, bool SP2 = true, bool BBLK = true>
; __device__ __forceinline__ void gemm_phase(LAS unsigned char* lds, const Gemm g, const Sched& S, const Epi& E) {
;     ...
;         for (int t = 0; t < nt; t += 2) {
;             const bool last = (t == nt - 2);
;             const char* a1 = a_tile(uA, tbA + t + 1);
;             const char* a2 = last ? a_tile(nuA, ntbA) : a_tile(uA, tbA + t + 2); const char* b2 = last ? nB : cB + (size_t)(t + 2) * kstepB;
;             const char* a3 = last ? a_tile(nuA, ntbA + 1) : a_tile(uA, tbA + t + 3); const char* b3 = b2 + kstepB;
;             if (last && has_next) S.a_ready(nxt);
;             if constexpr (SP2) {
;             PG8_LDB(B0, 0, 0); PG8_LDB(B1, 0, 1); PG8_SCHED; PG8_LDA(At, 0, 0); PG8_STAGE(PG8_SA(1, 1), a1 + hstepA, voffA);
;             PG8_WAIT_V(8); PG8_WAIT_L(0); PG8_BAR; PG8_MMA(0, 0, At, B0); PG8_MMA(0, 1, At, B1); PG8_BAR; PG8_SCHED;
;             PG8_LDA(At, 0, 1); PG8_STAGE(PG8_SB(0, 0), b2, voffB); PG8_STAGE(PG8_SB(0, 1), b2 + hstepB, voffB); PG8_STAGE(PG8_SA(0, 0), a2, voffA);
;             PG8_WAIT_V(8); PG8_WAIT_L(0); PG8_BAR; PG8_MMA(1, 0, At, B0); PG8_MMA(1, 1, At, B1); PG8_BAR; PG8_SCHED;
.LBB0_1842:
	ds_read_b128 v[172:175], v168
	ds_read_b128 v[176:179], v168 offset:1024
	ds_read_b128 v[180:183], v168 offset:2048
	ds_read_b128 v[184:187], v168 offset:3072
	ds_read_b128 v[188:191], v169
	ds_read_b128 v[192:195], v169 offset:1024
	ds_read_b128 v[196:199], v169 offset:2048
	ds_read_b128 v[200:203], v169 offset:3072
	s_add_u32 s30, s26, s28
	s_addc_u32 s31, s27, s29
	s_add_u32 s36, s30, 0x100
	s_addc_u32 s37, s31, 0
	s_add_u32 s30, s30, 0x180
	s_addc_u32 s31, s31, 0
	s_cmpk_eq_i32 s28, 0xf00
	s_cselect_b32 s31, s51, s31
	s_cselect_b32 s30, s23, s30
	s_cselect_b32 s35, s11, s53
	s_cselect_b32 s34, s15, s52
	s_cselect_b32 s37, s4, s37
	s_cselect_b32 s36, s5, s36
	s_mov_b32 m0, s47
	v_lshl_add_u64 v[236:237], v[164:165], 0, s[28:29]
	ds_read_b128 v[204:207], v170
	ds_read_b128 v[208:211], v170 offset:1024
	ds_read_b128 v[212:215], v170 offset:2048
	ds_read_b128 v[216:219], v170 offset:3072
	ds_read_b128 v[220:223], v170 offset:4096
	ds_read_b128 v[224:227], v170 offset:5120
	ds_read_b128 v[228:231], v170 offset:6144
	ds_read_b128 v[232:235], v170 offset:7168
	global_load_lds_dwordx4 v[236:237], off
	v_lshl_add_u64 v[236:237], v[166:167], 0, s[28:29]
	s_mov_b32 m0, s48
	s_nop 0
	global_load_lds_dwordx4 v[236:237], off
	s_waitcnt vmcnt(8)
	s_waitcnt lgkmcnt(0)
	s_barrier
	s_setprio 1
	s_waitcnt lgkmcnt(0)
	v_mfma_f32_16x16x32_bf16 v[126:129], v[172:175], v[204:207], v[126:129]
	v_mfma_f32_16x16x32_bf16 v[122:125], v[180:183], v[204:207], v[122:125]
	v_mfma_f32_16x16x32_bf16 v[110:113], v[172:175], v[212:215], v[110:113]
	v_mfma_f32_16x16x32_bf16 v[106:109], v[180:183], v[212:215], v[106:109]
	v_mfma_f32_16x16x32_bf16 v[94:97], v[172:175], v[220:223], v[94:97]
	v_mfma_f32_16x16x32_bf16 v[90:93], v[180:183], v[220:223], v[90:93]
	v_mfma_f32_16x16x32_bf16 v[78:81], v[172:175], v[228:231], v[78:81]
	v_mfma_f32_16x16x32_bf16 v[74:77], v[180:183], v[228:231], v[74:77]
	v_mfma_f32_16x16x32_bf16 v[126:129], v[176:179], v[208:211], v[126:129]
	v_mfma_f32_16x16x32_bf16 v[122:125], v[184:187], v[208:211], v[122:125]
	v_mfma_f32_16x16x32_bf16 v[110:113], v[176:179], v[216:219], v[110:113]
	v_mfma_f32_16x16x32_bf16 v[106:109], v[184:187], v[216:219], v[106:109]
	v_mfma_f32_16x16x32_bf16 v[94:97], v[176:179], v[224:227], v[94:97]
	v_mfma_f32_16x16x32_bf16 v[90:93], v[184:187], v[224:227], v[90:93]
	v_mfma_f32_16x16x32_bf16 v[78:81], v[176:179], v[232:235], v[78:81]
	v_mfma_f32_16x16x32_bf16 v[74:77], v[184:187], v[232:235], v[74:77]
	s_setprio 0
	s_setprio 1
	v_mfma_f32_16x16x32_bf16 v[118:121], v[188:191], v[204:207], v[118:121]
	v_mfma_f32_16x16x32_bf16 v[114:117], v[196:199], v[204:207], v[114:117]
	v_mfma_f32_16x16x32_bf16 v[102:105], v[188:191], v[212:215], v[102:105]
	v_mfma_f32_16x16x32_bf16 v[98:101], v[196:199], v[212:215], v[98:101]
	v_mfma_f32_16x16x32_bf16 v[86:89], v[188:191], v[220:223], v[86:89]
	v_mfma_f32_16x16x32_bf16 v[82:85], v[196:199], v[220:223], v[82:85]
	v_mfma_f32_16x16x32_bf16 v[70:73], v[188:191], v[228:231], v[70:73]
	v_mfma_f32_16x16x32_bf16 v[66:69], v[196:199], v[228:231], v[66:69]
	v_mfma_f32_16x16x32_bf16 v[118:121], v[192:195], v[208:211], v[118:121]
	v_mfma_f32_16x16x32_bf16 v[114:117], v[200:203], v[208:211], v[114:117]
	v_mfma_f32_16x16x32_bf16 v[102:105], v[192:195], v[216:219], v[102:105]
	v_mfma_f32_16x16x32_bf16 v[98:101], v[200:203], v[216:219], v[98:101]
	v_mfma_f32_16x16x32_bf16 v[86:89], v[192:195], v[224:227], v[86:89]
	v_mfma_f32_16x16x32_bf16 v[82:85], v[200:203], v[224:227], v[82:85]
	v_mfma_f32_16x16x32_bf16 v[70:73], v[192:195], v[232:235], v[70:73]
	v_mfma_f32_16x16x32_bf16 v[66:69], v[200:203], v[232:235], v[66:69]
	s_setprio 0
	s_barrier
	s_mov_b32 m0, s49
	s_add_u32 s56, s34, 0x4000
	ds_read_b128 v[204:207], v170 offset:16384
	ds_read_b128 v[208:211], v170 offset:17408
	ds_read_b128 v[212:215], v170 offset:18432
	ds_read_b128 v[216:219], v170 offset:19456
	ds_read_b128 v[220:223], v170 offset:20480
	ds_read_b128 v[224:227], v170 offset:21504
	ds_read_b128 v[228:231], v170 offset:22528
	ds_read_b128 v[232:235], v170 offset:23552
	global_load_lds_dwordx4 v134, s[34:35]
	s_mov_b32 m0, s50
	s_addc_u32 s57, s35, 0
	s_add_i32 s55, s73, s39
	global_load_lds_dwordx4 v130, s[34:35]
	s_mov_b32 m0, s55
	s_nop 0
	global_load_lds_dwordx4 v134, s[56:57]
	s_add_i32 m0, s55, 0x2000
	s_nop 0
	global_load_lds_dwordx4 v130, s[56:57]
	s_mov_b32 m0, s25
	s_nop 0
	global_load_lds_dwordx4 v136, s[36:37]
	s_mov_b32 m0, s40
	s_nop 0
	global_load_lds_dwordx4 v132, s[36:37]
	s_waitcnt vmcnt(8)
	s_waitcnt lgkmcnt(0)
	s_barrier
; #define PG8_STAGE(bufoff, gbase, voff) do { _Pragma("unroll") for (int _i = 0; _i < 2; ++_i) \
;         __builtin_amdgcn_global_load_lds((const unsigned*)((const char*)(gbase) + (voff)[_i]), (LAS unsigned*)(lds + (bufoff) + ldsw + _i * 8192), 16, 0, 0); } while (0)
; #define PG8_LDA(dst, b, h) do { _Pragma("unroll") for (int m = 0; m < 4; ++m) _Pragma("unroll") for (int k = 0; k < 2; ++k) dst[m][k] = *(const LAS bf16x8*)(lds + PG8_SA(b, h) + aoff + m * 2048 + k * 1024); } while (0)
; #define PG8_LDB(dst, b, h) do { _Pragma("unroll") for (int n = 0; n < 2; ++n) _Pragma("unroll") for (int k = 0; k < 2; ++k) dst[n][k] = *(const LAS bf16x8*)(lds + PG8_SB(b, h) + boff + n * 2048 + k * 1024); } while (0)
; #define PG8_MMA(ai, bj, At, Bt) do { __builtin_amdgcn_s_setprio(1); _Pragma("unroll") for (int m = 0; m < 4; ++m) _Pragma("unroll") for (int n = 0; n < 2; ++n) _Pragma("unroll") for (int k = 0; k < 2; ++k) \
;         acc[ai][bj][m][n] = __builtin_amdgcn_mfma_f32_16x16x32_bf16(Bt[n][k], At[m][k], acc[ai][bj][m][n], 0, 0, 0); __builtin_amdgcn_s_setprio(0); } while (0)
; #define PG8_WAIT_V(n) asm volatile("s_waitcnt vmcnt(" #n ")" ::: "memory")
; #define PG8_WAIT_L(n) asm volatile("s_waitcnt lgkmcnt(" #n ")" ::: "memory")
; #define PG8_BAR __builtin_amdgcn_s_barrier()
; #define PG8_SCHED __builtin_amdgcn_sched_barrier(0)
; template <class Epi, class Sched, bool ABLK = false, bool ALIGN_EPI = true, bool SP2 = true, bool BBLK = true>
; __device__ __forceinline__ void gemm_phase(LAS unsigned char* lds, const Gemm g, const Sched& S, const Epi& E) {
;     ...
;             PG8_WAIT_V(8); PG8_WAIT_L(0); PG8_BAR; PG8_MMA(1, 0, At, B0); PG8_MMA(1, 1, At, B1); PG8_BAR; PG8_SCHED;
;             PG8_LDB(B0, 1, 0); PG8_LDB(B1, 1, 1); PG8_SCHED; PG8_LDA(At, 1, 0); PG8_STAGE(PG8_SA(0, 1), a2 + hstepA, voffA);
;             PG8_WAIT_V(8); PG8_WAIT_L(0); PG8_BAR; PG8_MMA(0, 0, At, B0); PG8_MMA(0, 1, At, B1); PG8_BAR; PG8_SCHED;
	s_setprio 1
	s_waitcnt lgkmcnt(0)
	v_mfma_f32_16x16x32_bf16 v[62:65], v[172:175], v[204:207], v[62:65]
	v_mfma_f32_16x16x32_bf16 v[58:61], v[180:183], v[204:207], v[58:61]
	v_mfma_f32_16x16x32_bf16 v[46:49], v[172:175], v[212:215], v[46:49]
	v_mfma_f32_16x16x32_bf16 v[42:45], v[180:183], v[212:215], v[42:45]
	v_mfma_f32_16x16x32_bf16 v[30:33], v[172:175], v[220:223], v[30:33]
	v_mfma_f32_16x16x32_bf16 v[26:29], v[180:183], v[220:223], v[26:29]
	v_mfma_f32_16x16x32_bf16 v[14:17], v[172:175], v[228:231], v[14:17]
	v_mfma_f32_16x16x32_bf16 v[10:13], v[180:183], v[228:231], v[10:13]
	v_mfma_f32_16x16x32_bf16 v[62:65], v[176:179], v[208:211], v[62:65]
	v_mfma_f32_16x16x32_bf16 v[58:61], v[184:187], v[208:211], v[58:61]
	v_mfma_f32_16x16x32_bf16 v[46:49], v[176:179], v[216:219], v[46:49]
	v_mfma_f32_16x16x32_bf16 v[42:45], v[184:187], v[216:219], v[42:45]
	v_mfma_f32_16x16x32_bf16 v[30:33], v[176:179], v[224:227], v[30:33]
	v_mfma_f32_16x16x32_bf16 v[26:29], v[184:187], v[224:227], v[26:29]
	v_mfma_f32_16x16x32_bf16 v[14:17], v[176:179], v[232:235], v[14:17]
	v_mfma_f32_16x16x32_bf16 v[10:13], v[184:187], v[232:235], v[10:13]
	s_setprio 0
	s_setprio 1
	v_mfma_f32_16x16x32_bf16 v[54:57], v[188:191], v[204:207], v[54:57]
	v_mfma_f32_16x16x32_bf16 v[50:53], v[196:199], v[204:207], v[50:53]
	v_mfma_f32_16x16x32_bf16 v[38:41], v[188:191], v[212:215], v[38:41]
	v_mfma_f32_16x16x32_bf16 v[34:37], v[196:199], v[212:215], v[34:37]
	v_mfma_f32_16x16x32_bf16 v[22:25], v[188:191], v[220:223], v[22:25]
	v_mfma_f32_16x16x32_bf16 v[18:21], v[196:199], v[220:223], v[18:21]
	v_mfma_f32_16x16x32_bf16 v[6:9], v[188:191], v[228:231], v[6:9]
	v_mfma_f32_16x16x32_bf16 v[2:5], v[196:199], v[228:231], v[2:5]
	v_mfma_f32_16x16x32_bf16 v[54:57], v[192:195], v[208:211], v[54:57]
	v_mfma_f32_16x16x32_bf16 v[50:53], v[200:203], v[208:211], v[50:53]
	v_mfma_f32_16x16x32_bf16 v[38:41], v[192:195], v[216:219], v[38:41]
	v_mfma_f32_16x16x32_bf16 v[34:37], v[200:203], v[216:219], v[34:37]
	v_mfma_f32_16x16x32_bf16 v[22:25], v[192:195], v[224:227], v[22:25]
	v_mfma_f32_16x16x32_bf16 v[18:21], v[200:203], v[224:227], v[18:21]
	v_mfma_f32_16x16x32_bf16 v[6:9], v[192:195], v[232:235], v[6:9]
	v_mfma_f32_16x16x32_bf16 v[2:5], v[200:203], v[232:235], v[2:5]
	s_setprio 0
	s_barrier
	v_add_u32_e32 v171, s60, v1
	ds_read_b128 v[172:175], v171
	ds_read_b128 v[176:179], v171 offset:1024
	ds_read_b128 v[180:183], v171 offset:2048
	ds_read_b128 v[184:187], v171 offset:3072
	v_add_u32_e32 v171, s61, v1
	ds_read_b128 v[188:191], v171
	ds_read_b128 v[192:195], v171 offset:1024
	ds_read_b128 v[196:199], v171 offset:2048
	ds_read_b128 v[200:203], v171 offset:3072
	s_add_u32 s36, s36, 0x80000
	s_addc_u32 s37, s37, 0
	s_mov_b32 m0, s41
	ds_read_b128 v[204:207], v170 offset:32768
	ds_read_b128 v[208:211], v170 offset:33792
	ds_read_b128 v[212:215], v170 offset:34816
	ds_read_b128 v[216:219], v170 offset:35840
	ds_read_b128 v[220:223], v170 offset:36864
	ds_read_b128 v[224:227], v170 offset:37888
	ds_read_b128 v[228:231], v170 offset:38912
	ds_read_b128 v[232:235], v170 offset:39936
	global_load_lds_dwordx4 v136, s[36:37]
	s_mov_b32 m0, s42
	s_nop 0
	global_load_lds_dwordx4 v132, s[36:37]
	s_waitcnt vmcnt(8)
	s_waitcnt lgkmcnt(0)
	s_barrier
	s_setprio 1
	s_waitcnt lgkmcnt(0)
	v_mfma_f32_16x16x32_bf16 v[126:129], v[172:175], v[204:207], v[126:129]
	v_mfma_f32_16x16x32_bf16 v[122:125], v[180:183], v[204:207], v[122:125]
	v_mfma_f32_16x16x32_bf16 v[110:113], v[172:175], v[212:215], v[110:113]
	v_mfma_f32_16x16x32_bf16 v[106:109], v[180:183], v[212:215], v[106:109]
	v_mfma_f32_16x16x32_bf16 v[94:97], v[172:175], v[220:223], v[94:97]
	v_mfma_f32_16x16x32_bf16 v[90:93], v[180:183], v[220:223], v[90:93]
	v_mfma_f32_16x16x32_bf16 v[78:81], v[172:175], v[228:231], v[78:81]
	v_mfma_f32_16x16x32_bf16 v[74:77], v[180:183], v[228:231], v[74:77]
	v_mfma_f32_16x16x32_bf16 v[126:129], v[176:179], v[208:211], v[126:129]
	v_mfma_f32_16x16x32_bf16 v[122:125], v[184:187], v[208:211], v[122:125]
	v_mfma_f32_16x16x32_bf16 v[110:113], v[176:179], v[216:219], v[110:113]
	v_mfma_f32_16x16x32_bf16 v[106:109], v[184:187], v[216:219], v[106:109]
	v_mfma_f32_16x16x32_bf16 v[94:97], v[176:179], v[224:227], v[94:97]
	v_mfma_f32_16x16x32_bf16 v[90:93], v[184:187], v[224:227], v[90:93]
	v_mfma_f32_16x16x32_bf16 v[78:81], v[176:179], v[232:235], v[78:81]
	v_mfma_f32_16x16x32_bf16 v[74:77], v[184:187], v[232:235], v[74:77]
	s_setprio 0
	s_setprio 1
	v_mfma_f32_16x16x32_bf16 v[118:121], v[188:191], v[204:207], v[118:121]
	v_mfma_f32_16x16x32_bf16 v[114:117], v[196:199], v[204:207], v[114:117]
	v_mfma_f32_16x16x32_bf16 v[102:105], v[188:191], v[212:215], v[102:105]
	v_mfma_f32_16x16x32_bf16 v[98:101], v[196:199], v[212:215], v[98:101]
	v_mfma_f32_16x16x32_bf16 v[86:89], v[188:191], v[220:223], v[86:89]
	v_mfma_f32_16x16x32_bf16 v[82:85], v[196:199], v[220:223], v[82:85]
	v_mfma_f32_16x16x32_bf16 v[70:73], v[188:191], v[228:231], v[70:73]
	v_mfma_f32_16x16x32_bf16 v[66:69], v[196:199], v[228:231], v[66:69]
	v_mfma_f32_16x16x32_bf16 v[118:121], v[192:195], v[208:211], v[118:121]
	v_mfma_f32_16x16x32_bf16 v[114:117], v[200:203], v[208:211], v[114:117]
	v_mfma_f32_16x16x32_bf16 v[102:105], v[192:195], v[216:219], v[102:105]
	v_mfma_f32_16x16x32_bf16 v[98:101], v[200:203], v[216:219], v[98:101]
	v_mfma_f32_16x16x32_bf16 v[86:89], v[192:195], v[224:227], v[86:89]
	v_mfma_f32_16x16x32_bf16 v[82:85], v[200:203], v[224:227], v[82:85]
	v_mfma_f32_16x16x32_bf16 v[70:73], v[192:195], v[232:235], v[70:73]
	v_mfma_f32_16x16x32_bf16 v[66:69], v[200:203], v[232:235], v[66:69]
	s_setprio 0
	s_barrier
; #define PG8_STAGE(bufoff, gbase, voff) do { _Pragma("unroll") for (int _i = 0; _i < 2; ++_i) \
;         __builtin_amdgcn_global_load_lds((const unsigned*)((const char*)(gbase) + (voff)[_i]), (LAS unsigned*)(lds + (bufoff) + ldsw + _i * 8192), 16, 0, 0); } while (0)
; #define PG8_LDA(dst, b, h) do { _Pragma("unroll") for (int m = 0; m < 4; ++m) _Pragma("unroll") for (int k = 0; k < 2; ++k) dst[m][k] = *(const LAS bf16x8*)(lds + PG8_SA(b, h) + aoff + m * 2048 + k * 1024); } while (0)
; #define PG8_MMA(ai, bj, At, Bt) do { __builtin_amdgcn_s_setprio(1); _Pragma("unroll") for (int m = 0; m < 4; ++m) _Pragma("unroll") for (int n = 0; n < 2; ++n) _Pragma("unroll") for (int k = 0; k < 2; ++k) \
;         acc[ai][bj][m][n] = __builtin_amdgcn_mfma_f32_16x16x32_bf16(Bt[n][k], At[m][k], acc[ai][bj][m][n], 0, 0, 0); __builtin_amdgcn_s_setprio(0); } while (0)
; #define PG8_WAIT_V(n) asm volatile("s_waitcnt vmcnt(" #n ")" ::: "memory")
; #define PG8_WAIT_L(n) asm volatile("s_waitcnt lgkmcnt(" #n ")" ::: "memory")
; #define PG8_BAR __builtin_amdgcn_s_barrier()
; #define PG8_SCHED __builtin_amdgcn_sched_barrier(0)
; template <class Epi, class Sched, bool ABLK = false, bool ALIGN_EPI = true, bool SP2 = true, bool BBLK = true>
; __device__ __forceinline__ void gemm_phase(LAS unsigned char* lds, const Gemm g, const Sched& S, const Epi& E) {
;     ...
;         for (int t = 0; t < nt; t += 2) {
;     ...
;             PG8_LDA(At, 1, 1); PG8_STAGE(PG8_SB(1, 0), b3, voffB); PG8_STAGE(PG8_SB(1, 1), b3 + hstepB, voffB); PG8_STAGE(PG8_SA(1, 0), a3, voffA);
;             PG8_WAIT_V(8); PG8_WAIT_L(0); PG8_BAR; PG8_MMA(1, 0, At, B0); PG8_MMA(1, 1, At, B1); PG8_BAR; PG8_SCHED;
	s_add_u32 s36, s34, 0x8000
	s_addc_u32 s37, s35, 0
	s_add_i32 s55, s60, s39
	s_mov_b32 m0, s55
	ds_read_b128 v[204:207], v170 offset:49152
	ds_read_b128 v[208:211], v170 offset:50176
	ds_read_b128 v[212:215], v170 offset:51200
	ds_read_b128 v[216:219], v170 offset:52224
	ds_read_b128 v[220:223], v170 offset:53248
	ds_read_b128 v[224:227], v170 offset:54272
	ds_read_b128 v[228:231], v170 offset:55296
	ds_read_b128 v[232:235], v170 offset:56320
	global_load_lds_dwordx4 v134, s[36:37]
	s_add_i32 m0, s55, 0x2000
	s_add_u32 s34, s34, 0xc000
	v_lshl_add_u64 v[236:237], s[36:37], 0, v[130:131]
	s_addc_u32 s35, s35, 0
	s_add_i32 s36, s61, s39
	global_load_lds_dwordx4 v[236:237], off
	s_mov_b32 m0, s36
	s_nop 0
	global_load_lds_dwordx4 v134, s[34:35]
	s_add_i32 m0, s36, 0x2000
	s_nop 0
	global_load_lds_dwordx4 v130, s[34:35]
	s_mov_b32 m0, s45
	s_nop 0
	global_load_lds_dwordx4 v136, s[30:31]
	s_mov_b32 m0, s46
	s_nop 0
	global_load_lds_dwordx4 v132, s[30:31]
	s_waitcnt vmcnt(8)
	s_waitcnt lgkmcnt(0)
	s_barrier
	s_setprio 1
	s_waitcnt lgkmcnt(0)
	v_mfma_f32_16x16x32_bf16 v[62:65], v[172:175], v[204:207], v[62:65]
	v_mfma_f32_16x16x32_bf16 v[58:61], v[180:183], v[204:207], v[58:61]
	v_mfma_f32_16x16x32_bf16 v[46:49], v[172:175], v[212:215], v[46:49]
	v_mfma_f32_16x16x32_bf16 v[42:45], v[180:183], v[212:215], v[42:45]
	v_mfma_f32_16x16x32_bf16 v[30:33], v[172:175], v[220:223], v[30:33]
	v_mfma_f32_16x16x32_bf16 v[26:29], v[180:183], v[220:223], v[26:29]
	v_mfma_f32_16x16x32_bf16 v[14:17], v[172:175], v[228:231], v[14:17]
	v_mfma_f32_16x16x32_bf16 v[10:13], v[180:183], v[228:231], v[10:13]
	v_mfma_f32_16x16x32_bf16 v[62:65], v[176:179], v[208:211], v[62:65]
	v_mfma_f32_16x16x32_bf16 v[58:61], v[184:187], v[208:211], v[58:61]
	v_mfma_f32_16x16x32_bf16 v[46:49], v[176:179], v[216:219], v[46:49]
	v_mfma_f32_16x16x32_bf16 v[42:45], v[184:187], v[216:219], v[42:45]
	v_mfma_f32_16x16x32_bf16 v[30:33], v[176:179], v[224:227], v[30:33]
	v_mfma_f32_16x16x32_bf16 v[26:29], v[184:187], v[224:227], v[26:29]
	v_mfma_f32_16x16x32_bf16 v[14:17], v[176:179], v[232:235], v[14:17]
	v_mfma_f32_16x16x32_bf16 v[10:13], v[184:187], v[232:235], v[10:13]
	s_setprio 0
	s_setprio 1
	v_mfma_f32_16x16x32_bf16 v[54:57], v[188:191], v[204:207], v[54:57]
	v_mfma_f32_16x16x32_bf16 v[50:53], v[196:199], v[204:207], v[50:53]
	v_mfma_f32_16x16x32_bf16 v[38:41], v[188:191], v[212:215], v[38:41]
	v_mfma_f32_16x16x32_bf16 v[34:37], v[196:199], v[212:215], v[34:37]
	v_mfma_f32_16x16x32_bf16 v[22:25], v[188:191], v[220:223], v[22:25]
	v_mfma_f32_16x16x32_bf16 v[18:21], v[196:199], v[220:223], v[18:21]
	v_mfma_f32_16x16x32_bf16 v[6:9], v[188:191], v[228:231], v[6:9]
	v_mfma_f32_16x16x32_bf16 v[2:5], v[196:199], v[228:231], v[2:5]
	v_mfma_f32_16x16x32_bf16 v[54:57], v[192:195], v[208:211], v[54:57]
	v_mfma_f32_16x16x32_bf16 v[50:53], v[200:203], v[208:211], v[50:53]
	v_mfma_f32_16x16x32_bf16 v[38:41], v[192:195], v[216:219], v[38:41]
	v_mfma_f32_16x16x32_bf16 v[34:37], v[200:203], v[216:219], v[34:37]
	v_mfma_f32_16x16x32_bf16 v[22:25], v[192:195], v[224:227], v[22:25]
	v_mfma_f32_16x16x32_bf16 v[18:21], v[200:203], v[224:227], v[18:21]
	v_mfma_f32_16x16x32_bf16 v[6:9], v[192:195], v[232:235], v[6:9]
	v_mfma_f32_16x16x32_bf16 v[2:5], v[200:203], v[232:235], v[2:5]
	s_setprio 0
	s_barrier
	s_add_i32 s54, s54, 2
	s_add_u32 s28, s28, 0x100
	s_addc_u32 s29, s29, 0
	s_add_u32 s52, s52, 0x10000
	s_addc_u32 s53, s53, 0
	s_cmp_gt_u32 s54, 29
	s_cbranch_scc0 .LBB0_1842
	s_and_b64 vcc, exec, s[6:7]
	s_cbranch_vccz .LBB0_1845
	s_barrier

; #define PG8_STAGE(bufoff, gbase, voff) do { _Pragma("unroll") for (int _i = 0; _i < 2; ++_i) \
;         __builtin_amdgcn_global_load_lds((const unsigned*)((const char*)(gbase) + (voff)[_i]), (LAS unsigned*)(lds + (bufoff) + ldsw + _i * 8192), 16, 0, 0); } while (0)
; #define PG8_WAIT_V(n) asm volatile("s_waitcnt vmcnt(" #n ")" ::: "memory")
; #define PG8_BAR __builtin_amdgcn_s_barrier()
; template <class Epi, class Sched, bool ABLK = false, bool ALIGN_EPI = true, bool SP2 = true, bool BBLK = true>
; __device__ __forceinline__ void gemm_phase(LAS unsigned char* lds, const Gemm g, const Sched& S, const Epi& E) {
;     ...
;     const unsigned ldsw = (unsigned)wid * 1024u;
;     const int aoff = lds_byte(wr * 64 + fr, fq * 8), boff = lds_byte(wc * 32 + fr, fq * 8);
;     ...
;     if constexpr (SP2) {
;         PG8_STAGE(PG8_SB(0, 0), cB, voffB); PG8_STAGE(PG8_SB(0, 1), cB + hstepB, voffB); PG8_STAGE(PG8_SA(0, 0), cA, voffA); PG8_STAGE(PG8_SA(0, 1), cA + hstepA, voffA);
;         if (wr == 1) PG8_BAR;
;         PG8_WAIT_V(2); PG8_BAR;
;         PG8_STAGE(PG8_SB(1, 0), cB + kstepB, voffB); PG8_STAGE(PG8_SA(1, 0), a_tile(uA, tbA + 1), voffA); PG8_STAGE(PG8_SB(1, 1), cB + hstepB + kstepB, voffB);
;         PG8_WAIT_V(6); PG8_BAR;
.LBB0_1903:
	s_and_b32 s5, s5, 3
	s_lshl_b32 s7, s6, 13
	s_lshl_b32 s10, s5, 12
	s_add_u32 s8, s30, 0x8000
	s_addc_u32 s9, s31, 0
	s_add_i32 m0, s41, 0x18000
	v_lshl_add_u64 v[10:11], s[8:9], 0, v[130:131]
	s_waitcnt vmcnt(2)
	s_barrier
	global_load_lds_dwordx4 v[10:11], off
	s_add_i32 m0, s41, 0x1a000
	v_lshl_add_u64 v[10:11], s[8:9], 0, v[132:133]
	s_add_u32 s8, s34, 0x8000
	s_addc_u32 s9, s35, 0
	s_add_i32 s45, s41, 0x8000
	global_load_lds_dwordx4 v[10:11], off
	s_mov_b32 m0, s45
	s_add_i32 s46, s41, 0xa000
	global_load_lds_dwordx4 v130, s[8:9]
	v_lshl_add_u64 v[10:11], s[8:9], 0, v[132:133]
	s_add_u32 s8, s30, 0xc000
	s_mov_b32 m0, s46
	s_addc_u32 s9, s31, 0
	global_load_lds_dwordx4 v[10:11], off
	s_add_i32 m0, s41, 0x1c000
	s_nop 0
	global_load_lds_dwordx4 v130, s[8:9]
	s_add_i32 m0, s41, 0x1e000
	v_and_b32_e32 v9, 15, v4
	global_load_lds_dwordx4 v132, s[8:9]
	v_lshrrev_b32_e32 v10, 1, v4
	v_and_b32_e32 v10, 24, v10
	v_lshlrev_b32_e32 v11, 1, v10
	v_lshl_or_b32 v1, s6, 6, v9
	v_lshl_or_b32 v11, v9, 6, v11
	v_cmp_lt_u32_e64 s[8:9], 7, v9
	v_mov_b32_e32 v9, 0xffff8040
	v_lshlrev_b32_e32 v4, 2, v4
	v_cndmask_b32_e64 v134, 0, v9, s[8:9]
	v_mov_b32_e32 v9, 0x8000
	v_cndmask_b32_e64 v136, v9, 64, s[8:9]
	v_lshlrev_b32_e32 v9, 10, v2
	v_and_b32_e32 v9, 0xfffff800, v9
	v_lshl_add_u32 v3, v3, 7, v9
	v_and_b32_e32 v2, 1, v2
	v_and_b32_e32 v4, 32, v4
	v_lshl_or_b32 v2, v2, 6, v3
	v_bitop3_b32 v146, v11, s10, v4 bitop3:0xde
	s_mov_b64 s[10:11], 0xc000
	v_lshl_add_u32 v2, v5, 1, v2
	v_mov_b32_e32 v3, v131
	v_lshl_add_u64 v[138:139], v[2:3], 0, s[10:11]
	v_lshlrev_b32_e32 v2, 10, v6
	v_and_b32_e32 v2, 0xfffff800, v2
	v_lshl_add_u32 v2, v7, 7, v2
	v_and_b32_e32 v3, 1, v6
	s_waitcnt vmcnt(6)
	v_lshl_or_b32 v2, v3, 6, v2
	v_bitop3_b32 v4, v11, s7, v4 bitop3:0xde
	s_cmpk_lt_u32 s4, 0x100
	v_lshl_add_u32 v2, v8, 1, v2
	v_mov_b32_e32 v3, v131
	s_cselect_b64 s[6:7], -1, 0
	v_cndmask_b32_e64 v135, 0, -1, s[8:9]
	v_mov_b32_e32 v137, v131
	v_lshl_or_b32 v147, s5, 6, v10
	v_lshl_add_u64 v[140:141], v[2:3], 0, s[10:11]
	s_mov_b64 s[4:5], -1
	s_movk_i32 s48, 0x80
	v_add_u32_e32 v148, s72, v146
	v_add_u32_e32 v149, s73, v146
	v_add_u32_e32 v150, 0, v4
	s_mov_b64 s[14:15], 0x30000
	s_mov_b64 s[16:17], 0x80000
	s_mov_b64 s[18:19], 0x90000
	s_mov_b64 s[20:21], 0xa0000
	s_mov_b64 s[22:23], 0xb0000
	s_mov_b32 s49, s82
	s_mov_b32 s36, 0
	s_barrier
	s_branch .LBB0_1906

; #define PG8_STAGE(bufoff, gbase, voff) do { _Pragma("unroll") for (int _i = 0; _i < 2; ++_i) \
;         __builtin_amdgcn_global_load_lds((const unsigned*)((const char*)(gbase) + (voff)[_i]), (LAS unsigned*)(lds + (bufoff) + ldsw + _i * 8192), 16, 0, 0); } while (0)
; #define PG8_LDA(dst, b, h) do { _Pragma("unroll") for (int m = 0; m < 4; ++m) _Pragma("unroll") for (int k = 0; k < 2; ++k) dst[m][k] = *(const LAS bf16x8*)(lds + PG8_SA(b, h) + aoff + m * 2048 + k * 1024); } while (0)
; #define PG8_LDB(dst, b, h) do { _Pragma("unroll") for (int n = 0; n < 2; ++n) _Pragma("unroll") for (int k = 0; k < 2; ++k) dst[n][k] = *(const LAS bf16x8*)(lds + PG8_SB(b, h) + boff + n * 2048 + k * 1024); } while (0)
; #define PG8_MMA(ai, bj, At, Bt) do { __builtin_amdgcn_s_setprio(1); _Pragma("unroll") for (int m = 0; m < 4; ++m) _Pragma("unroll") for (int n = 0; n < 2; ++n) _Pragma("unroll") for (int k = 0; k < 2; ++k) \
;         acc[ai][bj][m][n] = __builtin_amdgcn_mfma_f32_16x16x32_bf16(Bt[n][k], At[m][k], acc[ai][bj][m][n], 0, 0, 0); __builtin_amdgcn_s_setprio(0); } while (0)
; #define PG8_WAIT_V(n) asm volatile("s_waitcnt vmcnt(" #n ")" ::: "memory")
; template <class Epi, class Sched, bool ABLK = false, bool ALIGN_EPI = true, bool SP2 = true, bool BBLK = true>
; __device__ __forceinline__ void gemm_phase(LAS unsigned char* lds, const Gemm g, const Sched& S, const Epi& E) {
;     ...
;         for (int t = 0; t < nt; t += 2) {
;             const bool last = (t == nt - 2);
;             const char* a1 = a_tile(uA, tbA + t + 1);
;             const char* a2 = last ? a_tile(nuA, ntbA) : a_tile(uA, tbA + t + 2); const char* b2 = last ? nB : cB + (size_t)(t + 2) * kstepB;
;             const char* a3 = last ? a_tile(nuA, ntbA + 1) : a_tile(uA, tbA + t + 3); const char* b3 = b2 + kstepB;
;             if (last && has_next) S.a_ready(nxt);
;             if constexpr (SP2) {
;             PG8_LDB(B0, 0, 0); PG8_LDB(B1, 0, 1); PG8_SCHED; PG8_LDA(At, 0, 0); PG8_STAGE(PG8_SA(1, 1), a1 + hstepA, voffA);
;             PG8_WAIT_V(8); PG8_WAIT_L(0); PG8_BAR; PG8_MMA(0, 0, At, B0); PG8_MMA(0, 1, At, B1); PG8_BAR; PG8_SCHED;
;             PG8_LDA(At, 0, 1); PG8_STAGE(PG8_SB(0, 0), b2, voffB); PG8_STAGE(PG8_SB(0, 1), b2 + hstepB, voffB); PG8_STAGE(PG8_SA(0, 0), a2, voffA);
;             PG8_WAIT_V(8); PG8_WAIT_L(0); PG8_BAR; PG8_MMA(1, 0, At, B0); PG8_MMA(1, 1, At, B1); PG8_BAR; PG8_SCHED;
.LBB0_1907:
	ds_read_b128 v[152:155], v148
	ds_read_b128 v[156:159], v148 offset:1024
	ds_read_b128 v[160:163], v148 offset:2048
	ds_read_b128 v[164:167], v148 offset:3072
	ds_read_b128 v[168:171], v149
	ds_read_b128 v[172:175], v149 offset:1024
	ds_read_b128 v[176:179], v149 offset:2048
	ds_read_b128 v[180:183], v149 offset:3072
	s_add_u32 s34, s55, s30
	s_addc_u32 s35, s56, s31
	s_add_u32 s38, s34, 0x10000
	s_addc_u32 s39, s35, 0
	s_add_i32 s58, s58, 2
	s_add_u32 s36, s53, s30
	s_addc_u32 s37, s54, s31
	s_add_u32 s34, s34, 0x18000
	s_addc_u32 s35, s35, 0
	s_cmp_eq_u32 s57, s30
	s_cselect_b32 s35, s52, s35
	s_cselect_b32 s34, s51, s34
	s_cselect_b32 s37, s4, s37
	s_cselect_b32 s36, s5, s36
	s_cselect_b32 s39, s50, s39
	s_cselect_b32 s38, s27, s38
	v_lshl_add_u64 v[216:217], v[142:143], 0, s[30:31]
	s_add_i32 m0, s41, 0xc000
	ds_read_b128 v[184:187], v150
	ds_read_b128 v[188:191], v150 offset:1024
	ds_read_b128 v[192:195], v150 offset:2048
	ds_read_b128 v[196:199], v150 offset:3072
	ds_read_b128 v[200:203], v150 offset:4096
	ds_read_b128 v[204:207], v150 offset:5120
	ds_read_b128 v[208:211], v150 offset:6144
	ds_read_b128 v[212:215], v150 offset:7168
	global_load_lds_dwordx4 v[216:217], off
	v_lshl_add_u64 v[216:217], v[144:145], 0, s[30:31]
	s_add_i32 m0, s41, 0xe000
	s_nop 0
	global_load_lds_dwordx4 v[216:217], off
	s_waitcnt vmcnt(8)
	s_waitcnt lgkmcnt(0)
	s_barrier
	s_setprio 1
	s_waitcnt lgkmcnt(0)
	v_mfma_f32_16x16x32_bf16 v[126:129], v[152:155], v[184:187], v[126:129]
	v_mfma_f32_16x16x32_bf16 v[122:125], v[160:163], v[184:187], v[122:125]
	v_mfma_f32_16x16x32_bf16 v[110:113], v[152:155], v[192:195], v[110:113]
	v_mfma_f32_16x16x32_bf16 v[106:109], v[160:163], v[192:195], v[106:109]
	v_mfma_f32_16x16x32_bf16 v[94:97], v[152:155], v[200:203], v[94:97]
	v_mfma_f32_16x16x32_bf16 v[90:93], v[160:163], v[200:203], v[90:93]
	v_mfma_f32_16x16x32_bf16 v[78:81], v[152:155], v[208:211], v[78:81]
	v_mfma_f32_16x16x32_bf16 v[74:77], v[160:163], v[208:211], v[74:77]
	v_mfma_f32_16x16x32_bf16 v[126:129], v[156:159], v[188:191], v[126:129]
	v_mfma_f32_16x16x32_bf16 v[122:125], v[164:167], v[188:191], v[122:125]
	v_mfma_f32_16x16x32_bf16 v[110:113], v[156:159], v[196:199], v[110:113]
	v_mfma_f32_16x16x32_bf16 v[106:109], v[164:167], v[196:199], v[106:109]
	v_mfma_f32_16x16x32_bf16 v[94:97], v[156:159], v[204:207], v[94:97]
	v_mfma_f32_16x16x32_bf16 v[90:93], v[164:167], v[204:207], v[90:93]
	v_mfma_f32_16x16x32_bf16 v[78:81], v[156:159], v[212:215], v[78:81]
	v_mfma_f32_16x16x32_bf16 v[74:77], v[164:167], v[212:215], v[74:77]
	s_setprio 0
	s_setprio 1
	v_mfma_f32_16x16x32_bf16 v[118:121], v[168:171], v[184:187], v[118:121]
	v_mfma_f32_16x16x32_bf16 v[114:117], v[176:179], v[184:187], v[114:117]
	v_mfma_f32_16x16x32_bf16 v[102:105], v[168:171], v[192:195], v[102:105]
	v_mfma_f32_16x16x32_bf16 v[98:101], v[176:179], v[192:195], v[98:101]
	v_mfma_f32_16x16x32_bf16 v[86:89], v[168:171], v[200:203], v[86:89]
	v_mfma_f32_16x16x32_bf16 v[82:85], v[176:179], v[200:203], v[82:85]
	v_mfma_f32_16x16x32_bf16 v[70:73], v[168:171], v[208:211], v[70:73]
	v_mfma_f32_16x16x32_bf16 v[66:69], v[176:179], v[208:211], v[66:69]
	v_mfma_f32_16x16x32_bf16 v[118:121], v[172:175], v[188:191], v[118:121]
	v_mfma_f32_16x16x32_bf16 v[114:117], v[180:183], v[188:191], v[114:117]
	v_mfma_f32_16x16x32_bf16 v[102:105], v[172:175], v[196:199], v[102:105]
	v_mfma_f32_16x16x32_bf16 v[98:101], v[180:183], v[196:199], v[98:101]
	v_mfma_f32_16x16x32_bf16 v[86:89], v[172:175], v[204:207], v[86:89]
	v_mfma_f32_16x16x32_bf16 v[82:85], v[180:183], v[204:207], v[82:85]
	v_mfma_f32_16x16x32_bf16 v[70:73], v[172:175], v[212:215], v[70:73]
	v_mfma_f32_16x16x32_bf16 v[66:69], v[180:183], v[212:215], v[66:69]
	s_setprio 0
	s_barrier
	s_add_i32 s59, s72, s40
	s_mov_b32 m0, s59
	ds_read_b128 v[184:187], v150 offset:16384
	ds_read_b128 v[188:191], v150 offset:17408
	ds_read_b128 v[192:195], v150 offset:18432
	ds_read_b128 v[196:199], v150 offset:19456
	ds_read_b128 v[200:203], v150 offset:20480
	ds_read_b128 v[204:207], v150 offset:21504
	ds_read_b128 v[208:211], v150 offset:22528
	ds_read_b128 v[212:215], v150 offset:23552
	global_load_lds_dwordx4 v130, s[36:37]
	s_add_i32 m0, s59, 0x2000
	s_add_u32 s64, s36, 0x4000
	s_addc_u32 s65, s37, 0
	s_add_i32 s59, s73, s40
	global_load_lds_dwordx4 v132, s[36:37]
	s_mov_b32 m0, s59
	s_nop 0
	global_load_lds_dwordx4 v130, s[64:65]
	s_add_i32 m0, s59, 0x2000
	s_nop 0
	global_load_lds_dwordx4 v132, s[64:65]
	s_mov_b32 m0, s41
	s_nop 0
	global_load_lds_dwordx4 v130, s[38:39]
	s_mov_b32 m0, s42
	s_nop 0
	global_load_lds_dwordx4 v132, s[38:39]
	s_waitcnt vmcnt(8)
	s_waitcnt lgkmcnt(0)
	s_barrier
; #define PG8_STAGE(bufoff, gbase, voff) do { _Pragma("unroll") for (int _i = 0; _i < 2; ++_i) \
;         __builtin_amdgcn_global_load_lds((const unsigned*)((const char*)(gbase) + (voff)[_i]), (LAS unsigned*)(lds + (bufoff) + ldsw + _i * 8192), 16, 0, 0); } while (0)
; #define PG8_LDA(dst, b, h) do { _Pragma("unroll") for (int m = 0; m < 4; ++m) _Pragma("unroll") for (int k = 0; k < 2; ++k) dst[m][k] = *(const LAS bf16x8*)(lds + PG8_SA(b, h) + aoff + m * 2048 + k * 1024); } while (0)
; #define PG8_LDB(dst, b, h) do { _Pragma("unroll") for (int n = 0; n < 2; ++n) _Pragma("unroll") for (int k = 0; k < 2; ++k) dst[n][k] = *(const LAS bf16x8*)(lds + PG8_SB(b, h) + boff + n * 2048 + k * 1024); } while (0)
; #define PG8_MMA(ai, bj, At, Bt) do { __builtin_amdgcn_s_setprio(1); _Pragma("unroll") for (int m = 0; m < 4; ++m) _Pragma("unroll") for (int n = 0; n < 2; ++n) _Pragma("unroll") for (int k = 0; k < 2; ++k) \
;         acc[ai][bj][m][n] = __builtin_amdgcn_mfma_f32_16x16x32_bf16(Bt[n][k], At[m][k], acc[ai][bj][m][n], 0, 0, 0); __builtin_amdgcn_s_setprio(0); } while (0)
; #define PG8_WAIT_V(n) asm volatile("s_waitcnt vmcnt(" #n ")" ::: "memory")
; #define PG8_WAIT_L(n) asm volatile("s_waitcnt lgkmcnt(" #n ")" ::: "memory")
; #define PG8_BAR __builtin_amdgcn_s_barrier()
; #define PG8_SCHED __builtin_amdgcn_sched_barrier(0)
; template <class Epi, class Sched, bool ABLK = false, bool ALIGN_EPI = true, bool SP2 = true, bool BBLK = true>
; __device__ __forceinline__ void gemm_phase(LAS unsigned char* lds, const Gemm g, const Sched& S, const Epi& E) {
;     ...
;             PG8_WAIT_V(8); PG8_WAIT_L(0); PG8_BAR; PG8_MMA(1, 0, At, B0); PG8_MMA(1, 1, At, B1); PG8_BAR; PG8_SCHED;
;             PG8_LDB(B0, 1, 0); PG8_LDB(B1, 1, 1); PG8_SCHED; PG8_LDA(At, 1, 0); PG8_STAGE(PG8_SA(0, 1), a2 + hstepA, voffA);
;             PG8_WAIT_V(8); PG8_WAIT_L(0); PG8_BAR; PG8_MMA(0, 0, At, B0); PG8_MMA(0, 1, At, B1); PG8_BAR; PG8_SCHED;
	s_setprio 1
	s_waitcnt lgkmcnt(0)
	v_mfma_f32_16x16x32_bf16 v[62:65], v[152:155], v[184:187], v[62:65]
	v_mfma_f32_16x16x32_bf16 v[58:61], v[160:163], v[184:187], v[58:61]
	v_mfma_f32_16x16x32_bf16 v[46:49], v[152:155], v[192:195], v[46:49]
	v_mfma_f32_16x16x32_bf16 v[42:45], v[160:163], v[192:195], v[42:45]
	v_mfma_f32_16x16x32_bf16 v[30:33], v[152:155], v[200:203], v[30:33]
	v_mfma_f32_16x16x32_bf16 v[26:29], v[160:163], v[200:203], v[26:29]
	v_mfma_f32_16x16x32_bf16 v[14:17], v[152:155], v[208:211], v[14:17]
	v_mfma_f32_16x16x32_bf16 v[10:13], v[160:163], v[208:211], v[10:13]
	v_mfma_f32_16x16x32_bf16 v[62:65], v[156:159], v[188:191], v[62:65]
	v_mfma_f32_16x16x32_bf16 v[58:61], v[164:167], v[188:191], v[58:61]
	v_mfma_f32_16x16x32_bf16 v[46:49], v[156:159], v[196:199], v[46:49]
	v_mfma_f32_16x16x32_bf16 v[42:45], v[164:167], v[196:199], v[42:45]
	v_mfma_f32_16x16x32_bf16 v[30:33], v[156:159], v[204:207], v[30:33]
	v_mfma_f32_16x16x32_bf16 v[26:29], v[164:167], v[204:207], v[26:29]
	v_mfma_f32_16x16x32_bf16 v[14:17], v[156:159], v[212:215], v[14:17]
	v_mfma_f32_16x16x32_bf16 v[10:13], v[164:167], v[212:215], v[10:13]
	s_setprio 0
	s_setprio 1
	v_mfma_f32_16x16x32_bf16 v[54:57], v[168:171], v[184:187], v[54:57]
	v_mfma_f32_16x16x32_bf16 v[50:53], v[176:179], v[184:187], v[50:53]
	v_mfma_f32_16x16x32_bf16 v[38:41], v[168:171], v[192:195], v[38:41]
	v_mfma_f32_16x16x32_bf16 v[34:37], v[176:179], v[192:195], v[34:37]
	v_mfma_f32_16x16x32_bf16 v[22:25], v[168:171], v[200:203], v[22:25]
	v_mfma_f32_16x16x32_bf16 v[18:21], v[176:179], v[200:203], v[18:21]
	v_mfma_f32_16x16x32_bf16 v[6:9], v[168:171], v[208:211], v[6:9]
	v_mfma_f32_16x16x32_bf16 v[2:5], v[176:179], v[208:211], v[2:5]
	v_mfma_f32_16x16x32_bf16 v[54:57], v[172:175], v[188:191], v[54:57]
	v_mfma_f32_16x16x32_bf16 v[50:53], v[180:183], v[188:191], v[50:53]
	v_mfma_f32_16x16x32_bf16 v[38:41], v[172:175], v[196:199], v[38:41]
	v_mfma_f32_16x16x32_bf16 v[34:37], v[180:183], v[196:199], v[34:37]
	v_mfma_f32_16x16x32_bf16 v[22:25], v[172:175], v[204:207], v[22:25]
	v_mfma_f32_16x16x32_bf16 v[18:21], v[180:183], v[204:207], v[18:21]
	v_mfma_f32_16x16x32_bf16 v[6:9], v[172:175], v[212:215], v[6:9]
	v_mfma_f32_16x16x32_bf16 v[2:5], v[180:183], v[212:215], v[2:5]
	s_setprio 0
	s_barrier
	v_add_u32_e32 v151, s60, v146
	ds_read_b128 v[152:155], v151
	ds_read_b128 v[156:159], v151 offset:1024
	ds_read_b128 v[160:163], v151 offset:2048
	ds_read_b128 v[164:167], v151 offset:3072
	v_add_u32_e32 v151, s61, v146
	ds_read_b128 v[168:171], v151
	ds_read_b128 v[172:175], v151 offset:1024
	ds_read_b128 v[176:179], v151 offset:2048
	ds_read_b128 v[180:183], v151 offset:3072
	s_add_u32 s38, s38, 0x4000
	s_addc_u32 s39, s39, 0
	s_mov_b32 m0, s43
	ds_read_b128 v[184:187], v150 offset:32768
	ds_read_b128 v[188:191], v150 offset:33792
	ds_read_b128 v[192:195], v150 offset:34816
	ds_read_b128 v[196:199], v150 offset:35840
	ds_read_b128 v[200:203], v150 offset:36864
	ds_read_b128 v[204:207], v150 offset:37888
	ds_read_b128 v[208:211], v150 offset:38912
	ds_read_b128 v[212:215], v150 offset:39936
	global_load_lds_dwordx4 v130, s[38:39]
	s_mov_b32 m0, s44
	s_nop 0
	global_load_lds_dwordx4 v132, s[38:39]
	s_waitcnt vmcnt(8)
	s_waitcnt lgkmcnt(0)
	s_barrier
	s_setprio 1
	s_waitcnt lgkmcnt(0)
	v_mfma_f32_16x16x32_bf16 v[126:129], v[152:155], v[184:187], v[126:129]
	v_mfma_f32_16x16x32_bf16 v[122:125], v[160:163], v[184:187], v[122:125]
	v_mfma_f32_16x16x32_bf16 v[110:113], v[152:155], v[192:195], v[110:113]
	v_mfma_f32_16x16x32_bf16 v[106:109], v[160:163], v[192:195], v[106:109]
	v_mfma_f32_16x16x32_bf16 v[94:97], v[152:155], v[200:203], v[94:97]
	v_mfma_f32_16x16x32_bf16 v[90:93], v[160:163], v[200:203], v[90:93]
	v_mfma_f32_16x16x32_bf16 v[78:81], v[152:155], v[208:211], v[78:81]
	v_mfma_f32_16x16x32_bf16 v[74:77], v[160:163], v[208:211], v[74:77]
	v_mfma_f32_16x16x32_bf16 v[126:129], v[156:159], v[188:191], v[126:129]
	v_mfma_f32_16x16x32_bf16 v[122:125], v[164:167], v[188:191], v[122:125]
	v_mfma_f32_16x16x32_bf16 v[110:113], v[156:159], v[196:199], v[110:113]
	v_mfma_f32_16x16x32_bf16 v[106:109], v[164:167], v[196:199], v[106:109]
	v_mfma_f32_16x16x32_bf16 v[94:97], v[156:159], v[204:207], v[94:97]
	v_mfma_f32_16x16x32_bf16 v[90:93], v[164:167], v[204:207], v[90:93]
	v_mfma_f32_16x16x32_bf16 v[78:81], v[156:159], v[212:215], v[78:81]
	v_mfma_f32_16x16x32_bf16 v[74:77], v[164:167], v[212:215], v[74:77]
	s_setprio 0
	s_setprio 1
	v_mfma_f32_16x16x32_bf16 v[118:121], v[168:171], v[184:187], v[118:121]
	v_mfma_f32_16x16x32_bf16 v[114:117], v[176:179], v[184:187], v[114:117]
	v_mfma_f32_16x16x32_bf16 v[102:105], v[168:171], v[192:195], v[102:105]
	v_mfma_f32_16x16x32_bf16 v[98:101], v[176:179], v[192:195], v[98:101]
	v_mfma_f32_16x16x32_bf16 v[86:89], v[168:171], v[200:203], v[86:89]
	v_mfma_f32_16x16x32_bf16 v[82:85], v[176:179], v[200:203], v[82:85]
	v_mfma_f32_16x16x32_bf16 v[70:73], v[168:171], v[208:211], v[70:73]
	v_mfma_f32_16x16x32_bf16 v[66:69], v[176:179], v[208:211], v[66:69]
	v_mfma_f32_16x16x32_bf16 v[118:121], v[172:175], v[188:191], v[118:121]
	v_mfma_f32_16x16x32_bf16 v[114:117], v[180:183], v[188:191], v[114:117]
	v_mfma_f32_16x16x32_bf16 v[102:105], v[172:175], v[196:199], v[102:105]
	v_mfma_f32_16x16x32_bf16 v[98:101], v[180:183], v[196:199], v[98:101]
	v_mfma_f32_16x16x32_bf16 v[86:89], v[172:175], v[204:207], v[86:89]
	v_mfma_f32_16x16x32_bf16 v[82:85], v[180:183], v[204:207], v[82:85]
	v_mfma_f32_16x16x32_bf16 v[70:73], v[172:175], v[212:215], v[70:73]
	v_mfma_f32_16x16x32_bf16 v[66:69], v[180:183], v[212:215], v[66:69]
	s_setprio 0
	s_barrier
; #define PG8_STAGE(bufoff, gbase, voff) do { _Pragma("unroll") for (int _i = 0; _i < 2; ++_i) \
;         __builtin_amdgcn_global_load_lds((const unsigned*)((const char*)(gbase) + (voff)[_i]), (LAS unsigned*)(lds + (bufoff) + ldsw + _i * 8192), 16, 0, 0); } while (0)
; #define PG8_LDA(dst, b, h) do { _Pragma("unroll") for (int m = 0; m < 4; ++m) _Pragma("unroll") for (int k = 0; k < 2; ++k) dst[m][k] = *(const LAS bf16x8*)(lds + PG8_SA(b, h) + aoff + m * 2048 + k * 1024); } while (0)
; #define PG8_MMA(ai, bj, At, Bt) do { __builtin_amdgcn_s_setprio(1); _Pragma("unroll") for (int m = 0; m < 4; ++m) _Pragma("unroll") for (int n = 0; n < 2; ++n) _Pragma("unroll") for (int k = 0; k < 2; ++k) \
;         acc[ai][bj][m][n] = __builtin_amdgcn_mfma_f32_16x16x32_bf16(Bt[n][k], At[m][k], acc[ai][bj][m][n], 0, 0, 0); __builtin_amdgcn_s_setprio(0); } while (0)
; #define PG8_WAIT_V(n) asm volatile("s_waitcnt vmcnt(" #n ")" ::: "memory")
; #define PG8_WAIT_L(n) asm volatile("s_waitcnt lgkmcnt(" #n ")" ::: "memory")
; #define PG8_BAR __builtin_amdgcn_s_barrier()
; #define PG8_SCHED __builtin_amdgcn_sched_barrier(0)
; template <class Epi, class Sched, bool ABLK = false, bool ALIGN_EPI = true, bool SP2 = true, bool BBLK = true>
; __device__ __forceinline__ void gemm_phase(LAS unsigned char* lds, const Gemm g, const Sched& S, const Epi& E) {
;     ...
;         for (int t = 0; t < nt; t += 2) {
;     ...
;             PG8_LDA(At, 1, 1); PG8_STAGE(PG8_SB(1, 0), b3, voffB); PG8_STAGE(PG8_SB(1, 1), b3 + hstepB, voffB); PG8_STAGE(PG8_SA(1, 0), a3, voffA);
;             PG8_WAIT_V(8); PG8_WAIT_L(0); PG8_BAR; PG8_MMA(1, 0, At, B0); PG8_MMA(1, 1, At, B1); PG8_BAR; PG8_SCHED;
	s_add_u32 s38, s36, 0x8000
	s_addc_u32 s39, s37, 0
	s_add_i32 s59, s60, s40
	s_mov_b32 m0, s59
	ds_read_b128 v[184:187], v150 offset:49152
	ds_read_b128 v[188:191], v150 offset:50176
	ds_read_b128 v[192:195], v150 offset:51200
	ds_read_b128 v[196:199], v150 offset:52224
	ds_read_b128 v[200:203], v150 offset:53248
	ds_read_b128 v[204:207], v150 offset:54272
	ds_read_b128 v[208:211], v150 offset:55296
	ds_read_b128 v[212:215], v150 offset:56320
	global_load_lds_dwordx4 v130, s[38:39]
	s_add_i32 m0, s59, 0x2000
	s_add_u32 s36, s36, 0xc000
	v_lshl_add_u64 v[216:217], s[38:39], 0, v[132:133]
	s_addc_u32 s37, s37, 0
	s_add_i32 s38, s61, s40
	global_load_lds_dwordx4 v[216:217], off
	s_mov_b32 m0, s38
	s_nop 0
	global_load_lds_dwordx4 v130, s[36:37]
	s_add_i32 m0, s38, 0x2000
	s_nop 0
	global_load_lds_dwordx4 v132, s[36:37]
	s_mov_b32 m0, s45
	s_nop 0
	global_load_lds_dwordx4 v130, s[34:35]
	s_mov_b32 m0, s46
	s_nop 0
	global_load_lds_dwordx4 v132, s[34:35]
	s_waitcnt vmcnt(8)
	s_waitcnt lgkmcnt(0)
	s_barrier
	s_setprio 1
	s_waitcnt lgkmcnt(0)
	v_mfma_f32_16x16x32_bf16 v[62:65], v[152:155], v[184:187], v[62:65]
	v_mfma_f32_16x16x32_bf16 v[58:61], v[160:163], v[184:187], v[58:61]
	v_mfma_f32_16x16x32_bf16 v[46:49], v[152:155], v[192:195], v[46:49]
	v_mfma_f32_16x16x32_bf16 v[42:45], v[160:163], v[192:195], v[42:45]
	v_mfma_f32_16x16x32_bf16 v[30:33], v[152:155], v[200:203], v[30:33]
	v_mfma_f32_16x16x32_bf16 v[26:29], v[160:163], v[200:203], v[26:29]
	v_mfma_f32_16x16x32_bf16 v[14:17], v[152:155], v[208:211], v[14:17]
	v_mfma_f32_16x16x32_bf16 v[10:13], v[160:163], v[208:211], v[10:13]
	v_mfma_f32_16x16x32_bf16 v[62:65], v[156:159], v[188:191], v[62:65]
	v_mfma_f32_16x16x32_bf16 v[58:61], v[164:167], v[188:191], v[58:61]
	v_mfma_f32_16x16x32_bf16 v[46:49], v[156:159], v[196:199], v[46:49]
	v_mfma_f32_16x16x32_bf16 v[42:45], v[164:167], v[196:199], v[42:45]
	v_mfma_f32_16x16x32_bf16 v[30:33], v[156:159], v[204:207], v[30:33]
	v_mfma_f32_16x16x32_bf16 v[26:29], v[164:167], v[204:207], v[26:29]
	v_mfma_f32_16x16x32_bf16 v[14:17], v[156:159], v[212:215], v[14:17]
	v_mfma_f32_16x16x32_bf16 v[10:13], v[164:167], v[212:215], v[10:13]
	s_setprio 0
	s_setprio 1
	v_mfma_f32_16x16x32_bf16 v[54:57], v[168:171], v[184:187], v[54:57]
	v_mfma_f32_16x16x32_bf16 v[50:53], v[176:179], v[184:187], v[50:53]
	v_mfma_f32_16x16x32_bf16 v[38:41], v[168:171], v[192:195], v[38:41]
	v_mfma_f32_16x16x32_bf16 v[34:37], v[176:179], v[192:195], v[34:37]
	v_mfma_f32_16x16x32_bf16 v[22:25], v[168:171], v[200:203], v[22:25]
	v_mfma_f32_16x16x32_bf16 v[18:21], v[176:179], v[200:203], v[18:21]
	v_mfma_f32_16x16x32_bf16 v[6:9], v[168:171], v[208:211], v[6:9]
	v_mfma_f32_16x16x32_bf16 v[2:5], v[176:179], v[208:211], v[2:5]
	v_mfma_f32_16x16x32_bf16 v[54:57], v[172:175], v[188:191], v[54:57]
	v_mfma_f32_16x16x32_bf16 v[50:53], v[180:183], v[188:191], v[50:53]
	v_mfma_f32_16x16x32_bf16 v[38:41], v[172:175], v[196:199], v[38:41]
	v_mfma_f32_16x16x32_bf16 v[34:37], v[180:183], v[196:199], v[34:37]
	v_mfma_f32_16x16x32_bf16 v[22:25], v[172:175], v[204:207], v[22:25]
	v_mfma_f32_16x16x32_bf16 v[18:21], v[180:183], v[204:207], v[18:21]
	v_mfma_f32_16x16x32_bf16 v[6:9], v[172:175], v[212:215], v[6:9]
	v_mfma_f32_16x16x32_bf16 v[2:5], v[180:183], v[212:215], v[2:5]
	s_setprio 0
	s_barrier
	s_add_u32 s30, s30, 0x10000
	s_addc_u32 s31, s31, 0
	s_cmp_ge_u32 s58, s48
	s_cbranch_scc0 .LBB0_1907
	s_and_b64 vcc, exec, s[6:7]
	s_cbranch_vccz .LBB0_1910
	s_barrier

; #define PG8_STAGE(bufoff, gbase, voff) do { _Pragma("unroll") for (int _i = 0; _i < 2; ++_i) \
;         __builtin_amdgcn_global_load_lds((const unsigned*)((const char*)(gbase) + (voff)[_i]), (LAS unsigned*)(lds + (bufoff) + ldsw + _i * 8192), 16, 0, 0); } while (0)
; #define PG8_WAIT_V(n) asm volatile("s_waitcnt vmcnt(" #n ")" ::: "memory")
; #define PG8_BAR __builtin_amdgcn_s_barrier()
; template <class Epi, class Sched, bool ABLK = false, bool ALIGN_EPI = true, bool SP2 = true, bool BBLK = true>
; __device__ __forceinline__ void gemm_phase(LAS unsigned char* lds, const Gemm g, const Sched& S, const Epi& E) {
;     ...
;     const unsigned ldsw = (unsigned)wid * 1024u;
;     const int aoff = lds_byte(wr * 64 + fr, fq * 8), boff = lds_byte(wc * 32 + fr, fq * 8);
;     ...
;     if constexpr (SP2) {
;         PG8_STAGE(PG8_SB(0, 0), cB, voffB); PG8_STAGE(PG8_SB(0, 1), cB + hstepB, voffB); PG8_STAGE(PG8_SA(0, 0), cA, voffA); PG8_STAGE(PG8_SA(0, 1), cA + hstepA, voffA);
;         if (wr == 1) PG8_BAR;
;         PG8_WAIT_V(2); PG8_BAR;
;         PG8_STAGE(PG8_SB(1, 0), cB + kstepB, voffB); PG8_STAGE(PG8_SA(1, 0), a_tile(uA, tbA + 1), voffA); PG8_STAGE(PG8_SB(1, 1), cB + hstepB + kstepB, voffB);
;         PG8_WAIT_V(6); PG8_BAR;
.LBB0_2132:
	s_lshl_b32 s6, s6, 5
	s_and_b32 s11, s6, 0x60
	s_lshl_b32 s10, s5, 13
	s_lshl_b32 s12, s11, 7
	s_add_u32 s6, s26, 0x8000
	s_addc_u32 s7, s27, 0
	s_add_i32 m0, s21, 0x18000
	v_lshl_add_u64 v[14:15], s[6:7], 0, v[134:135]
	s_waitcnt vmcnt(2)
	s_barrier
	global_load_lds_dwordx4 v[14:15], off
	v_lshl_add_u64 v[14:15], s[6:7], 0, v[130:131]
	s_add_i32 m0, s21, 0x1a000
	s_mov_b64 s[6:7], 0x80
	s_add_i32 s42, s21, 0x8000
	global_load_lds_dwordx4 v[14:15], off
	v_lshl_add_u64 v[2:3], v[2:3], 0, s[6:7]
	s_mov_b32 m0, s42
	s_add_i32 s43, s21, 0xa000
	global_load_lds_dwordx4 v[2:3], off
	v_lshl_add_u64 v[2:3], v[4:5], 0, s[6:7]
	s_add_u32 s6, s26, 0xc000
	s_mov_b32 m0, s43
	s_addc_u32 s7, s27, 0
	global_load_lds_dwordx4 v[2:3], off
	s_add_i32 m0, s21, 0x1c000
	s_nop 0
	global_load_lds_dwordx4 v134, s[6:7]
	s_add_i32 m0, s21, 0x1e000
	s_cmpk_lt_u32 s4, 0x100
	global_load_lds_dwordx4 v130, s[6:7]
	v_lshrrev_b32_e32 v3, 1, v6
	v_and_b32_e32 v3, 24, v3
	v_and_b32_e32 v2, 15, v6
	v_lshlrev_b32_e32 v4, 1, v3
	v_lshl_or_b32 v1, s5, 6, v2
	v_lshl_or_b32 v2, v2, 6, v4
	v_lshlrev_b32_e32 v4, 2, v6
	v_and_b32_e32 v4, 32, v4
	v_bitop3_b32 v5, v2, s10, v4 bitop3:0xde
	v_bitop3_b32 v146, v2, s12, v4 bitop3:0xde
	v_lshlrev_b32_e32 v2, 15, v10
	v_and_b32_e32 v2, 0xffff0000, v2
	v_or_b32_e32 v147, s11, v3
	v_lshl_add_u32 v2, v11, 12, v2
	v_and_b32_e32 v3, 1, v10
	v_lshl_or_b32 v2, v3, 6, v2
	v_lshl_add_u32 v2, v12, 1, v2
	v_mov_b32_e32 v3, v135
	s_mov_b64 s[4:5], 0x80080
	v_lshl_add_u64 v[138:139], v[2:3], 0, s[4:5]
	v_lshlrev_b32_e32 v2, 15, v7
	v_and_b32_e32 v2, 0xffff0000, v2
	v_lshl_add_u32 v2, v8, 12, v2
	v_and_b32_e32 v3, 1, v7
	s_waitcnt vmcnt(6)
	v_lshl_or_b32 v2, v3, 6, v2
	v_lshl_add_u32 v2, v9, 1, v2
	v_mov_b32_e32 v3, v135
	s_cselect_b64 s[6:7], -1, 0
	v_lshl_add_u64 v[140:141], v[2:3], 0, s[4:5]
	v_add_u32_e32 v148, s72, v146
	v_add_u32_e32 v149, s73, v146
	v_add_u32_e32 v150, 0, v5
	s_mov_b32 s44, 0x80000
	s_mov_b32 s45, 0x90000
	s_mov_b32 s46, 0xa0000
	s_add_i32 s47, s21, 0xc000
	s_barrier
	s_waitcnt vmcnt(0)
	s_branch .LBB0_2135

; #define PG8_STAGE(bufoff, gbase, voff) do { _Pragma("unroll") for (int _i = 0; _i < 2; ++_i) \
;         __builtin_amdgcn_global_load_lds((const unsigned*)((const char*)(gbase) + (voff)[_i]), (LAS unsigned*)(lds + (bufoff) + ldsw + _i * 8192), 16, 0, 0); } while (0)
; #define PG8_LDA(dst, b, h) do { _Pragma("unroll") for (int m = 0; m < 4; ++m) _Pragma("unroll") for (int k = 0; k < 2; ++k) dst[m][k] = *(const LAS bf16x8*)(lds + PG8_SA(b, h) + aoff + m * 2048 + k * 1024); } while (0)
; #define PG8_LDB(dst, b, h) do { _Pragma("unroll") for (int n = 0; n < 2; ++n) _Pragma("unroll") for (int k = 0; k < 2; ++k) dst[n][k] = *(const LAS bf16x8*)(lds + PG8_SB(b, h) + boff + n * 2048 + k * 1024); } while (0)
; #define PG8_MMA(ai, bj, At, Bt) do { __builtin_amdgcn_s_setprio(1); _Pragma("unroll") for (int m = 0; m < 4; ++m) _Pragma("unroll") for (int n = 0; n < 2; ++n) _Pragma("unroll") for (int k = 0; k < 2; ++k) \
;         acc[ai][bj][m][n] = __builtin_amdgcn_mfma_f32_16x16x32_bf16(Bt[n][k], At[m][k], acc[ai][bj][m][n], 0, 0, 0); __builtin_amdgcn_s_setprio(0); } while (0)
; #define PG8_WAIT_V(n) asm volatile("s_waitcnt vmcnt(" #n ")" ::: "memory")
; template <class Epi, class Sched, bool ABLK = false, bool ALIGN_EPI = true, bool SP2 = true, bool BBLK = true>
; __device__ __forceinline__ void gemm_phase(LAS unsigned char* lds, const Gemm g, const Sched& S, const Epi& E) {
;     ...
;         for (int t = 0; t < nt; t += 2) {
;             const bool last = (t == nt - 2);
;             const char* a1 = a_tile(uA, tbA + t + 1);
;             const char* a2 = last ? a_tile(nuA, ntbA) : a_tile(uA, tbA + t + 2); const char* b2 = last ? nB : cB + (size_t)(t + 2) * kstepB;
;             const char* a3 = last ? a_tile(nuA, ntbA + 1) : a_tile(uA, tbA + t + 3); const char* b3 = b2 + kstepB;
;             if (last && has_next) S.a_ready(nxt);
;             if constexpr (SP2) {
;             PG8_LDB(B0, 0, 0); PG8_LDB(B1, 0, 1); PG8_SCHED; PG8_LDA(At, 0, 0); PG8_STAGE(PG8_SA(1, 1), a1 + hstepA, voffA);
;             PG8_WAIT_V(8); PG8_WAIT_L(0); PG8_BAR; PG8_MMA(0, 0, At, B0); PG8_MMA(0, 1, At, B1); PG8_BAR; PG8_SCHED;
;             PG8_LDA(At, 0, 1); PG8_STAGE(PG8_SB(0, 0), b2, voffB); PG8_STAGE(PG8_SB(0, 1), b2 + hstepB, voffB); PG8_STAGE(PG8_SA(0, 0), a2, voffA);
;             PG8_WAIT_V(8); PG8_WAIT_L(0); PG8_BAR; PG8_MMA(1, 0, At, B0); PG8_MMA(1, 1, At, B1); PG8_BAR; PG8_SCHED;
.LBB0_2138:
	ds_read_b128 v[152:155], v148
	ds_read_b128 v[156:159], v148 offset:1024
	ds_read_b128 v[160:163], v148 offset:2048
	ds_read_b128 v[164:167], v148 offset:3072
	ds_read_b128 v[168:171], v149
	ds_read_b128 v[172:175], v149 offset:1024
	ds_read_b128 v[176:179], v149 offset:2048
	ds_read_b128 v[180:183], v149 offset:3072
	s_add_u32 s28, s24, s26
	s_addc_u32 s29, s25, s27
	s_add_u32 s34, s28, 0x100
	s_addc_u32 s35, s29, 0
	s_add_u32 s28, s28, 0x180
	s_addc_u32 s29, s29, 0
	s_cmpk_eq_i32 s26, 0xf00
	s_cselect_b32 s29, s49, s29
	s_cselect_b32 s28, s48, s28
	s_cselect_b32 s31, s11, s51
	s_cselect_b32 s30, s13, s50
	s_cselect_b32 s35, s4, s35
	s_cselect_b32 s34, s5, s34
	s_mov_b32 m0, s47
	v_lshl_add_u64 v[216:217], v[142:143], 0, s[26:27]
	ds_read_b128 v[184:187], v150
	ds_read_b128 v[188:191], v150 offset:1024
	ds_read_b128 v[192:195], v150 offset:2048
	ds_read_b128 v[196:199], v150 offset:3072
	ds_read_b128 v[200:203], v150 offset:4096
	ds_read_b128 v[204:207], v150 offset:5120
	ds_read_b128 v[208:211], v150 offset:6144
	ds_read_b128 v[212:215], v150 offset:7168
	global_load_lds_dwordx4 v[216:217], off
	v_lshl_add_u64 v[216:217], v[144:145], 0, s[26:27]
	s_add_i32 m0, s21, 0xe000
	s_nop 0
	global_load_lds_dwordx4 v[216:217], off
	s_waitcnt vmcnt(8)
	s_waitcnt lgkmcnt(0)
	s_barrier
	s_setprio 1
	s_waitcnt lgkmcnt(0)
	v_mfma_f32_16x16x32_bf16 v[122:125], v[152:155], v[184:187], v[122:125]
	v_mfma_f32_16x16x32_bf16 v[118:121], v[160:163], v[184:187], v[118:121]
	v_mfma_f32_16x16x32_bf16 v[106:109], v[152:155], v[192:195], v[106:109]
	v_mfma_f32_16x16x32_bf16 v[102:105], v[160:163], v[192:195], v[102:105]
	v_mfma_f32_16x16x32_bf16 v[90:93], v[152:155], v[200:203], v[90:93]
	v_mfma_f32_16x16x32_bf16 v[86:89], v[160:163], v[200:203], v[86:89]
	v_mfma_f32_16x16x32_bf16 v[74:77], v[152:155], v[208:211], v[74:77]
	v_mfma_f32_16x16x32_bf16 v[70:73], v[160:163], v[208:211], v[70:73]
	v_mfma_f32_16x16x32_bf16 v[122:125], v[156:159], v[188:191], v[122:125]
	v_mfma_f32_16x16x32_bf16 v[118:121], v[164:167], v[188:191], v[118:121]
	v_mfma_f32_16x16x32_bf16 v[106:109], v[156:159], v[196:199], v[106:109]
	v_mfma_f32_16x16x32_bf16 v[102:105], v[164:167], v[196:199], v[102:105]
	v_mfma_f32_16x16x32_bf16 v[90:93], v[156:159], v[204:207], v[90:93]
	v_mfma_f32_16x16x32_bf16 v[86:89], v[164:167], v[204:207], v[86:89]
	v_mfma_f32_16x16x32_bf16 v[74:77], v[156:159], v[212:215], v[74:77]
	v_mfma_f32_16x16x32_bf16 v[70:73], v[164:167], v[212:215], v[70:73]
	s_setprio 0
	s_setprio 1
	v_mfma_f32_16x16x32_bf16 v[126:129], v[168:171], v[184:187], v[126:129]
	v_mfma_f32_16x16x32_bf16 v[114:117], v[176:179], v[184:187], v[114:117]
	v_mfma_f32_16x16x32_bf16 v[110:113], v[168:171], v[192:195], v[110:113]
	v_mfma_f32_16x16x32_bf16 v[98:101], v[176:179], v[192:195], v[98:101]
	v_mfma_f32_16x16x32_bf16 v[94:97], v[168:171], v[200:203], v[94:97]
	v_mfma_f32_16x16x32_bf16 v[82:85], v[176:179], v[200:203], v[82:85]
	v_mfma_f32_16x16x32_bf16 v[78:81], v[168:171], v[208:211], v[78:81]
	v_mfma_f32_16x16x32_bf16 v[66:69], v[176:179], v[208:211], v[66:69]
	v_mfma_f32_16x16x32_bf16 v[126:129], v[172:175], v[188:191], v[126:129]
	v_mfma_f32_16x16x32_bf16 v[114:117], v[180:183], v[188:191], v[114:117]
	v_mfma_f32_16x16x32_bf16 v[110:113], v[172:175], v[196:199], v[110:113]
	v_mfma_f32_16x16x32_bf16 v[98:101], v[180:183], v[196:199], v[98:101]
	v_mfma_f32_16x16x32_bf16 v[94:97], v[172:175], v[204:207], v[94:97]
	v_mfma_f32_16x16x32_bf16 v[82:85], v[180:183], v[204:207], v[82:85]
	v_mfma_f32_16x16x32_bf16 v[78:81], v[172:175], v[212:215], v[78:81]
	v_mfma_f32_16x16x32_bf16 v[66:69], v[180:183], v[212:215], v[66:69]
	s_setprio 0
	s_barrier
	s_add_i32 s53, s72, s36
	s_mov_b32 m0, s53
	ds_read_b128 v[184:187], v150 offset:16384
	ds_read_b128 v[188:191], v150 offset:17408
	ds_read_b128 v[192:195], v150 offset:18432
	ds_read_b128 v[196:199], v150 offset:19456
	ds_read_b128 v[200:203], v150 offset:20480
	ds_read_b128 v[204:207], v150 offset:21504
	ds_read_b128 v[208:211], v150 offset:22528
	ds_read_b128 v[212:215], v150 offset:23552
	global_load_lds_dwordx4 v134, s[30:31]
	s_add_i32 m0, s53, 0x2000
	s_add_u32 s54, s30, 0x4000
	s_addc_u32 s55, s31, 0
	s_add_i32 s53, s73, s36
	global_load_lds_dwordx4 v130, s[30:31]
	s_mov_b32 m0, s53
	s_nop 0
	global_load_lds_dwordx4 v134, s[54:55]
	s_add_i32 m0, s53, 0x2000
	s_nop 0
	global_load_lds_dwordx4 v130, s[54:55]
	s_mov_b32 m0, s21
	s_nop 0
	global_load_lds_dwordx4 v136, s[34:35]
	s_mov_b32 m0, s23
	s_nop 0
	global_load_lds_dwordx4 v132, s[34:35]
	s_waitcnt vmcnt(8)
	s_waitcnt lgkmcnt(0)
	s_barrier
; #define PG8_STAGE(bufoff, gbase, voff) do { _Pragma("unroll") for (int _i = 0; _i < 2; ++_i) \
;         __builtin_amdgcn_global_load_lds((const unsigned*)((const char*)(gbase) + (voff)[_i]), (LAS unsigned*)(lds + (bufoff) + ldsw + _i * 8192), 16, 0, 0); } while (0)
; #define PG8_LDA(dst, b, h) do { _Pragma("unroll") for (int m = 0; m < 4; ++m) _Pragma("unroll") for (int k = 0; k < 2; ++k) dst[m][k] = *(const LAS bf16x8*)(lds + PG8_SA(b, h) + aoff + m * 2048 + k * 1024); } while (0)
; #define PG8_LDB(dst, b, h) do { _Pragma("unroll") for (int n = 0; n < 2; ++n) _Pragma("unroll") for (int k = 0; k < 2; ++k) dst[n][k] = *(const LAS bf16x8*)(lds + PG8_SB(b, h) + boff + n * 2048 + k * 1024); } while (0)
; #define PG8_MMA(ai, bj, At, Bt) do { __builtin_amdgcn_s_setprio(1); _Pragma("unroll") for (int m = 0; m < 4; ++m) _Pragma("unroll") for (int n = 0; n < 2; ++n) _Pragma("unroll") for (int k = 0; k < 2; ++k) \
;         acc[ai][bj][m][n] = __builtin_amdgcn_mfma_f32_16x16x32_bf16(Bt[n][k], At[m][k], acc[ai][bj][m][n], 0, 0, 0); __builtin_amdgcn_s_setprio(0); } while (0)
; #define PG8_WAIT_V(n) asm volatile("s_waitcnt vmcnt(" #n ")" ::: "memory")
; #define PG8_WAIT_L(n) asm volatile("s_waitcnt lgkmcnt(" #n ")" ::: "memory")
; #define PG8_BAR __builtin_amdgcn_s_barrier()
; #define PG8_SCHED __builtin_amdgcn_sched_barrier(0)
; template <class Epi, class Sched, bool ABLK = false, bool ALIGN_EPI = true, bool SP2 = true, bool BBLK = true>
; __device__ __forceinline__ void gemm_phase(LAS unsigned char* lds, const Gemm g, const Sched& S, const Epi& E) {
;     ...
;             PG8_WAIT_V(8); PG8_WAIT_L(0); PG8_BAR; PG8_MMA(1, 0, At, B0); PG8_MMA(1, 1, At, B1); PG8_BAR; PG8_SCHED;
;             PG8_LDB(B0, 1, 0); PG8_LDB(B1, 1, 1); PG8_SCHED; PG8_LDA(At, 1, 0); PG8_STAGE(PG8_SA(0, 1), a2 + hstepA, voffA);
;             PG8_WAIT_V(8); PG8_WAIT_L(0); PG8_BAR; PG8_MMA(0, 0, At, B0); PG8_MMA(0, 1, At, B1); PG8_BAR; PG8_SCHED;
	s_setprio 1
	s_waitcnt lgkmcnt(0)
	v_mfma_f32_16x16x32_bf16 v[58:61], v[152:155], v[184:187], v[58:61]
	v_mfma_f32_16x16x32_bf16 v[54:57], v[160:163], v[184:187], v[54:57]
	v_mfma_f32_16x16x32_bf16 v[42:45], v[152:155], v[192:195], v[42:45]
	v_mfma_f32_16x16x32_bf16 v[38:41], v[160:163], v[192:195], v[38:41]
	v_mfma_f32_16x16x32_bf16 v[26:29], v[152:155], v[200:203], v[26:29]
	v_mfma_f32_16x16x32_bf16 v[22:25], v[160:163], v[200:203], v[22:25]
	v_mfma_f32_16x16x32_bf16 v[10:13], v[152:155], v[208:211], v[10:13]
	v_mfma_f32_16x16x32_bf16 v[6:9], v[160:163], v[208:211], v[6:9]
	v_mfma_f32_16x16x32_bf16 v[58:61], v[156:159], v[188:191], v[58:61]
	v_mfma_f32_16x16x32_bf16 v[54:57], v[164:167], v[188:191], v[54:57]
	v_mfma_f32_16x16x32_bf16 v[42:45], v[156:159], v[196:199], v[42:45]
	v_mfma_f32_16x16x32_bf16 v[38:41], v[164:167], v[196:199], v[38:41]
	v_mfma_f32_16x16x32_bf16 v[26:29], v[156:159], v[204:207], v[26:29]
	v_mfma_f32_16x16x32_bf16 v[22:25], v[164:167], v[204:207], v[22:25]
	v_mfma_f32_16x16x32_bf16 v[10:13], v[156:159], v[212:215], v[10:13]
	v_mfma_f32_16x16x32_bf16 v[6:9], v[164:167], v[212:215], v[6:9]
	s_setprio 0
	s_setprio 1
	v_mfma_f32_16x16x32_bf16 v[62:65], v[168:171], v[184:187], v[62:65]
	v_mfma_f32_16x16x32_bf16 v[50:53], v[176:179], v[184:187], v[50:53]
	v_mfma_f32_16x16x32_bf16 v[46:49], v[168:171], v[192:195], v[46:49]
	v_mfma_f32_16x16x32_bf16 v[34:37], v[176:179], v[192:195], v[34:37]
	v_mfma_f32_16x16x32_bf16 v[30:33], v[168:171], v[200:203], v[30:33]
	v_mfma_f32_16x16x32_bf16 v[18:21], v[176:179], v[200:203], v[18:21]
	v_mfma_f32_16x16x32_bf16 v[14:17], v[168:171], v[208:211], v[14:17]
	v_mfma_f32_16x16x32_bf16 v[2:5], v[176:179], v[208:211], v[2:5]
	v_mfma_f32_16x16x32_bf16 v[62:65], v[172:175], v[188:191], v[62:65]
	v_mfma_f32_16x16x32_bf16 v[50:53], v[180:183], v[188:191], v[50:53]
	v_mfma_f32_16x16x32_bf16 v[46:49], v[172:175], v[196:199], v[46:49]
	v_mfma_f32_16x16x32_bf16 v[34:37], v[180:183], v[196:199], v[34:37]
	v_mfma_f32_16x16x32_bf16 v[30:33], v[172:175], v[204:207], v[30:33]
	v_mfma_f32_16x16x32_bf16 v[18:21], v[180:183], v[204:207], v[18:21]
	v_mfma_f32_16x16x32_bf16 v[14:17], v[172:175], v[212:215], v[14:17]
	v_mfma_f32_16x16x32_bf16 v[2:5], v[180:183], v[212:215], v[2:5]
	s_setprio 0
	s_barrier
	v_add_u32_e32 v151, s60, v146
	ds_read_b128 v[152:155], v151
	ds_read_b128 v[156:159], v151 offset:1024
	ds_read_b128 v[160:163], v151 offset:2048
	ds_read_b128 v[164:167], v151 offset:3072
	v_add_u32_e32 v151, s61, v146
	ds_read_b128 v[168:171], v151
	ds_read_b128 v[172:175], v151 offset:1024
	ds_read_b128 v[176:179], v151 offset:2048
	ds_read_b128 v[180:183], v151 offset:3072
	s_add_u32 s34, s34, 0x80000
	s_addc_u32 s35, s35, 0
	s_mov_b32 m0, s39
	ds_read_b128 v[184:187], v150 offset:32768
	ds_read_b128 v[188:191], v150 offset:33792
	ds_read_b128 v[192:195], v150 offset:34816
	ds_read_b128 v[196:199], v150 offset:35840
	ds_read_b128 v[200:203], v150 offset:36864
	ds_read_b128 v[204:207], v150 offset:37888
	ds_read_b128 v[208:211], v150 offset:38912
	ds_read_b128 v[212:215], v150 offset:39936
	global_load_lds_dwordx4 v136, s[34:35]
	s_mov_b32 m0, s40
	s_nop 0
	global_load_lds_dwordx4 v132, s[34:35]
	s_waitcnt vmcnt(8)
	s_waitcnt lgkmcnt(0)
	s_barrier
	s_setprio 1
	s_waitcnt lgkmcnt(0)
	v_mfma_f32_16x16x32_bf16 v[122:125], v[152:155], v[184:187], v[122:125]
	v_mfma_f32_16x16x32_bf16 v[118:121], v[160:163], v[184:187], v[118:121]
	v_mfma_f32_16x16x32_bf16 v[106:109], v[152:155], v[192:195], v[106:109]
	v_mfma_f32_16x16x32_bf16 v[102:105], v[160:163], v[192:195], v[102:105]
	v_mfma_f32_16x16x32_bf16 v[90:93], v[152:155], v[200:203], v[90:93]
	v_mfma_f32_16x16x32_bf16 v[86:89], v[160:163], v[200:203], v[86:89]
	v_mfma_f32_16x16x32_bf16 v[74:77], v[152:155], v[208:211], v[74:77]
	v_mfma_f32_16x16x32_bf16 v[70:73], v[160:163], v[208:211], v[70:73]
	v_mfma_f32_16x16x32_bf16 v[122:125], v[156:159], v[188:191], v[122:125]
	v_mfma_f32_16x16x32_bf16 v[118:121], v[164:167], v[188:191], v[118:121]
	v_mfma_f32_16x16x32_bf16 v[106:109], v[156:159], v[196:199], v[106:109]
	v_mfma_f32_16x16x32_bf16 v[102:105], v[164:167], v[196:199], v[102:105]
	v_mfma_f32_16x16x32_bf16 v[90:93], v[156:159], v[204:207], v[90:93]
	v_mfma_f32_16x16x32_bf16 v[86:89], v[164:167], v[204:207], v[86:89]
	v_mfma_f32_16x16x32_bf16 v[74:77], v[156:159], v[212:215], v[74:77]
	v_mfma_f32_16x16x32_bf16 v[70:73], v[164:167], v[212:215], v[70:73]
	s_setprio 0
	s_setprio 1
	v_mfma_f32_16x16x32_bf16 v[126:129], v[168:171], v[184:187], v[126:129]
	v_mfma_f32_16x16x32_bf16 v[114:117], v[176:179], v[184:187], v[114:117]
	v_mfma_f32_16x16x32_bf16 v[110:113], v[168:171], v[192:195], v[110:113]
	v_mfma_f32_16x16x32_bf16 v[98:101], v[176:179], v[192:195], v[98:101]
	v_mfma_f32_16x16x32_bf16 v[94:97], v[168:171], v[200:203], v[94:97]
	v_mfma_f32_16x16x32_bf16 v[82:85], v[176:179], v[200:203], v[82:85]
	v_mfma_f32_16x16x32_bf16 v[78:81], v[168:171], v[208:211], v[78:81]
	v_mfma_f32_16x16x32_bf16 v[66:69], v[176:179], v[208:211], v[66:69]
	v_mfma_f32_16x16x32_bf16 v[126:129], v[172:175], v[188:191], v[126:129]
	v_mfma_f32_16x16x32_bf16 v[114:117], v[180:183], v[188:191], v[114:117]
	v_mfma_f32_16x16x32_bf16 v[110:113], v[172:175], v[196:199], v[110:113]
	v_mfma_f32_16x16x32_bf16 v[98:101], v[180:183], v[196:199], v[98:101]
	v_mfma_f32_16x16x32_bf16 v[94:97], v[172:175], v[204:207], v[94:97]
	v_mfma_f32_16x16x32_bf16 v[82:85], v[180:183], v[204:207], v[82:85]
	v_mfma_f32_16x16x32_bf16 v[78:81], v[172:175], v[212:215], v[78:81]
	v_mfma_f32_16x16x32_bf16 v[66:69], v[180:183], v[212:215], v[66:69]
	s_setprio 0
	s_barrier
; #define PG8_STAGE(bufoff, gbase, voff) do { _Pragma("unroll") for (int _i = 0; _i < 2; ++_i) \
;         __builtin_amdgcn_global_load_lds((const unsigned*)((const char*)(gbase) + (voff)[_i]), (LAS unsigned*)(lds + (bufoff) + ldsw + _i * 8192), 16, 0, 0); } while (0)
; #define PG8_LDA(dst, b, h) do { _Pragma("unroll") for (int m = 0; m < 4; ++m) _Pragma("unroll") for (int k = 0; k < 2; ++k) dst[m][k] = *(const LAS bf16x8*)(lds + PG8_SA(b, h) + aoff + m * 2048 + k * 1024); } while (0)
; #define PG8_MMA(ai, bj, At, Bt) do { __builtin_amdgcn_s_setprio(1); _Pragma("unroll") for (int m = 0; m < 4; ++m) _Pragma("unroll") for (int n = 0; n < 2; ++n) _Pragma("unroll") for (int k = 0; k < 2; ++k) \
;         acc[ai][bj][m][n] = __builtin_amdgcn_mfma_f32_16x16x32_bf16(Bt[n][k], At[m][k], acc[ai][bj][m][n], 0, 0, 0); __builtin_amdgcn_s_setprio(0); } while (0)
; #define PG8_WAIT_V(n) asm volatile("s_waitcnt vmcnt(" #n ")" ::: "memory")
; #define PG8_WAIT_L(n) asm volatile("s_waitcnt lgkmcnt(" #n ")" ::: "memory")
; #define PG8_BAR __builtin_amdgcn_s_barrier()
; #define PG8_SCHED __builtin_amdgcn_sched_barrier(0)
; template <class Epi, class Sched, bool ABLK = false, bool ALIGN_EPI = true, bool SP2 = true, bool BBLK = true>
; __device__ __forceinline__ void gemm_phase(LAS unsigned char* lds, const Gemm g, const Sched& S, const Epi& E) {
;     ...
;         for (int t = 0; t < nt; t += 2) {
;     ...
;             PG8_LDA(At, 1, 1); PG8_STAGE(PG8_SB(1, 0), b3, voffB); PG8_STAGE(PG8_SB(1, 1), b3 + hstepB, voffB); PG8_STAGE(PG8_SA(1, 0), a3, voffA);
;             PG8_WAIT_V(8); PG8_WAIT_L(0); PG8_BAR; PG8_MMA(1, 0, At, B0); PG8_MMA(1, 1, At, B1); PG8_BAR; PG8_SCHED;
	s_add_u32 s34, s30, 0x8000
	s_addc_u32 s35, s31, 0
	s_add_i32 s53, s60, s36
	s_mov_b32 m0, s53
	ds_read_b128 v[184:187], v150 offset:49152
	ds_read_b128 v[188:191], v150 offset:50176
	ds_read_b128 v[192:195], v150 offset:51200
	ds_read_b128 v[196:199], v150 offset:52224
	ds_read_b128 v[200:203], v150 offset:53248
	ds_read_b128 v[204:207], v150 offset:54272
	ds_read_b128 v[208:211], v150 offset:55296
	ds_read_b128 v[212:215], v150 offset:56320
	global_load_lds_dwordx4 v134, s[34:35]
	s_add_i32 m0, s53, 0x2000
	s_add_u32 s30, s30, 0xc000
	v_lshl_add_u64 v[216:217], s[34:35], 0, v[130:131]
	s_addc_u32 s31, s31, 0
	s_add_i32 s34, s61, s36
	global_load_lds_dwordx4 v[216:217], off
	s_mov_b32 m0, s34
	s_nop 0
	global_load_lds_dwordx4 v134, s[30:31]
	s_add_i32 m0, s34, 0x2000
	s_nop 0
	global_load_lds_dwordx4 v130, s[30:31]
	s_mov_b32 m0, s42
	s_nop 0
	global_load_lds_dwordx4 v136, s[28:29]
	s_mov_b32 m0, s43
	s_nop 0
	global_load_lds_dwordx4 v132, s[28:29]
	s_waitcnt vmcnt(8)
	s_waitcnt lgkmcnt(0)
	s_barrier
	s_setprio 1
	s_waitcnt lgkmcnt(0)
	v_mfma_f32_16x16x32_bf16 v[58:61], v[152:155], v[184:187], v[58:61]
	v_mfma_f32_16x16x32_bf16 v[54:57], v[160:163], v[184:187], v[54:57]
	v_mfma_f32_16x16x32_bf16 v[42:45], v[152:155], v[192:195], v[42:45]
	v_mfma_f32_16x16x32_bf16 v[38:41], v[160:163], v[192:195], v[38:41]
	v_mfma_f32_16x16x32_bf16 v[26:29], v[152:155], v[200:203], v[26:29]
	v_mfma_f32_16x16x32_bf16 v[22:25], v[160:163], v[200:203], v[22:25]
	v_mfma_f32_16x16x32_bf16 v[10:13], v[152:155], v[208:211], v[10:13]
	v_mfma_f32_16x16x32_bf16 v[6:9], v[160:163], v[208:211], v[6:9]
	v_mfma_f32_16x16x32_bf16 v[58:61], v[156:159], v[188:191], v[58:61]
	v_mfma_f32_16x16x32_bf16 v[54:57], v[164:167], v[188:191], v[54:57]
	v_mfma_f32_16x16x32_bf16 v[42:45], v[156:159], v[196:199], v[42:45]
	v_mfma_f32_16x16x32_bf16 v[38:41], v[164:167], v[196:199], v[38:41]
	v_mfma_f32_16x16x32_bf16 v[26:29], v[156:159], v[204:207], v[26:29]
	v_mfma_f32_16x16x32_bf16 v[22:25], v[164:167], v[204:207], v[22:25]
	v_mfma_f32_16x16x32_bf16 v[10:13], v[156:159], v[212:215], v[10:13]
	v_mfma_f32_16x16x32_bf16 v[6:9], v[164:167], v[212:215], v[6:9]
	s_setprio 0
	s_setprio 1
	v_mfma_f32_16x16x32_bf16 v[62:65], v[168:171], v[184:187], v[62:65]
	v_mfma_f32_16x16x32_bf16 v[50:53], v[176:179], v[184:187], v[50:53]
	v_mfma_f32_16x16x32_bf16 v[46:49], v[168:171], v[192:195], v[46:49]
	v_mfma_f32_16x16x32_bf16 v[34:37], v[176:179], v[192:195], v[34:37]
	v_mfma_f32_16x16x32_bf16 v[30:33], v[168:171], v[200:203], v[30:33]
	v_mfma_f32_16x16x32_bf16 v[18:21], v[176:179], v[200:203], v[18:21]
	v_mfma_f32_16x16x32_bf16 v[14:17], v[168:171], v[208:211], v[14:17]
	v_mfma_f32_16x16x32_bf16 v[2:5], v[176:179], v[208:211], v[2:5]
	v_mfma_f32_16x16x32_bf16 v[62:65], v[172:175], v[188:191], v[62:65]
	v_mfma_f32_16x16x32_bf16 v[50:53], v[180:183], v[188:191], v[50:53]
	v_mfma_f32_16x16x32_bf16 v[46:49], v[172:175], v[196:199], v[46:49]
	v_mfma_f32_16x16x32_bf16 v[34:37], v[180:183], v[196:199], v[34:37]
	v_mfma_f32_16x16x32_bf16 v[30:33], v[172:175], v[204:207], v[30:33]
	v_mfma_f32_16x16x32_bf16 v[18:21], v[180:183], v[204:207], v[18:21]
	v_mfma_f32_16x16x32_bf16 v[14:17], v[172:175], v[212:215], v[14:17]
	v_mfma_f32_16x16x32_bf16 v[2:5], v[180:183], v[212:215], v[2:5]
	s_setprio 0
	s_barrier
	s_add_i32 s52, s52, 2
	s_add_u32 s26, s26, 0x100
	s_addc_u32 s27, s27, 0
	s_add_u32 s50, s50, 0x10000
	s_addc_u32 s51, s51, 0
	s_cmp_gt_u32 s52, 29
	s_cbranch_scc0 .LBB0_2138
	s_and_b64 vcc, exec, s[6:7]
	s_cbranch_vccz .LBB0_2141
	s_barrier

; #define PG8_STAGE(bufoff, gbase, voff) do { _Pragma("unroll") for (int _i = 0; _i < 2; ++_i) \
;         __builtin_amdgcn_global_load_lds((const unsigned*)((const char*)(gbase) + (voff)[_i]), (LAS unsigned*)(lds + (bufoff) + ldsw + _i * 8192), 16, 0, 0); } while (0)
; #define PG8_WAIT_V(n) asm volatile("s_waitcnt vmcnt(" #n ")" ::: "memory")
; #define PG8_BAR __builtin_amdgcn_s_barrier()
; template <class Epi, class Sched, bool ABLK = false, bool ALIGN_EPI = true, bool SP2 = true, bool BBLK = true>
; __device__ __forceinline__ void gemm_phase(LAS unsigned char* lds, const Gemm g, const Sched& S, const Epi& E) {
;     ...
;     const unsigned ldsw = (unsigned)wid * 1024u;
;     const int aoff = lds_byte(wr * 64 + fr, fq * 8), boff = lds_byte(wc * 32 + fr, fq * 8);
;     ...
;     if constexpr (SP2) {
;         PG8_STAGE(PG8_SB(0, 0), cB, voffB); PG8_STAGE(PG8_SB(0, 1), cB + hstepB, voffB); PG8_STAGE(PG8_SA(0, 0), cA, voffA); PG8_STAGE(PG8_SA(0, 1), cA + hstepA, voffA);
;         if (wr == 1) PG8_BAR;
;         PG8_WAIT_V(2); PG8_BAR;
;         PG8_STAGE(PG8_SB(1, 0), cB + kstepB, voffB); PG8_STAGE(PG8_SA(1, 0), a_tile(uA, tbA + 1), voffA); PG8_STAGE(PG8_SB(1, 1), cB + hstepB + kstepB, voffB);
;         PG8_WAIT_V(6); PG8_BAR;
.LBB0_2257:
	s_and_b32 s47, s10, 3
	s_lshl_b32 s12, s3, 13
	s_lshl_b32 s13, s47, 12
	s_add_u32 s10, s28, 0x8000
	s_addc_u32 s11, s29, 0
	s_add_i32 m0, s25, 0x18000
	v_lshl_add_u64 v[12:13], s[10:11], 0, v[134:135]
	s_waitcnt vmcnt(2)
	s_barrier
	global_load_lds_dwordx4 v[12:13], off
	v_lshl_add_u64 v[12:13], s[10:11], 0, v[130:131]
	s_add_i32 m0, s25, 0x1a000
	s_mov_b64 s[10:11], 0x80
	s_add_i32 s48, s25, 0x8000
	global_load_lds_dwordx4 v[12:13], off
	v_lshl_add_u64 v[2:3], v[2:3], 0, s[10:11]
	s_mov_b32 m0, s48
	s_add_i32 s49, s25, 0xa000
	global_load_lds_dwordx4 v[2:3], off
	v_lshl_add_u64 v[2:3], v[4:5], 0, s[10:11]
	s_add_u32 s10, s28, 0xc000
	s_mov_b32 m0, s49
	s_addc_u32 s11, s29, 0
	global_load_lds_dwordx4 v[2:3], off
	s_add_i32 m0, s25, 0x1c000
	s_nop 0
	global_load_lds_dwordx4 v134, s[10:11]
	s_add_i32 m0, s25, 0x1e000
	v_lshrrev_b32_e32 v4, 1, v1
	global_load_lds_dwordx4 v130, s[10:11]
	v_and_b32_e32 v4, 24, v4
	v_and_b32_e32 v3, 15, v1
	v_lshlrev_b32_e32 v5, 1, v4
	v_lshl_or_b32 v2, s3, 6, v3
	v_lshl_or_b32 v5, v3, 6, v5
	s_cmpk_lt_u32 s2, 0x100
	v_cmp_lt_u32_e64 s[2:3], 7, v3
	v_mov_b32_e32 v3, 0xfffffc40
	v_or_b32_e32 v12, 16, v2
	v_cndmask_b32_e64 v140, 0, v3, s[2:3]
	v_mov_b32_e32 v3, 0x400
	v_cndmask_b32_e64 v142, v3, 64, s[2:3]
	v_ashrrev_i32_e32 v3, 31, v2
	v_ashrrev_i32_e32 v13, 31, v12
	v_lshlrev_b64 v[144:145], 7, v[2:3]
	v_lshlrev_b64 v[146:147], 7, v[12:13]
	v_or_b32_e32 v12, 32, v2
	v_or_b32_e32 v2, 48, v2
	v_ashrrev_i32_e32 v3, 31, v2
	v_lshlrev_b64 v[150:151], 7, v[2:3]
	v_lshlrev_b32_e32 v2, 15, v9
	v_and_b32_e32 v2, 0xffff0000, v2
	v_lshl_add_u32 v2, v10, 12, v2
	v_and_b32_e32 v3, 1, v9
	v_lshl_or_b32 v2, v3, 6, v2
	v_lshl_add_u64 v[152:153], v[144:145], 0, s[4:5]
	s_mov_b64 s[4:5], 0x4800
	v_lshl_add_u32 v138, v11, 1, v2
	v_lshlrev_b32_e32 v2, 15, v6
	v_lshl_add_u64 v[154:155], v[144:145], 0, s[4:5]
	s_mov_b64 s[4:5], 0x5000
	v_and_b32_e32 v2, 0xffff0000, v2
	v_lshlrev_b32_e32 v1, 2, v1
	v_lshl_add_u64 v[156:157], v[144:145], 0, s[4:5]
	s_mov_b64 s[4:5], 0x5800
	v_lshl_add_u32 v2, v7, 12, v2
	v_and_b32_e32 v3, 1, v6
	v_and_b32_e32 v1, 32, v1
	s_waitcnt vmcnt(6)
	v_lshl_add_u64 v[158:159], v[144:145], 0, s[4:5]
	s_mov_b64 s[4:5], 0x80080
	v_lshl_or_b32 v2, v3, 6, v2
	v_bitop3_b32 v14, v5, s12, v1 bitop3:0xde
	v_bitop3_b32 v1, v5, s13, v1 bitop3:0xde
	s_cselect_b64 s[10:11], -1, 0
	v_ashrrev_i32_e32 v13, 31, v12
	v_lshl_add_u64 v[160:161], v[138:139], 0, s[4:5]
	v_lshl_add_u32 v138, v8, 1, v2
	s_add_i32 s52, s72, s40
	v_cndmask_b32_e64 v141, 0, -1, s[2:3]
	v_mov_b32_e32 v143, v139
	v_lshlrev_b64 v[148:149], 7, v[12:13]
	v_lshl_add_u64 v[162:163], v[138:139], 0, s[4:5]
	v_add_u32_e32 v168, s72, v1
	v_add_u32_e32 v169, s73, v1
	v_add_u32_e32 v170, 0, v14
	v_lshlrev_b32_e32 v138, 1, v4
	s_add_i32 s50, s25, 0xc000
	s_add_i32 s51, s25, 0xe000
	s_add_i32 s53, s52, 0x2000
	s_barrier
	s_branch .LBB0_2260

; #define PG8_STAGE(bufoff, gbase, voff) do { _Pragma("unroll") for (int _i = 0; _i < 2; ++_i) \
;         __builtin_amdgcn_global_load_lds((const unsigned*)((const char*)(gbase) + (voff)[_i]), (LAS unsigned*)(lds + (bufoff) + ldsw + _i * 8192), 16, 0, 0); } while (0)
; #define PG8_LDA(dst, b, h) do { _Pragma("unroll") for (int m = 0; m < 4; ++m) _Pragma("unroll") for (int k = 0; k < 2; ++k) dst[m][k] = *(const LAS bf16x8*)(lds + PG8_SA(b, h) + aoff + m * 2048 + k * 1024); } while (0)
; #define PG8_LDB(dst, b, h) do { _Pragma("unroll") for (int n = 0; n < 2; ++n) _Pragma("unroll") for (int k = 0; k < 2; ++k) dst[n][k] = *(const LAS bf16x8*)(lds + PG8_SB(b, h) + boff + n * 2048 + k * 1024); } while (0)
; #define PG8_MMA(ai, bj, At, Bt) do { __builtin_amdgcn_s_setprio(1); _Pragma("unroll") for (int m = 0; m < 4; ++m) _Pragma("unroll") for (int n = 0; n < 2; ++n) _Pragma("unroll") for (int k = 0; k < 2; ++k) \
;         acc[ai][bj][m][n] = __builtin_amdgcn_mfma_f32_16x16x32_bf16(Bt[n][k], At[m][k], acc[ai][bj][m][n], 0, 0, 0); __builtin_amdgcn_s_setprio(0); } while (0)
; #define PG8_WAIT_V(n) asm volatile("s_waitcnt vmcnt(" #n ")" ::: "memory")
; template <class Epi, class Sched, bool ABLK = false, bool ALIGN_EPI = true, bool SP2 = true, bool BBLK = true>
; __device__ __forceinline__ void gemm_phase(LAS unsigned char* lds, const Gemm g, const Sched& S, const Epi& E) {
;     ...
;         for (int t = 0; t < nt; t += 2) {
;             const bool last = (t == nt - 2);
;             const char* a1 = a_tile(uA, tbA + t + 1);
;             const char* a2 = last ? a_tile(nuA, ntbA) : a_tile(uA, tbA + t + 2); const char* b2 = last ? nB : cB + (size_t)(t + 2) * kstepB;
;             const char* a3 = last ? a_tile(nuA, ntbA + 1) : a_tile(uA, tbA + t + 3); const char* b3 = b2 + kstepB;
;             if (last && has_next) S.a_ready(nxt);
;             if constexpr (SP2) {
;             PG8_LDB(B0, 0, 0); PG8_LDB(B1, 0, 1); PG8_SCHED; PG8_LDA(At, 0, 0); PG8_STAGE(PG8_SA(1, 1), a1 + hstepA, voffA);
;             PG8_WAIT_V(8); PG8_WAIT_L(0); PG8_BAR; PG8_MMA(0, 0, At, B0); PG8_MMA(0, 1, At, B1); PG8_BAR; PG8_SCHED;
;             PG8_LDA(At, 0, 1); PG8_STAGE(PG8_SB(0, 0), b2, voffB); PG8_STAGE(PG8_SB(0, 1), b2 + hstepB, voffB); PG8_STAGE(PG8_SA(0, 0), a2, voffA);
;             PG8_WAIT_V(8); PG8_WAIT_L(0); PG8_BAR; PG8_MMA(1, 0, At, B0); PG8_MMA(1, 1, At, B1); PG8_BAR; PG8_SCHED;
.LBB0_2263:
	ds_read_b128 v[172:175], v168
	ds_read_b128 v[176:179], v168 offset:1024
	ds_read_b128 v[180:183], v168 offset:2048
	ds_read_b128 v[184:187], v168 offset:3072
	ds_read_b128 v[188:191], v169
	ds_read_b128 v[192:195], v169 offset:1024
	ds_read_b128 v[196:199], v169 offset:2048
	ds_read_b128 v[200:203], v169 offset:3072
	s_add_u32 s30, s26, s28
	s_addc_u32 s31, s27, s29
	s_add_u32 s36, s30, 0x100
	s_addc_u32 s37, s31, 0
	s_add_u32 s30, s30, 0x180
	s_addc_u32 s31, s31, 0
	s_cmpk_eq_i32 s28, 0xf00
	s_cselect_b32 s31, s54, s31
	s_cselect_b32 s30, s23, s30
	s_cselect_b32 s35, s13, s56
	s_cselect_b32 s34, s15, s55
	s_cselect_b32 s37, s4, s37
	s_cselect_b32 s36, s5, s36
	s_mov_b32 m0, s50
	v_lshl_add_u64 v[236:237], v[164:165], 0, s[28:29]
	ds_read_b128 v[204:207], v170
	ds_read_b128 v[208:211], v170 offset:1024
	ds_read_b128 v[212:215], v170 offset:2048
	ds_read_b128 v[216:219], v170 offset:3072
	ds_read_b128 v[220:223], v170 offset:4096
	ds_read_b128 v[224:227], v170 offset:5120
	ds_read_b128 v[228:231], v170 offset:6144
	ds_read_b128 v[232:235], v170 offset:7168
	global_load_lds_dwordx4 v[236:237], off
	v_lshl_add_u64 v[236:237], v[166:167], 0, s[28:29]
	s_mov_b32 m0, s51
	s_nop 0
	global_load_lds_dwordx4 v[236:237], off
	s_waitcnt vmcnt(8)
	s_waitcnt lgkmcnt(0)
	s_barrier
	s_setprio 1
	s_waitcnt lgkmcnt(0)
	v_mfma_f32_16x16x32_bf16 v[126:129], v[172:175], v[204:207], v[126:129]
	v_mfma_f32_16x16x32_bf16 v[122:125], v[180:183], v[204:207], v[122:125]
	v_mfma_f32_16x16x32_bf16 v[110:113], v[172:175], v[212:215], v[110:113]
	v_mfma_f32_16x16x32_bf16 v[106:109], v[180:183], v[212:215], v[106:109]
	v_mfma_f32_16x16x32_bf16 v[94:97], v[172:175], v[220:223], v[94:97]
	v_mfma_f32_16x16x32_bf16 v[90:93], v[180:183], v[220:223], v[90:93]
	v_mfma_f32_16x16x32_bf16 v[78:81], v[172:175], v[228:231], v[78:81]
	v_mfma_f32_16x16x32_bf16 v[74:77], v[180:183], v[228:231], v[74:77]
	v_mfma_f32_16x16x32_bf16 v[126:129], v[176:179], v[208:211], v[126:129]
	v_mfma_f32_16x16x32_bf16 v[122:125], v[184:187], v[208:211], v[122:125]
	v_mfma_f32_16x16x32_bf16 v[110:113], v[176:179], v[216:219], v[110:113]
	v_mfma_f32_16x16x32_bf16 v[106:109], v[184:187], v[216:219], v[106:109]
	v_mfma_f32_16x16x32_bf16 v[94:97], v[176:179], v[224:227], v[94:97]
	v_mfma_f32_16x16x32_bf16 v[90:93], v[184:187], v[224:227], v[90:93]
	v_mfma_f32_16x16x32_bf16 v[78:81], v[176:179], v[232:235], v[78:81]
	v_mfma_f32_16x16x32_bf16 v[74:77], v[184:187], v[232:235], v[74:77]
	s_setprio 0
	s_setprio 1
	v_mfma_f32_16x16x32_bf16 v[118:121], v[188:191], v[204:207], v[118:121]
	v_mfma_f32_16x16x32_bf16 v[114:117], v[196:199], v[204:207], v[114:117]
	v_mfma_f32_16x16x32_bf16 v[102:105], v[188:191], v[212:215], v[102:105]
	v_mfma_f32_16x16x32_bf16 v[98:101], v[196:199], v[212:215], v[98:101]
	v_mfma_f32_16x16x32_bf16 v[86:89], v[188:191], v[220:223], v[86:89]
	v_mfma_f32_16x16x32_bf16 v[82:85], v[196:199], v[220:223], v[82:85]
	v_mfma_f32_16x16x32_bf16 v[70:73], v[188:191], v[228:231], v[70:73]
	v_mfma_f32_16x16x32_bf16 v[66:69], v[196:199], v[228:231], v[66:69]
	v_mfma_f32_16x16x32_bf16 v[118:121], v[192:195], v[208:211], v[118:121]
	v_mfma_f32_16x16x32_bf16 v[114:117], v[200:203], v[208:211], v[114:117]
	v_mfma_f32_16x16x32_bf16 v[102:105], v[192:195], v[216:219], v[102:105]
	v_mfma_f32_16x16x32_bf16 v[98:101], v[200:203], v[216:219], v[98:101]
	v_mfma_f32_16x16x32_bf16 v[86:89], v[192:195], v[224:227], v[86:89]
	v_mfma_f32_16x16x32_bf16 v[82:85], v[200:203], v[224:227], v[82:85]
	v_mfma_f32_16x16x32_bf16 v[70:73], v[192:195], v[232:235], v[70:73]
	v_mfma_f32_16x16x32_bf16 v[66:69], v[200:203], v[232:235], v[66:69]
	s_setprio 0
	s_barrier
	s_mov_b32 m0, s52
	s_add_u32 s58, s34, 0x4000
	ds_read_b128 v[204:207], v170 offset:16384
	ds_read_b128 v[208:211], v170 offset:17408
	ds_read_b128 v[212:215], v170 offset:18432
	ds_read_b128 v[216:219], v170 offset:19456
	ds_read_b128 v[220:223], v170 offset:20480
	ds_read_b128 v[224:227], v170 offset:21504
	ds_read_b128 v[228:231], v170 offset:22528
	ds_read_b128 v[232:235], v170 offset:23552
	global_load_lds_dwordx4 v134, s[34:35]
	s_mov_b32 m0, s53
	s_addc_u32 s59, s35, 0
	s_add_i32 s62, s73, s40
	global_load_lds_dwordx4 v130, s[34:35]
	s_mov_b32 m0, s62
	s_nop 0
	global_load_lds_dwordx4 v134, s[58:59]
	s_add_i32 m0, s62, 0x2000
	s_nop 0
	global_load_lds_dwordx4 v130, s[58:59]
	s_mov_b32 m0, s25
	s_nop 0
	global_load_lds_dwordx4 v136, s[36:37]
	s_mov_b32 m0, s43
	s_nop 0
	global_load_lds_dwordx4 v132, s[36:37]
	s_waitcnt vmcnt(8)
	s_waitcnt lgkmcnt(0)
	s_barrier
; #define PG8_STAGE(bufoff, gbase, voff) do { _Pragma("unroll") for (int _i = 0; _i < 2; ++_i) \
;         __builtin_amdgcn_global_load_lds((const unsigned*)((const char*)(gbase) + (voff)[_i]), (LAS unsigned*)(lds + (bufoff) + ldsw + _i * 8192), 16, 0, 0); } while (0)
; #define PG8_LDA(dst, b, h) do { _Pragma("unroll") for (int m = 0; m < 4; ++m) _Pragma("unroll") for (int k = 0; k < 2; ++k) dst[m][k] = *(const LAS bf16x8*)(lds + PG8_SA(b, h) + aoff + m * 2048 + k * 1024); } while (0)
; #define PG8_LDB(dst, b, h) do { _Pragma("unroll") for (int n = 0; n < 2; ++n) _Pragma("unroll") for (int k = 0; k < 2; ++k) dst[n][k] = *(const LAS bf16x8*)(lds + PG8_SB(b, h) + boff + n * 2048 + k * 1024); } while (0)
; #define PG8_MMA(ai, bj, At, Bt) do { __builtin_amdgcn_s_setprio(1); _Pragma("unroll") for (int m = 0; m < 4; ++m) _Pragma("unroll") for (int n = 0; n < 2; ++n) _Pragma("unroll") for (int k = 0; k < 2; ++k) \
;         acc[ai][bj][m][n] = __builtin_amdgcn_mfma_f32_16x16x32_bf16(Bt[n][k], At[m][k], acc[ai][bj][m][n], 0, 0, 0); __builtin_amdgcn_s_setprio(0); } while (0)
; #define PG8_WAIT_V(n) asm volatile("s_waitcnt vmcnt(" #n ")" ::: "memory")
; #define PG8_WAIT_L(n) asm volatile("s_waitcnt lgkmcnt(" #n ")" ::: "memory")
; #define PG8_BAR __builtin_amdgcn_s_barrier()
; #define PG8_SCHED __builtin_amdgcn_sched_barrier(0)
; template <class Epi, class Sched, bool ABLK = false, bool ALIGN_EPI = true, bool SP2 = true, bool BBLK = true>
; __device__ __forceinline__ void gemm_phase(LAS unsigned char* lds, const Gemm g, const Sched& S, const Epi& E) {
;     ...
;             PG8_WAIT_V(8); PG8_WAIT_L(0); PG8_BAR; PG8_MMA(1, 0, At, B0); PG8_MMA(1, 1, At, B1); PG8_BAR; PG8_SCHED;
;             PG8_LDB(B0, 1, 0); PG8_LDB(B1, 1, 1); PG8_SCHED; PG8_LDA(At, 1, 0); PG8_STAGE(PG8_SA(0, 1), a2 + hstepA, voffA);
;             PG8_WAIT_V(8); PG8_WAIT_L(0); PG8_BAR; PG8_MMA(0, 0, At, B0); PG8_MMA(0, 1, At, B1); PG8_BAR; PG8_SCHED;
	s_setprio 1
	s_waitcnt lgkmcnt(0)
	v_mfma_f32_16x16x32_bf16 v[62:65], v[172:175], v[204:207], v[62:65]
	v_mfma_f32_16x16x32_bf16 v[58:61], v[180:183], v[204:207], v[58:61]
	v_mfma_f32_16x16x32_bf16 v[46:49], v[172:175], v[212:215], v[46:49]
	v_mfma_f32_16x16x32_bf16 v[42:45], v[180:183], v[212:215], v[42:45]
	v_mfma_f32_16x16x32_bf16 v[30:33], v[172:175], v[220:223], v[30:33]
	v_mfma_f32_16x16x32_bf16 v[26:29], v[180:183], v[220:223], v[26:29]
	v_mfma_f32_16x16x32_bf16 v[14:17], v[172:175], v[228:231], v[14:17]
	v_mfma_f32_16x16x32_bf16 v[10:13], v[180:183], v[228:231], v[10:13]
	v_mfma_f32_16x16x32_bf16 v[62:65], v[176:179], v[208:211], v[62:65]
	v_mfma_f32_16x16x32_bf16 v[58:61], v[184:187], v[208:211], v[58:61]
	v_mfma_f32_16x16x32_bf16 v[46:49], v[176:179], v[216:219], v[46:49]
	v_mfma_f32_16x16x32_bf16 v[42:45], v[184:187], v[216:219], v[42:45]
	v_mfma_f32_16x16x32_bf16 v[30:33], v[176:179], v[224:227], v[30:33]
	v_mfma_f32_16x16x32_bf16 v[26:29], v[184:187], v[224:227], v[26:29]
	v_mfma_f32_16x16x32_bf16 v[14:17], v[176:179], v[232:235], v[14:17]
	v_mfma_f32_16x16x32_bf16 v[10:13], v[184:187], v[232:235], v[10:13]
	s_setprio 0
	s_setprio 1
	v_mfma_f32_16x16x32_bf16 v[54:57], v[188:191], v[204:207], v[54:57]
	v_mfma_f32_16x16x32_bf16 v[50:53], v[196:199], v[204:207], v[50:53]
	v_mfma_f32_16x16x32_bf16 v[38:41], v[188:191], v[212:215], v[38:41]
	v_mfma_f32_16x16x32_bf16 v[34:37], v[196:199], v[212:215], v[34:37]
	v_mfma_f32_16x16x32_bf16 v[22:25], v[188:191], v[220:223], v[22:25]
	v_mfma_f32_16x16x32_bf16 v[18:21], v[196:199], v[220:223], v[18:21]
	v_mfma_f32_16x16x32_bf16 v[6:9], v[188:191], v[228:231], v[6:9]
	v_mfma_f32_16x16x32_bf16 v[2:5], v[196:199], v[228:231], v[2:5]
	v_mfma_f32_16x16x32_bf16 v[54:57], v[192:195], v[208:211], v[54:57]
	v_mfma_f32_16x16x32_bf16 v[50:53], v[200:203], v[208:211], v[50:53]
	v_mfma_f32_16x16x32_bf16 v[38:41], v[192:195], v[216:219], v[38:41]
	v_mfma_f32_16x16x32_bf16 v[34:37], v[200:203], v[216:219], v[34:37]
	v_mfma_f32_16x16x32_bf16 v[22:25], v[192:195], v[224:227], v[22:25]
	v_mfma_f32_16x16x32_bf16 v[18:21], v[200:203], v[224:227], v[18:21]
	v_mfma_f32_16x16x32_bf16 v[6:9], v[192:195], v[232:235], v[6:9]
	v_mfma_f32_16x16x32_bf16 v[2:5], v[200:203], v[232:235], v[2:5]
	s_setprio 0
	s_barrier
	v_add_u32_e32 v171, s60, v1
	ds_read_b128 v[172:175], v171
	ds_read_b128 v[176:179], v171 offset:1024
	ds_read_b128 v[180:183], v171 offset:2048
	ds_read_b128 v[184:187], v171 offset:3072
	v_add_u32_e32 v171, s61, v1
	ds_read_b128 v[188:191], v171
	ds_read_b128 v[192:195], v171 offset:1024
	ds_read_b128 v[196:199], v171 offset:2048
	ds_read_b128 v[200:203], v171 offset:3072
	s_add_u32 s36, s36, 0x80000
	s_addc_u32 s37, s37, 0
	s_mov_b32 m0, s44
	ds_read_b128 v[204:207], v170 offset:32768
	ds_read_b128 v[208:211], v170 offset:33792
	ds_read_b128 v[212:215], v170 offset:34816
	ds_read_b128 v[216:219], v170 offset:35840
	ds_read_b128 v[220:223], v170 offset:36864
	ds_read_b128 v[224:227], v170 offset:37888
	ds_read_b128 v[228:231], v170 offset:38912
	ds_read_b128 v[232:235], v170 offset:39936
	global_load_lds_dwordx4 v136, s[36:37]
	s_mov_b32 m0, s45
	s_nop 0
	global_load_lds_dwordx4 v132, s[36:37]
	s_waitcnt vmcnt(8)
	s_waitcnt lgkmcnt(0)
	s_barrier
	s_setprio 1
	s_waitcnt lgkmcnt(0)
	v_mfma_f32_16x16x32_bf16 v[126:129], v[172:175], v[204:207], v[126:129]
	v_mfma_f32_16x16x32_bf16 v[122:125], v[180:183], v[204:207], v[122:125]
	v_mfma_f32_16x16x32_bf16 v[110:113], v[172:175], v[212:215], v[110:113]
	v_mfma_f32_16x16x32_bf16 v[106:109], v[180:183], v[212:215], v[106:109]
	v_mfma_f32_16x16x32_bf16 v[94:97], v[172:175], v[220:223], v[94:97]
	v_mfma_f32_16x16x32_bf16 v[90:93], v[180:183], v[220:223], v[90:93]
	v_mfma_f32_16x16x32_bf16 v[78:81], v[172:175], v[228:231], v[78:81]
	v_mfma_f32_16x16x32_bf16 v[74:77], v[180:183], v[228:231], v[74:77]
	v_mfma_f32_16x16x32_bf16 v[126:129], v[176:179], v[208:211], v[126:129]
	v_mfma_f32_16x16x32_bf16 v[122:125], v[184:187], v[208:211], v[122:125]
	v_mfma_f32_16x16x32_bf16 v[110:113], v[176:179], v[216:219], v[110:113]
	v_mfma_f32_16x16x32_bf16 v[106:109], v[184:187], v[216:219], v[106:109]
	v_mfma_f32_16x16x32_bf16 v[94:97], v[176:179], v[224:227], v[94:97]
	v_mfma_f32_16x16x32_bf16 v[90:93], v[184:187], v[224:227], v[90:93]
	v_mfma_f32_16x16x32_bf16 v[78:81], v[176:179], v[232:235], v[78:81]
	v_mfma_f32_16x16x32_bf16 v[74:77], v[184:187], v[232:235], v[74:77]
	s_setprio 0
	s_setprio 1
	v_mfma_f32_16x16x32_bf16 v[118:121], v[188:191], v[204:207], v[118:121]
	v_mfma_f32_16x16x32_bf16 v[114:117], v[196:199], v[204:207], v[114:117]
	v_mfma_f32_16x16x32_bf16 v[102:105], v[188:191], v[212:215], v[102:105]
	v_mfma_f32_16x16x32_bf16 v[98:101], v[196:199], v[212:215], v[98:101]
	v_mfma_f32_16x16x32_bf16 v[86:89], v[188:191], v[220:223], v[86:89]
	v_mfma_f32_16x16x32_bf16 v[82:85], v[196:199], v[220:223], v[82:85]
	v_mfma_f32_16x16x32_bf16 v[70:73], v[188:191], v[228:231], v[70:73]
	v_mfma_f32_16x16x32_bf16 v[66:69], v[196:199], v[228:231], v[66:69]
	v_mfma_f32_16x16x32_bf16 v[118:121], v[192:195], v[208:211], v[118:121]
	v_mfma_f32_16x16x32_bf16 v[114:117], v[200:203], v[208:211], v[114:117]
	v_mfma_f32_16x16x32_bf16 v[102:105], v[192:195], v[216:219], v[102:105]
	v_mfma_f32_16x16x32_bf16 v[98:101], v[200:203], v[216:219], v[98:101]
	v_mfma_f32_16x16x32_bf16 v[86:89], v[192:195], v[224:227], v[86:89]
	v_mfma_f32_16x16x32_bf16 v[82:85], v[200:203], v[224:227], v[82:85]
	v_mfma_f32_16x16x32_bf16 v[70:73], v[192:195], v[232:235], v[70:73]
	v_mfma_f32_16x16x32_bf16 v[66:69], v[200:203], v[232:235], v[66:69]
	s_setprio 0
	s_barrier
; #define PG8_STAGE(bufoff, gbase, voff) do { _Pragma("unroll") for (int _i = 0; _i < 2; ++_i) \
;         __builtin_amdgcn_global_load_lds((const unsigned*)((const char*)(gbase) + (voff)[_i]), (LAS unsigned*)(lds + (bufoff) + ldsw + _i * 8192), 16, 0, 0); } while (0)
; #define PG8_LDA(dst, b, h) do { _Pragma("unroll") for (int m = 0; m < 4; ++m) _Pragma("unroll") for (int k = 0; k < 2; ++k) dst[m][k] = *(const LAS bf16x8*)(lds + PG8_SA(b, h) + aoff + m * 2048 + k * 1024); } while (0)
; #define PG8_MMA(ai, bj, At, Bt) do { __builtin_amdgcn_s_setprio(1); _Pragma("unroll") for (int m = 0; m < 4; ++m) _Pragma("unroll") for (int n = 0; n < 2; ++n) _Pragma("unroll") for (int k = 0; k < 2; ++k) \
;         acc[ai][bj][m][n] = __builtin_amdgcn_mfma_f32_16x16x32_bf16(Bt[n][k], At[m][k], acc[ai][bj][m][n], 0, 0, 0); __builtin_amdgcn_s_setprio(0); } while (0)
; #define PG8_WAIT_V(n) asm volatile("s_waitcnt vmcnt(" #n ")" ::: "memory")
; #define PG8_WAIT_L(n) asm volatile("s_waitcnt lgkmcnt(" #n ")" ::: "memory")
; #define PG8_BAR __builtin_amdgcn_s_barrier()
; #define PG8_SCHED __builtin_amdgcn_sched_barrier(0)
; template <class Epi, class Sched, bool ABLK = false, bool ALIGN_EPI = true, bool SP2 = true, bool BBLK = true>
; __device__ __forceinline__ void gemm_phase(LAS unsigned char* lds, const Gemm g, const Sched& S, const Epi& E) {
;     ...
;         for (int t = 0; t < nt; t += 2) {
;     ...
;             PG8_LDA(At, 1, 1); PG8_STAGE(PG8_SB(1, 0), b3, voffB); PG8_STAGE(PG8_SB(1, 1), b3 + hstepB, voffB); PG8_STAGE(PG8_SA(1, 0), a3, voffA);
;             PG8_WAIT_V(8); PG8_WAIT_L(0); PG8_BAR; PG8_MMA(1, 0, At, B0); PG8_MMA(1, 1, At, B1); PG8_BAR; PG8_SCHED;
	s_add_u32 s36, s34, 0x8000
	s_addc_u32 s37, s35, 0
	s_add_i32 s58, s60, s40
	s_mov_b32 m0, s58
	ds_read_b128 v[204:207], v170 offset:49152
	ds_read_b128 v[208:211], v170 offset:50176
	ds_read_b128 v[212:215], v170 offset:51200
	ds_read_b128 v[216:219], v170 offset:52224
	ds_read_b128 v[220:223], v170 offset:53248
	ds_read_b128 v[224:227], v170 offset:54272
	ds_read_b128 v[228:231], v170 offset:55296
	ds_read_b128 v[232:235], v170 offset:56320
	global_load_lds_dwordx4 v134, s[36:37]
	s_add_i32 m0, s58, 0x2000
	s_add_u32 s34, s34, 0xc000
	v_lshl_add_u64 v[236:237], s[36:37], 0, v[130:131]
	s_addc_u32 s35, s35, 0
	s_add_i32 s36, s61, s40
	global_load_lds_dwordx4 v[236:237], off
	s_mov_b32 m0, s36
	s_nop 0
	global_load_lds_dwordx4 v134, s[34:35]
	s_add_i32 m0, s36, 0x2000
	s_nop 0
	global_load_lds_dwordx4 v130, s[34:35]
	s_mov_b32 m0, s48
	s_nop 0
	global_load_lds_dwordx4 v136, s[30:31]
	s_mov_b32 m0, s49
	s_nop 0
	global_load_lds_dwordx4 v132, s[30:31]
	s_waitcnt vmcnt(8)
	s_waitcnt lgkmcnt(0)
	s_barrier
	s_setprio 1
	s_waitcnt lgkmcnt(0)
	v_mfma_f32_16x16x32_bf16 v[62:65], v[172:175], v[204:207], v[62:65]
	v_mfma_f32_16x16x32_bf16 v[58:61], v[180:183], v[204:207], v[58:61]
	v_mfma_f32_16x16x32_bf16 v[46:49], v[172:175], v[212:215], v[46:49]
	v_mfma_f32_16x16x32_bf16 v[42:45], v[180:183], v[212:215], v[42:45]
	v_mfma_f32_16x16x32_bf16 v[30:33], v[172:175], v[220:223], v[30:33]
	v_mfma_f32_16x16x32_bf16 v[26:29], v[180:183], v[220:223], v[26:29]
	v_mfma_f32_16x16x32_bf16 v[14:17], v[172:175], v[228:231], v[14:17]
	v_mfma_f32_16x16x32_bf16 v[10:13], v[180:183], v[228:231], v[10:13]
	v_mfma_f32_16x16x32_bf16 v[62:65], v[176:179], v[208:211], v[62:65]
	v_mfma_f32_16x16x32_bf16 v[58:61], v[184:187], v[208:211], v[58:61]
	v_mfma_f32_16x16x32_bf16 v[46:49], v[176:179], v[216:219], v[46:49]
	v_mfma_f32_16x16x32_bf16 v[42:45], v[184:187], v[216:219], v[42:45]
	v_mfma_f32_16x16x32_bf16 v[30:33], v[176:179], v[224:227], v[30:33]
	v_mfma_f32_16x16x32_bf16 v[26:29], v[184:187], v[224:227], v[26:29]
	v_mfma_f32_16x16x32_bf16 v[14:17], v[176:179], v[232:235], v[14:17]
	v_mfma_f32_16x16x32_bf16 v[10:13], v[184:187], v[232:235], v[10:13]
	s_setprio 0
	s_setprio 1
	v_mfma_f32_16x16x32_bf16 v[54:57], v[188:191], v[204:207], v[54:57]
	v_mfma_f32_16x16x32_bf16 v[50:53], v[196:199], v[204:207], v[50:53]
	v_mfma_f32_16x16x32_bf16 v[38:41], v[188:191], v[212:215], v[38:41]
	v_mfma_f32_16x16x32_bf16 v[34:37], v[196:199], v[212:215], v[34:37]
	v_mfma_f32_16x16x32_bf16 v[22:25], v[188:191], v[220:223], v[22:25]
	v_mfma_f32_16x16x32_bf16 v[18:21], v[196:199], v[220:223], v[18:21]
	v_mfma_f32_16x16x32_bf16 v[6:9], v[188:191], v[228:231], v[6:9]
	v_mfma_f32_16x16x32_bf16 v[2:5], v[196:199], v[228:231], v[2:5]
	v_mfma_f32_16x16x32_bf16 v[54:57], v[192:195], v[208:211], v[54:57]
	v_mfma_f32_16x16x32_bf16 v[50:53], v[200:203], v[208:211], v[50:53]
	v_mfma_f32_16x16x32_bf16 v[38:41], v[192:195], v[216:219], v[38:41]
	v_mfma_f32_16x16x32_bf16 v[34:37], v[200:203], v[216:219], v[34:37]
	v_mfma_f32_16x16x32_bf16 v[22:25], v[192:195], v[224:227], v[22:25]
	v_mfma_f32_16x16x32_bf16 v[18:21], v[200:203], v[224:227], v[18:21]
	v_mfma_f32_16x16x32_bf16 v[6:9], v[192:195], v[232:235], v[6:9]
	v_mfma_f32_16x16x32_bf16 v[2:5], v[200:203], v[232:235], v[2:5]
	s_setprio 0
	s_barrier
	s_add_i32 s57, s57, 2
	s_add_u32 s28, s28, 0x100
	s_addc_u32 s29, s29, 0
	s_add_u32 s55, s55, 0x10000
	s_addc_u32 s56, s56, 0
	s_cmp_gt_u32 s57, 29
	s_cbranch_scc0 .LBB0_2263
	s_and_b64 vcc, exec, s[10:11]
	s_cbranch_vccz .LBB0_2266
	s_barrier

; #define PG8_STAGE(bufoff, gbase, voff) do { _Pragma("unroll") for (int _i = 0; _i < 2; ++_i) \
;         __builtin_amdgcn_global_load_lds((const unsigned*)((const char*)(gbase) + (voff)[_i]), (LAS unsigned*)(lds + (bufoff) + ldsw + _i * 8192), 16, 0, 0); } while (0)
; #define PG8_WAIT_V(n) asm volatile("s_waitcnt vmcnt(" #n ")" ::: "memory")
; #define PG8_BAR __builtin_amdgcn_s_barrier()
; template <class Epi, class Sched, bool ABLK = false, bool ALIGN_EPI = true, bool SP2 = true, bool BBLK = true>
; __device__ __forceinline__ void gemm_phase(LAS unsigned char* lds, const Gemm g, const Sched& S, const Epi& E) {
;     ...
;     const unsigned ldsw = (unsigned)wid * 1024u;
;     const int aoff = lds_byte(wr * 64 + fr, fq * 8), boff = lds_byte(wc * 32 + fr, fq * 8);
;     ...
;     if constexpr (SP2) {
;         PG8_STAGE(PG8_SB(0, 0), cB, voffB); PG8_STAGE(PG8_SB(0, 1), cB + hstepB, voffB); PG8_STAGE(PG8_SA(0, 0), cA, voffA); PG8_STAGE(PG8_SA(0, 1), cA + hstepA, voffA);
;         if (wr == 1) PG8_BAR;
;         PG8_WAIT_V(2); PG8_BAR;
;         PG8_STAGE(PG8_SB(1, 0), cB + kstepB, voffB); PG8_STAGE(PG8_SA(1, 0), a_tile(uA, tbA + 1), voffA); PG8_STAGE(PG8_SB(1, 1), cB + hstepB + kstepB, voffB);
;         PG8_WAIT_V(6); PG8_BAR;
.LBB0_2324:
	s_and_b32 s6, s4, 3
	s_lshl_b32 s7, s3, 13
	s_lshl_b32 s14, s6, 12
	s_add_u32 s12, s68, 0x3c900000
	s_addc_u32 s13, s69, 0
	s_add_u32 s4, s38, 0x8000
	s_addc_u32 s5, s39, 0
	s_add_i32 m0, s49, 0x18000
	v_lshl_add_u64 v[10:11], s[4:5], 0, v[130:131]
	s_waitcnt vmcnt(2)
	s_barrier
	global_load_lds_dwordx4 v[10:11], off
	s_add_i32 m0, s49, 0x1a000
	v_lshl_add_u64 v[10:11], s[4:5], 0, v[132:133]
	s_add_u32 s4, s40, 0x8000
	s_addc_u32 s5, s41, 0
	s_add_i32 s53, s49, 0x8000
	global_load_lds_dwordx4 v[10:11], off
	s_mov_b32 m0, s53
	s_add_i32 s54, s49, 0xa000
	global_load_lds_dwordx4 v130, s[4:5]
	v_lshl_add_u64 v[10:11], s[4:5], 0, v[132:133]
	s_add_u32 s4, s38, 0xc000
	s_mov_b32 m0, s54
	s_addc_u32 s5, s39, 0
	global_load_lds_dwordx4 v[10:11], off
	s_add_i32 m0, s49, 0x1c000
	s_nop 0
	global_load_lds_dwordx4 v130, s[4:5]
	s_add_i32 m0, s49, 0x1e000
	v_and_b32_e32 v9, 15, v4
	global_load_lds_dwordx4 v132, s[4:5]
	v_lshrrev_b32_e32 v10, 1, v4
	v_and_b32_e32 v10, 24, v10
	v_lshlrev_b32_e32 v11, 1, v10
	v_lshl_or_b32 v1, s3, 6, v9
	v_lshl_or_b32 v11, v9, 6, v11
	s_cmpk_lt_u32 s2, 0x100
	v_cmp_lt_u32_e64 s[2:3], 7, v9
	v_mov_b32_e32 v9, 0xffff8040
	s_mov_b64 s[4:5], 0xc000
	v_cndmask_b32_e64 v134, 0, v9, s[2:3]
	v_mov_b32_e32 v9, 0x8000
	v_cndmask_b32_e64 v136, v9, 64, s[2:3]
	v_lshlrev_b32_e32 v9, 10, v2
	v_and_b32_e32 v9, 0xfffff800, v9
	v_lshl_add_u32 v3, v3, 7, v9
	v_and_b32_e32 v2, 1, v2
	v_lshl_or_b32 v2, v2, 6, v3
	v_lshl_add_u32 v2, v5, 1, v2
	v_mov_b32_e32 v3, v131
	v_lshl_add_u64 v[138:139], v[2:3], 0, s[4:5]
	v_lshlrev_b32_e32 v2, 10, v6
	v_and_b32_e32 v2, 0xfffff800, v2
	v_lshlrev_b32_e32 v4, 2, v4
	v_lshl_add_u32 v2, v7, 7, v2
	v_and_b32_e32 v3, 1, v6
	v_and_b32_e32 v4, 32, v4
	s_waitcnt vmcnt(6)
	v_lshl_or_b32 v2, v3, 6, v2
	v_bitop3_b32 v146, v11, s14, v4 bitop3:0xde
	v_bitop3_b32 v4, v11, s7, v4 bitop3:0xde
	v_lshl_add_u32 v2, v8, 1, v2
	v_mov_b32_e32 v3, v131
	s_cselect_b64 s[14:15], -1, 0
	v_cndmask_b32_e64 v135, 0, -1, s[2:3]
	v_mov_b32_e32 v137, v131
	v_lshl_or_b32 v147, s6, 6, v10
	v_lshl_add_u64 v[140:141], v[2:3], 0, s[4:5]
	s_mov_b64 s[4:5], -1
	s_movk_i32 s56, 0x80
	s_mov_b64 s[16:17], 0x10000
	v_add_u32_e32 v148, s72, v146
	v_add_u32_e32 v149, s73, v146
	v_add_u32_e32 v150, 0, v4
	s_mov_b64 s[18:19], 0x20000
	s_mov_b64 s[20:21], 0x30000
	s_mov_b64 s[22:23], 0x80000
	s_mov_b64 s[24:25], 0x90000
	s_mov_b64 s[26:27], 0xa0000
	s_mov_b64 s[28:29], 0xb0000
	s_mov_b32 s42, 0
	s_barrier
	s_branch .LBB0_2327

; #define PG8_STAGE(bufoff, gbase, voff) do { _Pragma("unroll") for (int _i = 0; _i < 2; ++_i) \
;         __builtin_amdgcn_global_load_lds((const unsigned*)((const char*)(gbase) + (voff)[_i]), (LAS unsigned*)(lds + (bufoff) + ldsw + _i * 8192), 16, 0, 0); } while (0)
; #define PG8_LDA(dst, b, h) do { _Pragma("unroll") for (int m = 0; m < 4; ++m) _Pragma("unroll") for (int k = 0; k < 2; ++k) dst[m][k] = *(const LAS bf16x8*)(lds + PG8_SA(b, h) + aoff + m * 2048 + k * 1024); } while (0)
; #define PG8_LDB(dst, b, h) do { _Pragma("unroll") for (int n = 0; n < 2; ++n) _Pragma("unroll") for (int k = 0; k < 2; ++k) dst[n][k] = *(const LAS bf16x8*)(lds + PG8_SB(b, h) + boff + n * 2048 + k * 1024); } while (0)
; #define PG8_MMA(ai, bj, At, Bt) do { __builtin_amdgcn_s_setprio(1); _Pragma("unroll") for (int m = 0; m < 4; ++m) _Pragma("unroll") for (int n = 0; n < 2; ++n) _Pragma("unroll") for (int k = 0; k < 2; ++k) \
;         acc[ai][bj][m][n] = __builtin_amdgcn_mfma_f32_16x16x32_bf16(Bt[n][k], At[m][k], acc[ai][bj][m][n], 0, 0, 0); __builtin_amdgcn_s_setprio(0); } while (0)
; #define PG8_WAIT_V(n) asm volatile("s_waitcnt vmcnt(" #n ")" ::: "memory")
; template <class Epi, class Sched, bool ABLK = false, bool ALIGN_EPI = true, bool SP2 = true, bool BBLK = true>
; __device__ __forceinline__ void gemm_phase(LAS unsigned char* lds, const Gemm g, const Sched& S, const Epi& E) {
;     ...
;         for (int t = 0; t < nt; t += 2) {
;             const bool last = (t == nt - 2);
;             const char* a1 = a_tile(uA, tbA + t + 1);
;             const char* a2 = last ? a_tile(nuA, ntbA) : a_tile(uA, tbA + t + 2); const char* b2 = last ? nB : cB + (size_t)(t + 2) * kstepB;
;             const char* a3 = last ? a_tile(nuA, ntbA + 1) : a_tile(uA, tbA + t + 3); const char* b3 = b2 + kstepB;
;             if (last && has_next) S.a_ready(nxt);
;             if constexpr (SP2) {
;             PG8_LDB(B0, 0, 0); PG8_LDB(B1, 0, 1); PG8_SCHED; PG8_LDA(At, 0, 0); PG8_STAGE(PG8_SA(1, 1), a1 + hstepA, voffA);
;             PG8_WAIT_V(8); PG8_WAIT_L(0); PG8_BAR; PG8_MMA(0, 0, At, B0); PG8_MMA(0, 1, At, B1); PG8_BAR; PG8_SCHED;
;             PG8_LDA(At, 0, 1); PG8_STAGE(PG8_SB(0, 0), b2, voffB); PG8_STAGE(PG8_SB(0, 1), b2 + hstepB, voffB); PG8_STAGE(PG8_SA(0, 0), a2, voffA);
;             PG8_WAIT_V(8); PG8_WAIT_L(0); PG8_BAR; PG8_MMA(1, 0, At, B0); PG8_MMA(1, 1, At, B1); PG8_BAR; PG8_SCHED;
.LBB0_2328:
	ds_read_b128 v[152:155], v148
	ds_read_b128 v[156:159], v148 offset:1024
	ds_read_b128 v[160:163], v148 offset:2048
	ds_read_b128 v[164:167], v148 offset:3072
	ds_read_b128 v[168:171], v149
	ds_read_b128 v[172:175], v149 offset:1024
	ds_read_b128 v[176:179], v149 offset:2048
	ds_read_b128 v[180:183], v149 offset:3072
	s_add_u32 s40, s64, s38
	s_addc_u32 s41, s65, s39
	s_add_u32 s44, s40, 0x10000
	s_addc_u32 s45, s41, 0
	s_add_i32 s67, s67, 2
	s_add_u32 s42, s62, s38
	s_addc_u32 s43, s63, s39
	s_add_u32 s40, s40, 0x18000
	s_addc_u32 s41, s41, 0
	s_cmp_eq_u32 s66, s38
	s_cselect_b32 s41, s59, s41
	s_cselect_b32 s40, s58, s40
	s_cselect_b32 s43, s4, s43
	s_cselect_b32 s42, s5, s42
	s_cselect_b32 s45, s57, s45
	s_cselect_b32 s44, s35, s44
	v_lshl_add_u64 v[216:217], v[142:143], 0, s[38:39]
	s_add_i32 m0, s49, 0xc000
	ds_read_b128 v[184:187], v150
	ds_read_b128 v[188:191], v150 offset:1024
	ds_read_b128 v[192:195], v150 offset:2048
	ds_read_b128 v[196:199], v150 offset:3072
	ds_read_b128 v[200:203], v150 offset:4096
	ds_read_b128 v[204:207], v150 offset:5120
	ds_read_b128 v[208:211], v150 offset:6144
	ds_read_b128 v[212:215], v150 offset:7168
	global_load_lds_dwordx4 v[216:217], off
	v_lshl_add_u64 v[216:217], v[144:145], 0, s[38:39]
	s_add_i32 m0, s49, 0xe000
	s_nop 0
	global_load_lds_dwordx4 v[216:217], off
	s_waitcnt vmcnt(8)
	s_waitcnt lgkmcnt(0)
	s_barrier
	s_setprio 1
	s_waitcnt lgkmcnt(0)
	v_mfma_f32_16x16x32_bf16 v[126:129], v[152:155], v[184:187], v[126:129]
	v_mfma_f32_16x16x32_bf16 v[122:125], v[160:163], v[184:187], v[122:125]
	v_mfma_f32_16x16x32_bf16 v[110:113], v[152:155], v[192:195], v[110:113]
	v_mfma_f32_16x16x32_bf16 v[106:109], v[160:163], v[192:195], v[106:109]
	v_mfma_f32_16x16x32_bf16 v[94:97], v[152:155], v[200:203], v[94:97]
	v_mfma_f32_16x16x32_bf16 v[90:93], v[160:163], v[200:203], v[90:93]
	v_mfma_f32_16x16x32_bf16 v[78:81], v[152:155], v[208:211], v[78:81]
	v_mfma_f32_16x16x32_bf16 v[74:77], v[160:163], v[208:211], v[74:77]
	v_mfma_f32_16x16x32_bf16 v[126:129], v[156:159], v[188:191], v[126:129]
	v_mfma_f32_16x16x32_bf16 v[122:125], v[164:167], v[188:191], v[122:125]
	v_mfma_f32_16x16x32_bf16 v[110:113], v[156:159], v[196:199], v[110:113]
	v_mfma_f32_16x16x32_bf16 v[106:109], v[164:167], v[196:199], v[106:109]
	v_mfma_f32_16x16x32_bf16 v[94:97], v[156:159], v[204:207], v[94:97]
	v_mfma_f32_16x16x32_bf16 v[90:93], v[164:167], v[204:207], v[90:93]
	v_mfma_f32_16x16x32_bf16 v[78:81], v[156:159], v[212:215], v[78:81]
	v_mfma_f32_16x16x32_bf16 v[74:77], v[164:167], v[212:215], v[74:77]
	s_setprio 0
	s_setprio 1
	v_mfma_f32_16x16x32_bf16 v[118:121], v[168:171], v[184:187], v[118:121]
	v_mfma_f32_16x16x32_bf16 v[114:117], v[176:179], v[184:187], v[114:117]
	v_mfma_f32_16x16x32_bf16 v[102:105], v[168:171], v[192:195], v[102:105]
	v_mfma_f32_16x16x32_bf16 v[98:101], v[176:179], v[192:195], v[98:101]
	v_mfma_f32_16x16x32_bf16 v[86:89], v[168:171], v[200:203], v[86:89]
	v_mfma_f32_16x16x32_bf16 v[82:85], v[176:179], v[200:203], v[82:85]
	v_mfma_f32_16x16x32_bf16 v[70:73], v[168:171], v[208:211], v[70:73]
	v_mfma_f32_16x16x32_bf16 v[66:69], v[176:179], v[208:211], v[66:69]
	v_mfma_f32_16x16x32_bf16 v[118:121], v[172:175], v[188:191], v[118:121]
	v_mfma_f32_16x16x32_bf16 v[114:117], v[180:183], v[188:191], v[114:117]
	v_mfma_f32_16x16x32_bf16 v[102:105], v[172:175], v[196:199], v[102:105]
	v_mfma_f32_16x16x32_bf16 v[98:101], v[180:183], v[196:199], v[98:101]
	v_mfma_f32_16x16x32_bf16 v[86:89], v[172:175], v[204:207], v[86:89]
	v_mfma_f32_16x16x32_bf16 v[82:85], v[180:183], v[204:207], v[82:85]
	v_mfma_f32_16x16x32_bf16 v[70:73], v[172:175], v[212:215], v[70:73]
	v_mfma_f32_16x16x32_bf16 v[66:69], v[180:183], v[212:215], v[66:69]
	s_setprio 0
	s_barrier
	s_add_i32 s70, s72, s48
	s_mov_b32 m0, s70
	ds_read_b128 v[184:187], v150 offset:16384
	ds_read_b128 v[188:191], v150 offset:17408
	ds_read_b128 v[192:195], v150 offset:18432
	ds_read_b128 v[196:199], v150 offset:19456
	ds_read_b128 v[200:203], v150 offset:20480
	ds_read_b128 v[204:207], v150 offset:21504
	ds_read_b128 v[208:211], v150 offset:22528
	ds_read_b128 v[212:215], v150 offset:23552
	global_load_lds_dwordx4 v130, s[42:43]
	s_add_i32 m0, s70, 0x2000
	s_add_u32 s76, s42, 0x4000
	s_addc_u32 s77, s43, 0
	s_add_i32 s70, s73, s48
	global_load_lds_dwordx4 v132, s[42:43]
	s_mov_b32 m0, s70
	s_nop 0
	global_load_lds_dwordx4 v130, s[76:77]
	s_add_i32 m0, s70, 0x2000
	s_nop 0
	global_load_lds_dwordx4 v132, s[76:77]
	s_mov_b32 m0, s49
	s_nop 0
	global_load_lds_dwordx4 v130, s[44:45]
	s_mov_b32 m0, s50
	s_nop 0
	global_load_lds_dwordx4 v132, s[44:45]
	s_waitcnt vmcnt(8)
	s_waitcnt lgkmcnt(0)
	s_barrier
; #define PG8_STAGE(bufoff, gbase, voff) do { _Pragma("unroll") for (int _i = 0; _i < 2; ++_i) \
;         __builtin_amdgcn_global_load_lds((const unsigned*)((const char*)(gbase) + (voff)[_i]), (LAS unsigned*)(lds + (bufoff) + ldsw + _i * 8192), 16, 0, 0); } while (0)
; #define PG8_LDA(dst, b, h) do { _Pragma("unroll") for (int m = 0; m < 4; ++m) _Pragma("unroll") for (int k = 0; k < 2; ++k) dst[m][k] = *(const LAS bf16x8*)(lds + PG8_SA(b, h) + aoff + m * 2048 + k * 1024); } while (0)
; #define PG8_LDB(dst, b, h) do { _Pragma("unroll") for (int n = 0; n < 2; ++n) _Pragma("unroll") for (int k = 0; k < 2; ++k) dst[n][k] = *(const LAS bf16x8*)(lds + PG8_SB(b, h) + boff + n * 2048 + k * 1024); } while (0)
; #define PG8_MMA(ai, bj, At, Bt) do { __builtin_amdgcn_s_setprio(1); _Pragma("unroll") for (int m = 0; m < 4; ++m) _Pragma("unroll") for (int n = 0; n < 2; ++n) _Pragma("unroll") for (int k = 0; k < 2; ++k) \
;         acc[ai][bj][m][n] = __builtin_amdgcn_mfma_f32_16x16x32_bf16(Bt[n][k], At[m][k], acc[ai][bj][m][n], 0, 0, 0); __builtin_amdgcn_s_setprio(0); } while (0)
; #define PG8_WAIT_V(n) asm volatile("s_waitcnt vmcnt(" #n ")" ::: "memory")
; #define PG8_WAIT_L(n) asm volatile("s_waitcnt lgkmcnt(" #n ")" ::: "memory")
; #define PG8_BAR __builtin_amdgcn_s_barrier()
; #define PG8_SCHED __builtin_amdgcn_sched_barrier(0)
; template <class Epi, class Sched, bool ABLK = false, bool ALIGN_EPI = true, bool SP2 = true, bool BBLK = true>
; __device__ __forceinline__ void gemm_phase(LAS unsigned char* lds, const Gemm g, const Sched& S, const Epi& E) {
;     ...
;             PG8_WAIT_V(8); PG8_WAIT_L(0); PG8_BAR; PG8_MMA(1, 0, At, B0); PG8_MMA(1, 1, At, B1); PG8_BAR; PG8_SCHED;
;             PG8_LDB(B0, 1, 0); PG8_LDB(B1, 1, 1); PG8_SCHED; PG8_LDA(At, 1, 0); PG8_STAGE(PG8_SA(0, 1), a2 + hstepA, voffA);
;             PG8_WAIT_V(8); PG8_WAIT_L(0); PG8_BAR; PG8_MMA(0, 0, At, B0); PG8_MMA(0, 1, At, B1); PG8_BAR; PG8_SCHED;
	s_setprio 1
	s_waitcnt lgkmcnt(0)
	v_mfma_f32_16x16x32_bf16 v[62:65], v[152:155], v[184:187], v[62:65]
	v_mfma_f32_16x16x32_bf16 v[58:61], v[160:163], v[184:187], v[58:61]
	v_mfma_f32_16x16x32_bf16 v[46:49], v[152:155], v[192:195], v[46:49]
	v_mfma_f32_16x16x32_bf16 v[42:45], v[160:163], v[192:195], v[42:45]
	v_mfma_f32_16x16x32_bf16 v[30:33], v[152:155], v[200:203], v[30:33]
	v_mfma_f32_16x16x32_bf16 v[26:29], v[160:163], v[200:203], v[26:29]
	v_mfma_f32_16x16x32_bf16 v[14:17], v[152:155], v[208:211], v[14:17]
	v_mfma_f32_16x16x32_bf16 v[10:13], v[160:163], v[208:211], v[10:13]
	v_mfma_f32_16x16x32_bf16 v[62:65], v[156:159], v[188:191], v[62:65]
	v_mfma_f32_16x16x32_bf16 v[58:61], v[164:167], v[188:191], v[58:61]
	v_mfma_f32_16x16x32_bf16 v[46:49], v[156:159], v[196:199], v[46:49]
	v_mfma_f32_16x16x32_bf16 v[42:45], v[164:167], v[196:199], v[42:45]
	v_mfma_f32_16x16x32_bf16 v[30:33], v[156:159], v[204:207], v[30:33]
	v_mfma_f32_16x16x32_bf16 v[26:29], v[164:167], v[204:207], v[26:29]
	v_mfma_f32_16x16x32_bf16 v[14:17], v[156:159], v[212:215], v[14:17]
	v_mfma_f32_16x16x32_bf16 v[10:13], v[164:167], v[212:215], v[10:13]
	s_setprio 0
	s_setprio 1
	v_mfma_f32_16x16x32_bf16 v[54:57], v[168:171], v[184:187], v[54:57]
	v_mfma_f32_16x16x32_bf16 v[50:53], v[176:179], v[184:187], v[50:53]
	v_mfma_f32_16x16x32_bf16 v[38:41], v[168:171], v[192:195], v[38:41]
	v_mfma_f32_16x16x32_bf16 v[34:37], v[176:179], v[192:195], v[34:37]
	v_mfma_f32_16x16x32_bf16 v[22:25], v[168:171], v[200:203], v[22:25]
	v_mfma_f32_16x16x32_bf16 v[18:21], v[176:179], v[200:203], v[18:21]
	v_mfma_f32_16x16x32_bf16 v[6:9], v[168:171], v[208:211], v[6:9]
	v_mfma_f32_16x16x32_bf16 v[2:5], v[176:179], v[208:211], v[2:5]
	v_mfma_f32_16x16x32_bf16 v[54:57], v[172:175], v[188:191], v[54:57]
	v_mfma_f32_16x16x32_bf16 v[50:53], v[180:183], v[188:191], v[50:53]
	v_mfma_f32_16x16x32_bf16 v[38:41], v[172:175], v[196:199], v[38:41]
	v_mfma_f32_16x16x32_bf16 v[34:37], v[180:183], v[196:199], v[34:37]
	v_mfma_f32_16x16x32_bf16 v[22:25], v[172:175], v[204:207], v[22:25]
	v_mfma_f32_16x16x32_bf16 v[18:21], v[180:183], v[204:207], v[18:21]
	v_mfma_f32_16x16x32_bf16 v[6:9], v[172:175], v[212:215], v[6:9]
	v_mfma_f32_16x16x32_bf16 v[2:5], v[180:183], v[212:215], v[2:5]
	s_setprio 0
	s_barrier
	v_add_u32_e32 v151, s60, v146
	ds_read_b128 v[152:155], v151
	ds_read_b128 v[156:159], v151 offset:1024
	ds_read_b128 v[160:163], v151 offset:2048
	ds_read_b128 v[164:167], v151 offset:3072
	v_add_u32_e32 v151, s61, v146
	ds_read_b128 v[168:171], v151
	ds_read_b128 v[172:175], v151 offset:1024
	ds_read_b128 v[176:179], v151 offset:2048
	ds_read_b128 v[180:183], v151 offset:3072
	s_add_u32 s44, s44, 0x4000
	s_addc_u32 s45, s45, 0
	s_mov_b32 m0, s51
	ds_read_b128 v[184:187], v150 offset:32768
	ds_read_b128 v[188:191], v150 offset:33792
	ds_read_b128 v[192:195], v150 offset:34816
	ds_read_b128 v[196:199], v150 offset:35840
	ds_read_b128 v[200:203], v150 offset:36864
	ds_read_b128 v[204:207], v150 offset:37888
	ds_read_b128 v[208:211], v150 offset:38912
	ds_read_b128 v[212:215], v150 offset:39936
	global_load_lds_dwordx4 v130, s[44:45]
	s_mov_b32 m0, s52
	s_nop 0
	global_load_lds_dwordx4 v132, s[44:45]
	s_waitcnt vmcnt(8)
	s_waitcnt lgkmcnt(0)
	s_barrier
	s_setprio 1
	s_waitcnt lgkmcnt(0)
	v_mfma_f32_16x16x32_bf16 v[126:129], v[152:155], v[184:187], v[126:129]
	v_mfma_f32_16x16x32_bf16 v[122:125], v[160:163], v[184:187], v[122:125]
	v_mfma_f32_16x16x32_bf16 v[110:113], v[152:155], v[192:195], v[110:113]
	v_mfma_f32_16x16x32_bf16 v[106:109], v[160:163], v[192:195], v[106:109]
	v_mfma_f32_16x16x32_bf16 v[94:97], v[152:155], v[200:203], v[94:97]
	v_mfma_f32_16x16x32_bf16 v[90:93], v[160:163], v[200:203], v[90:93]
	v_mfma_f32_16x16x32_bf16 v[78:81], v[152:155], v[208:211], v[78:81]
	v_mfma_f32_16x16x32_bf16 v[74:77], v[160:163], v[208:211], v[74:77]
	v_mfma_f32_16x16x32_bf16 v[126:129], v[156:159], v[188:191], v[126:129]
	v_mfma_f32_16x16x32_bf16 v[122:125], v[164:167], v[188:191], v[122:125]
	v_mfma_f32_16x16x32_bf16 v[110:113], v[156:159], v[196:199], v[110:113]
	v_mfma_f32_16x16x32_bf16 v[106:109], v[164:167], v[196:199], v[106:109]
	v_mfma_f32_16x16x32_bf16 v[94:97], v[156:159], v[204:207], v[94:97]
	v_mfma_f32_16x16x32_bf16 v[90:93], v[164:167], v[204:207], v[90:93]
	v_mfma_f32_16x16x32_bf16 v[78:81], v[156:159], v[212:215], v[78:81]
	v_mfma_f32_16x16x32_bf16 v[74:77], v[164:167], v[212:215], v[74:77]
	s_setprio 0
	s_setprio 1
	v_mfma_f32_16x16x32_bf16 v[118:121], v[168:171], v[184:187], v[118:121]
	v_mfma_f32_16x16x32_bf16 v[114:117], v[176:179], v[184:187], v[114:117]
	v_mfma_f32_16x16x32_bf16 v[102:105], v[168:171], v[192:195], v[102:105]
	v_mfma_f32_16x16x32_bf16 v[98:101], v[176:179], v[192:195], v[98:101]
	v_mfma_f32_16x16x32_bf16 v[86:89], v[168:171], v[200:203], v[86:89]
	v_mfma_f32_16x16x32_bf16 v[82:85], v[176:179], v[200:203], v[82:85]
	v_mfma_f32_16x16x32_bf16 v[70:73], v[168:171], v[208:211], v[70:73]
	v_mfma_f32_16x16x32_bf16 v[66:69], v[176:179], v[208:211], v[66:69]
	v_mfma_f32_16x16x32_bf16 v[118:121], v[172:175], v[188:191], v[118:121]
	v_mfma_f32_16x16x32_bf16 v[114:117], v[180:183], v[188:191], v[114:117]
	v_mfma_f32_16x16x32_bf16 v[102:105], v[172:175], v[196:199], v[102:105]
	v_mfma_f32_16x16x32_bf16 v[98:101], v[180:183], v[196:199], v[98:101]
	v_mfma_f32_16x16x32_bf16 v[86:89], v[172:175], v[204:207], v[86:89]
	v_mfma_f32_16x16x32_bf16 v[82:85], v[180:183], v[204:207], v[82:85]
	v_mfma_f32_16x16x32_bf16 v[70:73], v[172:175], v[212:215], v[70:73]
	v_mfma_f32_16x16x32_bf16 v[66:69], v[180:183], v[212:215], v[66:69]
	s_setprio 0
	s_barrier
; #define PG8_STAGE(bufoff, gbase, voff) do { _Pragma("unroll") for (int _i = 0; _i < 2; ++_i) \
;         __builtin_amdgcn_global_load_lds((const unsigned*)((const char*)(gbase) + (voff)[_i]), (LAS unsigned*)(lds + (bufoff) + ldsw + _i * 8192), 16, 0, 0); } while (0)
; #define PG8_LDA(dst, b, h) do { _Pragma("unroll") for (int m = 0; m < 4; ++m) _Pragma("unroll") for (int k = 0; k < 2; ++k) dst[m][k] = *(const LAS bf16x8*)(lds + PG8_SA(b, h) + aoff + m * 2048 + k * 1024); } while (0)
; #define PG8_MMA(ai, bj, At, Bt) do { __builtin_amdgcn_s_setprio(1); _Pragma("unroll") for (int m = 0; m < 4; ++m) _Pragma("unroll") for (int n = 0; n < 2; ++n) _Pragma("unroll") for (int k = 0; k < 2; ++k) \
;         acc[ai][bj][m][n] = __builtin_amdgcn_mfma_f32_16x16x32_bf16(Bt[n][k], At[m][k], acc[ai][bj][m][n], 0, 0, 0); __builtin_amdgcn_s_setprio(0); } while (0)
; #define PG8_WAIT_V(n) asm volatile("s_waitcnt vmcnt(" #n ")" ::: "memory")
; #define PG8_WAIT_L(n) asm volatile("s_waitcnt lgkmcnt(" #n ")" ::: "memory")
; #define PG8_BAR __builtin_amdgcn_s_barrier()
; #define PG8_SCHED __builtin_amdgcn_sched_barrier(0)
; template <class Epi, class Sched, bool ABLK = false, bool ALIGN_EPI = true, bool SP2 = true, bool BBLK = true>
; __device__ __forceinline__ void gemm_phase(LAS unsigned char* lds, const Gemm g, const Sched& S, const Epi& E) {
;     ...
;         for (int t = 0; t < nt; t += 2) {
;     ...
;             PG8_LDA(At, 1, 1); PG8_STAGE(PG8_SB(1, 0), b3, voffB); PG8_STAGE(PG8_SB(1, 1), b3 + hstepB, voffB); PG8_STAGE(PG8_SA(1, 0), a3, voffA);
;             PG8_WAIT_V(8); PG8_WAIT_L(0); PG8_BAR; PG8_MMA(1, 0, At, B0); PG8_MMA(1, 1, At, B1); PG8_BAR; PG8_SCHED;
	s_add_u32 s44, s42, 0x8000
	s_addc_u32 s45, s43, 0
	s_add_i32 s70, s60, s48
	s_mov_b32 m0, s70
	ds_read_b128 v[184:187], v150 offset:49152
	ds_read_b128 v[188:191], v150 offset:50176
	ds_read_b128 v[192:195], v150 offset:51200
	ds_read_b128 v[196:199], v150 offset:52224
	ds_read_b128 v[200:203], v150 offset:53248
	ds_read_b128 v[204:207], v150 offset:54272
	ds_read_b128 v[208:211], v150 offset:55296
	ds_read_b128 v[212:215], v150 offset:56320
	global_load_lds_dwordx4 v130, s[44:45]
	s_add_i32 m0, s70, 0x2000
	s_add_u32 s42, s42, 0xc000
	v_lshl_add_u64 v[216:217], s[44:45], 0, v[132:133]
	s_addc_u32 s43, s43, 0
	s_add_i32 s44, s61, s48
	global_load_lds_dwordx4 v[216:217], off
	s_mov_b32 m0, s44
	s_nop 0
	global_load_lds_dwordx4 v130, s[42:43]
	s_add_i32 m0, s44, 0x2000
	s_nop 0
	global_load_lds_dwordx4 v132, s[42:43]
	s_mov_b32 m0, s53
	s_nop 0
	global_load_lds_dwordx4 v130, s[40:41]
	s_mov_b32 m0, s54
	s_nop 0
	global_load_lds_dwordx4 v132, s[40:41]
	s_waitcnt vmcnt(8)
	s_waitcnt lgkmcnt(0)
	s_barrier
	s_setprio 1
	s_waitcnt lgkmcnt(0)
	v_mfma_f32_16x16x32_bf16 v[62:65], v[152:155], v[184:187], v[62:65]
	v_mfma_f32_16x16x32_bf16 v[58:61], v[160:163], v[184:187], v[58:61]
	v_mfma_f32_16x16x32_bf16 v[46:49], v[152:155], v[192:195], v[46:49]
	v_mfma_f32_16x16x32_bf16 v[42:45], v[160:163], v[192:195], v[42:45]
	v_mfma_f32_16x16x32_bf16 v[30:33], v[152:155], v[200:203], v[30:33]
	v_mfma_f32_16x16x32_bf16 v[26:29], v[160:163], v[200:203], v[26:29]
	v_mfma_f32_16x16x32_bf16 v[14:17], v[152:155], v[208:211], v[14:17]
	v_mfma_f32_16x16x32_bf16 v[10:13], v[160:163], v[208:211], v[10:13]
	v_mfma_f32_16x16x32_bf16 v[62:65], v[156:159], v[188:191], v[62:65]
	v_mfma_f32_16x16x32_bf16 v[58:61], v[164:167], v[188:191], v[58:61]
	v_mfma_f32_16x16x32_bf16 v[46:49], v[156:159], v[196:199], v[46:49]
	v_mfma_f32_16x16x32_bf16 v[42:45], v[164:167], v[196:199], v[42:45]
	v_mfma_f32_16x16x32_bf16 v[30:33], v[156:159], v[204:207], v[30:33]
	v_mfma_f32_16x16x32_bf16 v[26:29], v[164:167], v[204:207], v[26:29]
	v_mfma_f32_16x16x32_bf16 v[14:17], v[156:159], v[212:215], v[14:17]
	v_mfma_f32_16x16x32_bf16 v[10:13], v[164:167], v[212:215], v[10:13]
	s_setprio 0
	s_setprio 1
	v_mfma_f32_16x16x32_bf16 v[54:57], v[168:171], v[184:187], v[54:57]
	v_mfma_f32_16x16x32_bf16 v[50:53], v[176:179], v[184:187], v[50:53]
	v_mfma_f32_16x16x32_bf16 v[38:41], v[168:171], v[192:195], v[38:41]
	v_mfma_f32_16x16x32_bf16 v[34:37], v[176:179], v[192:195], v[34:37]
	v_mfma_f32_16x16x32_bf16 v[22:25], v[168:171], v[200:203], v[22:25]
	v_mfma_f32_16x16x32_bf16 v[18:21], v[176:179], v[200:203], v[18:21]
	v_mfma_f32_16x16x32_bf16 v[6:9], v[168:171], v[208:211], v[6:9]
	v_mfma_f32_16x16x32_bf16 v[2:5], v[176:179], v[208:211], v[2:5]
	v_mfma_f32_16x16x32_bf16 v[54:57], v[172:175], v[188:191], v[54:57]
	v_mfma_f32_16x16x32_bf16 v[50:53], v[180:183], v[188:191], v[50:53]
	v_mfma_f32_16x16x32_bf16 v[38:41], v[172:175], v[196:199], v[38:41]
	v_mfma_f32_16x16x32_bf16 v[34:37], v[180:183], v[196:199], v[34:37]
	v_mfma_f32_16x16x32_bf16 v[22:25], v[172:175], v[204:207], v[22:25]
	v_mfma_f32_16x16x32_bf16 v[18:21], v[180:183], v[204:207], v[18:21]
	v_mfma_f32_16x16x32_bf16 v[6:9], v[172:175], v[212:215], v[6:9]
	v_mfma_f32_16x16x32_bf16 v[2:5], v[180:183], v[212:215], v[2:5]
	s_setprio 0
	s_barrier
	s_add_u32 s38, s38, 0x10000
	s_addc_u32 s39, s39, 0
	s_cmp_ge_u32 s67, s56
	s_cbranch_scc0 .LBB0_2328
	s_and_b64 vcc, exec, s[14:15]
	s_cbranch_vccz .LBB0_2331
	s_barrier
